# GEMM K-loops: inverted setprio (priority raised in the load/stage section, lowered in the MFMA block)
# baseline (speedup 1.0000x reference)
; #define PG8_STAGE(bufoff, gbase, voff) do { _Pragma("unroll") for (int _i = 0; _i < 2; ++_i) \
;         __builtin_amdgcn_global_load_lds((const unsigned*)((const char*)(gbase) + (voff)[_i]), (PG8_LAS unsigned*)(lds + (bufoff) + ldsw + _i * 8192), 16, 0, 0); } while (0)
; #define PG8_LDA(dst, b, h) do { _Pragma("unroll") for (int m = 0; m < 4; ++m) _Pragma("unroll") for (int k = 0; k < 2; ++k) dst[m][k] = *(const PG8_LAS bf16x8*)(lds + PG8_SA(b, h) + aoff + m * 2048 + k * 1024); } while (0)
; #define PG8_LDB(dst, b, h) do { _Pragma("unroll") for (int n = 0; n < 2; ++n) _Pragma("unroll") for (int k = 0; k < 2; ++k) dst[n][k] = *(const PG8_LAS bf16x8*)(lds + PG8_SB(b, h) + boff + n * 2048 + k * 1024); } while (0)
; #define PG8_MMA(ai, bj, At, Bt) do { __builtin_amdgcn_s_setprio(1); _Pragma("unroll") for (int m = 0; m < 4; ++m) _Pragma("unroll") for (int n = 0; n < 2; ++n) _Pragma("unroll") for (int k = 0; k < 2; ++k) \
;         acc[ai][bj][m][n] = __builtin_amdgcn_mfma_f32_16x16x32_bf16(Bt[n][k], At[m][k], acc[ai][bj][m][n], 0, 0, 0); __builtin_amdgcn_s_setprio(0); } while (0)
; #define PG8_WAIT_L(n) asm volatile("s_waitcnt lgkmcnt(" #n ")" ::: "memory")
; #define PG8_BAR __builtin_amdgcn_s_barrier()
; #define PG8_SCHED __builtin_amdgcn_sched_barrier(0)
; template <class Epi, class Sched>
; __device__ __forceinline__ void gemm_phase(PG8_LAS unsigned char* lds, const Gemm g, const Sched& S, const Epi& E) {
;     ...
;             PG8_LDB(B0, 0, 0); PG8_SCHED; PG8_LDA(At, 0, 0); PG8_STAGE(PG8_SA(1, 1), a1 + hstep, voffA);
;             PG8_WAIT_L(8); PG8_BAR; PG8_WAIT_L(0); PG8_MMA(0, 0, At, B0); PG8_BAR; PG8_SCHED;
;             PG8_LDB(B1, 0, 1); PG8_STAGE(PG8_SB(0, 0), b2, voffB);
;             PG8_BAR; PG8_WAIT_L(0); PG8_MMA(0, 1, At, B1); PG8_BAR;
;             PG8_LDA(At, 0, 1); PG8_STAGE(PG8_SA(0, 0), a2, voffA);
;             PG8_BAR; PG8_WAIT_L(0); PG8_MMA(1, 0, At, B0); PG8_BAR; PG8_SCHED;
.LBB0_195:
	ds_read_b128 v[144:147], v151
	ds_read_b128 v[156:159], v151 offset:1024
	ds_read_b128 v[160:163], v151 offset:2048
	ds_read_b128 v[166:169], v151 offset:3072
	s_add_u32 s30, s28, 0xfffc0080
	s_addc_u32 s31, s29, -1
	s_cmp_eq_u32 s58, 12
	s_cselect_b32 s35, s17, s31
	s_cselect_b32 s34, s54, s30
	s_cselect_b32 s31, s15, s57
	s_cselect_b32 s30, s55, s56
	v_lshl_add_u64 v[174:175], s[28:29], 0, v[136:137]
	s_add_i32 m0, s27, 0xc000
	ds_read_b128 v[170:173], v153
	ds_read_b128 v[182:185], v153 offset:1024
	ds_read_b128 v[190:193], v153 offset:2048
	ds_read_b128 v[194:197], v153 offset:3072
	ds_read_b128 v[198:201], v153 offset:4096
	ds_read_b128 v[202:205], v153 offset:5120
	ds_read_b128 v[206:209], v153 offset:6144
	ds_read_b128 v[210:213], v153 offset:7168
	global_load_lds_dwordx4 v[174:175], off
	v_lshl_add_u64 v[174:175], s[28:29], 0, v[138:139]
	s_add_i32 m0, s27, 0xe000
	s_nop 0
	global_load_lds_dwordx4 v[174:175], off
	s_waitcnt lgkmcnt(8)
	s_barrier
	s_waitcnt lgkmcnt(0)
	s_setprio 0
	s_waitcnt lgkmcnt(0)
	v_mfma_f32_16x16x32_bf16 v[124:127], v[144:147], v[170:173], v[124:127]
	v_mfma_f32_16x16x32_bf16 v[120:123], v[160:163], v[170:173], v[120:123]
	v_mfma_f32_16x16x32_bf16 v[108:111], v[144:147], v[190:193], v[108:111]
	v_mfma_f32_16x16x32_bf16 v[104:107], v[160:163], v[190:193], v[104:107]
	v_mfma_f32_16x16x32_bf16 v[92:95], v[144:147], v[198:201], v[92:95]
	v_mfma_f32_16x16x32_bf16 v[88:91], v[160:163], v[198:201], v[88:91]
	v_mfma_f32_16x16x32_bf16 v[76:79], v[144:147], v[206:209], v[76:79]
	v_mfma_f32_16x16x32_bf16 v[72:75], v[160:163], v[206:209], v[72:75]
	v_mfma_f32_16x16x32_bf16 v[124:127], v[156:159], v[182:185], v[124:127]
	v_mfma_f32_16x16x32_bf16 v[120:123], v[166:169], v[182:185], v[120:123]
	v_mfma_f32_16x16x32_bf16 v[108:111], v[156:159], v[194:197], v[108:111]
	v_mfma_f32_16x16x32_bf16 v[104:107], v[166:169], v[194:197], v[104:107]
	v_mfma_f32_16x16x32_bf16 v[92:95], v[156:159], v[202:205], v[92:95]
	v_mfma_f32_16x16x32_bf16 v[88:91], v[166:169], v[202:205], v[88:91]
	v_mfma_f32_16x16x32_bf16 v[76:79], v[156:159], v[210:213], v[76:79]
	v_mfma_f32_16x16x32_bf16 v[72:75], v[166:169], v[210:213], v[72:75]
	s_setprio 1
	s_barrier
	s_add_i32 s59, s50, s40
	v_lshl_add_u64 v[174:175], s[30:31], 0, v[132:133]
	s_mov_b32 m0, s59
	ds_read_b128 v[214:217], v154
	ds_read_b128 v[218:221], v154 offset:1024
	ds_read_b128 v[222:225], v154 offset:2048
	ds_read_b128 v[226:229], v154 offset:3072
	global_load_lds_dwordx4 v[174:175], off
	v_lshl_add_u64 v[178:179], s[30:31], 0, v[128:129]
	s_add_i32 m0, s59, 0x2000
	s_nop 0
	global_load_lds_dwordx4 v[178:179], off
	s_barrier
	s_waitcnt lgkmcnt(0)
	s_setprio 0
	s_waitcnt lgkmcnt(0)
	v_mfma_f32_16x16x32_bf16 v[116:119], v[214:217], v[170:173], v[116:119]
	v_mfma_f32_16x16x32_bf16 v[112:115], v[222:225], v[170:173], v[112:115]
	v_mfma_f32_16x16x32_bf16 v[100:103], v[214:217], v[190:193], v[100:103]
	v_mfma_f32_16x16x32_bf16 v[96:99], v[222:225], v[190:193], v[96:99]
	v_mfma_f32_16x16x32_bf16 v[84:87], v[214:217], v[198:201], v[84:87]
	v_mfma_f32_16x16x32_bf16 v[80:83], v[222:225], v[198:201], v[80:83]
	v_mfma_f32_16x16x32_bf16 v[68:71], v[214:217], v[206:209], v[68:71]
	v_mfma_f32_16x16x32_bf16 v[64:67], v[222:225], v[206:209], v[64:67]
	v_mfma_f32_16x16x32_bf16 v[116:119], v[218:221], v[182:185], v[116:119]
	v_mfma_f32_16x16x32_bf16 v[112:115], v[226:229], v[182:185], v[112:115]
	v_mfma_f32_16x16x32_bf16 v[100:103], v[218:221], v[194:197], v[100:103]
	v_mfma_f32_16x16x32_bf16 v[96:99], v[226:229], v[194:197], v[96:99]
	v_mfma_f32_16x16x32_bf16 v[84:87], v[218:221], v[202:205], v[84:87]
	v_mfma_f32_16x16x32_bf16 v[80:83], v[226:229], v[202:205], v[80:83]
	v_mfma_f32_16x16x32_bf16 v[68:71], v[218:221], v[210:213], v[68:71]
	v_mfma_f32_16x16x32_bf16 v[64:67], v[226:229], v[210:213], v[64:67]
	s_setprio 1
	s_mov_b32 m0, s27
	v_lshl_add_u64 v[186:187], s[34:35], 0, v[134:135]
	s_barrier
	ds_read_b128 v[170:173], v153 offset:16384
	ds_read_b128 v[182:185], v153 offset:17408
	ds_read_b128 v[190:193], v153 offset:18432
	ds_read_b128 v[194:197], v153 offset:19456
	ds_read_b128 v[198:201], v153 offset:20480
	ds_read_b128 v[202:205], v153 offset:21504
	ds_read_b128 v[206:209], v153 offset:22528
	ds_read_b128 v[210:213], v153 offset:23552
	global_load_lds_dwordx4 v[186:187], off
	v_lshl_add_u64 v[230:231], s[34:35], 0, v[130:131]
	s_mov_b32 m0, s43
	s_nop 0
	global_load_lds_dwordx4 v[230:231], off
	s_barrier
	s_waitcnt lgkmcnt(0)
	s_setprio 0
	s_waitcnt lgkmcnt(0)
	v_mfma_f32_16x16x32_bf16 v[60:63], v[144:147], v[170:173], v[60:63]
	v_mfma_f32_16x16x32_bf16 v[56:59], v[160:163], v[170:173], v[56:59]
	v_mfma_f32_16x16x32_bf16 v[44:47], v[144:147], v[190:193], v[44:47]
	v_mfma_f32_16x16x32_bf16 v[40:43], v[160:163], v[190:193], v[40:43]
	v_mfma_f32_16x16x32_bf16 v[28:31], v[144:147], v[198:201], v[28:31]
	v_mfma_f32_16x16x32_bf16 v[24:27], v[160:163], v[198:201], v[24:27]
	v_mfma_f32_16x16x32_bf16 v[12:15], v[144:147], v[206:209], v[12:15]
	v_mfma_f32_16x16x32_bf16 v[8:11], v[160:163], v[206:209], v[8:11]
	v_mfma_f32_16x16x32_bf16 v[60:63], v[156:159], v[182:185], v[60:63]
	v_mfma_f32_16x16x32_bf16 v[56:59], v[166:169], v[182:185], v[56:59]
	v_mfma_f32_16x16x32_bf16 v[44:47], v[156:159], v[194:197], v[44:47]
	v_mfma_f32_16x16x32_bf16 v[40:43], v[166:169], v[194:197], v[40:43]
	v_mfma_f32_16x16x32_bf16 v[28:31], v[156:159], v[202:205], v[28:31]
	v_mfma_f32_16x16x32_bf16 v[24:27], v[166:169], v[202:205], v[24:27]
	v_mfma_f32_16x16x32_bf16 v[12:15], v[156:159], v[210:213], v[12:15]
	v_mfma_f32_16x16x32_bf16 v[8:11], v[166:169], v[210:213], v[8:11]
	s_setprio 1
	s_barrier
; #define PG8_STAGE(bufoff, gbase, voff) do { _Pragma("unroll") for (int _i = 0; _i < 2; ++_i) \
;         __builtin_amdgcn_global_load_lds((const unsigned*)((const char*)(gbase) + (voff)[_i]), (PG8_LAS unsigned*)(lds + (bufoff) + ldsw + _i * 8192), 16, 0, 0); } while (0)
; #define PG8_LDA(dst, b, h) do { _Pragma("unroll") for (int m = 0; m < 4; ++m) _Pragma("unroll") for (int k = 0; k < 2; ++k) dst[m][k] = *(const PG8_LAS bf16x8*)(lds + PG8_SA(b, h) + aoff + m * 2048 + k * 1024); } while (0)
; #define PG8_LDB(dst, b, h) do { _Pragma("unroll") for (int n = 0; n < 2; ++n) _Pragma("unroll") for (int k = 0; k < 2; ++k) dst[n][k] = *(const PG8_LAS bf16x8*)(lds + PG8_SB(b, h) + boff + n * 2048 + k * 1024); } while (0)
; #define PG8_MMA(ai, bj, At, Bt) do { __builtin_amdgcn_s_setprio(1); _Pragma("unroll") for (int m = 0; m < 4; ++m) _Pragma("unroll") for (int n = 0; n < 2; ++n) _Pragma("unroll") for (int k = 0; k < 2; ++k) \
;         acc[ai][bj][m][n] = __builtin_amdgcn_mfma_f32_16x16x32_bf16(Bt[n][k], At[m][k], acc[ai][bj][m][n], 0, 0, 0); __builtin_amdgcn_s_setprio(0); } while (0)
; #define PG8_WAIT_V(n) asm volatile("s_waitcnt vmcnt(" #n ")" ::: "memory")
; #define PG8_WAIT_L(n) asm volatile("s_waitcnt lgkmcnt(" #n ")" ::: "memory")
; #define PG8_BAR __builtin_amdgcn_s_barrier()
; #define PG8_SCHED __builtin_amdgcn_sched_barrier(0)
; template <class Epi, class Sched>
; __device__ __forceinline__ void gemm_phase(PG8_LAS unsigned char* lds, const Gemm g, const Sched& S, const Epi& E) {
;     ...
;             PG8_STAGE(PG8_SB(0, 1), b2 + hstep, voffB);
;             PG8_WAIT_V(6); PG8_BAR; PG8_MMA(1, 1, At, B1); PG8_BAR;
;             PG8_LDB(B0, 1, 0); PG8_SCHED; PG8_LDA(At, 1, 0); PG8_STAGE(PG8_SA(0, 1), a2 + hstep, voffA);
;             PG8_WAIT_L(8); PG8_BAR; PG8_WAIT_L(0); PG8_MMA(0, 0, At, B0); PG8_BAR; PG8_SCHED;
;             PG8_LDB(B1, 1, 1); PG8_STAGE(PG8_SB(1, 0), b3, voffB);
;             PG8_BAR; PG8_WAIT_L(0); PG8_MMA(0, 1, At, B1); PG8_BAR;
;             PG8_LDA(At, 1, 1); PG8_STAGE(PG8_SA(1, 0), a3, voffA);
	s_add_u32 s60, s30, 0x40000
	s_addc_u32 s61, s31, 0
	s_add_i32 s59, s51, s40
	v_lshl_add_u64 v[144:145], s[60:61], 0, v[132:133]
	s_mov_b32 m0, s59
	s_nop 0
	global_load_lds_dwordx4 v[144:145], off
	v_lshl_add_u64 v[144:145], s[60:61], 0, v[128:129]
	s_add_i32 m0, s59, 0x2000
	s_nop 0
	global_load_lds_dwordx4 v[144:145], off
	s_waitcnt vmcnt(6)
	s_barrier
	s_setprio 0
	v_mfma_f32_16x16x32_bf16 v[52:55], v[214:217], v[170:173], v[52:55]
	v_mfma_f32_16x16x32_bf16 v[48:51], v[222:225], v[170:173], v[48:51]
	v_mfma_f32_16x16x32_bf16 v[36:39], v[214:217], v[190:193], v[36:39]
	v_mfma_f32_16x16x32_bf16 v[32:35], v[222:225], v[190:193], v[32:35]
	v_mfma_f32_16x16x32_bf16 v[20:23], v[214:217], v[198:201], v[20:23]
	v_mfma_f32_16x16x32_bf16 v[16:19], v[222:225], v[198:201], v[16:19]
	v_mfma_f32_16x16x32_bf16 v[4:7], v[214:217], v[206:209], v[4:7]
	v_mfma_f32_16x16x32_bf16 v[0:3], v[222:225], v[206:209], v[0:3]
	v_mfma_f32_16x16x32_bf16 v[52:55], v[218:221], v[182:185], v[52:55]
	v_mfma_f32_16x16x32_bf16 v[48:51], v[226:229], v[182:185], v[48:51]
	v_mfma_f32_16x16x32_bf16 v[36:39], v[218:221], v[194:197], v[36:39]
	v_mfma_f32_16x16x32_bf16 v[32:35], v[226:229], v[194:197], v[32:35]
	v_mfma_f32_16x16x32_bf16 v[20:23], v[218:221], v[202:205], v[20:23]
	v_mfma_f32_16x16x32_bf16 v[16:19], v[226:229], v[202:205], v[16:19]
	v_mfma_f32_16x16x32_bf16 v[4:7], v[218:221], v[210:213], v[4:7]
	v_mfma_f32_16x16x32_bf16 v[0:3], v[226:229], v[210:213], v[0:3]
	s_setprio 1
	s_add_i32 s59, 0, 0x18000
	v_add_u32_e32 v155, s59, v149
	s_barrier
	ds_read_b128 v[144:147], v155
	ds_read_b128 v[156:159], v155 offset:1024
	ds_read_b128 v[160:163], v155 offset:2048
	ds_read_b128 v[166:169], v155 offset:3072
	s_add_u32 s34, s34, 0x40000
	s_addc_u32 s35, s35, 0
	s_mov_b32 m0, s44
	v_lshl_add_u64 v[214:215], s[34:35], 0, v[134:135]
	ds_read_b128 v[170:173], v153 offset:32768
	ds_read_b128 v[182:185], v153 offset:33792
	ds_read_b128 v[190:193], v153 offset:34816
	ds_read_b128 v[194:197], v153 offset:35840
	ds_read_b128 v[198:201], v153 offset:36864
	ds_read_b128 v[202:205], v153 offset:37888
	ds_read_b128 v[206:209], v153 offset:38912
	ds_read_b128 v[210:213], v153 offset:39936
	global_load_lds_dwordx4 v[214:215], off
	v_lshl_add_u64 v[214:215], s[34:35], 0, v[130:131]
	s_mov_b32 m0, s45
	s_nop 0
	global_load_lds_dwordx4 v[214:215], off
	s_waitcnt lgkmcnt(8)
	s_barrier
	s_waitcnt lgkmcnt(0)
	s_setprio 0
	s_waitcnt lgkmcnt(0)
	v_mfma_f32_16x16x32_bf16 v[124:127], v[144:147], v[170:173], v[124:127]
	v_mfma_f32_16x16x32_bf16 v[120:123], v[160:163], v[170:173], v[120:123]
	v_mfma_f32_16x16x32_bf16 v[108:111], v[144:147], v[190:193], v[108:111]
	v_mfma_f32_16x16x32_bf16 v[104:107], v[160:163], v[190:193], v[104:107]
	v_mfma_f32_16x16x32_bf16 v[92:95], v[144:147], v[198:201], v[92:95]
	v_mfma_f32_16x16x32_bf16 v[88:91], v[160:163], v[198:201], v[88:91]
	v_mfma_f32_16x16x32_bf16 v[76:79], v[144:147], v[206:209], v[76:79]
	v_mfma_f32_16x16x32_bf16 v[72:75], v[160:163], v[206:209], v[72:75]
	v_mfma_f32_16x16x32_bf16 v[124:127], v[156:159], v[182:185], v[124:127]
	v_mfma_f32_16x16x32_bf16 v[120:123], v[166:169], v[182:185], v[120:123]
	v_mfma_f32_16x16x32_bf16 v[108:111], v[156:159], v[194:197], v[108:111]
	v_mfma_f32_16x16x32_bf16 v[104:107], v[166:169], v[194:197], v[104:107]
	v_mfma_f32_16x16x32_bf16 v[92:95], v[156:159], v[202:205], v[92:95]
	v_mfma_f32_16x16x32_bf16 v[88:91], v[166:169], v[202:205], v[88:91]
	v_mfma_f32_16x16x32_bf16 v[76:79], v[156:159], v[210:213], v[76:79]
	v_mfma_f32_16x16x32_bf16 v[72:75], v[166:169], v[210:213], v[72:75]
	s_setprio 1
	s_barrier
	s_add_i32 s34, 0, 0x1c000
	s_add_i32 s35, s59, s40
	v_add_u32_e32 v155, s34, v149
	v_lshl_add_u64 v[174:175], v[174:175], 0, s[10:11]
	s_mov_b32 m0, s35
	ds_read_b128 v[214:217], v155
	ds_read_b128 v[218:221], v155 offset:1024
	ds_read_b128 v[222:225], v155 offset:2048
	ds_read_b128 v[226:229], v155 offset:3072
	global_load_lds_dwordx4 v[174:175], off
	v_lshl_add_u64 v[174:175], v[178:179], 0, s[10:11]
	s_add_i32 m0, s35, 0x2000
	s_nop 0
	global_load_lds_dwordx4 v[174:175], off
	s_barrier
	s_waitcnt lgkmcnt(0)
	s_setprio 0
	s_waitcnt lgkmcnt(0)
	v_mfma_f32_16x16x32_bf16 v[116:119], v[214:217], v[170:173], v[116:119]
	v_mfma_f32_16x16x32_bf16 v[112:115], v[222:225], v[170:173], v[112:115]
	v_mfma_f32_16x16x32_bf16 v[100:103], v[214:217], v[190:193], v[100:103]
	v_mfma_f32_16x16x32_bf16 v[96:99], v[222:225], v[190:193], v[96:99]
	v_mfma_f32_16x16x32_bf16 v[84:87], v[214:217], v[198:201], v[84:87]
	v_mfma_f32_16x16x32_bf16 v[80:83], v[222:225], v[198:201], v[80:83]
	v_mfma_f32_16x16x32_bf16 v[68:71], v[214:217], v[206:209], v[68:71]
	v_mfma_f32_16x16x32_bf16 v[64:67], v[222:225], v[206:209], v[64:67]
	v_mfma_f32_16x16x32_bf16 v[116:119], v[218:221], v[182:185], v[116:119]
	v_mfma_f32_16x16x32_bf16 v[112:115], v[226:229], v[182:185], v[112:115]
	v_mfma_f32_16x16x32_bf16 v[100:103], v[218:221], v[194:197], v[100:103]
	v_mfma_f32_16x16x32_bf16 v[96:99], v[226:229], v[194:197], v[96:99]
	v_mfma_f32_16x16x32_bf16 v[84:87], v[218:221], v[202:205], v[84:87]
	v_mfma_f32_16x16x32_bf16 v[80:83], v[226:229], v[202:205], v[80:83]
	v_mfma_f32_16x16x32_bf16 v[68:71], v[218:221], v[210:213], v[68:71]
	v_mfma_f32_16x16x32_bf16 v[64:67], v[226:229], v[210:213], v[64:67]
	s_setprio 1
	s_mov_b32 m0, s47
	v_lshl_add_u64 v[174:175], v[186:187], 0, s[10:11]
	s_barrier
	ds_read_b128 v[170:173], v153 offset:49152
	ds_read_b128 v[182:185], v153 offset:50176
	ds_read_b128 v[190:193], v153 offset:51200
	ds_read_b128 v[194:197], v153 offset:52224
	ds_read_b128 v[198:201], v153 offset:53248
	ds_read_b128 v[202:205], v153 offset:54272
	ds_read_b128 v[206:209], v153 offset:55296
	ds_read_b128 v[210:213], v153 offset:56320
	global_load_lds_dwordx4 v[174:175], off
	v_lshl_add_u64 v[174:175], v[230:231], 0, s[10:11]
	s_mov_b32 m0, s48
	s_nop 0
	global_load_lds_dwordx4 v[174:175], off
	s_barrier
; __device__ __forceinline__ unsigned cvt_pk_bf16(float lo, float hi) { unsigned r; asm volatile("v_cvt_pk_bf16_f32 %0, %1, %2" : "=v"(r) : "v"(lo), "v"(hi)); return r; }
; #define PG8_STAGE(bufoff, gbase, voff) do { _Pragma("unroll") for (int _i = 0; _i < 2; ++_i) \
;         __builtin_amdgcn_global_load_lds((const unsigned*)((const char*)(gbase) + (voff)[_i]), (PG8_LAS unsigned*)(lds + (bufoff) + ldsw + _i * 8192), 16, 0, 0); } while (0)
; #define PG8_MMA(ai, bj, At, Bt) do { __builtin_amdgcn_s_setprio(1); _Pragma("unroll") for (int m = 0; m < 4; ++m) _Pragma("unroll") for (int n = 0; n < 2; ++n) _Pragma("unroll") for (int k = 0; k < 2; ++k) \
;         acc[ai][bj][m][n] = __builtin_amdgcn_mfma_f32_16x16x32_bf16(Bt[n][k], At[m][k], acc[ai][bj][m][n], 0, 0, 0); __builtin_amdgcn_s_setprio(0); } while (0)
; #define PG8_WAIT_V(n) asm volatile("s_waitcnt vmcnt(" #n ")" ::: "memory")
; #define PG8_WAIT_L(n) asm volatile("s_waitcnt lgkmcnt(" #n ")" ::: "memory")
; #define PG8_BAR __builtin_amdgcn_s_barrier()
; #define PG8_SCHED __builtin_amdgcn_sched_barrier(0)
;     __device__ __forceinline__ void operator()(const f32x4 (&acc)[2][2][4][2], const Unit& u, int wr, int wc, int fr, int fq) const {
;     ...
;             for (int m = 0; m < 4; ++m) { bf16_t* rowp = O + (size_t)(row0 + ai * HALF + m * 16) * ldc + col0;
;                 f32x4 v0, v1;
; #pragma unroll
;                 for (int j = 0; j < 1; ++j) { v0 = acc[ai][0][m][0] * sigmoid4(acc[ai][0][m][0]) * acc[ai][1][m][0]; v1 = acc[ai][0][m][1] * sigmoid4(acc[ai][0][m][1]) * acc[ai][1][m][1]; }
;                 u32x4 w; w.x = cvt_pk_bf16(v0[0], v0[1]); w.y = cvt_pk_bf16(v0[2], v0[3]); w.z = cvt_pk_bf16(v1[0], v1[1]); w.w = cvt_pk_bf16(v1[2], v1[3]);
; template <class Epi, class Sched>
; __device__ __forceinline__ void gemm_phase(PG8_LAS unsigned char* lds, const Gemm g, const Sched& S, const Epi& E) {
;     ...
;             PG8_BAR; PG8_WAIT_L(0); PG8_MMA(1, 0, At, B0); PG8_BAR; PG8_SCHED;
;             PG8_STAGE(PG8_SB(1, 1), b3 + hstep, voffB);
;             PG8_WAIT_V(6); PG8_BAR; PG8_MMA(1, 1, At, B1); PG8_BAR;
	s_waitcnt lgkmcnt(0)
	s_setprio 0
	s_waitcnt lgkmcnt(0)
	v_mfma_f32_16x16x32_bf16 v[60:63], v[144:147], v[170:173], v[60:63]
	v_mfma_f32_16x16x32_bf16 v[56:59], v[160:163], v[170:173], v[56:59]
	v_mfma_f32_16x16x32_bf16 v[44:47], v[144:147], v[190:193], v[44:47]
	v_mfma_f32_16x16x32_bf16 v[40:43], v[160:163], v[190:193], v[40:43]
	v_mfma_f32_16x16x32_bf16 v[28:31], v[144:147], v[198:201], v[28:31]
	v_mfma_f32_16x16x32_bf16 v[24:27], v[160:163], v[198:201], v[24:27]
	v_mfma_f32_16x16x32_bf16 v[12:15], v[144:147], v[206:209], v[12:15]
	v_mfma_f32_16x16x32_bf16 v[8:11], v[160:163], v[206:209], v[8:11]
	v_mfma_f32_16x16x32_bf16 v[60:63], v[156:159], v[182:185], v[60:63]
	v_mfma_f32_16x16x32_bf16 v[56:59], v[166:169], v[182:185], v[56:59]
	v_mfma_f32_16x16x32_bf16 v[44:47], v[156:159], v[194:197], v[44:47]
	v_mfma_f32_16x16x32_bf16 v[40:43], v[166:169], v[194:197], v[40:43]
	v_mfma_f32_16x16x32_bf16 v[28:31], v[156:159], v[202:205], v[28:31]
	v_mfma_f32_16x16x32_bf16 v[24:27], v[166:169], v[202:205], v[24:27]
	v_mfma_f32_16x16x32_bf16 v[12:15], v[156:159], v[210:213], v[12:15]
	v_mfma_f32_16x16x32_bf16 v[8:11], v[166:169], v[210:213], v[8:11]
	s_setprio 1
	s_barrier
	s_add_u32 s30, s30, 0x40080
	s_addc_u32 s31, s31, 0
	s_add_i32 s34, s34, s40
	v_lshl_add_u64 v[144:145], s[30:31], 0, v[132:133]
	s_mov_b32 m0, s34
	s_nop 0
	global_load_lds_dwordx4 v[144:145], off
	v_lshl_add_u64 v[144:145], s[30:31], 0, v[128:129]
	s_add_i32 m0, s34, 0x2000
	s_nop 0
	global_load_lds_dwordx4 v[144:145], off
	s_waitcnt vmcnt(6)
	s_barrier
	s_setprio 0
	v_mfma_f32_16x16x32_bf16 v[52:55], v[214:217], v[170:173], v[52:55]
	v_mfma_f32_16x16x32_bf16 v[48:51], v[222:225], v[170:173], v[48:51]
	v_mfma_f32_16x16x32_bf16 v[36:39], v[214:217], v[190:193], v[36:39]
	v_mfma_f32_16x16x32_bf16 v[32:35], v[222:225], v[190:193], v[32:35]
	v_mfma_f32_16x16x32_bf16 v[20:23], v[214:217], v[198:201], v[20:23]
	v_mfma_f32_16x16x32_bf16 v[16:19], v[222:225], v[198:201], v[16:19]
	v_mfma_f32_16x16x32_bf16 v[4:7], v[214:217], v[206:209], v[4:7]
	v_mfma_f32_16x16x32_bf16 v[0:3], v[222:225], v[206:209], v[0:3]
	v_mfma_f32_16x16x32_bf16 v[52:55], v[218:221], v[182:185], v[52:55]
	v_mfma_f32_16x16x32_bf16 v[48:51], v[226:229], v[182:185], v[48:51]
	v_mfma_f32_16x16x32_bf16 v[36:39], v[218:221], v[194:197], v[36:39]
	v_mfma_f32_16x16x32_bf16 v[32:35], v[226:229], v[194:197], v[32:35]
	v_mfma_f32_16x16x32_bf16 v[20:23], v[218:221], v[202:205], v[20:23]
	v_mfma_f32_16x16x32_bf16 v[16:19], v[226:229], v[202:205], v[16:19]
	v_mfma_f32_16x16x32_bf16 v[4:7], v[218:221], v[210:213], v[4:7]
	v_mfma_f32_16x16x32_bf16 v[0:3], v[226:229], v[210:213], v[0:3]
	s_setprio 1
	s_add_i32 s58, s58, 2
	s_add_u32 s28, s28, 0x100
	s_addc_u32 s29, s29, 0
	s_add_u32 s56, s56, 0x100
	s_addc_u32 s57, s57, 0
	s_cmp_gt_u32 s58, 13
	s_barrier
	s_cbranch_scc0 .LBB0_195
	v_max_f32_e32 v144, v124, v124
	v_max_f32_e32 v144, 0xc1a00000, v144
	v_mul_f32_e32 v144, 0xbfb8aa3b, v144
	v_exp_f32_e32 v157, v144
	v_max_f32_e32 v144, v125, v125
	v_max_f32_e32 v144, 0xc1a00000, v144
	v_mul_f32_e32 v144, 0xbfb8aa3b, v144
	v_exp_f32_e32 v156, v144
	v_max_f32_e32 v144, v126, v126
	v_max_f32_e32 v144, 0xc1a00000, v144
	v_mul_f32_e32 v144, 0xbfb8aa3b, v144
	v_exp_f32_e32 v159, v144
	v_max_f32_e32 v144, v127, v127
	v_max_f32_e32 v144, 0xc1a00000, v144
	v_mul_f32_e32 v144, 0xbfb8aa3b, v144
	v_exp_f32_e32 v158, v144
	v_pk_add_f32 v[156:157], v[156:157], 1.0 op_sel_hi:[1,0]
	v_lshl_or_b32 v146, s53, 7, v150
	v_mov_b32_e32 v160, v157
	v_pk_add_f32 v[158:159], v[158:159], 1.0 op_sel_hi:[1,0]
	v_mov_b32_e32 v162, v156
	v_mov_b32_e32 v161, v159
	v_mov_b32_e32 v163, v158
	v_pk_mul_f32 v[160:161], v[160:161], v[162:163]
	v_lshl_add_u32 v155, s26, 8, v148
	v_mul_f32_e32 v162, v160, v161
	v_rcp_f32_e32 v166, v162
	v_ashrrev_i32_e32 v147, 31, v146
	v_mov_b64_e32 v[144:145], s[4:5]
	v_mad_i64_i32 v[162:163], s[28:29], v155, s52, v[144:145]
	v_mul_f32_e32 v160, v160, v166
	v_mul_f32_e32 v164, v161, v166
	v_pk_mul_f32 v[158:159], v[158:159], v[160:161] op_sel_hi:[1,0]
	v_max_f32_e32 v160, v120, v120
	v_max_f32_e32 v166, v122, v122
	v_max_f32_e32 v160, 0xc1a00000, v160
	v_max_f32_e32 v166, 0xc1a00000, v166
	v_mul_f32_e32 v160, 0xbfb8aa3b, v160
	v_mul_f32_e32 v166, 0xbfb8aa3b, v166
	v_exp_f32_e32 v161, v160
	v_max_f32_e32 v160, v121, v121
	v_exp_f32_e32 v167, v166
	v_max_f32_e32 v166, v123, v123
	v_max_f32_e32 v160, 0xc1a00000, v160
	v_max_f32_e32 v166, 0xc1a00000, v166
	v_mul_f32_e32 v160, 0xbfb8aa3b, v160
	v_mul_f32_e32 v166, 0xbfb8aa3b, v166
	v_exp_f32_e32 v160, v160
	v_exp_f32_e32 v166, v166
	v_pk_mul_f32 v[156:157], v[156:157], v[164:165] op_sel_hi:[1,0]
	v_pk_mul_f32 v[126:127], v[126:127], v[158:159]
	v_pk_mul_f32 v[124:125], v[124:125], v[156:157]
	v_pk_add_f32 v[156:157], v[160:161], 1.0 op_sel_hi:[1,0]
	v_pk_add_f32 v[160:161], v[166:167], 1.0 op_sel_hi:[1,0]
	v_mov_b32_e32 v166, v157
	v_mov_b32_e32 v167, v161
	v_mov_b32_e32 v168, v156
	v_mov_b32_e32 v169, v160
	v_pk_mul_f32 v[166:167], v[166:167], v[168:169]
	v_pk_mul_f32 v[118:119], v[126:127], v[118:119]
	v_mul_f32_e32 v164, v166, v167
	v_rcp_f32_e32 v164, v164
	v_pk_mul_f32 v[116:117], v[124:125], v[116:117]
	v_lshlrev_b64 v[146:147], 1, v[146:147]
	v_lshl_add_u64 v[162:163], v[162:163], 0, v[146:147]
	v_mul_f32_e32 v124, v167, v164
	v_mul_f32_e32 v126, v166, v164
	v_pk_mul_f32 v[126:127], v[160:161], v[126:127] op_sel_hi:[1,0]
	v_pk_mul_f32 v[124:125], v[156:157], v[124:125] op_sel_hi:[1,0]
	v_pk_mul_f32 v[122:123], v[122:123], v[126:127]
	v_pk_mul_f32 v[120:121], v[120:121], v[124:125]
	v_pk_mul_f32 v[122:123], v[122:123], v[114:115]
	v_pk_mul_f32 v[114:115], v[120:121], v[112:113]
; __device__ __forceinline__ unsigned cvt_pk_bf16(float lo, float hi) { unsigned r; asm volatile("v_cvt_pk_bf16_f32 %0, %1, %2" : "=v"(r) : "v"(lo), "v"(hi)); return r; }
; __device__ __forceinline__ f32x4 sigmoid4(f32x4 x) {
;     f32x4 d;
; #pragma unroll
;     for (int j = 0; j < 4; ++j) d[j] = 1.0f + __expf(-fmaxf(x[j], -20.0f));
;     const float p01 = d[0] * d[1], p23 = d[2] * d[3], r = __builtin_amdgcn_rcpf(p01 * p23), r01 = r * p23, r23 = r * p01;
;     return (f32x4){r01 * d[1], r01 * d[0], r23 * d[3], r23 * d[2]};
; }
;     __device__ __forceinline__ void operator()(const f32x4 (&acc)[2][2][4][2], const Unit& u, int wr, int wc, int fr, int fq) const {
;     ...
;         for (int ai = 0; ai < 2; ++ai)
; #pragma unroll
;             for (int m = 0; m < 4; ++m) { bf16_t* rowp = O + (size_t)(row0 + ai * HALF + m * 16) * ldc + col0;
;                 f32x4 v0, v1;
; #pragma unroll
;                 for (int j = 0; j < 1; ++j) { v0 = acc[ai][0][m][0] * sigmoid4(acc[ai][0][m][0]) * acc[ai][1][m][0]; v1 = acc[ai][0][m][1] * sigmoid4(acc[ai][0][m][1]) * acc[ai][1][m][1]; }
;                 u32x4 w; w.x = cvt_pk_bf16(v0[0], v0[1]); w.y = cvt_pk_bf16(v0[2], v0[3]); w.z = cvt_pk_bf16(v1[0], v1[1]); w.w = cvt_pk_bf16(v1[2], v1[3]);
;                 *(u32x4*)rowp = w; }
	v_cvt_pk_bf16_f32 v112, v116, v117
	v_cvt_pk_bf16_f32 v113, v118, v119
	v_max_f32_e32 v116, v108, v108
	v_max_f32_e32 v118, v110, v110
	v_max_f32_e32 v116, 0xc1a00000, v116
	v_max_f32_e32 v118, 0xc1a00000, v118
	v_mul_f32_e32 v116, 0xbfb8aa3b, v116
	v_mul_f32_e32 v118, 0xbfb8aa3b, v118
	v_exp_f32_e32 v117, v116
	v_max_f32_e32 v116, v109, v109
	v_exp_f32_e32 v119, v118
	v_max_f32_e32 v118, v111, v111
	v_max_f32_e32 v116, 0xc1a00000, v116
	v_max_f32_e32 v118, 0xc1a00000, v118
	v_mul_f32_e32 v116, 0xbfb8aa3b, v116
	v_mul_f32_e32 v118, 0xbfb8aa3b, v118
	v_exp_f32_e32 v116, v116
	v_exp_f32_e32 v118, v118
	v_cvt_pk_bf16_f32 v114, v114, v115
	v_cvt_pk_bf16_f32 v115, v122, v123
	global_store_dwordx4 v[162:163], v[112:115], off
	v_or_b32_e32 v120, 16, v155
	s_and_b64 vcc, exec, s[2:3]
	v_pk_add_f32 v[112:113], v[116:117], 1.0 op_sel_hi:[1,0]
	v_pk_add_f32 v[114:115], v[118:119], 1.0 op_sel_hi:[1,0]
	v_mov_b32_e32 v116, v113
	v_mov_b32_e32 v117, v115
	v_mov_b32_e32 v118, v112
	v_mov_b32_e32 v119, v114
	v_pk_mul_f32 v[116:117], v[116:117], v[118:119]
	s_mov_b32 s53, s14
	v_mul_f32_e32 v118, v116, v117
	v_rcp_f32_e32 v121, v118
	v_mad_i64_i32 v[118:119], s[28:29], v120, s52, v[144:145]
	v_lshl_add_u64 v[118:119], v[118:119], 0, v[146:147]
	v_mul_f32_e32 v116, v116, v121
	v_mul_f32_e32 v120, v117, v121
	v_pk_mul_f32 v[114:115], v[114:115], v[116:117] op_sel_hi:[1,0]
	v_max_f32_e32 v116, v104, v104
	v_max_f32_e32 v121, v106, v106
	v_max_f32_e32 v116, 0xc1a00000, v116
	v_max_f32_e32 v121, 0xc1a00000, v121
	v_mul_f32_e32 v116, 0xbfb8aa3b, v116
	v_mul_f32_e32 v121, 0xbfb8aa3b, v121
	v_exp_f32_e32 v117, v116
	v_max_f32_e32 v116, v105, v105
	v_exp_f32_e32 v123, v121
	v_max_f32_e32 v121, v107, v107
	v_max_f32_e32 v116, 0xc1a00000, v116
	v_max_f32_e32 v121, 0xc1a00000, v121
	v_mul_f32_e32 v116, 0xbfb8aa3b, v116
	v_mul_f32_e32 v121, 0xbfb8aa3b, v121
	v_exp_f32_e32 v116, v116
	v_exp_f32_e32 v122, v121
	v_pk_mul_f32 v[112:113], v[112:113], v[120:121] op_sel_hi:[1,0]
	v_pk_mul_f32 v[110:111], v[110:111], v[114:115]
	v_pk_mul_f32 v[108:109], v[108:109], v[112:113]
	v_pk_add_f32 v[112:113], v[116:117], 1.0 op_sel_hi:[1,0]
	v_pk_add_f32 v[116:117], v[122:123], 1.0 op_sel_hi:[1,0]
	v_mov_b32_e32 v120, v113
	v_mov_b32_e32 v121, v117
	v_mov_b32_e32 v122, v112
	v_mov_b32_e32 v123, v116
	v_pk_mul_f32 v[120:121], v[120:121], v[122:123]
	v_pk_mul_f32 v[102:103], v[110:111], v[102:103]
	v_mul_f32_e32 v122, v120, v121
	v_rcp_f32_e32 v122, v122
	v_pk_mul_f32 v[100:101], v[108:109], v[100:101]
	s_mov_b32 s26, s16
	s_mov_b64 s[30:31], s[24:25]
	v_mul_f32_e32 v108, v121, v122
	v_mul_f32_e32 v110, v120, v122
	v_pk_mul_f32 v[110:111], v[116:117], v[110:111] op_sel_hi:[1,0]
	v_pk_mul_f32 v[108:109], v[112:113], v[108:109] op_sel_hi:[1,0]
	v_pk_mul_f32 v[106:107], v[106:107], v[110:111]
	v_pk_mul_f32 v[104:105], v[104:105], v[108:109]
	v_pk_mul_f32 v[106:107], v[106:107], v[98:99]
	v_pk_mul_f32 v[98:99], v[104:105], v[96:97]
	v_cvt_pk_bf16_f32 v96, v100, v101
	v_cvt_pk_bf16_f32 v97, v102, v103
	v_max_f32_e32 v100, v92, v92
	v_max_f32_e32 v102, v94, v94
	v_max_f32_e32 v100, 0xc1a00000, v100
	v_max_f32_e32 v102, 0xc1a00000, v102
	v_mul_f32_e32 v100, 0xbfb8aa3b, v100
	v_mul_f32_e32 v102, 0xbfb8aa3b, v102
	v_exp_f32_e32 v101, v100
	v_max_f32_e32 v100, v93, v93
	v_exp_f32_e32 v103, v102
	v_max_f32_e32 v102, v95, v95
	v_max_f32_e32 v100, 0xc1a00000, v100
	v_max_f32_e32 v102, 0xc1a00000, v102
	v_mul_f32_e32 v100, 0xbfb8aa3b, v100
	v_mul_f32_e32 v102, 0xbfb8aa3b, v102
	v_exp_f32_e32 v100, v100
	v_exp_f32_e32 v102, v102
	v_cvt_pk_bf16_f32 v98, v98, v99
	v_cvt_pk_bf16_f32 v99, v106, v107
	global_store_dwordx4 v[118:119], v[96:99], off
	v_or_b32_e32 v104, 32, v155
	s_nop 0
	v_pk_add_f32 v[96:97], v[100:101], 1.0 op_sel_hi:[1,0]
	v_pk_add_f32 v[98:99], v[102:103], 1.0 op_sel_hi:[1,0]
	v_mov_b32_e32 v100, v97
	v_mov_b32_e32 v101, v99
	v_mov_b32_e32 v102, v96
	v_mov_b32_e32 v103, v98
	v_pk_mul_f32 v[100:101], v[100:101], v[102:103]
	s_nop 0
	v_mul_f32_e32 v102, v100, v101
	v_rcp_f32_e32 v105, v102
	v_mad_i64_i32 v[102:103], s[28:29], v104, s52, v[144:145]
	v_lshl_add_u64 v[102:103], v[102:103], 0, v[146:147]
	v_mul_f32_e32 v100, v100, v105
	v_mul_f32_e32 v104, v101, v105
	v_pk_mul_f32 v[98:99], v[98:99], v[100:101] op_sel_hi:[1,0]
	v_max_f32_e32 v100, v88, v88
	v_max_f32_e32 v105, v90, v90
	v_max_f32_e32 v100, 0xc1a00000, v100
	v_max_f32_e32 v105, 0xc1a00000, v105
	v_mul_f32_e32 v100, 0xbfb8aa3b, v100
	v_mul_f32_e32 v105, 0xbfb8aa3b, v105
	v_exp_f32_e32 v101, v100
	v_max_f32_e32 v100, v89, v89
	v_exp_f32_e32 v107, v105
	v_max_f32_e32 v105, v91, v91
	v_max_f32_e32 v100, 0xc1a00000, v100
	v_max_f32_e32 v105, 0xc1a00000, v105
	v_mul_f32_e32 v100, 0xbfb8aa3b, v100
	v_mul_f32_e32 v105, 0xbfb8aa3b, v105
	v_exp_f32_e32 v100, v100
	v_exp_f32_e32 v106, v105
	v_pk_mul_f32 v[96:97], v[96:97], v[104:105] op_sel_hi:[1,0]
	v_pk_mul_f32 v[94:95], v[94:95], v[98:99]
	v_pk_mul_f32 v[92:93], v[92:93], v[96:97]
	v_pk_add_f32 v[96:97], v[100:101], 1.0 op_sel_hi:[1,0]
	v_pk_add_f32 v[100:101], v[106:107], 1.0 op_sel_hi:[1,0]
	v_mov_b32_e32 v104, v97
	v_mov_b32_e32 v105, v101
	v_mov_b32_e32 v106, v96
	v_mov_b32_e32 v107, v100
	v_pk_mul_f32 v[104:105], v[104:105], v[106:107]
	v_pk_mul_f32 v[86:87], v[94:95], v[86:87]
	v_mul_f32_e32 v106, v104, v105
	v_rcp_f32_e32 v106, v106
	v_pk_mul_f32 v[84:85], v[92:93], v[84:85]
	v_mul_f32_e32 v92, v105, v106
	v_mul_f32_e32 v94, v104, v106
	v_pk_mul_f32 v[94:95], v[100:101], v[94:95] op_sel_hi:[1,0]
	v_pk_mul_f32 v[92:93], v[96:97], v[92:93] op_sel_hi:[1,0]
	v_pk_mul_f32 v[90:91], v[90:91], v[94:95]
	v_pk_mul_f32 v[88:89], v[88:89], v[92:93]
	v_pk_mul_f32 v[90:91], v[90:91], v[82:83]
; __device__ __forceinline__ unsigned cvt_pk_bf16(float lo, float hi) { unsigned r; asm volatile("v_cvt_pk_bf16_f32 %0, %1, %2" : "=v"(r) : "v"(lo), "v"(hi)); return r; }
; __device__ __forceinline__ f32x4 sigmoid4(f32x4 x) {
;     f32x4 d;
; #pragma unroll
;     for (int j = 0; j < 4; ++j) d[j] = 1.0f + __expf(-fmaxf(x[j], -20.0f));
;     const float p01 = d[0] * d[1], p23 = d[2] * d[3], r = __builtin_amdgcn_rcpf(p01 * p23), r01 = r * p23, r23 = r * p01;
;     return (f32x4){r01 * d[1], r01 * d[0], r23 * d[3], r23 * d[2]};
; }
;     __device__ __forceinline__ void operator()(const f32x4 (&acc)[2][2][4][2], const Unit& u, int wr, int wc, int fr, int fq) const {
;     ...
;         for (int ai = 0; ai < 2; ++ai)
; #pragma unroll
;             for (int m = 0; m < 4; ++m) { bf16_t* rowp = O + (size_t)(row0 + ai * HALF + m * 16) * ldc + col0;
;                 f32x4 v0, v1;
; #pragma unroll
;                 for (int j = 0; j < 1; ++j) { v0 = acc[ai][0][m][0] * sigmoid4(acc[ai][0][m][0]) * acc[ai][1][m][0]; v1 = acc[ai][0][m][1] * sigmoid4(acc[ai][0][m][1]) * acc[ai][1][m][1]; }
;                 u32x4 w; w.x = cvt_pk_bf16(v0[0], v0[1]); w.y = cvt_pk_bf16(v0[2], v0[3]); w.z = cvt_pk_bf16(v1[0], v1[1]); w.w = cvt_pk_bf16(v1[2], v1[3]);
;                 *(u32x4*)rowp = w; }
	v_pk_mul_f32 v[82:83], v[88:89], v[80:81]
	v_cvt_pk_bf16_f32 v80, v84, v85
	v_cvt_pk_bf16_f32 v81, v86, v87
	v_max_f32_e32 v84, v76, v76
	v_max_f32_e32 v86, v78, v78
	v_max_f32_e32 v84, 0xc1a00000, v84
	v_max_f32_e32 v86, 0xc1a00000, v86
	v_mul_f32_e32 v84, 0xbfb8aa3b, v84
	v_mul_f32_e32 v86, 0xbfb8aa3b, v86
	v_exp_f32_e32 v85, v84
	v_max_f32_e32 v84, v77, v77
	v_exp_f32_e32 v87, v86
	v_max_f32_e32 v86, v79, v79
	v_max_f32_e32 v84, 0xc1a00000, v84
	v_max_f32_e32 v86, 0xc1a00000, v86
	v_mul_f32_e32 v84, 0xbfb8aa3b, v84
	v_mul_f32_e32 v86, 0xbfb8aa3b, v86
	v_exp_f32_e32 v84, v84
	v_exp_f32_e32 v86, v86
	v_cvt_pk_bf16_f32 v82, v82, v83
	v_cvt_pk_bf16_f32 v83, v90, v91
	global_store_dwordx4 v[102:103], v[80:83], off
	v_or_b32_e32 v88, 48, v155
	s_nop 0
	v_pk_add_f32 v[80:81], v[84:85], 1.0 op_sel_hi:[1,0]
	v_pk_add_f32 v[82:83], v[86:87], 1.0 op_sel_hi:[1,0]
	v_mov_b32_e32 v84, v81
	v_mov_b32_e32 v85, v83
	v_mov_b32_e32 v86, v80
	v_mov_b32_e32 v87, v82
	v_pk_mul_f32 v[84:85], v[84:85], v[86:87]
	s_nop 0
	v_mul_f32_e32 v86, v84, v85
	v_rcp_f32_e32 v89, v86
	v_mad_i64_i32 v[86:87], s[28:29], v88, s52, v[144:145]
	v_lshl_add_u64 v[86:87], v[86:87], 0, v[146:147]
	v_mul_f32_e32 v84, v84, v89
	v_mul_f32_e32 v88, v85, v89
	v_pk_mul_f32 v[82:83], v[82:83], v[84:85] op_sel_hi:[1,0]
	v_max_f32_e32 v84, v72, v72
	v_max_f32_e32 v89, v74, v74
	v_max_f32_e32 v84, 0xc1a00000, v84
	v_max_f32_e32 v89, 0xc1a00000, v89
	v_mul_f32_e32 v84, 0xbfb8aa3b, v84
	v_mul_f32_e32 v89, 0xbfb8aa3b, v89
	v_exp_f32_e32 v85, v84
	v_max_f32_e32 v84, v73, v73
	v_exp_f32_e32 v91, v89
	v_max_f32_e32 v89, v75, v75
	v_max_f32_e32 v84, 0xc1a00000, v84
	v_max_f32_e32 v89, 0xc1a00000, v89
	v_mul_f32_e32 v84, 0xbfb8aa3b, v84
	v_mul_f32_e32 v89, 0xbfb8aa3b, v89
	v_exp_f32_e32 v84, v84
	v_exp_f32_e32 v90, v89
	v_pk_mul_f32 v[80:81], v[80:81], v[88:89] op_sel_hi:[1,0]
	v_pk_mul_f32 v[78:79], v[78:79], v[82:83]
	v_pk_mul_f32 v[76:77], v[76:77], v[80:81]
	v_pk_add_f32 v[80:81], v[84:85], 1.0 op_sel_hi:[1,0]
	v_pk_add_f32 v[84:85], v[90:91], 1.0 op_sel_hi:[1,0]
	v_mov_b32_e32 v88, v81
	v_mov_b32_e32 v89, v85
	v_mov_b32_e32 v90, v80
	v_mov_b32_e32 v91, v84
	v_pk_mul_f32 v[88:89], v[88:89], v[90:91]
	v_pk_mul_f32 v[70:71], v[78:79], v[70:71]
	v_mul_f32_e32 v90, v88, v89
	v_rcp_f32_e32 v90, v90
	v_pk_mul_f32 v[68:69], v[76:77], v[68:69]
	v_mul_f32_e32 v76, v89, v90
	v_mul_f32_e32 v78, v88, v90
	v_pk_mul_f32 v[78:79], v[84:85], v[78:79] op_sel_hi:[1,0]
	v_pk_mul_f32 v[76:77], v[80:81], v[76:77] op_sel_hi:[1,0]
	v_pk_mul_f32 v[74:75], v[74:75], v[78:79]
	v_pk_mul_f32 v[72:73], v[72:73], v[76:77]
	v_pk_mul_f32 v[74:75], v[74:75], v[66:67]
	v_pk_mul_f32 v[66:67], v[72:73], v[64:65]
	v_cvt_pk_bf16_f32 v64, v68, v69
	v_cvt_pk_bf16_f32 v65, v70, v71
	v_max_f32_e32 v68, v60, v60
	v_max_f32_e32 v70, v62, v62
	v_max_f32_e32 v68, 0xc1a00000, v68
	v_max_f32_e32 v70, 0xc1a00000, v70
	v_mul_f32_e32 v68, 0xbfb8aa3b, v68
	v_mul_f32_e32 v70, 0xbfb8aa3b, v70
	v_exp_f32_e32 v69, v68
	v_max_f32_e32 v68, v61, v61
	v_exp_f32_e32 v71, v70
	v_max_f32_e32 v70, v63, v63
	v_max_f32_e32 v68, 0xc1a00000, v68
	v_max_f32_e32 v70, 0xc1a00000, v70
	v_mul_f32_e32 v68, 0xbfb8aa3b, v68
	v_mul_f32_e32 v70, 0xbfb8aa3b, v70
	v_exp_f32_e32 v68, v68
	v_exp_f32_e32 v70, v70
	v_cvt_pk_bf16_f32 v66, v66, v67
	v_cvt_pk_bf16_f32 v67, v74, v75
	global_store_dwordx4 v[86:87], v[64:67], off
	v_add_u32_e32 v72, 0x80, v155
	s_nop 0
	v_pk_add_f32 v[64:65], v[68:69], 1.0 op_sel_hi:[1,0]
	v_pk_add_f32 v[66:67], v[70:71], 1.0 op_sel_hi:[1,0]
	v_mov_b32_e32 v68, v65
	v_mov_b32_e32 v69, v67
	v_mov_b32_e32 v70, v64
	v_mov_b32_e32 v71, v66
	v_pk_mul_f32 v[68:69], v[68:69], v[70:71]
	s_nop 0
	v_mul_f32_e32 v70, v68, v69
	v_rcp_f32_e32 v73, v70
	v_mad_i64_i32 v[70:71], s[28:29], v72, s52, v[144:145]
	v_lshl_add_u64 v[70:71], v[70:71], 0, v[146:147]
	v_mul_f32_e32 v68, v68, v73
	v_mul_f32_e32 v72, v69, v73
	v_pk_mul_f32 v[66:67], v[66:67], v[68:69] op_sel_hi:[1,0]
	v_max_f32_e32 v68, v56, v56
	v_max_f32_e32 v73, v58, v58
	v_max_f32_e32 v68, 0xc1a00000, v68
	v_max_f32_e32 v73, 0xc1a00000, v73
	v_mul_f32_e32 v68, 0xbfb8aa3b, v68
	v_mul_f32_e32 v73, 0xbfb8aa3b, v73
	v_exp_f32_e32 v69, v68
	v_max_f32_e32 v68, v57, v57
	v_exp_f32_e32 v75, v73
	v_max_f32_e32 v73, v59, v59
	v_max_f32_e32 v68, 0xc1a00000, v68
	v_max_f32_e32 v73, 0xc1a00000, v73
	v_mul_f32_e32 v68, 0xbfb8aa3b, v68
	v_mul_f32_e32 v73, 0xbfb8aa3b, v73
	v_exp_f32_e32 v68, v68
	v_exp_f32_e32 v74, v73
	v_pk_mul_f32 v[64:65], v[64:65], v[72:73] op_sel_hi:[1,0]
	v_pk_mul_f32 v[62:63], v[62:63], v[66:67]
	v_pk_mul_f32 v[60:61], v[60:61], v[64:65]
	v_pk_add_f32 v[64:65], v[68:69], 1.0 op_sel_hi:[1,0]
	v_pk_add_f32 v[68:69], v[74:75], 1.0 op_sel_hi:[1,0]
	v_mov_b32_e32 v72, v65
	v_mov_b32_e32 v73, v69
	v_mov_b32_e32 v74, v64
	v_mov_b32_e32 v75, v68
	v_pk_mul_f32 v[72:73], v[72:73], v[74:75]
	v_pk_mul_f32 v[54:55], v[62:63], v[54:55]
	v_mul_f32_e32 v74, v72, v73
	v_rcp_f32_e32 v74, v74
	v_pk_mul_f32 v[52:53], v[60:61], v[52:53]
	v_mul_f32_e32 v60, v73, v74
	v_mul_f32_e32 v62, v72, v74
	v_pk_mul_f32 v[62:63], v[68:69], v[62:63] op_sel_hi:[1,0]
	v_pk_mul_f32 v[60:61], v[64:65], v[60:61] op_sel_hi:[1,0]
	v_pk_mul_f32 v[58:59], v[58:59], v[62:63]
	v_pk_mul_f32 v[56:57], v[56:57], v[60:61]
	v_pk_mul_f32 v[58:59], v[58:59], v[50:51]
	v_pk_mul_f32 v[50:51], v[56:57], v[48:49]
	v_cvt_pk_bf16_f32 v48, v52, v53
	v_cvt_pk_bf16_f32 v49, v54, v55
	v_max_f32_e32 v52, v44, v44
	v_max_f32_e32 v54, v46, v46
	v_max_f32_e32 v52, 0xc1a00000, v52
	v_max_f32_e32 v54, 0xc1a00000, v54
	v_mul_f32_e32 v52, 0xbfb8aa3b, v52
	v_mul_f32_e32 v54, 0xbfb8aa3b, v54
	v_exp_f32_e32 v53, v52
	v_max_f32_e32 v52, v45, v45
	v_exp_f32_e32 v55, v54
; __device__ __forceinline__ unsigned cvt_pk_bf16(float lo, float hi) { unsigned r; asm volatile("v_cvt_pk_bf16_f32 %0, %1, %2" : "=v"(r) : "v"(lo), "v"(hi)); return r; }
; __device__ __forceinline__ f32x4 sigmoid4(f32x4 x) {
;     f32x4 d;
; #pragma unroll
;     for (int j = 0; j < 4; ++j) d[j] = 1.0f + __expf(-fmaxf(x[j], -20.0f));
;     const float p01 = d[0] * d[1], p23 = d[2] * d[3], r = __builtin_amdgcn_rcpf(p01 * p23), r01 = r * p23, r23 = r * p01;
;     return (f32x4){r01 * d[1], r01 * d[0], r23 * d[3], r23 * d[2]};
; }
;     __device__ __forceinline__ void operator()(const f32x4 (&acc)[2][2][4][2], const Unit& u, int wr, int wc, int fr, int fq) const {
;     ...
;         for (int ai = 0; ai < 2; ++ai)
; #pragma unroll
;             for (int m = 0; m < 4; ++m) { bf16_t* rowp = O + (size_t)(row0 + ai * HALF + m * 16) * ldc + col0;
;                 f32x4 v0, v1;
; #pragma unroll
;                 for (int j = 0; j < 1; ++j) { v0 = acc[ai][0][m][0] * sigmoid4(acc[ai][0][m][0]) * acc[ai][1][m][0]; v1 = acc[ai][0][m][1] * sigmoid4(acc[ai][0][m][1]) * acc[ai][1][m][1]; }
;                 u32x4 w; w.x = cvt_pk_bf16(v0[0], v0[1]); w.y = cvt_pk_bf16(v0[2], v0[3]); w.z = cvt_pk_bf16(v1[0], v1[1]); w.w = cvt_pk_bf16(v1[2], v1[3]);
;                 *(u32x4*)rowp = w; }
	v_max_f32_e32 v54, v47, v47
	v_max_f32_e32 v52, 0xc1a00000, v52
	v_max_f32_e32 v54, 0xc1a00000, v54
	v_mul_f32_e32 v52, 0xbfb8aa3b, v52
	v_mul_f32_e32 v54, 0xbfb8aa3b, v54
	v_exp_f32_e32 v52, v52
	v_exp_f32_e32 v54, v54
	v_cvt_pk_bf16_f32 v50, v50, v51
	v_cvt_pk_bf16_f32 v51, v58, v59
	global_store_dwordx4 v[70:71], v[48:51], off
	v_add_u32_e32 v56, 0x90, v155
	s_nop 0
	v_pk_add_f32 v[48:49], v[52:53], 1.0 op_sel_hi:[1,0]
	v_pk_add_f32 v[50:51], v[54:55], 1.0 op_sel_hi:[1,0]
	v_mov_b32_e32 v52, v49
	v_mov_b32_e32 v53, v51
	v_mov_b32_e32 v54, v48
	v_mov_b32_e32 v55, v50
	v_pk_mul_f32 v[52:53], v[52:53], v[54:55]
	s_nop 0
	v_mul_f32_e32 v54, v52, v53
	v_rcp_f32_e32 v57, v54
	v_mad_i64_i32 v[54:55], s[28:29], v56, s52, v[144:145]
	v_lshl_add_u64 v[54:55], v[54:55], 0, v[146:147]
	v_mul_f32_e32 v52, v52, v57
	v_mul_f32_e32 v56, v53, v57
	v_pk_mul_f32 v[50:51], v[50:51], v[52:53] op_sel_hi:[1,0]
	v_max_f32_e32 v52, v40, v40
	v_max_f32_e32 v57, v42, v42
	v_max_f32_e32 v52, 0xc1a00000, v52
	v_max_f32_e32 v57, 0xc1a00000, v57
	v_mul_f32_e32 v52, 0xbfb8aa3b, v52
	v_mul_f32_e32 v57, 0xbfb8aa3b, v57
	v_exp_f32_e32 v53, v52
	v_max_f32_e32 v52, v41, v41
	v_exp_f32_e32 v59, v57
	v_max_f32_e32 v57, v43, v43
	v_max_f32_e32 v52, 0xc1a00000, v52
	v_max_f32_e32 v57, 0xc1a00000, v57
	v_mul_f32_e32 v52, 0xbfb8aa3b, v52
	v_mul_f32_e32 v57, 0xbfb8aa3b, v57
	v_exp_f32_e32 v52, v52
	v_exp_f32_e32 v58, v57
	v_pk_mul_f32 v[48:49], v[48:49], v[56:57] op_sel_hi:[1,0]
	v_pk_mul_f32 v[46:47], v[46:47], v[50:51]
	v_pk_mul_f32 v[44:45], v[44:45], v[48:49]
	v_pk_add_f32 v[48:49], v[52:53], 1.0 op_sel_hi:[1,0]
	v_pk_add_f32 v[52:53], v[58:59], 1.0 op_sel_hi:[1,0]
	v_mov_b32_e32 v56, v49
	v_mov_b32_e32 v57, v53
	v_mov_b32_e32 v58, v48
	v_mov_b32_e32 v59, v52
	v_pk_mul_f32 v[56:57], v[56:57], v[58:59]
	v_pk_mul_f32 v[38:39], v[46:47], v[38:39]
	v_mul_f32_e32 v58, v56, v57
	v_rcp_f32_e32 v58, v58
	v_pk_mul_f32 v[36:37], v[44:45], v[36:37]
	v_mul_f32_e32 v44, v57, v58
	v_mul_f32_e32 v46, v56, v58
	v_pk_mul_f32 v[46:47], v[52:53], v[46:47] op_sel_hi:[1,0]
	v_pk_mul_f32 v[44:45], v[48:49], v[44:45] op_sel_hi:[1,0]
	v_pk_mul_f32 v[42:43], v[42:43], v[46:47]
	v_pk_mul_f32 v[40:41], v[40:41], v[44:45]
	v_pk_mul_f32 v[42:43], v[42:43], v[34:35]
	v_pk_mul_f32 v[34:35], v[40:41], v[32:33]
	v_cvt_pk_bf16_f32 v32, v36, v37
	v_cvt_pk_bf16_f32 v33, v38, v39
	v_max_f32_e32 v36, v28, v28
	v_max_f32_e32 v38, v30, v30
	v_max_f32_e32 v36, 0xc1a00000, v36
	v_max_f32_e32 v38, 0xc1a00000, v38
	v_mul_f32_e32 v36, 0xbfb8aa3b, v36
	v_mul_f32_e32 v38, 0xbfb8aa3b, v38
	v_exp_f32_e32 v37, v36
	v_max_f32_e32 v36, v29, v29
	v_exp_f32_e32 v39, v38
	v_max_f32_e32 v38, v31, v31
	v_max_f32_e32 v36, 0xc1a00000, v36
	v_max_f32_e32 v38, 0xc1a00000, v38
	v_mul_f32_e32 v36, 0xbfb8aa3b, v36
	v_mul_f32_e32 v38, 0xbfb8aa3b, v38
	v_exp_f32_e32 v36, v36
	v_exp_f32_e32 v38, v38
	v_cvt_pk_bf16_f32 v34, v34, v35
	v_cvt_pk_bf16_f32 v35, v42, v43
	global_store_dwordx4 v[54:55], v[32:35], off
	v_add_u32_e32 v40, 0xa0, v155
	s_nop 0
	v_pk_add_f32 v[32:33], v[36:37], 1.0 op_sel_hi:[1,0]
	v_pk_add_f32 v[34:35], v[38:39], 1.0 op_sel_hi:[1,0]
	v_mov_b32_e32 v36, v33
	v_mov_b32_e32 v37, v35
	v_mov_b32_e32 v38, v32
	v_mov_b32_e32 v39, v34
	v_pk_mul_f32 v[36:37], v[36:37], v[38:39]
	s_nop 0
	v_mul_f32_e32 v38, v36, v37
	v_rcp_f32_e32 v41, v38
	v_mad_i64_i32 v[38:39], s[28:29], v40, s52, v[144:145]
	v_lshl_add_u64 v[38:39], v[38:39], 0, v[146:147]
	v_mul_f32_e32 v36, v36, v41
	v_mul_f32_e32 v40, v37, v41
	v_pk_mul_f32 v[34:35], v[34:35], v[36:37] op_sel_hi:[1,0]
	v_max_f32_e32 v36, v24, v24
	v_max_f32_e32 v41, v26, v26
	v_max_f32_e32 v36, 0xc1a00000, v36
	v_max_f32_e32 v41, 0xc1a00000, v41
	v_mul_f32_e32 v36, 0xbfb8aa3b, v36
	v_mul_f32_e32 v41, 0xbfb8aa3b, v41
	v_exp_f32_e32 v37, v36
	v_max_f32_e32 v36, v25, v25
	v_exp_f32_e32 v43, v41
	v_max_f32_e32 v41, v27, v27
	v_max_f32_e32 v36, 0xc1a00000, v36
	v_max_f32_e32 v41, 0xc1a00000, v41
; __device__ __forceinline__ unsigned cvt_pk_bf16(float lo, float hi) { unsigned r; asm volatile("v_cvt_pk_bf16_f32 %0, %1, %2" : "=v"(r) : "v"(lo), "v"(hi)); return r; }
; __device__ __forceinline__ f32x4 sigmoid4(f32x4 x) {
;     f32x4 d;
; #pragma unroll
;     for (int j = 0; j < 4; ++j) d[j] = 1.0f + __expf(-fmaxf(x[j], -20.0f));
;     const float p01 = d[0] * d[1], p23 = d[2] * d[3], r = __builtin_amdgcn_rcpf(p01 * p23), r01 = r * p23, r23 = r * p01;
;     return (f32x4){r01 * d[1], r01 * d[0], r23 * d[3], r23 * d[2]};
; }
;     __device__ __forceinline__ void operator()(const f32x4 (&acc)[2][2][4][2], const Unit& u, int wr, int wc, int fr, int fq) const {
;     ...
;         for (int ai = 0; ai < 2; ++ai)
; #pragma unroll
;             for (int m = 0; m < 4; ++m) { bf16_t* rowp = O + (size_t)(row0 + ai * HALF + m * 16) * ldc + col0;
;                 f32x4 v0, v1;
; #pragma unroll
;                 for (int j = 0; j < 1; ++j) { v0 = acc[ai][0][m][0] * sigmoid4(acc[ai][0][m][0]) * acc[ai][1][m][0]; v1 = acc[ai][0][m][1] * sigmoid4(acc[ai][0][m][1]) * acc[ai][1][m][1]; }
;                 u32x4 w; w.x = cvt_pk_bf16(v0[0], v0[1]); w.y = cvt_pk_bf16(v0[2], v0[3]); w.z = cvt_pk_bf16(v1[0], v1[1]); w.w = cvt_pk_bf16(v1[2], v1[3]);
;                 *(u32x4*)rowp = w; }
	v_mul_f32_e32 v36, 0xbfb8aa3b, v36
	v_mul_f32_e32 v41, 0xbfb8aa3b, v41
	v_exp_f32_e32 v36, v36
	v_exp_f32_e32 v42, v41
	v_pk_mul_f32 v[32:33], v[32:33], v[40:41] op_sel_hi:[1,0]
	v_pk_mul_f32 v[30:31], v[30:31], v[34:35]
	v_pk_mul_f32 v[28:29], v[28:29], v[32:33]
	v_pk_add_f32 v[32:33], v[36:37], 1.0 op_sel_hi:[1,0]
	v_pk_add_f32 v[36:37], v[42:43], 1.0 op_sel_hi:[1,0]
	v_mov_b32_e32 v40, v33
	v_mov_b32_e32 v41, v37
	v_mov_b32_e32 v42, v32
	v_mov_b32_e32 v43, v36
	v_pk_mul_f32 v[40:41], v[40:41], v[42:43]
	v_pk_mul_f32 v[22:23], v[30:31], v[22:23]
	v_mul_f32_e32 v42, v40, v41
	v_rcp_f32_e32 v42, v42
	v_pk_mul_f32 v[20:21], v[28:29], v[20:21]
	v_mul_f32_e32 v28, v41, v42
	v_mul_f32_e32 v30, v40, v42
	v_pk_mul_f32 v[30:31], v[36:37], v[30:31] op_sel_hi:[1,0]
	v_pk_mul_f32 v[28:29], v[32:33], v[28:29] op_sel_hi:[1,0]
	v_pk_mul_f32 v[26:27], v[26:27], v[30:31]
	v_pk_mul_f32 v[24:25], v[24:25], v[28:29]
	v_pk_mul_f32 v[26:27], v[26:27], v[18:19]
	v_pk_mul_f32 v[18:19], v[24:25], v[16:17]
	v_cvt_pk_bf16_f32 v16, v20, v21
	v_cvt_pk_bf16_f32 v17, v22, v23
	v_max_f32_e32 v20, v12, v12
	v_max_f32_e32 v22, v14, v14
	v_max_f32_e32 v20, 0xc1a00000, v20
	v_max_f32_e32 v22, 0xc1a00000, v22
	v_mul_f32_e32 v20, 0xbfb8aa3b, v20
	v_mul_f32_e32 v22, 0xbfb8aa3b, v22
	v_exp_f32_e32 v21, v20
	v_max_f32_e32 v20, v13, v13
	v_exp_f32_e32 v23, v22
	v_max_f32_e32 v22, v15, v15
	v_max_f32_e32 v20, 0xc1a00000, v20
	v_max_f32_e32 v22, 0xc1a00000, v22
	v_mul_f32_e32 v20, 0xbfb8aa3b, v20
	v_mul_f32_e32 v22, 0xbfb8aa3b, v22
	v_exp_f32_e32 v20, v20
	v_exp_f32_e32 v22, v22
	v_cvt_pk_bf16_f32 v18, v18, v19
	v_cvt_pk_bf16_f32 v19, v26, v27
	global_store_dwordx4 v[38:39], v[16:19], off
	v_add_u32_e32 v24, 0xb0, v155
	s_nop 0
	v_pk_add_f32 v[16:17], v[20:21], 1.0 op_sel_hi:[1,0]
	v_pk_add_f32 v[18:19], v[22:23], 1.0 op_sel_hi:[1,0]
	v_mov_b32_e32 v20, v17
	v_mov_b32_e32 v21, v19
	v_mov_b32_e32 v22, v16
	v_mov_b32_e32 v23, v18
	v_pk_mul_f32 v[20:21], v[20:21], v[22:23]
	s_nop 0
	v_mul_f32_e32 v22, v20, v21
	v_rcp_f32_e32 v25, v22
	v_mad_i64_i32 v[22:23], s[28:29], v24, s52, v[144:145]
	v_lshl_add_u64 v[22:23], v[22:23], 0, v[146:147]
	v_mul_f32_e32 v20, v20, v25
	v_mul_f32_e32 v24, v21, v25
	v_pk_mul_f32 v[18:19], v[18:19], v[20:21] op_sel_hi:[1,0]
	v_max_f32_e32 v20, v8, v8
	v_max_f32_e32 v25, v10, v10
	v_max_f32_e32 v20, 0xc1a00000, v20
	v_max_f32_e32 v25, 0xc1a00000, v25
	v_mul_f32_e32 v20, 0xbfb8aa3b, v20
	v_mul_f32_e32 v25, 0xbfb8aa3b, v25
	v_exp_f32_e32 v21, v20
	v_max_f32_e32 v20, v9, v9
	v_exp_f32_e32 v27, v25
	v_max_f32_e32 v25, v11, v11
	v_max_f32_e32 v20, 0xc1a00000, v20
	v_max_f32_e32 v25, 0xc1a00000, v25
	v_mul_f32_e32 v20, 0xbfb8aa3b, v20
	v_mul_f32_e32 v25, 0xbfb8aa3b, v25
	v_exp_f32_e32 v20, v20
	v_exp_f32_e32 v26, v25
	v_pk_mul_f32 v[16:17], v[16:17], v[24:25] op_sel_hi:[1,0]
	v_pk_mul_f32 v[14:15], v[14:15], v[18:19]
	v_pk_mul_f32 v[12:13], v[12:13], v[16:17]
	v_pk_add_f32 v[16:17], v[20:21], 1.0 op_sel_hi:[1,0]
	v_pk_add_f32 v[20:21], v[26:27], 1.0 op_sel_hi:[1,0]
	v_mov_b32_e32 v24, v17
	v_mov_b32_e32 v25, v21
	v_mov_b32_e32 v26, v16
	v_mov_b32_e32 v27, v20
	v_pk_mul_f32 v[24:25], v[24:25], v[26:27]
	v_pk_mul_f32 v[6:7], v[14:15], v[6:7]
	v_mul_f32_e32 v26, v24, v25
	v_rcp_f32_e32 v26, v26
	v_pk_mul_f32 v[4:5], v[12:13], v[4:5]
	s_mov_b64 s[28:29], s[18:19]
	v_mul_f32_e32 v12, v25, v26
	v_mul_f32_e32 v14, v24, v26
	v_pk_mul_f32 v[14:15], v[20:21], v[14:15] op_sel_hi:[1,0]
	v_pk_mul_f32 v[12:13], v[16:17], v[12:13] op_sel_hi:[1,0]
	v_pk_mul_f32 v[10:11], v[10:11], v[14:15]
	v_pk_mul_f32 v[8:9], v[8:9], v[12:13]
	v_pk_mul_f32 v[10:11], v[10:11], v[2:3]
	v_pk_mul_f32 v[2:3], v[8:9], v[0:1]
	v_cvt_pk_bf16_f32 v0, v4, v5
	v_cvt_pk_bf16_f32 v1, v6, v7
	s_nop 0
	v_cvt_pk_bf16_f32 v2, v2, v3
	v_cvt_pk_bf16_f32 v3, v10, v11
	global_store_dwordx4 v[22:23], v[0:3], off
	s_cbranch_vccz .LBB0_192
	s_waitcnt vmcnt(0)
	s_cmpk_gt_u32 s37, 0xff
	s_cbranch_scc1 .LBB0_199
	s_barrier

; #define PG8_STAGE(bufoff, gbase, voff) do { _Pragma("unroll") for (int _i = 0; _i < 2; ++_i) \
;         __builtin_amdgcn_global_load_lds((const unsigned*)((const char*)(gbase) + (voff)[_i]), (PG8_LAS unsigned*)(lds + (bufoff) + ldsw + _i * 8192), 16, 0, 0); } while (0)
; #define PG8_LDA(dst, b, h) do { _Pragma("unroll") for (int m = 0; m < 4; ++m) _Pragma("unroll") for (int k = 0; k < 2; ++k) dst[m][k] = *(const PG8_LAS bf16x8*)(lds + PG8_SA(b, h) + aoff + m * 2048 + k * 1024); } while (0)
; #define PG8_LDB(dst, b, h) do { _Pragma("unroll") for (int n = 0; n < 2; ++n) _Pragma("unroll") for (int k = 0; k < 2; ++k) dst[n][k] = *(const PG8_LAS bf16x8*)(lds + PG8_SB(b, h) + boff + n * 2048 + k * 1024); } while (0)
; #define PG8_MMA(ai, bj, At, Bt) do { __builtin_amdgcn_s_setprio(1); _Pragma("unroll") for (int m = 0; m < 4; ++m) _Pragma("unroll") for (int n = 0; n < 2; ++n) _Pragma("unroll") for (int k = 0; k < 2; ++k) \
;         acc[ai][bj][m][n] = __builtin_amdgcn_mfma_f32_16x16x32_bf16(Bt[n][k], At[m][k], acc[ai][bj][m][n], 0, 0, 0); __builtin_amdgcn_s_setprio(0); } while (0)
; #define PG8_WAIT_L(n) asm volatile("s_waitcnt lgkmcnt(" #n ")" ::: "memory")
; #define PG8_BAR __builtin_amdgcn_s_barrier()
; #define PG8_SCHED __builtin_amdgcn_sched_barrier(0)
; template <class Epi, class Sched>
; __device__ __forceinline__ void gemm_phase(PG8_LAS unsigned char* lds, const Gemm g, const Sched& S, const Epi& E) {
;     ...
;             PG8_LDB(B0, 0, 0); PG8_SCHED; PG8_LDA(At, 0, 0); PG8_STAGE(PG8_SA(1, 1), a1 + hstep, voffA);
;             PG8_WAIT_L(8); PG8_BAR; PG8_WAIT_L(0); PG8_MMA(0, 0, At, B0); PG8_BAR; PG8_SCHED;
;             PG8_LDB(B1, 0, 1); PG8_STAGE(PG8_SB(0, 0), b2, voffB);
;             PG8_BAR; PG8_WAIT_L(0); PG8_MMA(0, 1, At, B1); PG8_BAR;
;             PG8_LDA(At, 0, 1); PG8_STAGE(PG8_SA(0, 0), a2, voffA);
;             PG8_BAR; PG8_WAIT_L(0); PG8_MMA(1, 0, At, B0); PG8_BAR; PG8_SCHED;
.LBB0_286:
	ds_read_b128 v[154:157], v149
	ds_read_b128 v[158:161], v149 offset:1024
	ds_read_b128 v[166:169], v149 offset:2048
	ds_read_b128 v[170:173], v149 offset:3072
	s_add_u32 s24, s22, 0x100
	s_addc_u32 s25, s23, 0
	s_cmp_eq_u32 s57, 40
	s_cselect_b32 s29, s1, s25
	s_cselect_b32 s28, s0, s24
	s_cselect_b32 s27, s5, s56
	s_cselect_b32 s26, s4, s55
	v_lshl_add_u64 v[144:145], s[22:23], 0, v[136:137]
	s_add_i32 m0, s38, 0xc000
	ds_read_b128 v[182:185], v150
	ds_read_b128 v[190:193], v150 offset:1024
	ds_read_b128 v[194:197], v150 offset:2048
	ds_read_b128 v[198:201], v150 offset:3072
	ds_read_b128 v[202:205], v150 offset:4096
	ds_read_b128 v[206:209], v150 offset:5120
	ds_read_b128 v[210:213], v150 offset:6144
	ds_read_b128 v[214:217], v150 offset:7168
	global_load_lds_dwordx4 v[144:145], off
	v_lshl_add_u64 v[144:145], s[22:23], 0, v[138:139]
	s_add_i32 m0, s38, 0xe000
	s_nop 0
	global_load_lds_dwordx4 v[144:145], off
	s_waitcnt lgkmcnt(8)
	s_barrier
	s_waitcnt lgkmcnt(0)
	s_setprio 0
	s_waitcnt lgkmcnt(0)
	v_mfma_f32_16x16x32_bf16 v[124:127], v[154:157], v[182:185], v[124:127]
	v_mfma_f32_16x16x32_bf16 v[120:123], v[166:169], v[182:185], v[120:123]
	v_mfma_f32_16x16x32_bf16 v[108:111], v[154:157], v[194:197], v[108:111]
	v_mfma_f32_16x16x32_bf16 v[104:107], v[166:169], v[194:197], v[104:107]
	v_mfma_f32_16x16x32_bf16 v[92:95], v[154:157], v[202:205], v[92:95]
	v_mfma_f32_16x16x32_bf16 v[88:91], v[166:169], v[202:205], v[88:91]
	v_mfma_f32_16x16x32_bf16 v[76:79], v[154:157], v[210:213], v[76:79]
	v_mfma_f32_16x16x32_bf16 v[72:75], v[166:169], v[210:213], v[72:75]
	v_mfma_f32_16x16x32_bf16 v[124:127], v[158:161], v[190:193], v[124:127]
	v_mfma_f32_16x16x32_bf16 v[120:123], v[170:173], v[190:193], v[120:123]
	v_mfma_f32_16x16x32_bf16 v[108:111], v[158:161], v[198:201], v[108:111]
	v_mfma_f32_16x16x32_bf16 v[104:107], v[170:173], v[198:201], v[104:107]
	v_mfma_f32_16x16x32_bf16 v[92:95], v[158:161], v[206:209], v[92:95]
	v_mfma_f32_16x16x32_bf16 v[88:91], v[170:173], v[206:209], v[88:91]
	v_mfma_f32_16x16x32_bf16 v[76:79], v[158:161], v[214:217], v[76:79]
	v_mfma_f32_16x16x32_bf16 v[72:75], v[170:173], v[214:217], v[72:75]
	s_setprio 1
	s_barrier
	s_add_i32 s22, s46, s37
	v_lshl_add_u64 v[144:145], s[26:27], 0, v[130:131]
	s_mov_b32 m0, s22
	ds_read_b128 v[218:221], v151
	ds_read_b128 v[222:225], v151 offset:1024
	ds_read_b128 v[226:229], v151 offset:2048
	ds_read_b128 v[230:233], v151 offset:3072
	global_load_lds_dwordx4 v[144:145], off
	v_lshl_add_u64 v[162:163], s[26:27], 0, v[134:135]
	s_add_i32 m0, s22, 0x2000
	s_nop 0
	global_load_lds_dwordx4 v[162:163], off
	s_barrier
	s_waitcnt lgkmcnt(0)
	s_setprio 0
	s_waitcnt lgkmcnt(0)
	v_mfma_f32_16x16x32_bf16 v[116:119], v[218:221], v[182:185], v[116:119]
	v_mfma_f32_16x16x32_bf16 v[112:115], v[226:229], v[182:185], v[112:115]
	v_mfma_f32_16x16x32_bf16 v[100:103], v[218:221], v[194:197], v[100:103]
	v_mfma_f32_16x16x32_bf16 v[96:99], v[226:229], v[194:197], v[96:99]
	v_mfma_f32_16x16x32_bf16 v[84:87], v[218:221], v[202:205], v[84:87]
	v_mfma_f32_16x16x32_bf16 v[80:83], v[226:229], v[202:205], v[80:83]
	v_mfma_f32_16x16x32_bf16 v[68:71], v[218:221], v[210:213], v[68:71]
	v_mfma_f32_16x16x32_bf16 v[64:67], v[226:229], v[210:213], v[64:67]
	v_mfma_f32_16x16x32_bf16 v[116:119], v[222:225], v[190:193], v[116:119]
	v_mfma_f32_16x16x32_bf16 v[112:115], v[230:233], v[190:193], v[112:115]
	v_mfma_f32_16x16x32_bf16 v[100:103], v[222:225], v[198:201], v[100:103]
	v_mfma_f32_16x16x32_bf16 v[96:99], v[230:233], v[198:201], v[96:99]
	v_mfma_f32_16x16x32_bf16 v[84:87], v[222:225], v[206:209], v[84:87]
	v_mfma_f32_16x16x32_bf16 v[80:83], v[230:233], v[206:209], v[80:83]
	v_mfma_f32_16x16x32_bf16 v[68:71], v[222:225], v[214:217], v[68:71]
	v_mfma_f32_16x16x32_bf16 v[64:67], v[230:233], v[214:217], v[64:67]
	s_setprio 1
	s_mov_b32 m0, s38
	v_lshl_add_u64 v[174:175], s[28:29], 0, v[128:129]
	s_barrier
	ds_read_b128 v[182:185], v150 offset:16384
	ds_read_b128 v[190:193], v150 offset:17408
	ds_read_b128 v[194:197], v150 offset:18432
	ds_read_b128 v[198:201], v150 offset:19456
	ds_read_b128 v[202:205], v150 offset:20480
	ds_read_b128 v[206:209], v150 offset:21504
	ds_read_b128 v[210:213], v150 offset:22528
	ds_read_b128 v[214:217], v150 offset:23552
	global_load_lds_dwordx4 v[174:175], off
	v_lshl_add_u64 v[178:179], s[28:29], 0, v[132:133]
	s_mov_b32 m0, s39
	s_nop 0
	global_load_lds_dwordx4 v[178:179], off
	s_barrier
	s_waitcnt lgkmcnt(0)
	s_setprio 0
	s_waitcnt lgkmcnt(0)
	v_mfma_f32_16x16x32_bf16 v[60:63], v[154:157], v[182:185], v[60:63]
	v_mfma_f32_16x16x32_bf16 v[56:59], v[166:169], v[182:185], v[56:59]
	v_mfma_f32_16x16x32_bf16 v[48:51], v[154:157], v[194:197], v[48:51]
	v_mfma_f32_16x16x32_bf16 v[40:43], v[166:169], v[194:197], v[40:43]
	v_mfma_f32_16x16x32_bf16 v[32:35], v[154:157], v[202:205], v[32:35]
	v_mfma_f32_16x16x32_bf16 v[24:27], v[166:169], v[202:205], v[24:27]
	v_mfma_f32_16x16x32_bf16 v[16:19], v[154:157], v[210:213], v[16:19]
	v_mfma_f32_16x16x32_bf16 v[8:11], v[166:169], v[210:213], v[8:11]
	v_mfma_f32_16x16x32_bf16 v[60:63], v[158:161], v[190:193], v[60:63]
	v_mfma_f32_16x16x32_bf16 v[56:59], v[170:173], v[190:193], v[56:59]
	v_mfma_f32_16x16x32_bf16 v[48:51], v[158:161], v[198:201], v[48:51]
	v_mfma_f32_16x16x32_bf16 v[40:43], v[170:173], v[198:201], v[40:43]
	v_mfma_f32_16x16x32_bf16 v[32:35], v[158:161], v[206:209], v[32:35]
	v_mfma_f32_16x16x32_bf16 v[24:27], v[170:173], v[206:209], v[24:27]
	v_mfma_f32_16x16x32_bf16 v[16:19], v[158:161], v[214:217], v[16:19]
	v_mfma_f32_16x16x32_bf16 v[8:11], v[170:173], v[214:217], v[8:11]
	s_setprio 1
	s_barrier
; #define PG8_STAGE(bufoff, gbase, voff) do { _Pragma("unroll") for (int _i = 0; _i < 2; ++_i) \
;         __builtin_amdgcn_global_load_lds((const unsigned*)((const char*)(gbase) + (voff)[_i]), (PG8_LAS unsigned*)(lds + (bufoff) + ldsw + _i * 8192), 16, 0, 0); } while (0)
; #define PG8_LDA(dst, b, h) do { _Pragma("unroll") for (int m = 0; m < 4; ++m) _Pragma("unroll") for (int k = 0; k < 2; ++k) dst[m][k] = *(const PG8_LAS bf16x8*)(lds + PG8_SA(b, h) + aoff + m * 2048 + k * 1024); } while (0)
; #define PG8_LDB(dst, b, h) do { _Pragma("unroll") for (int n = 0; n < 2; ++n) _Pragma("unroll") for (int k = 0; k < 2; ++k) dst[n][k] = *(const PG8_LAS bf16x8*)(lds + PG8_SB(b, h) + boff + n * 2048 + k * 1024); } while (0)
; #define PG8_MMA(ai, bj, At, Bt) do { __builtin_amdgcn_s_setprio(1); _Pragma("unroll") for (int m = 0; m < 4; ++m) _Pragma("unroll") for (int n = 0; n < 2; ++n) _Pragma("unroll") for (int k = 0; k < 2; ++k) \
;         acc[ai][bj][m][n] = __builtin_amdgcn_mfma_f32_16x16x32_bf16(Bt[n][k], At[m][k], acc[ai][bj][m][n], 0, 0, 0); __builtin_amdgcn_s_setprio(0); } while (0)
; #define PG8_WAIT_V(n) asm volatile("s_waitcnt vmcnt(" #n ")" ::: "memory")
; #define PG8_WAIT_L(n) asm volatile("s_waitcnt lgkmcnt(" #n ")" ::: "memory")
; #define PG8_BAR __builtin_amdgcn_s_barrier()
; #define PG8_SCHED __builtin_amdgcn_sched_barrier(0)
; template <class Epi, class Sched>
; __device__ __forceinline__ void gemm_phase(PG8_LAS unsigned char* lds, const Gemm g, const Sched& S, const Epi& E) {
;     ...
;             PG8_STAGE(PG8_SB(0, 1), b2 + hstep, voffB);
;             PG8_WAIT_V(6); PG8_BAR; PG8_MMA(1, 1, At, B1); PG8_BAR;
;             PG8_LDB(B0, 1, 0); PG8_SCHED; PG8_LDA(At, 1, 0); PG8_STAGE(PG8_SA(0, 1), a2 + hstep, voffA);
;             PG8_WAIT_L(8); PG8_BAR; PG8_WAIT_L(0); PG8_MMA(0, 0, At, B0); PG8_BAR; PG8_SCHED;
;             PG8_LDB(B1, 1, 1); PG8_STAGE(PG8_SB(1, 0), b3, voffB);
;             PG8_BAR; PG8_WAIT_L(0); PG8_MMA(0, 1, At, B1); PG8_BAR;
;             PG8_LDA(At, 1, 1); PG8_STAGE(PG8_SA(1, 0), a3, voffA);
	s_add_u32 s22, s26, 0xb0000
	s_addc_u32 s23, s27, 0
	s_add_i32 s58, s47, s37
	v_lshl_add_u64 v[154:155], s[22:23], 0, v[130:131]
	s_mov_b32 m0, s58
	s_nop 0
	global_load_lds_dwordx4 v[154:155], off
	v_lshl_add_u64 v[154:155], s[22:23], 0, v[134:135]
	s_add_i32 m0, s58, 0x2000
	s_nop 0
	global_load_lds_dwordx4 v[154:155], off
	s_waitcnt vmcnt(6)
	s_barrier
	s_setprio 0
	v_mfma_f32_16x16x32_bf16 v[52:55], v[218:221], v[182:185], v[52:55]
	v_mfma_f32_16x16x32_bf16 v[44:47], v[226:229], v[182:185], v[44:47]
	v_mfma_f32_16x16x32_bf16 v[36:39], v[218:221], v[194:197], v[36:39]
	v_mfma_f32_16x16x32_bf16 v[28:31], v[226:229], v[194:197], v[28:31]
	v_mfma_f32_16x16x32_bf16 v[20:23], v[218:221], v[202:205], v[20:23]
	v_mfma_f32_16x16x32_bf16 v[12:15], v[226:229], v[202:205], v[12:15]
	v_mfma_f32_16x16x32_bf16 v[4:7], v[218:221], v[210:213], v[4:7]
	v_mfma_f32_16x16x32_bf16 v[0:3], v[226:229], v[210:213], v[0:3]
	v_mfma_f32_16x16x32_bf16 v[52:55], v[222:225], v[190:193], v[52:55]
	v_mfma_f32_16x16x32_bf16 v[44:47], v[230:233], v[190:193], v[44:47]
	v_mfma_f32_16x16x32_bf16 v[36:39], v[222:225], v[198:201], v[36:39]
	v_mfma_f32_16x16x32_bf16 v[28:31], v[230:233], v[198:201], v[28:31]
	v_mfma_f32_16x16x32_bf16 v[20:23], v[222:225], v[206:209], v[20:23]
	v_mfma_f32_16x16x32_bf16 v[12:15], v[230:233], v[206:209], v[12:15]
	v_mfma_f32_16x16x32_bf16 v[4:7], v[222:225], v[214:217], v[4:7]
	v_mfma_f32_16x16x32_bf16 v[0:3], v[230:233], v[214:217], v[0:3]
	s_setprio 1
	s_add_i32 s58, 0, 0x18000
	v_add_u32_e32 v153, s58, v147
	s_barrier
	ds_read_b128 v[154:157], v153
	ds_read_b128 v[158:161], v153 offset:1024
	ds_read_b128 v[166:169], v153 offset:2048
	ds_read_b128 v[170:173], v153 offset:3072
	s_add_u32 s22, s28, 0xb0000
	s_addc_u32 s23, s29, 0
	s_mov_b32 m0, s40
	v_lshl_add_u64 v[186:187], s[22:23], 0, v[128:129]
	ds_read_b128 v[182:185], v150 offset:32768
	ds_read_b128 v[190:193], v150 offset:33792
	ds_read_b128 v[194:197], v150 offset:34816
	ds_read_b128 v[198:201], v150 offset:35840
	ds_read_b128 v[202:205], v150 offset:36864
	ds_read_b128 v[206:209], v150 offset:37888
	ds_read_b128 v[210:213], v150 offset:38912
	ds_read_b128 v[214:217], v150 offset:39936
	global_load_lds_dwordx4 v[186:187], off
	v_lshl_add_u64 v[186:187], s[22:23], 0, v[132:133]
	s_mov_b32 m0, s41
	s_nop 0
	global_load_lds_dwordx4 v[186:187], off
	s_waitcnt lgkmcnt(8)
	s_barrier
	s_waitcnt lgkmcnt(0)
	s_setprio 0
	s_waitcnt lgkmcnt(0)
	v_mfma_f32_16x16x32_bf16 v[124:127], v[154:157], v[182:185], v[124:127]
	v_mfma_f32_16x16x32_bf16 v[120:123], v[166:169], v[182:185], v[120:123]
	v_mfma_f32_16x16x32_bf16 v[108:111], v[154:157], v[194:197], v[108:111]
	v_mfma_f32_16x16x32_bf16 v[104:107], v[166:169], v[194:197], v[104:107]
	v_mfma_f32_16x16x32_bf16 v[92:95], v[154:157], v[202:205], v[92:95]
	v_mfma_f32_16x16x32_bf16 v[88:91], v[166:169], v[202:205], v[88:91]
	v_mfma_f32_16x16x32_bf16 v[76:79], v[154:157], v[210:213], v[76:79]
	v_mfma_f32_16x16x32_bf16 v[72:75], v[166:169], v[210:213], v[72:75]
	v_mfma_f32_16x16x32_bf16 v[124:127], v[158:161], v[190:193], v[124:127]
	v_mfma_f32_16x16x32_bf16 v[120:123], v[170:173], v[190:193], v[120:123]
	v_mfma_f32_16x16x32_bf16 v[108:111], v[158:161], v[198:201], v[108:111]
	v_mfma_f32_16x16x32_bf16 v[104:107], v[170:173], v[198:201], v[104:107]
	v_mfma_f32_16x16x32_bf16 v[92:95], v[158:161], v[206:209], v[92:95]
	v_mfma_f32_16x16x32_bf16 v[88:91], v[170:173], v[206:209], v[88:91]
	v_mfma_f32_16x16x32_bf16 v[76:79], v[158:161], v[214:217], v[76:79]
	v_mfma_f32_16x16x32_bf16 v[72:75], v[170:173], v[214:217], v[72:75]
	s_setprio 1
	s_barrier
	s_add_i32 s28, 0, 0x1c000
	s_add_i32 s22, s58, s37
	v_add_u32_e32 v153, s28, v147
	v_lshl_add_u64 v[144:145], v[144:145], 0, s[14:15]
	s_mov_b32 m0, s22
	ds_read_b128 v[218:221], v153
	ds_read_b128 v[222:225], v153 offset:1024
	ds_read_b128 v[226:229], v153 offset:2048
	ds_read_b128 v[230:233], v153 offset:3072
	global_load_lds_dwordx4 v[144:145], off
	v_lshl_add_u64 v[144:145], v[162:163], 0, s[14:15]
	s_add_i32 m0, s22, 0x2000
	s_nop 0
	global_load_lds_dwordx4 v[144:145], off
	s_barrier
	s_waitcnt lgkmcnt(0)
	s_setprio 0
	s_waitcnt lgkmcnt(0)
	v_mfma_f32_16x16x32_bf16 v[116:119], v[218:221], v[182:185], v[116:119]
	v_mfma_f32_16x16x32_bf16 v[112:115], v[226:229], v[182:185], v[112:115]
	v_mfma_f32_16x16x32_bf16 v[100:103], v[218:221], v[194:197], v[100:103]
	v_mfma_f32_16x16x32_bf16 v[96:99], v[226:229], v[194:197], v[96:99]
	v_mfma_f32_16x16x32_bf16 v[84:87], v[218:221], v[202:205], v[84:87]
	v_mfma_f32_16x16x32_bf16 v[80:83], v[226:229], v[202:205], v[80:83]
	v_mfma_f32_16x16x32_bf16 v[68:71], v[218:221], v[210:213], v[68:71]
	v_mfma_f32_16x16x32_bf16 v[64:67], v[226:229], v[210:213], v[64:67]
	v_mfma_f32_16x16x32_bf16 v[116:119], v[222:225], v[190:193], v[116:119]
	v_mfma_f32_16x16x32_bf16 v[112:115], v[230:233], v[190:193], v[112:115]
	v_mfma_f32_16x16x32_bf16 v[100:103], v[222:225], v[198:201], v[100:103]
	v_mfma_f32_16x16x32_bf16 v[96:99], v[230:233], v[198:201], v[96:99]
	v_mfma_f32_16x16x32_bf16 v[84:87], v[222:225], v[206:209], v[84:87]
	v_mfma_f32_16x16x32_bf16 v[80:83], v[230:233], v[206:209], v[80:83]
	v_mfma_f32_16x16x32_bf16 v[68:71], v[222:225], v[214:217], v[68:71]
	v_mfma_f32_16x16x32_bf16 v[64:67], v[230:233], v[214:217], v[64:67]
	s_setprio 1
	s_mov_b32 m0, s43
	v_lshl_add_u64 v[144:145], v[174:175], 0, s[14:15]
	s_barrier
	ds_read_b128 v[182:185], v150 offset:49152
	ds_read_b128 v[190:193], v150 offset:50176
	ds_read_b128 v[194:197], v150 offset:51200
	ds_read_b128 v[198:201], v150 offset:52224
	ds_read_b128 v[202:205], v150 offset:53248
	ds_read_b128 v[206:209], v150 offset:54272
	ds_read_b128 v[210:213], v150 offset:55296
	ds_read_b128 v[214:217], v150 offset:56320
	global_load_lds_dwordx4 v[144:145], off
	v_lshl_add_u64 v[144:145], v[178:179], 0, s[14:15]
	s_mov_b32 m0, s44
	s_nop 0
	global_load_lds_dwordx4 v[144:145], off
	s_barrier
; __device__ __forceinline__ unsigned cvt_pk_bf16(float lo, float hi) { unsigned r; asm volatile("v_cvt_pk_bf16_f32 %0, %1, %2" : "=v"(r) : "v"(lo), "v"(hi)); return r; }
; __device__ __forceinline__ float flogsig16(float x) { return (fminf(x, 0.f) - __logf(1.0f + __expf(-fabsf(x)))) * 0.0625f; }
; #define PG8_STAGE(bufoff, gbase, voff) do { _Pragma("unroll") for (int _i = 0; _i < 2; ++_i) \
;         __builtin_amdgcn_global_load_lds((const unsigned*)((const char*)(gbase) + (voff)[_i]), (PG8_LAS unsigned*)(lds + (bufoff) + ldsw + _i * 8192), 16, 0, 0); } while (0)
; #define PG8_WAIT_V(n) asm volatile("s_waitcnt vmcnt(" #n ")" ::: "memory")
; #define PG8_WAIT_L(n) asm volatile("s_waitcnt lgkmcnt(" #n ")" ::: "memory")
; #define PG8_BAR __builtin_amdgcn_s_barrier()
; #define PG8_SCHED __builtin_amdgcn_sched_barrier(0)
;     __device__ __forceinline__ void operator()(const f32x4 (&acc)[2][2][4][2], const Unit& u, int wr, int wc, int fr, int fq) const {
;     ...
;             for (int m = 0; m < 4; ++m) { bf16_t* rowp = O + (size_t)(row0 + ai * HALF + m * 16) * ldc + col0;
; #pragma unroll
;                 for (int bj = 0; bj < 2; ++bj) { f32x4 v0 = acc[ai][bj][m][0] + bv[bj][0], v1 = acc[ai][bj][m][1] + bv[bj][1];
;                     if (act == 1) {
; #pragma unroll
;                         for (int j = 0; j < 1; ++j) { v0 = v0 * sigmoid4(v0); v1 = v1 * sigmoid4(v1); } }
;                     else if (act == 2) {
; #pragma unroll
;                         for (int j = 0; j < 1; ++j) { v0 = sigmoid4(v0); v1 = sigmoid4(v1); } }
;                     else if (act == 3) {
; #pragma unroll
;                         for (int j = 0; j < 4; ++j) { v0[j] = flogsig16(v0[j]); v1[j] = flogsig16(v1[j]); } }
;                     u32x4 w; w.x = cvt_pk_bf16(v0[0], v0[1]); w.y = cvt_pk_bf16(v0[2], v0[3]); w.z = cvt_pk_bf16(v1[0], v1[1]); w.w = cvt_pk_bf16(v1[2], v1[3]);
;                     *(u32x4*)(rowp + bj * HALF) = w; } }
; template <class Epi, class Sched>
; __device__ __forceinline__ void gemm_phase(PG8_LAS unsigned char* lds, const Gemm g, const Sched& S, const Epi& E) {
;     ...
;             PG8_BAR; PG8_WAIT_L(0); PG8_MMA(1, 0, At, B0); PG8_BAR; PG8_SCHED;
;             PG8_STAGE(PG8_SB(1, 1), b3 + hstep, voffB);
;             PG8_WAIT_V(6); PG8_BAR; PG8_MMA(1, 1, At, B1); PG8_BAR;
	s_waitcnt lgkmcnt(0)
	s_setprio 0
	s_waitcnt lgkmcnt(0)
	v_mfma_f32_16x16x32_bf16 v[60:63], v[154:157], v[182:185], v[60:63]
	v_mfma_f32_16x16x32_bf16 v[56:59], v[166:169], v[182:185], v[56:59]
	v_mfma_f32_16x16x32_bf16 v[48:51], v[154:157], v[194:197], v[48:51]
	v_mfma_f32_16x16x32_bf16 v[40:43], v[166:169], v[194:197], v[40:43]
	v_mfma_f32_16x16x32_bf16 v[32:35], v[154:157], v[202:205], v[32:35]
	v_mfma_f32_16x16x32_bf16 v[24:27], v[166:169], v[202:205], v[24:27]
	v_mfma_f32_16x16x32_bf16 v[16:19], v[154:157], v[210:213], v[16:19]
	v_mfma_f32_16x16x32_bf16 v[8:11], v[166:169], v[210:213], v[8:11]
	v_mfma_f32_16x16x32_bf16 v[60:63], v[158:161], v[190:193], v[60:63]
	v_mfma_f32_16x16x32_bf16 v[56:59], v[170:173], v[190:193], v[56:59]
	v_mfma_f32_16x16x32_bf16 v[48:51], v[158:161], v[198:201], v[48:51]
	v_mfma_f32_16x16x32_bf16 v[40:43], v[170:173], v[198:201], v[40:43]
	v_mfma_f32_16x16x32_bf16 v[32:35], v[158:161], v[206:209], v[32:35]
	v_mfma_f32_16x16x32_bf16 v[24:27], v[170:173], v[206:209], v[24:27]
	v_mfma_f32_16x16x32_bf16 v[16:19], v[158:161], v[214:217], v[16:19]
	v_mfma_f32_16x16x32_bf16 v[8:11], v[170:173], v[214:217], v[8:11]
	s_setprio 1
	s_barrier
	s_add_u32 s22, s26, 0xb0080
	s_addc_u32 s23, s27, 0
	s_add_i32 s26, s28, s37
	v_lshl_add_u64 v[144:145], s[22:23], 0, v[130:131]
	s_mov_b32 m0, s26
	s_nop 0
	global_load_lds_dwordx4 v[144:145], off
	v_lshl_add_u64 v[144:145], s[22:23], 0, v[134:135]
	s_add_i32 m0, s26, 0x2000
	s_nop 0
	global_load_lds_dwordx4 v[144:145], off
	s_waitcnt vmcnt(6)
	s_barrier
	s_setprio 0
	v_mfma_f32_16x16x32_bf16 v[52:55], v[218:221], v[182:185], v[52:55]
	v_mfma_f32_16x16x32_bf16 v[44:47], v[226:229], v[182:185], v[44:47]
	v_mfma_f32_16x16x32_bf16 v[36:39], v[218:221], v[194:197], v[36:39]
	v_mfma_f32_16x16x32_bf16 v[28:31], v[226:229], v[194:197], v[28:31]
	v_mfma_f32_16x16x32_bf16 v[20:23], v[218:221], v[202:205], v[20:23]
	v_mfma_f32_16x16x32_bf16 v[12:15], v[226:229], v[202:205], v[12:15]
	v_mfma_f32_16x16x32_bf16 v[4:7], v[218:221], v[210:213], v[4:7]
	v_mfma_f32_16x16x32_bf16 v[0:3], v[226:229], v[210:213], v[0:3]
	v_mfma_f32_16x16x32_bf16 v[52:55], v[222:225], v[190:193], v[52:55]
	v_mfma_f32_16x16x32_bf16 v[44:47], v[230:233], v[190:193], v[44:47]
	v_mfma_f32_16x16x32_bf16 v[36:39], v[222:225], v[198:201], v[36:39]
	v_mfma_f32_16x16x32_bf16 v[28:31], v[230:233], v[198:201], v[28:31]
	v_mfma_f32_16x16x32_bf16 v[20:23], v[222:225], v[206:209], v[20:23]
	v_mfma_f32_16x16x32_bf16 v[12:15], v[230:233], v[206:209], v[12:15]
	v_mfma_f32_16x16x32_bf16 v[4:7], v[222:225], v[214:217], v[4:7]
	v_mfma_f32_16x16x32_bf16 v[0:3], v[230:233], v[214:217], v[0:3]
	s_setprio 1
	s_add_i32 s57, s57, 2
	s_add_u32 s55, s55, 0x100
	s_addc_u32 s56, s56, 0
	s_cmp_gt_u32 s57, 41
	s_mov_b64 s[22:23], s[24:25]
	s_barrier
	s_cbranch_scc0 .LBB0_286
	v_lshl_add_u32 v154, s53, 8, v146
	v_lshl_or_b32 v144, s54, 8, v148
	v_ashrrev_i32_e32 v155, 31, v154
	v_ashrrev_i32_e32 v145, 31, v144
	v_lshlrev_b64 v[156:157], 11, v[154:155]
	v_lshl_add_u64 v[156:157], s[10:11], 0, v[156:157]
	v_lshlrev_b64 v[158:159], 1, v[144:145]
	v_lshl_add_u64 v[144:145], v[156:157], 0, v[158:159]
	v_pk_add_f32 v[126:127], v[126:127], 0 op_sel_hi:[1,0]
	v_pk_add_f32 v[124:125], v[124:125], 0 op_sel_hi:[1,0]
	v_pk_add_f32 v[156:157], v[122:123], 0 op_sel_hi:[1,0]
	v_pk_add_f32 v[122:123], v[120:121], 0 op_sel_hi:[1,0]
	v_cvt_pk_bf16_f32 v120, v124, v125
	v_cvt_pk_bf16_f32 v121, v126, v127
	v_pk_add_f32 v[116:117], v[116:117], 0 op_sel_hi:[1,0]
	v_cvt_pk_bf16_f32 v122, v122, v123
	v_cvt_pk_bf16_f32 v123, v156, v157
	global_store_dwordx4 v[144:145], v[120:123], off
	v_pk_add_f32 v[118:119], v[118:119], 0 op_sel_hi:[1,0]
	v_pk_add_f32 v[110:111], v[110:111], 0 op_sel_hi:[1,0]
	v_pk_add_f32 v[120:121], v[114:115], 0 op_sel_hi:[1,0]
	v_pk_add_f32 v[114:115], v[112:113], 0 op_sel_hi:[1,0]
	v_cvt_pk_bf16_f32 v112, v116, v117
	v_cvt_pk_bf16_f32 v113, v118, v119
	v_pk_add_f32 v[108:109], v[108:109], 0 op_sel_hi:[1,0]
	v_cvt_pk_bf16_f32 v114, v114, v115
	v_cvt_pk_bf16_f32 v115, v120, v121
	global_store_dwordx4 v[144:145], v[112:115], off offset:256
	v_pk_add_f32 v[100:101], v[100:101], 0 op_sel_hi:[1,0]
	v_pk_add_f32 v[102:103], v[102:103], 0 op_sel_hi:[1,0]
	v_or_b32_e32 v112, 16, v154
	v_ashrrev_i32_e32 v113, 31, v112
	v_lshlrev_b64 v[112:113], 11, v[112:113]
	v_lshl_add_u64 v[112:113], s[10:11], 0, v[112:113]
	v_lshl_add_u64 v[112:113], v[112:113], 0, v[158:159]
	v_pk_add_f32 v[114:115], v[106:107], 0 op_sel_hi:[1,0]
	v_pk_add_f32 v[106:107], v[104:105], 0 op_sel_hi:[1,0]
	v_cvt_pk_bf16_f32 v104, v108, v109
	v_cvt_pk_bf16_f32 v105, v110, v111
	v_pk_add_f32 v[94:95], v[94:95], 0 op_sel_hi:[1,0]
	v_cvt_pk_bf16_f32 v106, v106, v107
	v_cvt_pk_bf16_f32 v107, v114, v115
	global_store_dwordx4 v[112:113], v[104:107], off
	v_pk_add_f32 v[92:93], v[92:93], 0 op_sel_hi:[1,0]
	v_pk_add_f32 v[84:85], v[84:85], 0 op_sel_hi:[1,0]
	v_pk_add_f32 v[104:105], v[98:99], 0 op_sel_hi:[1,0]
	v_pk_add_f32 v[98:99], v[96:97], 0 op_sel_hi:[1,0]
	v_cvt_pk_bf16_f32 v96, v100, v101
	v_cvt_pk_bf16_f32 v97, v102, v103
	v_pk_add_f32 v[86:87], v[86:87], 0 op_sel_hi:[1,0]
	v_cvt_pk_bf16_f32 v98, v98, v99
	v_cvt_pk_bf16_f32 v99, v104, v105
	global_store_dwordx4 v[112:113], v[96:99], off offset:256
	v_pk_add_f32 v[78:79], v[78:79], 0 op_sel_hi:[1,0]
	v_pk_add_f32 v[76:77], v[76:77], 0 op_sel_hi:[1,0]
	v_or_b32_e32 v96, 32, v154
	v_ashrrev_i32_e32 v97, 31, v96
	v_lshlrev_b64 v[96:97], 11, v[96:97]
	v_lshl_add_u64 v[96:97], s[10:11], 0, v[96:97]
; __device__ __forceinline__ unsigned cvt_pk_bf16(float lo, float hi) { unsigned r; asm volatile("v_cvt_pk_bf16_f32 %0, %1, %2" : "=v"(r) : "v"(lo), "v"(hi)); return r; }
; __device__ __forceinline__ float flogsig16(float x) { return (fminf(x, 0.f) - __logf(1.0f + __expf(-fabsf(x)))) * 0.0625f; }
;     __device__ __forceinline__ void operator()(const f32x4 (&acc)[2][2][4][2], const Unit& u, int wr, int wc, int fr, int fq) const {
;     ...
;             for (int m = 0; m < 4; ++m) { bf16_t* rowp = O + (size_t)(row0 + ai * HALF + m * 16) * ldc + col0;
; #pragma unroll
;                 for (int bj = 0; bj < 2; ++bj) { f32x4 v0 = acc[ai][bj][m][0] + bv[bj][0], v1 = acc[ai][bj][m][1] + bv[bj][1];
;                     if (act == 1) {
; #pragma unroll
;                         for (int j = 0; j < 1; ++j) { v0 = v0 * sigmoid4(v0); v1 = v1 * sigmoid4(v1); } }
;                     else if (act == 2) {
; #pragma unroll
;                         for (int j = 0; j < 1; ++j) { v0 = sigmoid4(v0); v1 = sigmoid4(v1); } }
;                     else if (act == 3) {
; #pragma unroll
;                         for (int j = 0; j < 4; ++j) { v0[j] = flogsig16(v0[j]); v1[j] = flogsig16(v1[j]); } }
;                     u32x4 w; w.x = cvt_pk_bf16(v0[0], v0[1]); w.y = cvt_pk_bf16(v0[2], v0[3]); w.z = cvt_pk_bf16(v1[0], v1[1]); w.w = cvt_pk_bf16(v1[2], v1[3]);
;                     *(u32x4*)(rowp + bj * HALF) = w; } }
	v_lshl_add_u64 v[96:97], v[96:97], 0, v[158:159]
	v_pk_add_f32 v[98:99], v[90:91], 0 op_sel_hi:[1,0]
	v_pk_add_f32 v[90:91], v[88:89], 0 op_sel_hi:[1,0]
	v_cvt_pk_bf16_f32 v88, v92, v93
	v_cvt_pk_bf16_f32 v89, v94, v95
	v_pk_add_f32 v[70:71], v[70:71], 0 op_sel_hi:[1,0]
	v_cvt_pk_bf16_f32 v90, v90, v91
	v_cvt_pk_bf16_f32 v91, v98, v99
	global_store_dwordx4 v[96:97], v[88:91], off
	v_pk_add_f32 v[68:69], v[68:69], 0 op_sel_hi:[1,0]
	s_mov_b64 s[22:23], 0x40000
	v_pk_add_f32 v[88:89], v[82:83], 0 op_sel_hi:[1,0]
	v_pk_add_f32 v[82:83], v[80:81], 0 op_sel_hi:[1,0]
	v_cvt_pk_bf16_f32 v80, v84, v85
	v_cvt_pk_bf16_f32 v81, v86, v87
	v_pk_add_f32 v[60:61], v[60:61], 0 op_sel_hi:[1,0]
	v_cvt_pk_bf16_f32 v82, v82, v83
	v_cvt_pk_bf16_f32 v83, v88, v89
	global_store_dwordx4 v[96:97], v[80:83], off offset:256
	v_pk_add_f32 v[62:63], v[62:63], 0 op_sel_hi:[1,0]
	v_pk_add_f32 v[54:55], v[54:55], 0 op_sel_hi:[1,0]
	v_or_b32_e32 v80, 48, v154
	v_ashrrev_i32_e32 v81, 31, v80
	v_lshlrev_b64 v[80:81], 11, v[80:81]
	v_lshl_add_u64 v[80:81], s[10:11], 0, v[80:81]
	v_lshl_add_u64 v[80:81], v[80:81], 0, v[158:159]
	v_pk_add_f32 v[82:83], v[74:75], 0 op_sel_hi:[1,0]
	v_pk_add_f32 v[74:75], v[72:73], 0 op_sel_hi:[1,0]
	v_cvt_pk_bf16_f32 v72, v76, v77
	v_cvt_pk_bf16_f32 v73, v78, v79
	v_pk_add_f32 v[52:53], v[52:53], 0 op_sel_hi:[1,0]
	v_cvt_pk_bf16_f32 v74, v74, v75
	v_cvt_pk_bf16_f32 v75, v82, v83
	global_store_dwordx4 v[80:81], v[72:75], off
	v_pk_add_f32 v[48:49], v[48:49], 0 op_sel_hi:[1,0]
	v_pk_add_f32 v[38:39], v[38:39], 0 op_sel_hi:[1,0]
	v_pk_add_f32 v[72:73], v[66:67], 0 op_sel_hi:[1,0]
	v_pk_add_f32 v[66:67], v[64:65], 0 op_sel_hi:[1,0]
	v_cvt_pk_bf16_f32 v64, v68, v69
	v_cvt_pk_bf16_f32 v65, v70, v71
	v_pk_add_f32 v[36:37], v[36:37], 0 op_sel_hi:[1,0]
	v_cvt_pk_bf16_f32 v66, v66, v67
	v_cvt_pk_bf16_f32 v67, v72, v73
	global_store_dwordx4 v[80:81], v[64:67], off offset:256
	v_pk_add_f32 v[32:33], v[32:33], 0 op_sel_hi:[1,0]
	v_pk_add_f32 v[22:23], v[22:23], 0 op_sel_hi:[1,0]
	v_lshl_add_u64 v[64:65], v[144:145], 0, s[22:23]
	s_mov_b32 s22, 0x40000
	v_pk_add_f32 v[66:67], v[58:59], 0 op_sel_hi:[1,0]
	v_pk_add_f32 v[58:59], v[56:57], 0 op_sel_hi:[1,0]
	v_cvt_pk_bf16_f32 v56, v60, v61
	v_add_co_u32_e32 v60, vcc, s22, v144
	v_cvt_pk_bf16_f32 v57, v62, v63
	v_cvt_pk_bf16_f32 v58, v58, v59
	v_cvt_pk_bf16_f32 v59, v66, v67
	s_mov_b64 s[22:23], 0x48000
	s_nop 0
	v_addc_co_u32_e32 v61, vcc, 0, v145, vcc
	global_store_dwordx4 v[60:61], v[56:59], off
	v_pk_add_f32 v[20:21], v[20:21], 0 op_sel_hi:[1,0]
	v_pk_add_f32 v[16:17], v[16:17], 0 op_sel_hi:[1,0]
	v_pk_add_f32 v[56:57], v[46:47], 0 op_sel_hi:[1,0]
	v_pk_add_f32 v[46:47], v[44:45], 0 op_sel_hi:[1,0]
	v_cvt_pk_bf16_f32 v44, v52, v53
	v_cvt_pk_bf16_f32 v45, v54, v55
	s_mov_b32 s54, s51
	v_cvt_pk_bf16_f32 v46, v46, v47
	v_cvt_pk_bf16_f32 v47, v56, v57
	global_store_dwordx4 v[64:65], v[44:47], off offset:256
	s_mov_b32 s53, s52
	s_mov_b64 s[24:25], s[4:5]
	v_pk_add_f32 v[46:47], v[50:51], 0 op_sel_hi:[1,0]
	v_pk_add_f32 v[50:51], v[42:43], 0 op_sel_hi:[1,0]
	v_pk_add_f32 v[42:43], v[40:41], 0 op_sel_hi:[1,0]
	v_cvt_pk_bf16_f32 v40, v48, v49
	v_cvt_pk_bf16_f32 v41, v46, v47
	v_add_co_u32_e32 v46, vcc, s48, v144
	v_cvt_pk_bf16_f32 v42, v42, v43
	v_cvt_pk_bf16_f32 v43, v50, v51
	v_lshl_add_u64 v[44:45], v[144:145], 0, s[22:23]
	s_nop 0
	v_addc_co_u32_e32 v47, vcc, 0, v145, vcc
	global_store_dwordx4 v[46:47], v[40:43], off
	s_mov_b64 s[22:23], s[0:1]
	v_pk_add_f32 v[6:7], v[6:7], 0 op_sel_hi:[1,0]
	v_pk_add_f32 v[40:41], v[30:31], 0 op_sel_hi:[1,0]
	v_pk_add_f32 v[30:31], v[28:29], 0 op_sel_hi:[1,0]
	v_cvt_pk_bf16_f32 v28, v36, v37
	v_cvt_pk_bf16_f32 v29, v38, v39
	v_pk_add_f32 v[4:5], v[4:5], 0 op_sel_hi:[1,0]
	v_cvt_pk_bf16_f32 v30, v30, v31
	v_cvt_pk_bf16_f32 v31, v40, v41
	global_store_dwordx4 v[44:45], v[28:31], off offset:256
	s_nop 1
	v_pk_add_f32 v[30:31], v[34:35], 0 op_sel_hi:[1,0]
	v_pk_add_f32 v[34:35], v[26:27], 0 op_sel_hi:[1,0]
	v_pk_add_f32 v[26:27], v[24:25], 0 op_sel_hi:[1,0]
	v_cvt_pk_bf16_f32 v24, v32, v33
	v_cvt_pk_bf16_f32 v25, v30, v31
	v_add_co_u32_e32 v30, vcc, s49, v144
	v_cvt_pk_bf16_f32 v26, v26, v27
	v_cvt_pk_bf16_f32 v27, v34, v35
	v_lshl_add_u64 v[28:29], v[144:145], 0, s[16:17]
	s_nop 0
	v_addc_co_u32_e32 v31, vcc, 0, v145, vcc
	global_store_dwordx4 v[30:31], v[24:27], off
	s_nop 1
	v_pk_add_f32 v[24:25], v[14:15], 0 op_sel_hi:[1,0]
	v_pk_add_f32 v[14:15], v[12:13], 0 op_sel_hi:[1,0]
	v_cvt_pk_bf16_f32 v12, v20, v21
	v_cvt_pk_bf16_f32 v13, v22, v23
	s_nop 0
	v_cvt_pk_bf16_f32 v14, v14, v15
	v_cvt_pk_bf16_f32 v15, v24, v25
	global_store_dwordx4 v[28:29], v[12:15], off offset:256
	s_nop 1
	v_pk_add_f32 v[14:15], v[18:19], 0 op_sel_hi:[1,0]
	v_pk_add_f32 v[18:19], v[10:11], 0 op_sel_hi:[1,0]
	v_pk_add_f32 v[10:11], v[8:9], 0 op_sel_hi:[1,0]
	v_cvt_pk_bf16_f32 v8, v16, v17
	v_cvt_pk_bf16_f32 v9, v14, v15
	v_add_co_u32_e32 v14, vcc, s50, v144
	v_lshl_add_u64 v[12:13], v[144:145], 0, s[18:19]
	s_nop 0
	v_addc_co_u32_e32 v15, vcc, 0, v145, vcc
	v_cvt_pk_bf16_f32 v10, v10, v11
	v_cvt_pk_bf16_f32 v11, v18, v19
	global_store_dwordx4 v[14:15], v[8:11], off
	s_and_b64 vcc, exec, s[2:3]
	s_nop 0
	v_pk_add_f32 v[8:9], v[2:3], 0 op_sel_hi:[1,0]
	v_pk_add_f32 v[2:3], v[0:1], 0 op_sel_hi:[1,0]
	v_cvt_pk_bf16_f32 v0, v4, v5
	v_cvt_pk_bf16_f32 v1, v6, v7
	s_nop 0
	v_cvt_pk_bf16_f32 v2, v2, v3
	v_cvt_pk_bf16_f32 v3, v8, v9
	global_store_dwordx4 v[12:13], v[0:3], off offset:256
	s_cbranch_vccz .LBB0_275
	s_waitcnt vmcnt(0)
	s_cmpk_gt_u32 s31, 0xff
	s_cbranch_scc1 .LBB0_290
	s_barrier

; #define PG8_STAGE(bufoff, gbase, voff) do { _Pragma("unroll") for (int _i = 0; _i < 2; ++_i) \
;         __builtin_amdgcn_global_load_lds((const unsigned*)((const char*)(gbase) + (voff)[_i]), (PG8_LAS unsigned*)(lds + (bufoff) + ldsw + _i * 8192), 16, 0, 0); } while (0)
; #define PG8_LDA(dst, b, h) do { _Pragma("unroll") for (int m = 0; m < 4; ++m) _Pragma("unroll") for (int k = 0; k < 2; ++k) dst[m][k] = *(const PG8_LAS bf16x8*)(lds + PG8_SA(b, h) + aoff + m * 2048 + k * 1024); } while (0)
; #define PG8_LDB(dst, b, h) do { _Pragma("unroll") for (int n = 0; n < 2; ++n) _Pragma("unroll") for (int k = 0; k < 2; ++k) dst[n][k] = *(const PG8_LAS bf16x8*)(lds + PG8_SB(b, h) + boff + n * 2048 + k * 1024); } while (0)
; #define PG8_MMA(ai, bj, At, Bt) do { __builtin_amdgcn_s_setprio(1); _Pragma("unroll") for (int m = 0; m < 4; ++m) _Pragma("unroll") for (int n = 0; n < 2; ++n) _Pragma("unroll") for (int k = 0; k < 2; ++k) \
;         acc[ai][bj][m][n] = __builtin_amdgcn_mfma_f32_16x16x32_bf16(Bt[n][k], At[m][k], acc[ai][bj][m][n], 0, 0, 0); __builtin_amdgcn_s_setprio(0); } while (0)
; #define PG8_WAIT_L(n) asm volatile("s_waitcnt lgkmcnt(" #n ")" ::: "memory")
; #define PG8_BAR __builtin_amdgcn_s_barrier()
; #define PG8_SCHED __builtin_amdgcn_sched_barrier(0)
; template <class Epi, class Sched>
; __device__ __forceinline__ void gemm_phase(PG8_LAS unsigned char* lds, const Gemm g, const Sched& S, const Epi& E) {
;     ...
;             PG8_LDB(B0, 0, 0); PG8_SCHED; PG8_LDA(At, 0, 0); PG8_STAGE(PG8_SA(1, 1), a1 + hstep, voffA);
;             PG8_WAIT_L(8); PG8_BAR; PG8_WAIT_L(0); PG8_MMA(0, 0, At, B0); PG8_BAR; PG8_SCHED;
;             PG8_LDB(B1, 0, 1); PG8_STAGE(PG8_SB(0, 0), b2, voffB);
;             PG8_BAR; PG8_WAIT_L(0); PG8_MMA(0, 1, At, B1); PG8_BAR;
;             PG8_LDA(At, 0, 1); PG8_STAGE(PG8_SA(0, 0), a2, voffA);
;             PG8_BAR; PG8_WAIT_L(0); PG8_MMA(1, 0, At, B0); PG8_BAR; PG8_SCHED;
.LBB0_416:
	ds_read_b128 v[24:27], v186
	ds_read_b128 v[28:31], v186 offset:1024
	ds_read_b128 v[40:43], v186 offset:2048
	ds_read_b128 v[44:47], v186 offset:3072
	s_add_u32 s4, s0, 0xfffc0080
	s_addc_u32 s5, s1, -1
	s_cmp_eq_u32 s53, 12
	s_cselect_b32 s29, s7, s5
	s_cselect_b32 s28, s10, s4
	s_cselect_b32 s5, s19, s52
	s_cselect_b32 s4, s21, s51
	v_lshl_add_u64 v[174:175], s[0:1], 0, v[166:167]
	s_add_i32 m0, s27, 0xc000
	ds_read_b128 v[144:147], v187
	ds_read_b128 v[148:151], v187 offset:1024
	ds_read_b128 v[182:185], v187 offset:2048
	ds_read_b128 v[192:195], v187 offset:3072
	ds_read_b128 v[196:199], v187 offset:4096
	ds_read_b128 v[200:203], v187 offset:5120
	ds_read_b128 v[204:207], v187 offset:6144
	ds_read_b128 v[208:211], v187 offset:7168
	global_load_lds_dwordx4 v[174:175], off
	v_lshl_add_u64 v[174:175], s[0:1], 0, v[168:169]
	s_add_i32 m0, s27, 0xe000
	s_nop 0
	global_load_lds_dwordx4 v[174:175], off
	s_waitcnt lgkmcnt(8)
	s_barrier
	s_waitcnt lgkmcnt(0)
	s_setprio 0
	s_waitcnt lgkmcnt(0)
	v_mfma_f32_16x16x32_bf16 v[140:143], v[24:27], v[144:147], v[140:143]
	v_mfma_f32_16x16x32_bf16 v[136:139], v[40:43], v[144:147], v[136:139]
	v_mfma_f32_16x16x32_bf16 v[124:127], v[24:27], v[182:185], v[124:127]
	v_mfma_f32_16x16x32_bf16 v[120:123], v[40:43], v[182:185], v[120:123]
	v_mfma_f32_16x16x32_bf16 v[108:111], v[24:27], v[196:199], v[108:111]
	v_mfma_f32_16x16x32_bf16 v[104:107], v[40:43], v[196:199], v[104:107]
	v_mfma_f32_16x16x32_bf16 v[92:95], v[24:27], v[204:207], v[92:95]
	v_mfma_f32_16x16x32_bf16 v[88:91], v[40:43], v[204:207], v[88:91]
	v_mfma_f32_16x16x32_bf16 v[140:143], v[28:31], v[148:151], v[140:143]
	v_mfma_f32_16x16x32_bf16 v[136:139], v[44:47], v[148:151], v[136:139]
	v_mfma_f32_16x16x32_bf16 v[124:127], v[28:31], v[192:195], v[124:127]
	v_mfma_f32_16x16x32_bf16 v[120:123], v[44:47], v[192:195], v[120:123]
	v_mfma_f32_16x16x32_bf16 v[108:111], v[28:31], v[200:203], v[108:111]
	v_mfma_f32_16x16x32_bf16 v[104:107], v[44:47], v[200:203], v[104:107]
	v_mfma_f32_16x16x32_bf16 v[92:95], v[28:31], v[208:211], v[92:95]
	v_mfma_f32_16x16x32_bf16 v[88:91], v[44:47], v[208:211], v[88:91]
	s_setprio 1
	s_barrier
	s_add_i32 s54, s43, s35
	v_lshl_add_u64 v[174:175], s[4:5], 0, v[156:157]
	s_mov_b32 m0, s54
	ds_read_b128 v[212:215], v189
	ds_read_b128 v[216:219], v189 offset:1024
	ds_read_b128 v[220:223], v189 offset:2048
	ds_read_b128 v[224:227], v189 offset:3072
	global_load_lds_dwordx4 v[174:175], off
	v_lshl_add_u64 v[228:229], s[4:5], 0, v[160:161]
	s_add_i32 m0, s54, 0x2000
	s_nop 0
	global_load_lds_dwordx4 v[228:229], off
	s_barrier
	s_waitcnt lgkmcnt(0)
	s_setprio 0
	s_waitcnt lgkmcnt(0)
	v_mfma_f32_16x16x32_bf16 v[132:135], v[212:215], v[144:147], v[132:135]
	v_mfma_f32_16x16x32_bf16 v[128:131], v[220:223], v[144:147], v[128:131]
	v_mfma_f32_16x16x32_bf16 v[116:119], v[212:215], v[182:185], v[116:119]
	v_mfma_f32_16x16x32_bf16 v[112:115], v[220:223], v[182:185], v[112:115]
	v_mfma_f32_16x16x32_bf16 v[100:103], v[212:215], v[196:199], v[100:103]
	v_mfma_f32_16x16x32_bf16 v[96:99], v[220:223], v[196:199], v[96:99]
	v_mfma_f32_16x16x32_bf16 v[84:87], v[212:215], v[204:207], v[84:87]
	v_mfma_f32_16x16x32_bf16 v[80:83], v[220:223], v[204:207], v[80:83]
	v_mfma_f32_16x16x32_bf16 v[132:135], v[216:219], v[148:151], v[132:135]
	v_mfma_f32_16x16x32_bf16 v[128:131], v[224:227], v[148:151], v[128:131]
	v_mfma_f32_16x16x32_bf16 v[116:119], v[216:219], v[192:195], v[116:119]
	v_mfma_f32_16x16x32_bf16 v[112:115], v[224:227], v[192:195], v[112:115]
	v_mfma_f32_16x16x32_bf16 v[100:103], v[216:219], v[200:203], v[100:103]
	v_mfma_f32_16x16x32_bf16 v[96:99], v[224:227], v[200:203], v[96:99]
	v_mfma_f32_16x16x32_bf16 v[84:87], v[216:219], v[208:211], v[84:87]
	v_mfma_f32_16x16x32_bf16 v[80:83], v[224:227], v[208:211], v[80:83]
	s_setprio 1
	s_mov_b32 m0, s27
	v_lshl_add_u64 v[230:231], s[28:29], 0, v[154:155]
	s_barrier
	ds_read_b128 v[144:147], v187 offset:16384
	ds_read_b128 v[148:151], v187 offset:17408
	ds_read_b128 v[182:185], v187 offset:18432
	ds_read_b128 v[192:195], v187 offset:19456
	ds_read_b128 v[196:199], v187 offset:20480
	ds_read_b128 v[200:203], v187 offset:21504
	ds_read_b128 v[204:207], v187 offset:22528
	ds_read_b128 v[208:211], v187 offset:23552
	global_load_lds_dwordx4 v[230:231], off
	v_lshl_add_u64 v[232:233], s[28:29], 0, v[158:159]
	s_mov_b32 m0, s36
	s_nop 0
	global_load_lds_dwordx4 v[232:233], off
	s_barrier
	s_waitcnt lgkmcnt(0)
	s_setprio 0
	s_waitcnt lgkmcnt(0)
	v_mfma_f32_16x16x32_bf16 v[76:79], v[24:27], v[144:147], v[76:79]
	v_mfma_f32_16x16x32_bf16 v[72:75], v[40:43], v[144:147], v[72:75]
	v_mfma_f32_16x16x32_bf16 v[60:63], v[24:27], v[182:185], v[60:63]
	v_mfma_f32_16x16x32_bf16 v[56:59], v[40:43], v[182:185], v[56:59]
	v_mfma_f32_16x16x32_bf16 v[36:39], v[24:27], v[196:199], v[36:39]
	v_mfma_f32_16x16x32_bf16 v[32:35], v[40:43], v[196:199], v[32:35]
	v_mfma_f32_16x16x32_bf16 v[12:15], v[24:27], v[204:207], v[12:15]
	v_mfma_f32_16x16x32_bf16 v[8:11], v[40:43], v[204:207], v[8:11]
	v_mfma_f32_16x16x32_bf16 v[76:79], v[28:31], v[148:151], v[76:79]
	v_mfma_f32_16x16x32_bf16 v[72:75], v[44:47], v[148:151], v[72:75]
	v_mfma_f32_16x16x32_bf16 v[60:63], v[28:31], v[192:195], v[60:63]
	v_mfma_f32_16x16x32_bf16 v[56:59], v[44:47], v[192:195], v[56:59]
	v_mfma_f32_16x16x32_bf16 v[36:39], v[28:31], v[200:203], v[36:39]
	v_mfma_f32_16x16x32_bf16 v[32:35], v[44:47], v[200:203], v[32:35]
	v_mfma_f32_16x16x32_bf16 v[12:15], v[28:31], v[208:211], v[12:15]
	v_mfma_f32_16x16x32_bf16 v[8:11], v[44:47], v[208:211], v[8:11]
	s_setprio 1
	s_barrier
; #define PG8_STAGE(bufoff, gbase, voff) do { _Pragma("unroll") for (int _i = 0; _i < 2; ++_i) \
;         __builtin_amdgcn_global_load_lds((const unsigned*)((const char*)(gbase) + (voff)[_i]), (PG8_LAS unsigned*)(lds + (bufoff) + ldsw + _i * 8192), 16, 0, 0); } while (0)
; #define PG8_LDA(dst, b, h) do { _Pragma("unroll") for (int m = 0; m < 4; ++m) _Pragma("unroll") for (int k = 0; k < 2; ++k) dst[m][k] = *(const PG8_LAS bf16x8*)(lds + PG8_SA(b, h) + aoff + m * 2048 + k * 1024); } while (0)
; #define PG8_LDB(dst, b, h) do { _Pragma("unroll") for (int n = 0; n < 2; ++n) _Pragma("unroll") for (int k = 0; k < 2; ++k) dst[n][k] = *(const PG8_LAS bf16x8*)(lds + PG8_SB(b, h) + boff + n * 2048 + k * 1024); } while (0)
; #define PG8_MMA(ai, bj, At, Bt) do { __builtin_amdgcn_s_setprio(1); _Pragma("unroll") for (int m = 0; m < 4; ++m) _Pragma("unroll") for (int n = 0; n < 2; ++n) _Pragma("unroll") for (int k = 0; k < 2; ++k) \
;         acc[ai][bj][m][n] = __builtin_amdgcn_mfma_f32_16x16x32_bf16(Bt[n][k], At[m][k], acc[ai][bj][m][n], 0, 0, 0); __builtin_amdgcn_s_setprio(0); } while (0)
; #define PG8_WAIT_V(n) asm volatile("s_waitcnt vmcnt(" #n ")" ::: "memory")
; #define PG8_WAIT_L(n) asm volatile("s_waitcnt lgkmcnt(" #n ")" ::: "memory")
; #define PG8_BAR __builtin_amdgcn_s_barrier()
; #define PG8_SCHED __builtin_amdgcn_sched_barrier(0)
; template <class Epi, class Sched>
; __device__ __forceinline__ void gemm_phase(PG8_LAS unsigned char* lds, const Gemm g, const Sched& S, const Epi& E) {
;     ...
;             PG8_STAGE(PG8_SB(0, 1), b2 + hstep, voffB);
;             PG8_WAIT_V(6); PG8_BAR; PG8_MMA(1, 1, At, B1); PG8_BAR;
;             PG8_LDB(B0, 1, 0); PG8_SCHED; PG8_LDA(At, 1, 0); PG8_STAGE(PG8_SA(0, 1), a2 + hstep, voffA);
;             PG8_WAIT_L(8); PG8_BAR; PG8_WAIT_L(0); PG8_MMA(0, 0, At, B0); PG8_BAR; PG8_SCHED;
;             PG8_LDB(B1, 1, 1); PG8_STAGE(PG8_SB(1, 0), b3, voffB);
;             PG8_BAR; PG8_WAIT_L(0); PG8_MMA(0, 1, At, B1); PG8_BAR;
;             PG8_LDA(At, 1, 1); PG8_STAGE(PG8_SA(1, 0), a3, voffA);
	s_add_u32 s54, s4, 0x40000
	s_addc_u32 s55, s5, 0
	s_add_i32 s56, s44, s35
	v_lshl_add_u64 v[24:25], s[54:55], 0, v[156:157]
	s_mov_b32 m0, s56
	s_nop 0
	global_load_lds_dwordx4 v[24:25], off
	v_lshl_add_u64 v[24:25], s[54:55], 0, v[160:161]
	s_add_i32 m0, s56, 0x2000
	s_nop 0
	global_load_lds_dwordx4 v[24:25], off
	s_waitcnt vmcnt(6)
	s_barrier
	s_setprio 0
	v_mfma_f32_16x16x32_bf16 v[20:23], v[212:215], v[196:199], v[20:23]
	v_mfma_f32_16x16x32_bf16 v[16:19], v[220:223], v[196:199], v[16:19]
	v_mfma_f32_16x16x32_bf16 v[4:7], v[212:215], v[204:207], v[4:7]
	v_mfma_f32_16x16x32_bf16 v[0:3], v[220:223], v[204:207], v[0:3]
	v_mfma_f32_16x16x32_bf16 v[24:27], v[212:215], v[144:147], v[68:71]
	v_mfma_f32_16x16x32_bf16 v[28:31], v[220:223], v[144:147], v[64:67]
	v_mfma_f32_16x16x32_bf16 v[40:43], v[212:215], v[182:185], v[52:55]
	v_mfma_f32_16x16x32_bf16 v[44:47], v[220:223], v[182:185], v[48:51]
	v_mfma_f32_16x16x32_bf16 v[20:23], v[216:219], v[200:203], v[20:23]
	v_mfma_f32_16x16x32_bf16 v[16:19], v[224:227], v[200:203], v[16:19]
	v_mfma_f32_16x16x32_bf16 v[4:7], v[216:219], v[208:211], v[4:7]
	v_mfma_f32_16x16x32_bf16 v[0:3], v[224:227], v[208:211], v[0:3]
	v_mfma_f32_16x16x32_bf16 v[24:27], v[216:219], v[148:151], v[24:27]
	v_mfma_f32_16x16x32_bf16 v[28:31], v[224:227], v[148:151], v[28:31]
	v_mfma_f32_16x16x32_bf16 v[40:43], v[216:219], v[192:195], v[40:43]
	v_mfma_f32_16x16x32_bf16 v[44:47], v[224:227], v[192:195], v[44:47]
	s_setprio 1
	s_add_i32 s54, 0, 0x18000
	v_add_u32_e32 v68, s54, v179
	s_barrier
	ds_read_b128 v[48:51], v68
	ds_read_b128 v[52:55], v68 offset:1024
	ds_read_b128 v[64:67], v68 offset:2048
	ds_read_b128 v[68:71], v68 offset:3072
	s_add_u32 s28, s28, 0x40000
	s_addc_u32 s29, s29, 0
	s_mov_b32 m0, s37
	v_lshl_add_u64 v[212:213], s[28:29], 0, v[154:155]
	ds_read_b128 v[144:147], v187 offset:32768
	ds_read_b128 v[148:151], v187 offset:33792
	ds_read_b128 v[182:185], v187 offset:34816
	ds_read_b128 v[192:195], v187 offset:35840
	ds_read_b128 v[196:199], v187 offset:36864
	ds_read_b128 v[200:203], v187 offset:37888
	ds_read_b128 v[204:207], v187 offset:38912
	ds_read_b128 v[208:211], v187 offset:39936
	global_load_lds_dwordx4 v[212:213], off
	v_lshl_add_u64 v[212:213], s[28:29], 0, v[158:159]
	s_mov_b32 m0, s38
	s_nop 0
	global_load_lds_dwordx4 v[212:213], off
	s_waitcnt lgkmcnt(8)
	s_barrier
	s_waitcnt lgkmcnt(0)
	s_setprio 0
	s_waitcnt lgkmcnt(0)
	v_mfma_f32_16x16x32_bf16 v[140:143], v[48:51], v[144:147], v[140:143]
	v_mfma_f32_16x16x32_bf16 v[136:139], v[64:67], v[144:147], v[136:139]
	v_mfma_f32_16x16x32_bf16 v[124:127], v[48:51], v[182:185], v[124:127]
	v_mfma_f32_16x16x32_bf16 v[120:123], v[64:67], v[182:185], v[120:123]
	v_mfma_f32_16x16x32_bf16 v[108:111], v[48:51], v[196:199], v[108:111]
	v_mfma_f32_16x16x32_bf16 v[104:107], v[64:67], v[196:199], v[104:107]
	v_mfma_f32_16x16x32_bf16 v[92:95], v[48:51], v[204:207], v[92:95]
	v_mfma_f32_16x16x32_bf16 v[88:91], v[64:67], v[204:207], v[88:91]
	v_mfma_f32_16x16x32_bf16 v[140:143], v[52:55], v[148:151], v[140:143]
	v_mfma_f32_16x16x32_bf16 v[136:139], v[68:71], v[148:151], v[136:139]
	v_mfma_f32_16x16x32_bf16 v[124:127], v[52:55], v[192:195], v[124:127]
	v_mfma_f32_16x16x32_bf16 v[120:123], v[68:71], v[192:195], v[120:123]
	v_mfma_f32_16x16x32_bf16 v[108:111], v[52:55], v[200:203], v[108:111]
	v_mfma_f32_16x16x32_bf16 v[104:107], v[68:71], v[200:203], v[104:107]
	v_mfma_f32_16x16x32_bf16 v[92:95], v[52:55], v[208:211], v[92:95]
	v_mfma_f32_16x16x32_bf16 v[88:91], v[68:71], v[208:211], v[88:91]
	s_setprio 1
	s_barrier
	s_add_i32 s28, 0, 0x1c000
	s_add_i32 s29, s54, s35
	v_add_u32_e32 v162, s28, v179
	v_lshl_add_u64 v[174:175], v[174:175], 0, s[14:15]
	s_mov_b32 m0, s29
	ds_read_b128 v[212:215], v162
	ds_read_b128 v[216:219], v162 offset:1024
	ds_read_b128 v[220:223], v162 offset:2048
	ds_read_b128 v[224:227], v162 offset:3072
	global_load_lds_dwordx4 v[174:175], off
	v_lshl_add_u64 v[174:175], v[228:229], 0, s[14:15]
	s_add_i32 m0, s29, 0x2000
	s_nop 0
	global_load_lds_dwordx4 v[174:175], off
	s_barrier
	s_waitcnt lgkmcnt(0)
	s_setprio 0
	s_waitcnt lgkmcnt(0)
	v_mfma_f32_16x16x32_bf16 v[132:135], v[212:215], v[144:147], v[132:135]
	v_mfma_f32_16x16x32_bf16 v[128:131], v[220:223], v[144:147], v[128:131]
	v_mfma_f32_16x16x32_bf16 v[116:119], v[212:215], v[182:185], v[116:119]
	v_mfma_f32_16x16x32_bf16 v[112:115], v[220:223], v[182:185], v[112:115]
	v_mfma_f32_16x16x32_bf16 v[100:103], v[212:215], v[196:199], v[100:103]
	v_mfma_f32_16x16x32_bf16 v[96:99], v[220:223], v[196:199], v[96:99]
	v_mfma_f32_16x16x32_bf16 v[84:87], v[212:215], v[204:207], v[84:87]
	v_mfma_f32_16x16x32_bf16 v[80:83], v[220:223], v[204:207], v[80:83]
	v_mfma_f32_16x16x32_bf16 v[132:135], v[216:219], v[148:151], v[132:135]
	v_mfma_f32_16x16x32_bf16 v[128:131], v[224:227], v[148:151], v[128:131]
	v_mfma_f32_16x16x32_bf16 v[116:119], v[216:219], v[192:195], v[116:119]
	v_mfma_f32_16x16x32_bf16 v[112:115], v[224:227], v[192:195], v[112:115]
	v_mfma_f32_16x16x32_bf16 v[100:103], v[216:219], v[200:203], v[100:103]
	v_mfma_f32_16x16x32_bf16 v[96:99], v[224:227], v[200:203], v[96:99]
	v_mfma_f32_16x16x32_bf16 v[84:87], v[216:219], v[208:211], v[84:87]
	v_mfma_f32_16x16x32_bf16 v[80:83], v[224:227], v[208:211], v[80:83]
	s_setprio 1
	s_mov_b32 m0, s39
	v_lshl_add_u64 v[174:175], v[230:231], 0, s[14:15]
	s_barrier
; #define PG8_STAGE(bufoff, gbase, voff) do { _Pragma("unroll") for (int _i = 0; _i < 2; ++_i) \
;         __builtin_amdgcn_global_load_lds((const unsigned*)((const char*)(gbase) + (voff)[_i]), (PG8_LAS unsigned*)(lds + (bufoff) + ldsw + _i * 8192), 16, 0, 0); } while (0)
; #define PG8_LDA(dst, b, h) do { _Pragma("unroll") for (int m = 0; m < 4; ++m) _Pragma("unroll") for (int k = 0; k < 2; ++k) dst[m][k] = *(const PG8_LAS bf16x8*)(lds + PG8_SA(b, h) + aoff + m * 2048 + k * 1024); } while (0)
; #define PG8_MMA(ai, bj, At, Bt) do { __builtin_amdgcn_s_setprio(1); _Pragma("unroll") for (int m = 0; m < 4; ++m) _Pragma("unroll") for (int n = 0; n < 2; ++n) _Pragma("unroll") for (int k = 0; k < 2; ++k) \
;         acc[ai][bj][m][n] = __builtin_amdgcn_mfma_f32_16x16x32_bf16(Bt[n][k], At[m][k], acc[ai][bj][m][n], 0, 0, 0); __builtin_amdgcn_s_setprio(0); } while (0)
; #define PG8_WAIT_V(n) asm volatile("s_waitcnt vmcnt(" #n ")" ::: "memory")
; #define PG8_WAIT_L(n) asm volatile("s_waitcnt lgkmcnt(" #n ")" ::: "memory")
; #define PG8_BAR __builtin_amdgcn_s_barrier()
; #define PG8_SCHED __builtin_amdgcn_sched_barrier(0)
;     __device__ __forceinline__ void operator()(const f32x4 (&acc)[2][2][4][2], const Unit& u, int wr, int wc, int fr, int fq) const {
;     ...
;         if (mode == 1) { if (u.pn >= 8 && u.pn < 12) act = 1; else if (u.pn >= 12) { act = 3; bias = (u.pn >= 14) ? bias_b + (u.pn - 14) * 256 : bias_f + (u.pn - 12) * 256; } }
;         else if (mode == 2) { if (u.pn >= 6) act = 2; }
;         const int row0 = u.pm * BM + wr * 64 + fr, col0 = u.pn * BM + wc * 32 + 8 * fq, bcol0 = wc * 32 + 8 * fq;
;         f32x4 bv[2][2];
; #pragma unroll
;         for (int bj = 0; bj < 2; ++bj)
; #pragma unroll
;             for (int n = 0; n < 2; ++n) bv[bj][n] = bias ? *(const f32x4*)(bias + bcol0 + bj * HALF + 4 * n) : (f32x4){0.f, 0.f, 0.f, 0.f};
; template <class Epi, class Sched>
; __device__ __forceinline__ void gemm_phase(PG8_LAS unsigned char* lds, const Gemm g, const Sched& S, const Epi& E) {
;     ...
;             PG8_LDA(At, 1, 1); PG8_STAGE(PG8_SA(1, 0), a3, voffA);
;             PG8_BAR; PG8_WAIT_L(0); PG8_MMA(1, 0, At, B0); PG8_BAR; PG8_SCHED;
;             PG8_STAGE(PG8_SB(1, 1), b3 + hstep, voffB);
;             PG8_WAIT_V(6); PG8_BAR; PG8_MMA(1, 1, At, B1); PG8_BAR;
;         }
	ds_read_b128 v[144:147], v187 offset:49152
	ds_read_b128 v[148:151], v187 offset:50176
	ds_read_b128 v[182:185], v187 offset:51200
	ds_read_b128 v[192:195], v187 offset:52224
	ds_read_b128 v[196:199], v187 offset:53248
	ds_read_b128 v[200:203], v187 offset:54272
	ds_read_b128 v[204:207], v187 offset:55296
	ds_read_b128 v[208:211], v187 offset:56320
	global_load_lds_dwordx4 v[174:175], off
	v_lshl_add_u64 v[174:175], v[232:233], 0, s[14:15]
	s_mov_b32 m0, s40
	s_nop 0
	global_load_lds_dwordx4 v[174:175], off
	s_barrier
	s_waitcnt lgkmcnt(0)
	s_setprio 0
	s_waitcnt lgkmcnt(0)
	v_mfma_f32_16x16x32_bf16 v[76:79], v[48:51], v[144:147], v[76:79]
	v_mfma_f32_16x16x32_bf16 v[72:75], v[64:67], v[144:147], v[72:75]
	v_mfma_f32_16x16x32_bf16 v[60:63], v[48:51], v[182:185], v[60:63]
	v_mfma_f32_16x16x32_bf16 v[56:59], v[64:67], v[182:185], v[56:59]
	v_mfma_f32_16x16x32_bf16 v[36:39], v[48:51], v[196:199], v[36:39]
	v_mfma_f32_16x16x32_bf16 v[32:35], v[64:67], v[196:199], v[32:35]
	v_mfma_f32_16x16x32_bf16 v[12:15], v[48:51], v[204:207], v[12:15]
	v_mfma_f32_16x16x32_bf16 v[8:11], v[64:67], v[204:207], v[8:11]
	v_mfma_f32_16x16x32_bf16 v[76:79], v[52:55], v[148:151], v[76:79]
	v_mfma_f32_16x16x32_bf16 v[72:75], v[68:71], v[148:151], v[72:75]
	v_mfma_f32_16x16x32_bf16 v[60:63], v[52:55], v[192:195], v[60:63]
	v_mfma_f32_16x16x32_bf16 v[56:59], v[68:71], v[192:195], v[56:59]
	v_mfma_f32_16x16x32_bf16 v[36:39], v[52:55], v[200:203], v[36:39]
	v_mfma_f32_16x16x32_bf16 v[32:35], v[68:71], v[200:203], v[32:35]
	v_mfma_f32_16x16x32_bf16 v[12:15], v[52:55], v[208:211], v[12:15]
	v_mfma_f32_16x16x32_bf16 v[8:11], v[68:71], v[208:211], v[8:11]
	s_setprio 1
	s_barrier
	s_add_u32 s4, s4, 0x40080
	s_addc_u32 s5, s5, 0
	s_add_i32 s28, s28, s35
	v_lshl_add_u64 v[48:49], s[4:5], 0, v[156:157]
	s_mov_b32 m0, s28
	s_nop 0
	global_load_lds_dwordx4 v[48:49], off
	v_lshl_add_u64 v[48:49], s[4:5], 0, v[160:161]
	s_add_i32 m0, s28, 0x2000
	s_nop 0
	global_load_lds_dwordx4 v[48:49], off
	s_waitcnt vmcnt(6)
	s_barrier
	s_setprio 0
	v_mfma_f32_16x16x32_bf16 v[24:27], v[212:215], v[144:147], v[24:27]
	v_mfma_f32_16x16x32_bf16 v[68:71], v[216:219], v[148:151], v[24:27]
	v_mfma_f32_16x16x32_bf16 v[24:27], v[220:223], v[144:147], v[28:31]
	v_mfma_f32_16x16x32_bf16 v[64:67], v[224:227], v[148:151], v[24:27]
	v_mfma_f32_16x16x32_bf16 v[24:27], v[212:215], v[182:185], v[40:43]
	v_mfma_f32_16x16x32_bf16 v[52:55], v[216:219], v[192:195], v[24:27]
	v_mfma_f32_16x16x32_bf16 v[24:27], v[220:223], v[182:185], v[44:47]
	v_mfma_f32_16x16x32_bf16 v[20:23], v[212:215], v[196:199], v[20:23]
	v_mfma_f32_16x16x32_bf16 v[16:19], v[220:223], v[196:199], v[16:19]
	v_mfma_f32_16x16x32_bf16 v[4:7], v[212:215], v[204:207], v[4:7]
	v_mfma_f32_16x16x32_bf16 v[0:3], v[220:223], v[204:207], v[0:3]
	v_mfma_f32_16x16x32_bf16 v[48:51], v[224:227], v[192:195], v[24:27]
	v_mfma_f32_16x16x32_bf16 v[20:23], v[216:219], v[200:203], v[20:23]
	v_mfma_f32_16x16x32_bf16 v[16:19], v[224:227], v[200:203], v[16:19]
	v_mfma_f32_16x16x32_bf16 v[4:7], v[216:219], v[208:211], v[4:7]
	v_mfma_f32_16x16x32_bf16 v[0:3], v[224:227], v[208:211], v[0:3]
	s_setprio 1
	s_add_i32 s53, s53, 2
	s_add_u32 s0, s0, 0x100
	s_addc_u32 s1, s1, 0
	s_add_u32 s51, s51, 0x100
	s_addc_u32 s52, s52, 0
	s_cmp_gt_u32 s53, 13
	s_barrier
	s_cbranch_scc0 .LBB0_416
	s_cmp_gt_i32 s26, 11
	s_cselect_b64 s[4:5], -1, 0
	s_cmp_lt_i32 s26, 12
	s_mov_b64 s[0:1], 0
	s_cbranch_scc1 .LBB0_422
	s_lshl_b32 s10, s26, 8
	s_cmp_lt_u32 s26, 14
	s_mov_b64 s[28:29], -1
	s_cbranch_scc0 .LBB0_420
	s_lshl_b64 s[0:1], s[10:11], 2
	v_readlane_b32 s52, v245, 0
	v_readlane_b32 s53, v245, 1
	s_add_u32 s0, s52, s0
	s_addc_u32 s1, s53, s1
	s_add_u32 s0, s0, 0xffffd000
	v_readlane_b32 s54, v245, 2
	v_readlane_b32 s55, v245, 3
	v_readlane_b32 s56, v245, 4
	v_readlane_b32 s57, v245, 5
	v_readlane_b32 s58, v245, 6
	v_readlane_b32 s59, v245, 7
	v_readlane_b32 s60, v245, 8
	v_readlane_b32 s61, v245, 9
	v_readlane_b32 s62, v245, 10
	v_readlane_b32 s63, v245, 11
	v_readlane_b32 s64, v245, 12
	v_readlane_b32 s65, v245, 13
	v_readlane_b32 s66, v245, 14
	v_readlane_b32 s67, v245, 15
	s_addc_u32 s1, s1, -1
	s_mov_b64 s[28:29], 0

; #define PG8_STAGE(bufoff, gbase, voff) do { _Pragma("unroll") for (int _i = 0; _i < 2; ++_i) \
;         __builtin_amdgcn_global_load_lds((const unsigned*)((const char*)(gbase) + (voff)[_i]), (PG8_LAS unsigned*)(lds + (bufoff) + ldsw + _i * 8192), 16, 0, 0); } while (0)
; #define PG8_LDA(dst, b, h) do { _Pragma("unroll") for (int m = 0; m < 4; ++m) _Pragma("unroll") for (int k = 0; k < 2; ++k) dst[m][k] = *(const PG8_LAS bf16x8*)(lds + PG8_SA(b, h) + aoff + m * 2048 + k * 1024); } while (0)
; #define PG8_LDB(dst, b, h) do { _Pragma("unroll") for (int n = 0; n < 2; ++n) _Pragma("unroll") for (int k = 0; k < 2; ++k) dst[n][k] = *(const PG8_LAS bf16x8*)(lds + PG8_SB(b, h) + boff + n * 2048 + k * 1024); } while (0)
; #define PG8_MMA(ai, bj, At, Bt) do { __builtin_amdgcn_s_setprio(1); _Pragma("unroll") for (int m = 0; m < 4; ++m) _Pragma("unroll") for (int n = 0; n < 2; ++n) _Pragma("unroll") for (int k = 0; k < 2; ++k) \
;         acc[ai][bj][m][n] = __builtin_amdgcn_mfma_f32_16x16x32_bf16(Bt[n][k], At[m][k], acc[ai][bj][m][n], 0, 0, 0); __builtin_amdgcn_s_setprio(0); } while (0)
; #define PG8_WAIT_L(n) asm volatile("s_waitcnt lgkmcnt(" #n ")" ::: "memory")
; #define PG8_BAR __builtin_amdgcn_s_barrier()
; #define PG8_SCHED __builtin_amdgcn_sched_barrier(0)
; template <class Epi, class Sched>
; __device__ __forceinline__ void gemm_phase(PG8_LAS unsigned char* lds, const Gemm g, const Sched& S, const Epi& E) {
;     ...
;             PG8_LDB(B0, 0, 0); PG8_SCHED; PG8_LDA(At, 0, 0); PG8_STAGE(PG8_SA(1, 1), a1 + hstep, voffA);
;             PG8_WAIT_L(8); PG8_BAR; PG8_WAIT_L(0); PG8_MMA(0, 0, At, B0); PG8_BAR; PG8_SCHED;
;             PG8_LDB(B1, 0, 1); PG8_STAGE(PG8_SB(0, 0), b2, voffB);
;             PG8_BAR; PG8_WAIT_L(0); PG8_MMA(0, 1, At, B1); PG8_BAR;
;             PG8_LDA(At, 0, 1); PG8_STAGE(PG8_SA(0, 0), a2, voffA);
;             PG8_BAR; PG8_WAIT_L(0); PG8_MMA(1, 0, At, B0); PG8_BAR; PG8_SCHED;
.LBB0_724:
	ds_read_b128 v[144:147], v151
	ds_read_b128 v[156:159], v151 offset:1024
	ds_read_b128 v[160:163], v151 offset:2048
	ds_read_b128 v[166:169], v151 offset:3072
	s_add_u32 s20, s18, 0xfffc0080
	s_addc_u32 s21, s19, -1
	s_cmp_eq_u32 s48, 12
	s_cselect_b32 s23, s5, s21
	s_cselect_b32 s22, s11, s20
	s_cselect_b32 s21, s9, s47
	s_cselect_b32 s20, s45, s46
	v_lshl_add_u64 v[174:175], s[18:19], 0, v[136:137]
	s_add_i32 m0, s17, 0xc000
	ds_read_b128 v[170:173], v153
	ds_read_b128 v[182:185], v153 offset:1024
	ds_read_b128 v[190:193], v153 offset:2048
	ds_read_b128 v[194:197], v153 offset:3072
	ds_read_b128 v[198:201], v153 offset:4096
	ds_read_b128 v[202:205], v153 offset:5120
	ds_read_b128 v[206:209], v153 offset:6144
	ds_read_b128 v[210:213], v153 offset:7168
	global_load_lds_dwordx4 v[174:175], off
	v_lshl_add_u64 v[174:175], s[18:19], 0, v[138:139]
	s_add_i32 m0, s17, 0xe000
	s_nop 0
	global_load_lds_dwordx4 v[174:175], off
	s_waitcnt lgkmcnt(8)
	s_barrier
	s_waitcnt lgkmcnt(0)
	s_setprio 0
	s_waitcnt lgkmcnt(0)
	v_mfma_f32_16x16x32_bf16 v[124:127], v[144:147], v[170:173], v[124:127]
	v_mfma_f32_16x16x32_bf16 v[120:123], v[160:163], v[170:173], v[120:123]
	v_mfma_f32_16x16x32_bf16 v[108:111], v[144:147], v[190:193], v[108:111]
	v_mfma_f32_16x16x32_bf16 v[104:107], v[160:163], v[190:193], v[104:107]
	v_mfma_f32_16x16x32_bf16 v[92:95], v[144:147], v[198:201], v[92:95]
	v_mfma_f32_16x16x32_bf16 v[88:91], v[160:163], v[198:201], v[88:91]
	v_mfma_f32_16x16x32_bf16 v[76:79], v[144:147], v[206:209], v[76:79]
	v_mfma_f32_16x16x32_bf16 v[72:75], v[160:163], v[206:209], v[72:75]
	v_mfma_f32_16x16x32_bf16 v[124:127], v[156:159], v[182:185], v[124:127]
	v_mfma_f32_16x16x32_bf16 v[120:123], v[166:169], v[182:185], v[120:123]
	v_mfma_f32_16x16x32_bf16 v[108:111], v[156:159], v[194:197], v[108:111]
	v_mfma_f32_16x16x32_bf16 v[104:107], v[166:169], v[194:197], v[104:107]
	v_mfma_f32_16x16x32_bf16 v[92:95], v[156:159], v[202:205], v[92:95]
	v_mfma_f32_16x16x32_bf16 v[88:91], v[166:169], v[202:205], v[88:91]
	v_mfma_f32_16x16x32_bf16 v[76:79], v[156:159], v[210:213], v[76:79]
	v_mfma_f32_16x16x32_bf16 v[72:75], v[166:169], v[210:213], v[72:75]
	s_setprio 1
	s_barrier
	s_add_i32 s49, s42, s30
	v_lshl_add_u64 v[174:175], s[20:21], 0, v[130:131]
	s_mov_b32 m0, s49
	ds_read_b128 v[214:217], v154
	ds_read_b128 v[218:221], v154 offset:1024
	ds_read_b128 v[222:225], v154 offset:2048
	ds_read_b128 v[226:229], v154 offset:3072
	global_load_lds_dwordx4 v[174:175], off
	v_lshl_add_u64 v[186:187], s[20:21], 0, v[134:135]
	s_add_i32 m0, s49, 0x2000
	s_nop 0
	global_load_lds_dwordx4 v[186:187], off
	s_barrier
	s_waitcnt lgkmcnt(0)
	s_setprio 0
	s_waitcnt lgkmcnt(0)
	v_mfma_f32_16x16x32_bf16 v[116:119], v[214:217], v[170:173], v[116:119]
	v_mfma_f32_16x16x32_bf16 v[112:115], v[222:225], v[170:173], v[112:115]
	v_mfma_f32_16x16x32_bf16 v[100:103], v[214:217], v[190:193], v[100:103]
	v_mfma_f32_16x16x32_bf16 v[96:99], v[222:225], v[190:193], v[96:99]
	v_mfma_f32_16x16x32_bf16 v[84:87], v[214:217], v[198:201], v[84:87]
	v_mfma_f32_16x16x32_bf16 v[80:83], v[222:225], v[198:201], v[80:83]
	v_mfma_f32_16x16x32_bf16 v[68:71], v[214:217], v[206:209], v[68:71]
	v_mfma_f32_16x16x32_bf16 v[64:67], v[222:225], v[206:209], v[64:67]
	v_mfma_f32_16x16x32_bf16 v[116:119], v[218:221], v[182:185], v[116:119]
	v_mfma_f32_16x16x32_bf16 v[112:115], v[226:229], v[182:185], v[112:115]
	v_mfma_f32_16x16x32_bf16 v[100:103], v[218:221], v[194:197], v[100:103]
	v_mfma_f32_16x16x32_bf16 v[96:99], v[226:229], v[194:197], v[96:99]
	v_mfma_f32_16x16x32_bf16 v[84:87], v[218:221], v[202:205], v[84:87]
	v_mfma_f32_16x16x32_bf16 v[80:83], v[226:229], v[202:205], v[80:83]
	v_mfma_f32_16x16x32_bf16 v[68:71], v[218:221], v[210:213], v[68:71]
	v_mfma_f32_16x16x32_bf16 v[64:67], v[226:229], v[210:213], v[64:67]
	s_setprio 1
	s_mov_b32 m0, s17
	v_lshl_add_u64 v[230:231], s[22:23], 0, v[128:129]
	s_barrier
	ds_read_b128 v[170:173], v153 offset:16384
	ds_read_b128 v[182:185], v153 offset:17408
	ds_read_b128 v[190:193], v153 offset:18432
	ds_read_b128 v[194:197], v153 offset:19456
	ds_read_b128 v[198:201], v153 offset:20480
	ds_read_b128 v[202:205], v153 offset:21504
	ds_read_b128 v[206:209], v153 offset:22528
	ds_read_b128 v[210:213], v153 offset:23552
	global_load_lds_dwordx4 v[230:231], off
	v_lshl_add_u64 v[232:233], s[22:23], 0, v[132:133]
	s_mov_b32 m0, s31
	s_nop 0
	global_load_lds_dwordx4 v[232:233], off
	s_barrier
	s_waitcnt lgkmcnt(0)
	s_setprio 0
	s_waitcnt lgkmcnt(0)
	v_mfma_f32_16x16x32_bf16 v[60:63], v[144:147], v[170:173], v[60:63]
	v_mfma_f32_16x16x32_bf16 v[56:59], v[160:163], v[170:173], v[56:59]
	v_mfma_f32_16x16x32_bf16 v[44:47], v[144:147], v[190:193], v[44:47]
	v_mfma_f32_16x16x32_bf16 v[40:43], v[160:163], v[190:193], v[40:43]
	v_mfma_f32_16x16x32_bf16 v[28:31], v[144:147], v[198:201], v[28:31]
	v_mfma_f32_16x16x32_bf16 v[24:27], v[160:163], v[198:201], v[24:27]
	v_mfma_f32_16x16x32_bf16 v[12:15], v[144:147], v[206:209], v[12:15]
	v_mfma_f32_16x16x32_bf16 v[8:11], v[160:163], v[206:209], v[8:11]
	v_mfma_f32_16x16x32_bf16 v[60:63], v[156:159], v[182:185], v[60:63]
	v_mfma_f32_16x16x32_bf16 v[56:59], v[166:169], v[182:185], v[56:59]
	v_mfma_f32_16x16x32_bf16 v[44:47], v[156:159], v[194:197], v[44:47]
	v_mfma_f32_16x16x32_bf16 v[40:43], v[166:169], v[194:197], v[40:43]
	v_mfma_f32_16x16x32_bf16 v[28:31], v[156:159], v[202:205], v[28:31]
	v_mfma_f32_16x16x32_bf16 v[24:27], v[166:169], v[202:205], v[24:27]
	v_mfma_f32_16x16x32_bf16 v[12:15], v[156:159], v[210:213], v[12:15]
	v_mfma_f32_16x16x32_bf16 v[8:11], v[166:169], v[210:213], v[8:11]
	s_setprio 1
	s_barrier
; #define PG8_STAGE(bufoff, gbase, voff) do { _Pragma("unroll") for (int _i = 0; _i < 2; ++_i) \
;         __builtin_amdgcn_global_load_lds((const unsigned*)((const char*)(gbase) + (voff)[_i]), (PG8_LAS unsigned*)(lds + (bufoff) + ldsw + _i * 8192), 16, 0, 0); } while (0)
; #define PG8_LDA(dst, b, h) do { _Pragma("unroll") for (int m = 0; m < 4; ++m) _Pragma("unroll") for (int k = 0; k < 2; ++k) dst[m][k] = *(const PG8_LAS bf16x8*)(lds + PG8_SA(b, h) + aoff + m * 2048 + k * 1024); } while (0)
; #define PG8_LDB(dst, b, h) do { _Pragma("unroll") for (int n = 0; n < 2; ++n) _Pragma("unroll") for (int k = 0; k < 2; ++k) dst[n][k] = *(const PG8_LAS bf16x8*)(lds + PG8_SB(b, h) + boff + n * 2048 + k * 1024); } while (0)
; #define PG8_MMA(ai, bj, At, Bt) do { __builtin_amdgcn_s_setprio(1); _Pragma("unroll") for (int m = 0; m < 4; ++m) _Pragma("unroll") for (int n = 0; n < 2; ++n) _Pragma("unroll") for (int k = 0; k < 2; ++k) \
;         acc[ai][bj][m][n] = __builtin_amdgcn_mfma_f32_16x16x32_bf16(Bt[n][k], At[m][k], acc[ai][bj][m][n], 0, 0, 0); __builtin_amdgcn_s_setprio(0); } while (0)
; #define PG8_WAIT_V(n) asm volatile("s_waitcnt vmcnt(" #n ")" ::: "memory")
; #define PG8_WAIT_L(n) asm volatile("s_waitcnt lgkmcnt(" #n ")" ::: "memory")
; #define PG8_BAR __builtin_amdgcn_s_barrier()
; #define PG8_SCHED __builtin_amdgcn_sched_barrier(0)
; template <class Epi, class Sched>
; __device__ __forceinline__ void gemm_phase(PG8_LAS unsigned char* lds, const Gemm g, const Sched& S, const Epi& E) {
;     ...
;             PG8_STAGE(PG8_SB(0, 1), b2 + hstep, voffB);
;             PG8_WAIT_V(6); PG8_BAR; PG8_MMA(1, 1, At, B1); PG8_BAR;
;             PG8_LDB(B0, 1, 0); PG8_SCHED; PG8_LDA(At, 1, 0); PG8_STAGE(PG8_SA(0, 1), a2 + hstep, voffA);
;             PG8_WAIT_L(8); PG8_BAR; PG8_WAIT_L(0); PG8_MMA(0, 0, At, B0); PG8_BAR; PG8_SCHED;
;             PG8_LDB(B1, 1, 1); PG8_STAGE(PG8_SB(1, 0), b3, voffB);
;             PG8_BAR; PG8_WAIT_L(0); PG8_MMA(0, 1, At, B1); PG8_BAR;
;             PG8_LDA(At, 1, 1); PG8_STAGE(PG8_SA(1, 0), a3, voffA);
	s_add_u32 s50, s20, 0x40000
	s_addc_u32 s51, s21, 0
	s_add_i32 s49, s43, s30
	v_lshl_add_u64 v[144:145], s[50:51], 0, v[130:131]
	s_mov_b32 m0, s49
	s_nop 0
	global_load_lds_dwordx4 v[144:145], off
	v_lshl_add_u64 v[144:145], s[50:51], 0, v[134:135]
	s_add_i32 m0, s49, 0x2000
	s_nop 0
	global_load_lds_dwordx4 v[144:145], off
	s_waitcnt vmcnt(6)
	s_barrier
	s_setprio 0
	v_mfma_f32_16x16x32_bf16 v[52:55], v[214:217], v[170:173], v[52:55]
	v_mfma_f32_16x16x32_bf16 v[48:51], v[222:225], v[170:173], v[48:51]
	v_mfma_f32_16x16x32_bf16 v[36:39], v[214:217], v[190:193], v[36:39]
	v_mfma_f32_16x16x32_bf16 v[32:35], v[222:225], v[190:193], v[32:35]
	v_mfma_f32_16x16x32_bf16 v[20:23], v[214:217], v[198:201], v[20:23]
	v_mfma_f32_16x16x32_bf16 v[16:19], v[222:225], v[198:201], v[16:19]
	v_mfma_f32_16x16x32_bf16 v[4:7], v[214:217], v[206:209], v[4:7]
	v_mfma_f32_16x16x32_bf16 v[0:3], v[222:225], v[206:209], v[0:3]
	v_mfma_f32_16x16x32_bf16 v[52:55], v[218:221], v[182:185], v[52:55]
	v_mfma_f32_16x16x32_bf16 v[48:51], v[226:229], v[182:185], v[48:51]
	v_mfma_f32_16x16x32_bf16 v[36:39], v[218:221], v[194:197], v[36:39]
	v_mfma_f32_16x16x32_bf16 v[32:35], v[226:229], v[194:197], v[32:35]
	v_mfma_f32_16x16x32_bf16 v[20:23], v[218:221], v[202:205], v[20:23]
	v_mfma_f32_16x16x32_bf16 v[16:19], v[226:229], v[202:205], v[16:19]
	v_mfma_f32_16x16x32_bf16 v[4:7], v[218:221], v[210:213], v[4:7]
	v_mfma_f32_16x16x32_bf16 v[0:3], v[226:229], v[210:213], v[0:3]
	s_setprio 1
	s_add_i32 s49, 0, 0x18000
	v_add_u32_e32 v155, s49, v149
	s_barrier
	ds_read_b128 v[144:147], v155
	ds_read_b128 v[156:159], v155 offset:1024
	ds_read_b128 v[160:163], v155 offset:2048
	ds_read_b128 v[166:169], v155 offset:3072
	s_add_u32 s22, s22, 0x40000
	s_addc_u32 s23, s23, 0
	s_mov_b32 m0, s34
	v_lshl_add_u64 v[214:215], s[22:23], 0, v[128:129]
	ds_read_b128 v[170:173], v153 offset:32768
	ds_read_b128 v[182:185], v153 offset:33792
	ds_read_b128 v[190:193], v153 offset:34816
	ds_read_b128 v[194:197], v153 offset:35840
	ds_read_b128 v[198:201], v153 offset:36864
	ds_read_b128 v[202:205], v153 offset:37888
	ds_read_b128 v[206:209], v153 offset:38912
	ds_read_b128 v[210:213], v153 offset:39936
	global_load_lds_dwordx4 v[214:215], off
	v_lshl_add_u64 v[214:215], s[22:23], 0, v[132:133]
	s_mov_b32 m0, s35
	s_nop 0
	global_load_lds_dwordx4 v[214:215], off
	s_waitcnt lgkmcnt(8)
	s_barrier
	s_waitcnt lgkmcnt(0)
	s_setprio 0
	s_waitcnt lgkmcnt(0)
	v_mfma_f32_16x16x32_bf16 v[124:127], v[144:147], v[170:173], v[124:127]
	v_mfma_f32_16x16x32_bf16 v[120:123], v[160:163], v[170:173], v[120:123]
	v_mfma_f32_16x16x32_bf16 v[108:111], v[144:147], v[190:193], v[108:111]
	v_mfma_f32_16x16x32_bf16 v[104:107], v[160:163], v[190:193], v[104:107]
	v_mfma_f32_16x16x32_bf16 v[92:95], v[144:147], v[198:201], v[92:95]
	v_mfma_f32_16x16x32_bf16 v[88:91], v[160:163], v[198:201], v[88:91]
	v_mfma_f32_16x16x32_bf16 v[76:79], v[144:147], v[206:209], v[76:79]
	v_mfma_f32_16x16x32_bf16 v[72:75], v[160:163], v[206:209], v[72:75]
	v_mfma_f32_16x16x32_bf16 v[124:127], v[156:159], v[182:185], v[124:127]
	v_mfma_f32_16x16x32_bf16 v[120:123], v[166:169], v[182:185], v[120:123]
	v_mfma_f32_16x16x32_bf16 v[108:111], v[156:159], v[194:197], v[108:111]
	v_mfma_f32_16x16x32_bf16 v[104:107], v[166:169], v[194:197], v[104:107]
	v_mfma_f32_16x16x32_bf16 v[92:95], v[156:159], v[202:205], v[92:95]
	v_mfma_f32_16x16x32_bf16 v[88:91], v[166:169], v[202:205], v[88:91]
	v_mfma_f32_16x16x32_bf16 v[76:79], v[156:159], v[210:213], v[76:79]
	v_mfma_f32_16x16x32_bf16 v[72:75], v[166:169], v[210:213], v[72:75]
	s_setprio 1
	s_barrier
	s_add_i32 s22, 0, 0x1c000
	s_add_i32 s23, s49, s30
	v_add_u32_e32 v155, s22, v149
	v_lshl_add_u64 v[174:175], v[174:175], 0, s[6:7]
	s_mov_b32 m0, s23
	ds_read_b128 v[214:217], v155
	ds_read_b128 v[218:221], v155 offset:1024
	ds_read_b128 v[222:225], v155 offset:2048
	ds_read_b128 v[226:229], v155 offset:3072
	global_load_lds_dwordx4 v[174:175], off
	v_lshl_add_u64 v[174:175], v[186:187], 0, s[6:7]
	s_add_i32 m0, s23, 0x2000
	s_nop 0
	global_load_lds_dwordx4 v[174:175], off
	s_barrier
	s_waitcnt lgkmcnt(0)
	s_setprio 0
	s_waitcnt lgkmcnt(0)
	v_mfma_f32_16x16x32_bf16 v[116:119], v[214:217], v[170:173], v[116:119]
	v_mfma_f32_16x16x32_bf16 v[112:115], v[222:225], v[170:173], v[112:115]
	v_mfma_f32_16x16x32_bf16 v[100:103], v[214:217], v[190:193], v[100:103]
	v_mfma_f32_16x16x32_bf16 v[96:99], v[222:225], v[190:193], v[96:99]
	v_mfma_f32_16x16x32_bf16 v[84:87], v[214:217], v[198:201], v[84:87]
	v_mfma_f32_16x16x32_bf16 v[80:83], v[222:225], v[198:201], v[80:83]
	v_mfma_f32_16x16x32_bf16 v[68:71], v[214:217], v[206:209], v[68:71]
	v_mfma_f32_16x16x32_bf16 v[64:67], v[222:225], v[206:209], v[64:67]
	v_mfma_f32_16x16x32_bf16 v[116:119], v[218:221], v[182:185], v[116:119]
	v_mfma_f32_16x16x32_bf16 v[112:115], v[226:229], v[182:185], v[112:115]
	v_mfma_f32_16x16x32_bf16 v[100:103], v[218:221], v[194:197], v[100:103]
	v_mfma_f32_16x16x32_bf16 v[96:99], v[226:229], v[194:197], v[96:99]
	v_mfma_f32_16x16x32_bf16 v[84:87], v[218:221], v[202:205], v[84:87]
	v_mfma_f32_16x16x32_bf16 v[80:83], v[226:229], v[202:205], v[80:83]
	v_mfma_f32_16x16x32_bf16 v[68:71], v[218:221], v[210:213], v[68:71]
	v_mfma_f32_16x16x32_bf16 v[64:67], v[226:229], v[210:213], v[64:67]
	s_setprio 1
	s_mov_b32 m0, s37
	v_lshl_add_u64 v[174:175], v[230:231], 0, s[6:7]
	s_barrier
; #define PG8_STAGE(bufoff, gbase, voff) do { _Pragma("unroll") for (int _i = 0; _i < 2; ++_i) \
;         __builtin_amdgcn_global_load_lds((const unsigned*)((const char*)(gbase) + (voff)[_i]), (PG8_LAS unsigned*)(lds + (bufoff) + ldsw + _i * 8192), 16, 0, 0); } while (0)
; #define PG8_LDA(dst, b, h) do { _Pragma("unroll") for (int m = 0; m < 4; ++m) _Pragma("unroll") for (int k = 0; k < 2; ++k) dst[m][k] = *(const PG8_LAS bf16x8*)(lds + PG8_SA(b, h) + aoff + m * 2048 + k * 1024); } while (0)
; #define PG8_MMA(ai, bj, At, Bt) do { __builtin_amdgcn_s_setprio(1); _Pragma("unroll") for (int m = 0; m < 4; ++m) _Pragma("unroll") for (int n = 0; n < 2; ++n) _Pragma("unroll") for (int k = 0; k < 2; ++k) \
;         acc[ai][bj][m][n] = __builtin_amdgcn_mfma_f32_16x16x32_bf16(Bt[n][k], At[m][k], acc[ai][bj][m][n], 0, 0, 0); __builtin_amdgcn_s_setprio(0); } while (0)
; #define PG8_WAIT_V(n) asm volatile("s_waitcnt vmcnt(" #n ")" ::: "memory")
; #define PG8_WAIT_L(n) asm volatile("s_waitcnt lgkmcnt(" #n ")" ::: "memory")
; #define PG8_BAR __builtin_amdgcn_s_barrier()
; #define PG8_SCHED __builtin_amdgcn_sched_barrier(0)
; __device__ __forceinline__ f32x4 sigmoid4(f32x4 x) {
;     f32x4 d;
; #pragma unroll
;     for (int j = 0; j < 4; ++j) d[j] = 1.0f + __expf(-fmaxf(x[j], -20.0f));
;     const float p01 = d[0] * d[1], p23 = d[2] * d[3], r = __builtin_amdgcn_rcpf(p01 * p23), r01 = r * p23, r23 = r * p01;
;     return (f32x4){r01 * d[1], r01 * d[0], r23 * d[3], r23 * d[2]};
; }
; template <class Epi, class Sched>
; __device__ __forceinline__ void gemm_phase(PG8_LAS unsigned char* lds, const Gemm g, const Sched& S, const Epi& E) {
;     ...
;             PG8_LDA(At, 1, 1); PG8_STAGE(PG8_SA(1, 0), a3, voffA);
;             PG8_BAR; PG8_WAIT_L(0); PG8_MMA(1, 0, At, B0); PG8_BAR; PG8_SCHED;
;             PG8_STAGE(PG8_SB(1, 1), b3 + hstep, voffB);
;             PG8_WAIT_V(6); PG8_BAR; PG8_MMA(1, 1, At, B1); PG8_BAR;
;         }
	ds_read_b128 v[170:173], v153 offset:49152
	ds_read_b128 v[182:185], v153 offset:50176
	ds_read_b128 v[190:193], v153 offset:51200
	ds_read_b128 v[194:197], v153 offset:52224
	ds_read_b128 v[198:201], v153 offset:53248
	ds_read_b128 v[202:205], v153 offset:54272
	ds_read_b128 v[206:209], v153 offset:55296
	ds_read_b128 v[210:213], v153 offset:56320
	global_load_lds_dwordx4 v[174:175], off
	v_lshl_add_u64 v[174:175], v[232:233], 0, s[6:7]
	s_mov_b32 m0, s38
	s_nop 0
	global_load_lds_dwordx4 v[174:175], off
	s_barrier
	s_waitcnt lgkmcnt(0)
	s_setprio 0
	s_waitcnt lgkmcnt(0)
	v_mfma_f32_16x16x32_bf16 v[60:63], v[144:147], v[170:173], v[60:63]
	v_mfma_f32_16x16x32_bf16 v[56:59], v[160:163], v[170:173], v[56:59]
	v_mfma_f32_16x16x32_bf16 v[44:47], v[144:147], v[190:193], v[44:47]
	v_mfma_f32_16x16x32_bf16 v[40:43], v[160:163], v[190:193], v[40:43]
	v_mfma_f32_16x16x32_bf16 v[28:31], v[144:147], v[198:201], v[28:31]
	v_mfma_f32_16x16x32_bf16 v[24:27], v[160:163], v[198:201], v[24:27]
	v_mfma_f32_16x16x32_bf16 v[12:15], v[144:147], v[206:209], v[12:15]
	v_mfma_f32_16x16x32_bf16 v[8:11], v[160:163], v[206:209], v[8:11]
	v_mfma_f32_16x16x32_bf16 v[60:63], v[156:159], v[182:185], v[60:63]
	v_mfma_f32_16x16x32_bf16 v[56:59], v[166:169], v[182:185], v[56:59]
	v_mfma_f32_16x16x32_bf16 v[44:47], v[156:159], v[194:197], v[44:47]
	v_mfma_f32_16x16x32_bf16 v[40:43], v[166:169], v[194:197], v[40:43]
	v_mfma_f32_16x16x32_bf16 v[28:31], v[156:159], v[202:205], v[28:31]
	v_mfma_f32_16x16x32_bf16 v[24:27], v[166:169], v[202:205], v[24:27]
	v_mfma_f32_16x16x32_bf16 v[12:15], v[156:159], v[210:213], v[12:15]
	v_mfma_f32_16x16x32_bf16 v[8:11], v[166:169], v[210:213], v[8:11]
	s_setprio 1
	s_barrier
	s_add_u32 s20, s20, 0x40080
	s_addc_u32 s21, s21, 0
	s_add_i32 s22, s22, s30
	v_lshl_add_u64 v[144:145], s[20:21], 0, v[130:131]
	s_mov_b32 m0, s22
	s_nop 0
	global_load_lds_dwordx4 v[144:145], off
	v_lshl_add_u64 v[144:145], s[20:21], 0, v[134:135]
	s_add_i32 m0, s22, 0x2000
	s_nop 0
	global_load_lds_dwordx4 v[144:145], off
	s_waitcnt vmcnt(6)
	s_barrier
	s_setprio 0
	v_mfma_f32_16x16x32_bf16 v[52:55], v[214:217], v[170:173], v[52:55]
	v_mfma_f32_16x16x32_bf16 v[48:51], v[222:225], v[170:173], v[48:51]
	v_mfma_f32_16x16x32_bf16 v[36:39], v[214:217], v[190:193], v[36:39]
	v_mfma_f32_16x16x32_bf16 v[32:35], v[222:225], v[190:193], v[32:35]
	v_mfma_f32_16x16x32_bf16 v[20:23], v[214:217], v[198:201], v[20:23]
	v_mfma_f32_16x16x32_bf16 v[16:19], v[222:225], v[198:201], v[16:19]
	v_mfma_f32_16x16x32_bf16 v[4:7], v[214:217], v[206:209], v[4:7]
	v_mfma_f32_16x16x32_bf16 v[0:3], v[222:225], v[206:209], v[0:3]
	v_mfma_f32_16x16x32_bf16 v[52:55], v[218:221], v[182:185], v[52:55]
	v_mfma_f32_16x16x32_bf16 v[48:51], v[226:229], v[182:185], v[48:51]
	v_mfma_f32_16x16x32_bf16 v[36:39], v[218:221], v[194:197], v[36:39]
	v_mfma_f32_16x16x32_bf16 v[32:35], v[226:229], v[194:197], v[32:35]
	v_mfma_f32_16x16x32_bf16 v[20:23], v[218:221], v[202:205], v[20:23]
	v_mfma_f32_16x16x32_bf16 v[16:19], v[226:229], v[202:205], v[16:19]
	v_mfma_f32_16x16x32_bf16 v[4:7], v[218:221], v[210:213], v[4:7]
	v_mfma_f32_16x16x32_bf16 v[0:3], v[226:229], v[210:213], v[0:3]
	s_setprio 1
	s_add_i32 s48, s48, 2
	s_add_u32 s18, s18, 0x100
	s_addc_u32 s19, s19, 0
	s_add_u32 s46, s46, 0x100
	s_addc_u32 s47, s47, 0
	s_cmp_gt_u32 s48, 13
	s_barrier
	s_cbranch_scc0 .LBB0_724
	s_cmp_gt_i32 s4, 5
	s_cselect_b64 s[18:19], -1, 0
	s_cmp_lt_i32 s4, 6
	v_pk_add_f32 v[144:145], v[126:127], 0 op_sel_hi:[1,0]
	v_pk_add_f32 v[146:147], v[124:125], 0 op_sel_hi:[1,0]
	v_pk_add_f32 v[124:125], v[122:123], 0 op_sel_hi:[1,0]
	v_pk_add_f32 v[126:127], v[120:121], 0 op_sel_hi:[1,0]
	s_cbranch_scc1 .LBB0_727
	v_max_f32_e32 v122, v144, v144
	v_max_f32_e32 v122, 0xc1a00000, v122
	v_mul_f32_e32 v122, 0xbfb8aa3b, v122
	v_max_f32_e32 v120, v146, v146
	v_max_f32_e32 v121, v147, v147
	v_exp_f32_e32 v123, v122
	v_max_f32_e32 v122, v145, v145
	v_max_f32_e32 v120, 0xc1a00000, v120
	v_max_f32_e32 v121, 0xc1a00000, v121
	v_max_f32_e32 v122, 0xc1a00000, v122
	v_mul_f32_e32 v120, 0xbfb8aa3b, v120
	v_mul_f32_e32 v121, 0xbfb8aa3b, v121
	v_mul_f32_e32 v122, 0xbfb8aa3b, v122
	v_exp_f32_e32 v120, v120
	v_exp_f32_e32 v121, v121
	v_exp_f32_e32 v122, v122
	v_max_f32_e32 v124, v124, v124
	v_max_f32_e32 v124, 0xc1a00000, v124
	v_pk_add_f32 v[120:121], v[120:121], 1.0 op_sel_hi:[1,0]
	v_pk_add_f32 v[122:123], v[122:123], 1.0 op_sel_hi:[1,0]
	v_mov_b32_e32 v144, v120
	v_mov_b32_e32 v145, v123
	v_pk_mov_b32 v[146:147], v[120:121], v[122:123] op_sel:[1,0]
	v_mul_f32_e32 v124, 0xbfb8aa3b, v124
	v_pk_mul_f32 v[144:145], v[144:145], v[146:147]
	v_max_f32_e32 v126, v126, v126
	v_max_f32_e32 v127, v127, v127
	v_exp_f32_e32 v147, v124
	v_max_f32_e32 v124, v125, v125
	v_max_f32_e32 v126, 0xc1a00000, v126
	v_max_f32_e32 v127, 0xc1a00000, v127
	v_max_f32_e32 v124, 0xc1a00000, v124
	v_mul_f32_e32 v146, v144, v145
	v_mul_f32_e32 v126, 0xbfb8aa3b, v126
	v_mul_f32_e32 v127, 0xbfb8aa3b, v127
	v_mul_f32_e32 v124, 0xbfb8aa3b, v124
	v_rcp_f32_e32 v155, v146
	v_exp_f32_e32 v126, v126
	v_exp_f32_e32 v127, v127
	v_exp_f32_e32 v146, v124
	v_mul_f32_e32 v124, v145, v155
	v_mul_f32_e32 v144, v144, v155
	v_pk_add_f32 v[126:127], v[126:127], 1.0 op_sel_hi:[1,0]
	v_pk_add_f32 v[156:157], v[146:147], 1.0 op_sel_hi:[1,0]
	v_mov_b32_e32 v146, v126
	v_mov_b32_e32 v147, v157
	v_pk_mov_b32 v[158:159], v[126:127], v[156:157] op_sel:[1,0]
	v_pk_mul_f32 v[144:145], v[122:123], v[144:145] op_sel_hi:[1,0]
	v_pk_mul_f32 v[158:159], v[146:147], v[158:159]
	s_nop 0
	v_mul_f32_e32 v125, v158, v159
	v_rcp_f32_e32 v125, v125
	s_nop 0
	v_pk_mul_f32 v[146:147], v[120:121], v[124:125] op_sel:[1,0] op_sel_hi:[0,0]
	v_mul_f32_e32 v120, v159, v125
	v_mul_f32_e32 v122, v158, v125
	v_pk_mul_f32 v[124:125], v[156:157], v[122:123] op_sel_hi:[1,0]
	v_pk_mul_f32 v[126:127], v[126:127], v[120:121] op_sel:[1,0] op_sel_hi:[0,0]

; #define PG8_STAGE(bufoff, gbase, voff) do { _Pragma("unroll") for (int _i = 0; _i < 2; ++_i) \
;         __builtin_amdgcn_global_load_lds((const unsigned*)((const char*)(gbase) + (voff)[_i]), (PG8_LAS unsigned*)(lds + (bufoff) + ldsw + _i * 8192), 16, 0, 0); } while (0)
; #define PG8_LDA(dst, b, h) do { _Pragma("unroll") for (int m = 0; m < 4; ++m) _Pragma("unroll") for (int k = 0; k < 2; ++k) dst[m][k] = *(const PG8_LAS bf16x8*)(lds + PG8_SA(b, h) + aoff + m * 2048 + k * 1024); } while (0)
; #define PG8_LDB(dst, b, h) do { _Pragma("unroll") for (int n = 0; n < 2; ++n) _Pragma("unroll") for (int k = 0; k < 2; ++k) dst[n][k] = *(const PG8_LAS bf16x8*)(lds + PG8_SB(b, h) + boff + n * 2048 + k * 1024); } while (0)
; #define PG8_MMA(ai, bj, At, Bt) do { __builtin_amdgcn_s_setprio(1); _Pragma("unroll") for (int m = 0; m < 4; ++m) _Pragma("unroll") for (int n = 0; n < 2; ++n) _Pragma("unroll") for (int k = 0; k < 2; ++k) \
;         acc[ai][bj][m][n] = __builtin_amdgcn_mfma_f32_16x16x32_bf16(Bt[n][k], At[m][k], acc[ai][bj][m][n], 0, 0, 0); __builtin_amdgcn_s_setprio(0); } while (0)
; #define PG8_WAIT_L(n) asm volatile("s_waitcnt lgkmcnt(" #n ")" ::: "memory")
; #define PG8_BAR __builtin_amdgcn_s_barrier()
; #define PG8_SCHED __builtin_amdgcn_sched_barrier(0)
; template <class Epi, class Sched>
; __device__ __forceinline__ void gemm_phase(PG8_LAS unsigned char* lds, const Gemm g, const Sched& S, const Epi& E) {
;     ...
;             PG8_LDB(B0, 0, 0); PG8_SCHED; PG8_LDA(At, 0, 0); PG8_STAGE(PG8_SA(1, 1), a1 + hstep, voffA);
;             PG8_WAIT_L(8); PG8_BAR; PG8_WAIT_L(0); PG8_MMA(0, 0, At, B0); PG8_BAR; PG8_SCHED;
;             PG8_LDB(B1, 0, 1); PG8_STAGE(PG8_SB(0, 0), b2, voffB);
;             PG8_BAR; PG8_WAIT_L(0); PG8_MMA(0, 1, At, B1); PG8_BAR;
;             PG8_LDA(At, 0, 1); PG8_STAGE(PG8_SA(0, 0), a2, voffA);
;             PG8_BAR; PG8_WAIT_L(0); PG8_MMA(1, 0, At, B0); PG8_BAR; PG8_SCHED;
.LBB0_991:
	ds_read_b128 v[144:147], v153
	ds_read_b128 v[156:159], v153 offset:1024
	ds_read_b128 v[160:163], v153 offset:2048
	ds_read_b128 v[164:167], v153 offset:3072
	s_add_u32 s20, s18, 0xfffc0080
	s_addc_u32 s21, s19, -1
	s_cmp_eq_u32 s47, 12
	s_cselect_b32 s23, s11, s21
	s_cselect_b32 s22, s43, s20
	s_cselect_b32 s21, s9, s46
	s_cselect_b32 s20, s44, s45
	v_lshl_add_u64 v[148:149], s[18:19], 0, v[136:137]
	s_add_i32 m0, s17, 0xc000
	ds_read_b128 v[168:171], v154
	ds_read_b128 v[172:175], v154 offset:1024
	ds_read_b128 v[182:185], v154 offset:2048
	ds_read_b128 v[190:193], v154 offset:3072
	ds_read_b128 v[194:197], v154 offset:4096
	ds_read_b128 v[198:201], v154 offset:5120
	ds_read_b128 v[202:205], v154 offset:6144
	ds_read_b128 v[206:209], v154 offset:7168
	global_load_lds_dwordx4 v[148:149], off
	v_lshl_add_u64 v[148:149], s[18:19], 0, v[138:139]
	s_add_i32 m0, s17, 0xe000
	s_nop 0
	global_load_lds_dwordx4 v[148:149], off
	s_waitcnt lgkmcnt(8)
	s_barrier
	s_waitcnt lgkmcnt(0)
	s_setprio 0
	s_waitcnt lgkmcnt(0)
	v_mfma_f32_16x16x32_bf16 v[124:127], v[144:147], v[168:171], v[124:127]
	v_mfma_f32_16x16x32_bf16 v[120:123], v[160:163], v[168:171], v[120:123]
	v_mfma_f32_16x16x32_bf16 v[112:115], v[144:147], v[182:185], v[112:115]
	v_mfma_f32_16x16x32_bf16 v[104:107], v[160:163], v[182:185], v[104:107]
	v_mfma_f32_16x16x32_bf16 v[96:99], v[144:147], v[194:197], v[96:99]
	v_mfma_f32_16x16x32_bf16 v[88:91], v[160:163], v[194:197], v[88:91]
	v_mfma_f32_16x16x32_bf16 v[80:83], v[144:147], v[202:205], v[80:83]
	v_mfma_f32_16x16x32_bf16 v[72:75], v[160:163], v[202:205], v[72:75]
	v_mfma_f32_16x16x32_bf16 v[124:127], v[156:159], v[172:175], v[124:127]
	v_mfma_f32_16x16x32_bf16 v[120:123], v[164:167], v[172:175], v[120:123]
	v_mfma_f32_16x16x32_bf16 v[112:115], v[156:159], v[190:193], v[112:115]
	v_mfma_f32_16x16x32_bf16 v[104:107], v[164:167], v[190:193], v[104:107]
	v_mfma_f32_16x16x32_bf16 v[96:99], v[156:159], v[198:201], v[96:99]
	v_mfma_f32_16x16x32_bf16 v[88:91], v[164:167], v[198:201], v[88:91]
	v_mfma_f32_16x16x32_bf16 v[80:83], v[156:159], v[206:209], v[80:83]
	v_mfma_f32_16x16x32_bf16 v[72:75], v[164:167], v[206:209], v[72:75]
	s_setprio 1
	s_barrier
	s_add_i32 s48, s39, s29
	v_lshl_add_u64 v[148:149], s[20:21], 0, v[130:131]
	s_mov_b32 m0, s48
	ds_read_b128 v[210:213], v155
	ds_read_b128 v[214:217], v155 offset:1024
	ds_read_b128 v[218:221], v155 offset:2048
	ds_read_b128 v[222:225], v155 offset:3072
	global_load_lds_dwordx4 v[148:149], off
	v_lshl_add_u64 v[186:187], s[20:21], 0, v[134:135]
	s_add_i32 m0, s48, 0x2000
	s_nop 0
	global_load_lds_dwordx4 v[186:187], off
	s_barrier
	s_waitcnt lgkmcnt(0)
	s_setprio 0
	s_waitcnt lgkmcnt(0)
	v_mfma_f32_16x16x32_bf16 v[116:119], v[210:213], v[168:171], v[116:119]
	v_mfma_f32_16x16x32_bf16 v[108:111], v[218:221], v[168:171], v[108:111]
	v_mfma_f32_16x16x32_bf16 v[100:103], v[210:213], v[182:185], v[100:103]
	v_mfma_f32_16x16x32_bf16 v[92:95], v[218:221], v[182:185], v[92:95]
	v_mfma_f32_16x16x32_bf16 v[84:87], v[210:213], v[194:197], v[84:87]
	v_mfma_f32_16x16x32_bf16 v[76:79], v[218:221], v[194:197], v[76:79]
	v_mfma_f32_16x16x32_bf16 v[68:71], v[210:213], v[202:205], v[68:71]
	v_mfma_f32_16x16x32_bf16 v[64:67], v[218:221], v[202:205], v[64:67]
	v_mfma_f32_16x16x32_bf16 v[116:119], v[214:217], v[172:175], v[116:119]
	v_mfma_f32_16x16x32_bf16 v[108:111], v[222:225], v[172:175], v[108:111]
	v_mfma_f32_16x16x32_bf16 v[100:103], v[214:217], v[190:193], v[100:103]
	v_mfma_f32_16x16x32_bf16 v[92:95], v[222:225], v[190:193], v[92:95]
	v_mfma_f32_16x16x32_bf16 v[84:87], v[214:217], v[198:201], v[84:87]
	v_mfma_f32_16x16x32_bf16 v[76:79], v[222:225], v[198:201], v[76:79]
	v_mfma_f32_16x16x32_bf16 v[68:71], v[214:217], v[206:209], v[68:71]
	v_mfma_f32_16x16x32_bf16 v[64:67], v[222:225], v[206:209], v[64:67]
	s_setprio 1
	s_mov_b32 m0, s17
	v_lshl_add_u64 v[226:227], s[22:23], 0, v[128:129]
	s_barrier
	ds_read_b128 v[168:171], v154 offset:16384
	ds_read_b128 v[172:175], v154 offset:17408
	ds_read_b128 v[182:185], v154 offset:18432
	ds_read_b128 v[190:193], v154 offset:19456
	ds_read_b128 v[194:197], v154 offset:20480
	ds_read_b128 v[198:201], v154 offset:21504
	ds_read_b128 v[202:205], v154 offset:22528
	ds_read_b128 v[206:209], v154 offset:23552
	global_load_lds_dwordx4 v[226:227], off
	v_lshl_add_u64 v[228:229], s[22:23], 0, v[132:133]
	s_mov_b32 m0, s30
	s_nop 0
	global_load_lds_dwordx4 v[228:229], off
	s_barrier
	s_waitcnt lgkmcnt(0)
	s_setprio 0
	s_waitcnt lgkmcnt(0)
	v_mfma_f32_16x16x32_bf16 v[60:63], v[144:147], v[168:171], v[60:63]
	v_mfma_f32_16x16x32_bf16 v[56:59], v[160:163], v[168:171], v[56:59]
	v_mfma_f32_16x16x32_bf16 v[48:51], v[144:147], v[182:185], v[48:51]
	v_mfma_f32_16x16x32_bf16 v[40:43], v[160:163], v[182:185], v[40:43]
	v_mfma_f32_16x16x32_bf16 v[32:35], v[144:147], v[194:197], v[32:35]
	v_mfma_f32_16x16x32_bf16 v[24:27], v[160:163], v[194:197], v[24:27]
	v_mfma_f32_16x16x32_bf16 v[16:19], v[144:147], v[202:205], v[16:19]
	v_mfma_f32_16x16x32_bf16 v[8:11], v[160:163], v[202:205], v[8:11]
	v_mfma_f32_16x16x32_bf16 v[60:63], v[156:159], v[172:175], v[60:63]
	v_mfma_f32_16x16x32_bf16 v[56:59], v[164:167], v[172:175], v[56:59]
	v_mfma_f32_16x16x32_bf16 v[48:51], v[156:159], v[190:193], v[48:51]
	v_mfma_f32_16x16x32_bf16 v[40:43], v[164:167], v[190:193], v[40:43]
	v_mfma_f32_16x16x32_bf16 v[32:35], v[156:159], v[198:201], v[32:35]
	v_mfma_f32_16x16x32_bf16 v[24:27], v[164:167], v[198:201], v[24:27]
	v_mfma_f32_16x16x32_bf16 v[16:19], v[156:159], v[206:209], v[16:19]
	v_mfma_f32_16x16x32_bf16 v[8:11], v[164:167], v[206:209], v[8:11]
	s_setprio 1
	s_barrier
; #define PG8_STAGE(bufoff, gbase, voff) do { _Pragma("unroll") for (int _i = 0; _i < 2; ++_i) \
;         __builtin_amdgcn_global_load_lds((const unsigned*)((const char*)(gbase) + (voff)[_i]), (PG8_LAS unsigned*)(lds + (bufoff) + ldsw + _i * 8192), 16, 0, 0); } while (0)
; #define PG8_LDA(dst, b, h) do { _Pragma("unroll") for (int m = 0; m < 4; ++m) _Pragma("unroll") for (int k = 0; k < 2; ++k) dst[m][k] = *(const PG8_LAS bf16x8*)(lds + PG8_SA(b, h) + aoff + m * 2048 + k * 1024); } while (0)
; #define PG8_LDB(dst, b, h) do { _Pragma("unroll") for (int n = 0; n < 2; ++n) _Pragma("unroll") for (int k = 0; k < 2; ++k) dst[n][k] = *(const PG8_LAS bf16x8*)(lds + PG8_SB(b, h) + boff + n * 2048 + k * 1024); } while (0)
; #define PG8_MMA(ai, bj, At, Bt) do { __builtin_amdgcn_s_setprio(1); _Pragma("unroll") for (int m = 0; m < 4; ++m) _Pragma("unroll") for (int n = 0; n < 2; ++n) _Pragma("unroll") for (int k = 0; k < 2; ++k) \
;         acc[ai][bj][m][n] = __builtin_amdgcn_mfma_f32_16x16x32_bf16(Bt[n][k], At[m][k], acc[ai][bj][m][n], 0, 0, 0); __builtin_amdgcn_s_setprio(0); } while (0)
; #define PG8_WAIT_V(n) asm volatile("s_waitcnt vmcnt(" #n ")" ::: "memory")
; #define PG8_WAIT_L(n) asm volatile("s_waitcnt lgkmcnt(" #n ")" ::: "memory")
; #define PG8_BAR __builtin_amdgcn_s_barrier()
; #define PG8_SCHED __builtin_amdgcn_sched_barrier(0)
; template <class Epi, class Sched>
; __device__ __forceinline__ void gemm_phase(PG8_LAS unsigned char* lds, const Gemm g, const Sched& S, const Epi& E) {
;     ...
;             PG8_STAGE(PG8_SB(0, 1), b2 + hstep, voffB);
;             PG8_WAIT_V(6); PG8_BAR; PG8_MMA(1, 1, At, B1); PG8_BAR;
;             PG8_LDB(B0, 1, 0); PG8_SCHED; PG8_LDA(At, 1, 0); PG8_STAGE(PG8_SA(0, 1), a2 + hstep, voffA);
;             PG8_WAIT_L(8); PG8_BAR; PG8_WAIT_L(0); PG8_MMA(0, 0, At, B0); PG8_BAR; PG8_SCHED;
;             PG8_LDB(B1, 1, 1); PG8_STAGE(PG8_SB(1, 0), b3, voffB);
;             PG8_BAR; PG8_WAIT_L(0); PG8_MMA(0, 1, At, B1); PG8_BAR;
;             PG8_LDA(At, 1, 1); PG8_STAGE(PG8_SA(1, 0), a3, voffA);
	s_add_u32 s48, s20, 0x40000
	s_addc_u32 s49, s21, 0
	s_add_i32 s50, s40, s29
	v_lshl_add_u64 v[144:145], s[48:49], 0, v[130:131]
	s_mov_b32 m0, s50
	s_nop 0
	global_load_lds_dwordx4 v[144:145], off
	v_lshl_add_u64 v[144:145], s[48:49], 0, v[134:135]
	s_add_i32 m0, s50, 0x2000
	s_nop 0
	global_load_lds_dwordx4 v[144:145], off
	s_waitcnt vmcnt(6)
	s_barrier
	s_setprio 0
	v_mfma_f32_16x16x32_bf16 v[52:55], v[210:213], v[168:171], v[52:55]
	v_mfma_f32_16x16x32_bf16 v[44:47], v[218:221], v[168:171], v[44:47]
	v_mfma_f32_16x16x32_bf16 v[36:39], v[210:213], v[182:185], v[36:39]
	v_mfma_f32_16x16x32_bf16 v[28:31], v[218:221], v[182:185], v[28:31]
	v_mfma_f32_16x16x32_bf16 v[20:23], v[210:213], v[194:197], v[20:23]
	v_mfma_f32_16x16x32_bf16 v[12:15], v[218:221], v[194:197], v[12:15]
	v_mfma_f32_16x16x32_bf16 v[4:7], v[210:213], v[202:205], v[4:7]
	v_mfma_f32_16x16x32_bf16 v[0:3], v[218:221], v[202:205], v[0:3]
	v_mfma_f32_16x16x32_bf16 v[52:55], v[214:217], v[172:175], v[52:55]
	v_mfma_f32_16x16x32_bf16 v[44:47], v[222:225], v[172:175], v[44:47]
	v_mfma_f32_16x16x32_bf16 v[36:39], v[214:217], v[190:193], v[36:39]
	v_mfma_f32_16x16x32_bf16 v[28:31], v[222:225], v[190:193], v[28:31]
	v_mfma_f32_16x16x32_bf16 v[20:23], v[214:217], v[198:201], v[20:23]
	v_mfma_f32_16x16x32_bf16 v[12:15], v[222:225], v[198:201], v[12:15]
	v_mfma_f32_16x16x32_bf16 v[4:7], v[214:217], v[206:209], v[4:7]
	v_mfma_f32_16x16x32_bf16 v[0:3], v[222:225], v[206:209], v[0:3]
	s_setprio 1
	s_add_i32 s48, 0, 0x18000
	v_add_u32_e32 v164, s48, v151
	s_barrier
	ds_read_b128 v[144:147], v164
	ds_read_b128 v[156:159], v164 offset:1024
	ds_read_b128 v[160:163], v164 offset:2048
	ds_read_b128 v[164:167], v164 offset:3072
	s_add_u32 s22, s22, 0x40000
	s_addc_u32 s23, s23, 0
	s_mov_b32 m0, s31
	v_lshl_add_u64 v[210:211], s[22:23], 0, v[128:129]
	ds_read_b128 v[168:171], v154 offset:32768
	ds_read_b128 v[172:175], v154 offset:33792
	ds_read_b128 v[182:185], v154 offset:34816
	ds_read_b128 v[190:193], v154 offset:35840
	ds_read_b128 v[194:197], v154 offset:36864
	ds_read_b128 v[198:201], v154 offset:37888
	ds_read_b128 v[202:205], v154 offset:38912
	ds_read_b128 v[206:209], v154 offset:39936
	global_load_lds_dwordx4 v[210:211], off
	v_lshl_add_u64 v[210:211], s[22:23], 0, v[132:133]
	s_mov_b32 m0, s34
	s_nop 0
	global_load_lds_dwordx4 v[210:211], off
	s_waitcnt lgkmcnt(8)
	s_barrier
	s_waitcnt lgkmcnt(0)
	s_setprio 0
	s_waitcnt lgkmcnt(0)
	v_mfma_f32_16x16x32_bf16 v[124:127], v[144:147], v[168:171], v[124:127]
	v_mfma_f32_16x16x32_bf16 v[120:123], v[160:163], v[168:171], v[120:123]
	v_mfma_f32_16x16x32_bf16 v[112:115], v[144:147], v[182:185], v[112:115]
	v_mfma_f32_16x16x32_bf16 v[104:107], v[160:163], v[182:185], v[104:107]
	v_mfma_f32_16x16x32_bf16 v[96:99], v[144:147], v[194:197], v[96:99]
	v_mfma_f32_16x16x32_bf16 v[88:91], v[160:163], v[194:197], v[88:91]
	v_mfma_f32_16x16x32_bf16 v[80:83], v[144:147], v[202:205], v[80:83]
	v_mfma_f32_16x16x32_bf16 v[72:75], v[160:163], v[202:205], v[72:75]
	v_mfma_f32_16x16x32_bf16 v[124:127], v[156:159], v[172:175], v[124:127]
	v_mfma_f32_16x16x32_bf16 v[120:123], v[164:167], v[172:175], v[120:123]
	v_mfma_f32_16x16x32_bf16 v[112:115], v[156:159], v[190:193], v[112:115]
	v_mfma_f32_16x16x32_bf16 v[104:107], v[164:167], v[190:193], v[104:107]
	v_mfma_f32_16x16x32_bf16 v[96:99], v[156:159], v[198:201], v[96:99]
	v_mfma_f32_16x16x32_bf16 v[88:91], v[164:167], v[198:201], v[88:91]
	v_mfma_f32_16x16x32_bf16 v[80:83], v[156:159], v[206:209], v[80:83]
	v_mfma_f32_16x16x32_bf16 v[72:75], v[164:167], v[206:209], v[72:75]
	s_setprio 1
	s_barrier
	s_add_i32 s22, 0, 0x1c000
	s_add_i32 s23, s48, s29
	v_add_u32_e32 v179, s22, v151
	v_lshl_add_u64 v[148:149], v[148:149], 0, s[6:7]
	s_mov_b32 m0, s23
	ds_read_b128 v[210:213], v179
	ds_read_b128 v[214:217], v179 offset:1024
	ds_read_b128 v[218:221], v179 offset:2048
	ds_read_b128 v[222:225], v179 offset:3072
	global_load_lds_dwordx4 v[148:149], off
	v_lshl_add_u64 v[148:149], v[186:187], 0, s[6:7]
	s_add_i32 m0, s23, 0x2000
	s_nop 0
	global_load_lds_dwordx4 v[148:149], off
	s_barrier
	s_waitcnt lgkmcnt(0)
	s_setprio 0
	s_waitcnt lgkmcnt(0)
	v_mfma_f32_16x16x32_bf16 v[116:119], v[210:213], v[168:171], v[116:119]
	v_mfma_f32_16x16x32_bf16 v[108:111], v[218:221], v[168:171], v[108:111]
	v_mfma_f32_16x16x32_bf16 v[100:103], v[210:213], v[182:185], v[100:103]
	v_mfma_f32_16x16x32_bf16 v[92:95], v[218:221], v[182:185], v[92:95]
	v_mfma_f32_16x16x32_bf16 v[84:87], v[210:213], v[194:197], v[84:87]
	v_mfma_f32_16x16x32_bf16 v[76:79], v[218:221], v[194:197], v[76:79]
	v_mfma_f32_16x16x32_bf16 v[68:71], v[210:213], v[202:205], v[68:71]
	v_mfma_f32_16x16x32_bf16 v[64:67], v[218:221], v[202:205], v[64:67]
	v_mfma_f32_16x16x32_bf16 v[116:119], v[214:217], v[172:175], v[116:119]
	v_mfma_f32_16x16x32_bf16 v[108:111], v[222:225], v[172:175], v[108:111]
	v_mfma_f32_16x16x32_bf16 v[100:103], v[214:217], v[190:193], v[100:103]
	v_mfma_f32_16x16x32_bf16 v[92:95], v[222:225], v[190:193], v[92:95]
	v_mfma_f32_16x16x32_bf16 v[84:87], v[214:217], v[198:201], v[84:87]
	v_mfma_f32_16x16x32_bf16 v[76:79], v[222:225], v[198:201], v[76:79]
	v_mfma_f32_16x16x32_bf16 v[68:71], v[214:217], v[206:209], v[68:71]
	v_mfma_f32_16x16x32_bf16 v[64:67], v[222:225], v[206:209], v[64:67]
	s_setprio 1
	s_mov_b32 m0, s36
	v_lshl_add_u64 v[148:149], v[226:227], 0, s[6:7]
	s_barrier
	ds_read_b128 v[168:171], v154 offset:49152
	ds_read_b128 v[172:175], v154 offset:50176
	ds_read_b128 v[182:185], v154 offset:51200
	ds_read_b128 v[190:193], v154 offset:52224
	ds_read_b128 v[194:197], v154 offset:53248
	ds_read_b128 v[198:201], v154 offset:54272
	ds_read_b128 v[202:205], v154 offset:55296
	ds_read_b128 v[206:209], v154 offset:56320
	global_load_lds_dwordx4 v[148:149], off
	v_lshl_add_u64 v[148:149], v[228:229], 0, s[6:7]
	s_mov_b32 m0, s37
	s_nop 0
	global_load_lds_dwordx4 v[148:149], off
	s_barrier
; __device__ __forceinline__ unsigned cvt_pk_bf16(float lo, float hi) { unsigned r; asm volatile("v_cvt_pk_bf16_f32 %0, %1, %2" : "=v"(r) : "v"(lo), "v"(hi)); return r; }
; __device__ __forceinline__ float bf_lo(unsigned u) { return __uint_as_float(u << 16); }
; __device__ __forceinline__ float bf_hi(unsigned u) { return __uint_as_float(u & 0xffff0000u); }
; #define PG8_STAGE(bufoff, gbase, voff) do { _Pragma("unroll") for (int _i = 0; _i < 2; ++_i) \
;         __builtin_amdgcn_global_load_lds((const unsigned*)((const char*)(gbase) + (voff)[_i]), (PG8_LAS unsigned*)(lds + (bufoff) + ldsw + _i * 8192), 16, 0, 0); } while (0)
; #define PG8_BAR __builtin_amdgcn_s_barrier()
;     __device__ __forceinline__ void operator()(const f32x4 (&acc)[2][2][4][2], const Unit& u, int wr, int wc, int fr, int fq) const {
;     ...
;             for (int m = 0; m < 4; ++m) { const size_t r = (size_t)(row0 + ai * HALF + m * 16); bf16_t* rowp = O + r * ldc + col0; const bf16_t* gp = G + r * ldg + col0;
; #pragma unroll
;                 for (int bj = 0; bj < 2; ++bj) { const u32x4 gw = *(const u32x4*)(gp + bj * HALF);
;                     f32x4 v0 = acc[ai][bj][m][0], v1 = acc[ai][bj][m][1];
;                     v0[0] *= bf_lo(gw.x); v0[1] *= bf_hi(gw.x); v0[2] *= bf_lo(gw.y); v0[3] *= bf_hi(gw.y);
;                     v1[0] *= bf_lo(gw.z); v1[1] *= bf_hi(gw.z); v1[2] *= bf_lo(gw.w); v1[3] *= bf_hi(gw.w);
;                     if (ACCUM) { const u32x4 pw = *(const u32x4*)(rowp + bj * HALF);
;                         v0[0] += bf_lo(pw.x); v0[1] += bf_hi(pw.x); v0[2] += bf_lo(pw.y); v0[3] += bf_hi(pw.y);
;                         v1[0] += bf_lo(pw.z); v1[1] += bf_hi(pw.z); v1[2] += bf_lo(pw.w); v1[3] += bf_hi(pw.w); }
;                     u32x4 w; w.x = cvt_pk_bf16(v0[0], v0[1]); w.y = cvt_pk_bf16(v0[2], v0[3]); w.z = cvt_pk_bf16(v1[0], v1[1]); w.w = cvt_pk_bf16(v1[2], v1[3]);
;                     *(u32x4*)(rowp + bj * HALF) = w; } }
; template <class Epi, class Sched>
; __device__ __forceinline__ void gemm_phase(PG8_LAS unsigned char* lds, const Gemm g, const Sched& S, const Epi& E) {
;     ...
;             PG8_LDA(At, 1, 1); PG8_STAGE(PG8_SA(1, 0), a3, voffA);
;             PG8_BAR; PG8_WAIT_L(0); PG8_MMA(1, 0, At, B0); PG8_BAR; PG8_SCHED;
;             PG8_STAGE(PG8_SB(1, 1), b3 + hstep, voffB);
;             PG8_WAIT_V(6); PG8_BAR; PG8_MMA(1, 1, At, B1); PG8_BAR;
;         }
	s_waitcnt lgkmcnt(0)
	s_setprio 0
	s_waitcnt lgkmcnt(0)
	v_mfma_f32_16x16x32_bf16 v[60:63], v[144:147], v[168:171], v[60:63]
	v_mfma_f32_16x16x32_bf16 v[56:59], v[160:163], v[168:171], v[56:59]
	v_mfma_f32_16x16x32_bf16 v[48:51], v[144:147], v[182:185], v[48:51]
	v_mfma_f32_16x16x32_bf16 v[40:43], v[160:163], v[182:185], v[40:43]
	v_mfma_f32_16x16x32_bf16 v[32:35], v[144:147], v[194:197], v[32:35]
	v_mfma_f32_16x16x32_bf16 v[24:27], v[160:163], v[194:197], v[24:27]
	v_mfma_f32_16x16x32_bf16 v[16:19], v[144:147], v[202:205], v[16:19]
	v_mfma_f32_16x16x32_bf16 v[8:11], v[160:163], v[202:205], v[8:11]
	v_mfma_f32_16x16x32_bf16 v[60:63], v[156:159], v[172:175], v[60:63]
	v_mfma_f32_16x16x32_bf16 v[56:59], v[164:167], v[172:175], v[56:59]
	v_mfma_f32_16x16x32_bf16 v[48:51], v[156:159], v[190:193], v[48:51]
	v_mfma_f32_16x16x32_bf16 v[40:43], v[164:167], v[190:193], v[40:43]
	v_mfma_f32_16x16x32_bf16 v[32:35], v[156:159], v[198:201], v[32:35]
	v_mfma_f32_16x16x32_bf16 v[24:27], v[164:167], v[198:201], v[24:27]
	v_mfma_f32_16x16x32_bf16 v[16:19], v[156:159], v[206:209], v[16:19]
	v_mfma_f32_16x16x32_bf16 v[8:11], v[164:167], v[206:209], v[8:11]
	s_setprio 1
	s_barrier
	s_add_u32 s20, s20, 0x40080
	s_addc_u32 s21, s21, 0
	s_add_i32 s22, s22, s29
	v_lshl_add_u64 v[144:145], s[20:21], 0, v[130:131]
	s_mov_b32 m0, s22
	s_nop 0
	global_load_lds_dwordx4 v[144:145], off
	v_lshl_add_u64 v[144:145], s[20:21], 0, v[134:135]
	s_add_i32 m0, s22, 0x2000
	s_nop 0
	global_load_lds_dwordx4 v[144:145], off
	s_waitcnt vmcnt(6)
	s_barrier
	s_setprio 0
	v_mfma_f32_16x16x32_bf16 v[52:55], v[210:213], v[168:171], v[52:55]
	v_mfma_f32_16x16x32_bf16 v[44:47], v[218:221], v[168:171], v[44:47]
	v_mfma_f32_16x16x32_bf16 v[36:39], v[210:213], v[182:185], v[36:39]
	v_mfma_f32_16x16x32_bf16 v[28:31], v[218:221], v[182:185], v[28:31]
	v_mfma_f32_16x16x32_bf16 v[20:23], v[210:213], v[194:197], v[20:23]
	v_mfma_f32_16x16x32_bf16 v[12:15], v[218:221], v[194:197], v[12:15]
	v_mfma_f32_16x16x32_bf16 v[4:7], v[210:213], v[202:205], v[4:7]
	v_mfma_f32_16x16x32_bf16 v[0:3], v[218:221], v[202:205], v[0:3]
	v_mfma_f32_16x16x32_bf16 v[52:55], v[214:217], v[172:175], v[52:55]
	v_mfma_f32_16x16x32_bf16 v[44:47], v[222:225], v[172:175], v[44:47]
	v_mfma_f32_16x16x32_bf16 v[36:39], v[214:217], v[190:193], v[36:39]
	v_mfma_f32_16x16x32_bf16 v[28:31], v[222:225], v[190:193], v[28:31]
	v_mfma_f32_16x16x32_bf16 v[20:23], v[214:217], v[198:201], v[20:23]
	v_mfma_f32_16x16x32_bf16 v[12:15], v[222:225], v[198:201], v[12:15]
	v_mfma_f32_16x16x32_bf16 v[4:7], v[214:217], v[206:209], v[4:7]
	v_mfma_f32_16x16x32_bf16 v[0:3], v[222:225], v[206:209], v[0:3]
	s_setprio 1
	s_add_i32 s47, s47, 2
	s_add_u32 s18, s18, 0x100
	s_addc_u32 s19, s19, 0
	s_add_u32 s45, s45, 0x100
	s_addc_u32 s46, s46, 0
	s_cmp_gt_u32 s47, 13
	s_barrier
	s_cbranch_scc0 .LBB0_991
	v_lshl_or_b32 v144, s42, 8, v152
	v_lshl_add_u32 v146, s16, 8, v150
	v_ashrrev_i32_e32 v145, 31, v144
	v_mov_b64_e32 v[148:149], s[4:5]
	v_lshlrev_b64 v[144:145], 1, v[144:145]
	v_mad_i64_i32 v[156:157], s[18:19], v146, s41, v[148:149]
	v_lshl_add_u64 v[160:161], v[156:157], 0, v[144:145]
	global_load_dwordx4 v[156:159], v[160:161], off offset:3072
	s_and_b64 vcc, exec, s[2:3]
	s_mov_b32 s42, s8
	s_mov_b32 s16, s10
	s_mov_b64 s[20:21], s[14:15]
	s_waitcnt vmcnt(0)
	v_lshlrev_b32_e32 v147, 16, v156
	v_and_b32_e32 v156, 0xffff0000, v156
	v_lshlrev_b32_e32 v162, 16, v157
	v_and_b32_e32 v157, 0xffff0000, v157
	v_lshlrev_b32_e32 v164, 16, v159
	v_and_b32_e32 v159, 0xffff0000, v159
	v_lshlrev_b32_e32 v163, 16, v158
	v_and_b32_e32 v158, 0xffff0000, v158
	v_mul_f32_e32 v124, v124, v147
	v_mul_f32_e32 v125, v125, v156
	v_mul_f32_e32 v126, v126, v162
	v_mul_f32_e32 v127, v127, v157
	v_mul_f32_e32 v123, v123, v159
	v_mul_f32_e32 v147, v120, v163
	v_mul_f32_e32 v156, v121, v158
	v_mul_f32_e32 v157, v122, v164
	v_cvt_pk_bf16_f32 v120, v124, v125
	v_cvt_pk_bf16_f32 v121, v126, v127
	v_cvt_pk_bf16_f32 v122, v147, v156
	v_cvt_pk_bf16_f32 v123, v157, v123
	global_load_dwordx4 v[124:127], v[160:161], off offset:3328
	v_ashrrev_i32_e32 v147, 31, v146
	v_lshlrev_b64 v[158:159], 11, v[146:147]
	v_lshl_add_u64 v[158:159], s[0:1], 0, v[158:159]
	v_or_b32_e32 v156, 16, v146
	v_lshl_add_u64 v[158:159], v[158:159], 0, v[144:145]
	v_mad_i64_i32 v[160:161], s[18:19], v156, s41, v[148:149]
	global_store_dwordx4 v[158:159], v[120:123], off
	v_lshl_add_u64 v[160:161], v[160:161], 0, v[144:145]
	v_ashrrev_i32_e32 v157, 31, v156
	s_waitcnt vmcnt(0)
	v_lshlrev_b32_e32 v120, 16, v124
	v_and_b32_e32 v121, 0xffff0000, v124
	v_lshlrev_b32_e32 v122, 16, v125
	v_and_b32_e32 v123, 0xffff0000, v125
	v_lshlrev_b32_e32 v124, 16, v126
	v_and_b32_e32 v125, 0xffff0000, v126
	v_lshlrev_b32_e32 v126, 16, v127
	v_and_b32_e32 v127, 0xffff0000, v127
	v_mul_f32_e32 v116, v116, v120
	v_mul_f32_e32 v117, v117, v121
	v_mul_f32_e32 v118, v118, v122
	v_mul_f32_e32 v119, v119, v123
	v_mul_f32_e32 v111, v111, v127
	v_mul_f32_e32 v120, v108, v124
	v_mul_f32_e32 v121, v109, v125
	v_mul_f32_e32 v122, v110, v126
	v_cvt_pk_bf16_f32 v108, v116, v117
	v_cvt_pk_bf16_f32 v109, v118, v119
	v_cvt_pk_bf16_f32 v110, v120, v121
	v_cvt_pk_bf16_f32 v111, v122, v111
	global_load_dwordx4 v[116:119], v[160:161], off offset:3072
	s_nop 0
	global_store_dwordx4 v[158:159], v[108:111], off offset:256
	s_waitcnt vmcnt(0)
; __device__ __forceinline__ unsigned cvt_pk_bf16(float lo, float hi) { unsigned r; asm volatile("v_cvt_pk_bf16_f32 %0, %1, %2" : "=v"(r) : "v"(lo), "v"(hi)); return r; }
; __device__ __forceinline__ float bf_lo(unsigned u) { return __uint_as_float(u << 16); }
; __device__ __forceinline__ float bf_hi(unsigned u) { return __uint_as_float(u & 0xffff0000u); }
;     __device__ __forceinline__ void operator()(const f32x4 (&acc)[2][2][4][2], const Unit& u, int wr, int wc, int fr, int fq) const {
;     ...
;             for (int m = 0; m < 4; ++m) { const size_t r = (size_t)(row0 + ai * HALF + m * 16); bf16_t* rowp = O + r * ldc + col0; const bf16_t* gp = G + r * ldg + col0;
; #pragma unroll
;                 for (int bj = 0; bj < 2; ++bj) { const u32x4 gw = *(const u32x4*)(gp + bj * HALF);
;                     f32x4 v0 = acc[ai][bj][m][0], v1 = acc[ai][bj][m][1];
;                     v0[0] *= bf_lo(gw.x); v0[1] *= bf_hi(gw.x); v0[2] *= bf_lo(gw.y); v0[3] *= bf_hi(gw.y);
;                     v1[0] *= bf_lo(gw.z); v1[1] *= bf_hi(gw.z); v1[2] *= bf_lo(gw.w); v1[3] *= bf_hi(gw.w);
;                     if (ACCUM) { const u32x4 pw = *(const u32x4*)(rowp + bj * HALF);
;                         v0[0] += bf_lo(pw.x); v0[1] += bf_hi(pw.x); v0[2] += bf_lo(pw.y); v0[3] += bf_hi(pw.y);
;                         v1[0] += bf_lo(pw.z); v1[1] += bf_hi(pw.z); v1[2] += bf_lo(pw.w); v1[3] += bf_hi(pw.w); }
;                     u32x4 w; w.x = cvt_pk_bf16(v0[0], v0[1]); w.y = cvt_pk_bf16(v0[2], v0[3]); w.z = cvt_pk_bf16(v1[0], v1[1]); w.w = cvt_pk_bf16(v1[2], v1[3]);
;                     *(u32x4*)(rowp + bj * HALF) = w; } }
	s_nop 0
	v_lshlrev_b32_e32 v108, 16, v116
	v_and_b32_e32 v109, 0xffff0000, v116
	v_lshlrev_b32_e32 v110, 16, v117
	v_and_b32_e32 v111, 0xffff0000, v117
	v_lshlrev_b32_e32 v116, 16, v118
	v_and_b32_e32 v117, 0xffff0000, v118
	v_lshlrev_b32_e32 v118, 16, v119
	v_and_b32_e32 v119, 0xffff0000, v119
	v_mul_f32_e32 v108, v112, v108
	v_mul_f32_e32 v109, v113, v109
	v_mul_f32_e32 v110, v114, v110
	v_mul_f32_e32 v111, v115, v111
	v_mul_f32_e32 v107, v107, v119
	v_mul_f32_e32 v112, v104, v116
	v_mul_f32_e32 v113, v105, v117
	v_mul_f32_e32 v114, v106, v118
	v_cvt_pk_bf16_f32 v104, v108, v109
	v_cvt_pk_bf16_f32 v105, v110, v111
	v_cvt_pk_bf16_f32 v106, v112, v113
	v_cvt_pk_bf16_f32 v107, v114, v107
	global_load_dwordx4 v[108:111], v[160:161], off offset:3328
	v_lshlrev_b64 v[116:117], 11, v[156:157]
	v_lshl_add_u64 v[116:117], s[0:1], 0, v[116:117]
	v_or_b32_e32 v112, 32, v146
	v_lshl_add_u64 v[116:117], v[116:117], 0, v[144:145]
	v_mad_i64_i32 v[114:115], s[18:19], v112, s41, v[148:149]
	global_store_dwordx4 v[116:117], v[104:107], off
	v_lshl_add_u64 v[114:115], v[114:115], 0, v[144:145]
	v_ashrrev_i32_e32 v113, 31, v112
	s_waitcnt vmcnt(0)
	v_lshlrev_b32_e32 v104, 16, v108
	v_and_b32_e32 v105, 0xffff0000, v108
	v_lshlrev_b32_e32 v106, 16, v109
	v_and_b32_e32 v107, 0xffff0000, v109
	v_lshlrev_b32_e32 v108, 16, v110
	v_and_b32_e32 v109, 0xffff0000, v110
	v_lshlrev_b32_e32 v110, 16, v111
	v_and_b32_e32 v111, 0xffff0000, v111
	v_mul_f32_e32 v100, v100, v104
	v_mul_f32_e32 v101, v101, v105
	v_mul_f32_e32 v102, v102, v106
	v_mul_f32_e32 v103, v103, v107
	v_mul_f32_e32 v95, v95, v111
	v_mul_f32_e32 v104, v92, v108
	v_mul_f32_e32 v105, v93, v109
	v_mul_f32_e32 v106, v94, v110
	v_cvt_pk_bf16_f32 v92, v100, v101
	v_cvt_pk_bf16_f32 v93, v102, v103
	v_cvt_pk_bf16_f32 v94, v104, v105
	v_cvt_pk_bf16_f32 v95, v106, v95
	global_load_dwordx4 v[100:103], v[114:115], off offset:3072
	s_nop 0
	global_store_dwordx4 v[116:117], v[92:95], off offset:256
	s_waitcnt vmcnt(0)
	s_nop 0
	v_lshlrev_b32_e32 v92, 16, v100
	v_and_b32_e32 v93, 0xffff0000, v100
	v_lshlrev_b32_e32 v94, 16, v101
	v_and_b32_e32 v95, 0xffff0000, v101
	v_lshlrev_b32_e32 v100, 16, v102
	v_and_b32_e32 v101, 0xffff0000, v102
	v_lshlrev_b32_e32 v102, 16, v103
	v_and_b32_e32 v103, 0xffff0000, v103
	v_mul_f32_e32 v92, v96, v92
	v_mul_f32_e32 v93, v97, v93
	v_mul_f32_e32 v94, v98, v94
	v_mul_f32_e32 v95, v99, v95
	v_mul_f32_e32 v91, v91, v103
	v_mul_f32_e32 v96, v88, v100
	v_mul_f32_e32 v97, v89, v101
	v_mul_f32_e32 v98, v90, v102
	v_cvt_pk_bf16_f32 v88, v92, v93
	v_cvt_pk_bf16_f32 v89, v94, v95
	v_cvt_pk_bf16_f32 v90, v96, v97
	v_cvt_pk_bf16_f32 v91, v98, v91
	global_load_dwordx4 v[92:95], v[114:115], off offset:3328
	v_lshlrev_b64 v[100:101], 11, v[112:113]
	v_lshl_add_u64 v[100:101], s[0:1], 0, v[100:101]
	v_or_b32_e32 v96, 48, v146
	v_lshl_add_u64 v[100:101], v[100:101], 0, v[144:145]
	v_mad_i64_i32 v[98:99], s[18:19], v96, s41, v[148:149]
	global_store_dwordx4 v[100:101], v[88:91], off
	v_lshl_add_u64 v[98:99], v[98:99], 0, v[144:145]
	v_ashrrev_i32_e32 v97, 31, v96
	s_waitcnt vmcnt(0)
	v_lshlrev_b32_e32 v88, 16, v92
	v_and_b32_e32 v89, 0xffff0000, v92
	v_lshlrev_b32_e32 v90, 16, v93
	v_and_b32_e32 v91, 0xffff0000, v93
	v_lshlrev_b32_e32 v92, 16, v94
	v_and_b32_e32 v93, 0xffff0000, v94
	v_lshlrev_b32_e32 v94, 16, v95
	v_and_b32_e32 v95, 0xffff0000, v95
	v_mul_f32_e32 v84, v84, v88
	v_mul_f32_e32 v85, v85, v89
	v_mul_f32_e32 v86, v86, v90
	v_mul_f32_e32 v87, v87, v91
	v_mul_f32_e32 v79, v79, v95
	v_mul_f32_e32 v88, v76, v92
	v_mul_f32_e32 v89, v77, v93
	v_mul_f32_e32 v90, v78, v94
	v_cvt_pk_bf16_f32 v76, v84, v85
	v_cvt_pk_bf16_f32 v77, v86, v87
	v_cvt_pk_bf16_f32 v78, v88, v89
	v_cvt_pk_bf16_f32 v79, v90, v79
	global_load_dwordx4 v[84:87], v[98:99], off offset:3072
	s_nop 0
	global_store_dwordx4 v[100:101], v[76:79], off offset:256
	s_waitcnt vmcnt(0)
	s_nop 0
	v_lshlrev_b32_e32 v76, 16, v84
	v_and_b32_e32 v77, 0xffff0000, v84
	v_lshlrev_b32_e32 v78, 16, v85
	v_and_b32_e32 v79, 0xffff0000, v85
	v_lshlrev_b32_e32 v84, 16, v86
	v_and_b32_e32 v85, 0xffff0000, v86
	v_lshlrev_b32_e32 v86, 16, v87
	v_and_b32_e32 v87, 0xffff0000, v87
	v_mul_f32_e32 v76, v80, v76
	v_mul_f32_e32 v77, v81, v77
	v_mul_f32_e32 v78, v82, v78
	v_mul_f32_e32 v79, v83, v79
	v_mul_f32_e32 v75, v75, v87
	v_mul_f32_e32 v80, v72, v84
	v_mul_f32_e32 v81, v73, v85
	v_mul_f32_e32 v82, v74, v86
	v_cvt_pk_bf16_f32 v72, v76, v77
	v_cvt_pk_bf16_f32 v73, v78, v79
	v_cvt_pk_bf16_f32 v74, v80, v81
	v_cvt_pk_bf16_f32 v75, v82, v75
	global_load_dwordx4 v[76:79], v[98:99], off offset:3328
	v_lshlrev_b64 v[84:85], 11, v[96:97]
	v_lshl_add_u64 v[84:85], s[0:1], 0, v[84:85]
	v_add_u32_e32 v80, 0x80, v146
	v_lshl_add_u64 v[84:85], v[84:85], 0, v[144:145]
	v_mad_i64_i32 v[82:83], s[18:19], v80, s41, v[148:149]
	global_store_dwordx4 v[84:85], v[72:75], off
	v_lshl_add_u64 v[82:83], v[82:83], 0, v[144:145]
	v_ashrrev_i32_e32 v81, 31, v80
	s_waitcnt vmcnt(0)
	v_lshlrev_b32_e32 v72, 16, v76
	v_and_b32_e32 v73, 0xffff0000, v76
	v_lshlrev_b32_e32 v74, 16, v77
	v_and_b32_e32 v75, 0xffff0000, v77
	v_lshlrev_b32_e32 v76, 16, v78
	v_and_b32_e32 v77, 0xffff0000, v78
	v_lshlrev_b32_e32 v78, 16, v79
	v_and_b32_e32 v79, 0xffff0000, v79
	v_mul_f32_e32 v68, v68, v72
	v_mul_f32_e32 v69, v69, v73
	v_mul_f32_e32 v70, v70, v74
	v_mul_f32_e32 v71, v71, v75
	v_mul_f32_e32 v67, v67, v79
	v_mul_f32_e32 v72, v64, v76
	v_mul_f32_e32 v73, v65, v77
	v_mul_f32_e32 v74, v66, v78
	v_cvt_pk_bf16_f32 v64, v68, v69
	v_cvt_pk_bf16_f32 v65, v70, v71
	v_cvt_pk_bf16_f32 v66, v72, v73
	v_cvt_pk_bf16_f32 v67, v74, v67
	global_load_dwordx4 v[68:71], v[82:83], off offset:3072
	s_nop 0
	global_store_dwordx4 v[84:85], v[64:67], off offset:256
	s_waitcnt vmcnt(0)
; __device__ __forceinline__ unsigned cvt_pk_bf16(float lo, float hi) { unsigned r; asm volatile("v_cvt_pk_bf16_f32 %0, %1, %2" : "=v"(r) : "v"(lo), "v"(hi)); return r; }
; __device__ __forceinline__ float bf_lo(unsigned u) { return __uint_as_float(u << 16); }
; __device__ __forceinline__ float bf_hi(unsigned u) { return __uint_as_float(u & 0xffff0000u); }
;     __device__ __forceinline__ void operator()(const f32x4 (&acc)[2][2][4][2], const Unit& u, int wr, int wc, int fr, int fq) const {
;     ...
;             for (int m = 0; m < 4; ++m) { const size_t r = (size_t)(row0 + ai * HALF + m * 16); bf16_t* rowp = O + r * ldc + col0; const bf16_t* gp = G + r * ldg + col0;
; #pragma unroll
;                 for (int bj = 0; bj < 2; ++bj) { const u32x4 gw = *(const u32x4*)(gp + bj * HALF);
;                     f32x4 v0 = acc[ai][bj][m][0], v1 = acc[ai][bj][m][1];
;                     v0[0] *= bf_lo(gw.x); v0[1] *= bf_hi(gw.x); v0[2] *= bf_lo(gw.y); v0[3] *= bf_hi(gw.y);
;                     v1[0] *= bf_lo(gw.z); v1[1] *= bf_hi(gw.z); v1[2] *= bf_lo(gw.w); v1[3] *= bf_hi(gw.w);
;                     if (ACCUM) { const u32x4 pw = *(const u32x4*)(rowp + bj * HALF);
;                         v0[0] += bf_lo(pw.x); v0[1] += bf_hi(pw.x); v0[2] += bf_lo(pw.y); v0[3] += bf_hi(pw.y);
;                         v1[0] += bf_lo(pw.z); v1[1] += bf_hi(pw.z); v1[2] += bf_lo(pw.w); v1[3] += bf_hi(pw.w); }
;                     u32x4 w; w.x = cvt_pk_bf16(v0[0], v0[1]); w.y = cvt_pk_bf16(v0[2], v0[3]); w.z = cvt_pk_bf16(v1[0], v1[1]); w.w = cvt_pk_bf16(v1[2], v1[3]);
;                     *(u32x4*)(rowp + bj * HALF) = w; } }
	s_nop 0
	v_lshlrev_b32_e32 v64, 16, v68
	v_and_b32_e32 v65, 0xffff0000, v68
	v_lshlrev_b32_e32 v66, 16, v69
	v_and_b32_e32 v67, 0xffff0000, v69
	v_lshlrev_b32_e32 v68, 16, v70
	v_and_b32_e32 v69, 0xffff0000, v70
	v_lshlrev_b32_e32 v70, 16, v71
	v_and_b32_e32 v71, 0xffff0000, v71
	v_mul_f32_e32 v60, v60, v64
	v_mul_f32_e32 v61, v61, v65
	v_mul_f32_e32 v62, v62, v66
	v_mul_f32_e32 v63, v63, v67
	v_mul_f32_e32 v59, v59, v71
	v_mul_f32_e32 v64, v56, v68
	v_mul_f32_e32 v65, v57, v69
	v_mul_f32_e32 v66, v58, v70
	v_cvt_pk_bf16_f32 v56, v60, v61
	v_cvt_pk_bf16_f32 v57, v62, v63
	v_cvt_pk_bf16_f32 v58, v64, v65
	v_cvt_pk_bf16_f32 v59, v66, v59
	global_load_dwordx4 v[60:63], v[82:83], off offset:3328
	v_lshlrev_b64 v[68:69], 11, v[80:81]
	v_lshl_add_u64 v[68:69], s[0:1], 0, v[68:69]
	v_add_u32_e32 v64, 0x90, v146
	v_lshl_add_u64 v[68:69], v[68:69], 0, v[144:145]
	v_mad_i64_i32 v[66:67], s[18:19], v64, s41, v[148:149]
	global_store_dwordx4 v[68:69], v[56:59], off
	v_lshl_add_u64 v[66:67], v[66:67], 0, v[144:145]
	v_ashrrev_i32_e32 v65, 31, v64
	s_waitcnt vmcnt(0)
	v_lshlrev_b32_e32 v56, 16, v60
	v_and_b32_e32 v57, 0xffff0000, v60
	v_lshlrev_b32_e32 v58, 16, v61
	v_and_b32_e32 v59, 0xffff0000, v61
	v_lshlrev_b32_e32 v60, 16, v62
	v_and_b32_e32 v61, 0xffff0000, v62
	v_lshlrev_b32_e32 v62, 16, v63
	v_and_b32_e32 v63, 0xffff0000, v63
	v_mul_f32_e32 v52, v52, v56
	v_mul_f32_e32 v53, v53, v57
	v_mul_f32_e32 v54, v54, v58
	v_mul_f32_e32 v55, v55, v59
	v_mul_f32_e32 v47, v47, v63
	v_mul_f32_e32 v56, v44, v60
	v_mul_f32_e32 v57, v45, v61
	v_mul_f32_e32 v58, v46, v62
	v_cvt_pk_bf16_f32 v44, v52, v53
	v_cvt_pk_bf16_f32 v45, v54, v55
	v_cvt_pk_bf16_f32 v46, v56, v57
	v_cvt_pk_bf16_f32 v47, v58, v47
	global_load_dwordx4 v[52:55], v[66:67], off offset:3072
	s_nop 0
	global_store_dwordx4 v[68:69], v[44:47], off offset:256
	s_waitcnt vmcnt(0)
	s_nop 0
	v_lshlrev_b32_e32 v44, 16, v52
	v_and_b32_e32 v45, 0xffff0000, v52
	v_lshlrev_b32_e32 v46, 16, v53
	v_and_b32_e32 v47, 0xffff0000, v53
	v_lshlrev_b32_e32 v52, 16, v54
	v_and_b32_e32 v53, 0xffff0000, v54
	v_lshlrev_b32_e32 v54, 16, v55
	v_and_b32_e32 v55, 0xffff0000, v55
	v_mul_f32_e32 v44, v48, v44
	v_mul_f32_e32 v45, v49, v45
	v_mul_f32_e32 v46, v50, v46
	v_mul_f32_e32 v47, v51, v47
	v_mul_f32_e32 v43, v43, v55
	v_mul_f32_e32 v48, v40, v52
	v_mul_f32_e32 v49, v41, v53
	v_mul_f32_e32 v50, v42, v54
	v_cvt_pk_bf16_f32 v40, v44, v45
	v_cvt_pk_bf16_f32 v41, v46, v47
	v_cvt_pk_bf16_f32 v42, v48, v49
	v_cvt_pk_bf16_f32 v43, v50, v43
	global_load_dwordx4 v[44:47], v[66:67], off offset:3328
	v_lshlrev_b64 v[52:53], 11, v[64:65]
	v_lshl_add_u64 v[52:53], s[0:1], 0, v[52:53]
	v_add_u32_e32 v48, 0xa0, v146
	v_lshl_add_u64 v[52:53], v[52:53], 0, v[144:145]
	v_mad_i64_i32 v[50:51], s[18:19], v48, s41, v[148:149]
	global_store_dwordx4 v[52:53], v[40:43], off
	v_lshl_add_u64 v[50:51], v[50:51], 0, v[144:145]
	v_ashrrev_i32_e32 v49, 31, v48
	s_waitcnt vmcnt(0)
	v_lshlrev_b32_e32 v40, 16, v44
	v_and_b32_e32 v41, 0xffff0000, v44
	v_lshlrev_b32_e32 v42, 16, v45
	v_and_b32_e32 v43, 0xffff0000, v45
	v_lshlrev_b32_e32 v44, 16, v46
	v_and_b32_e32 v45, 0xffff0000, v46
	v_lshlrev_b32_e32 v46, 16, v47
	v_and_b32_e32 v47, 0xffff0000, v47
	v_mul_f32_e32 v36, v36, v40
	v_mul_f32_e32 v37, v37, v41
	v_mul_f32_e32 v38, v38, v42
	v_mul_f32_e32 v39, v39, v43
	v_mul_f32_e32 v31, v31, v47
	v_mul_f32_e32 v40, v28, v44
	v_mul_f32_e32 v41, v29, v45
	v_mul_f32_e32 v42, v30, v46
	v_cvt_pk_bf16_f32 v28, v36, v37
	v_cvt_pk_bf16_f32 v29, v38, v39
	v_cvt_pk_bf16_f32 v30, v40, v41
	v_cvt_pk_bf16_f32 v31, v42, v31
	global_load_dwordx4 v[36:39], v[50:51], off offset:3072
	s_nop 0
	global_store_dwordx4 v[52:53], v[28:31], off offset:256
	s_waitcnt vmcnt(0)
; __device__ __forceinline__ unsigned cvt_pk_bf16(float lo, float hi) { unsigned r; asm volatile("v_cvt_pk_bf16_f32 %0, %1, %2" : "=v"(r) : "v"(lo), "v"(hi)); return r; }
; __device__ __forceinline__ float bf_lo(unsigned u) { return __uint_as_float(u << 16); }
; __device__ __forceinline__ float bf_hi(unsigned u) { return __uint_as_float(u & 0xffff0000u); }
; #define PG8_WAIT_V(n) asm volatile("s_waitcnt vmcnt(" #n ")" ::: "memory")
;     __device__ __forceinline__ void operator()(const f32x4 (&acc)[2][2][4][2], const Unit& u, int wr, int wc, int fr, int fq) const {
;     ...
;             for (int m = 0; m < 4; ++m) { const size_t r = (size_t)(row0 + ai * HALF + m * 16); bf16_t* rowp = O + r * ldc + col0; const bf16_t* gp = G + r * ldg + col0;
; #pragma unroll
;                 for (int bj = 0; bj < 2; ++bj) { const u32x4 gw = *(const u32x4*)(gp + bj * HALF);
;                     f32x4 v0 = acc[ai][bj][m][0], v1 = acc[ai][bj][m][1];
;                     v0[0] *= bf_lo(gw.x); v0[1] *= bf_hi(gw.x); v0[2] *= bf_lo(gw.y); v0[3] *= bf_hi(gw.y);
;                     v1[0] *= bf_lo(gw.z); v1[1] *= bf_hi(gw.z); v1[2] *= bf_lo(gw.w); v1[3] *= bf_hi(gw.w);
;                     if (ACCUM) { const u32x4 pw = *(const u32x4*)(rowp + bj * HALF);
;                         v0[0] += bf_lo(pw.x); v0[1] += bf_hi(pw.x); v0[2] += bf_lo(pw.y); v0[3] += bf_hi(pw.y);
;                         v1[0] += bf_lo(pw.z); v1[1] += bf_hi(pw.z); v1[2] += bf_lo(pw.w); v1[3] += bf_hi(pw.w); }
;                     u32x4 w; w.x = cvt_pk_bf16(v0[0], v0[1]); w.y = cvt_pk_bf16(v0[2], v0[3]); w.z = cvt_pk_bf16(v1[0], v1[1]); w.w = cvt_pk_bf16(v1[2], v1[3]);
;                     *(u32x4*)(rowp + bj * HALF) = w; } }
; template <class Epi, class Sched>
; __device__ __forceinline__ void gemm_phase(PG8_LAS unsigned char* lds, const Gemm g, const Sched& S, const Epi& E) {
;     ...
;         if constexpr (!Epi::AFTER_DRAIN) { E(acc, cur, wr, wc, fr, fq); S.done(cur); }
;         if (!has_next) break;
; #pragma unroll
;         for (int a = 0; a < 2; ++a)
; #pragma unroll
;             for (int b = 0; b < 2; ++b)
; #pragma unroll
;                 for (int m = 0; m < 4; ++m)
; #pragma unroll
;                     for (int n = 0; n < 2; ++n) acc[a][b][m][n] = (f32x4){0.f, 0.f, 0.f, 0.f};
;         cur = nxt; cA = nA; cB = nB; ++ui;
;     }
;     PG8_WAIT_V(0);
;     if (wr == 0) PG8_BAR;
	s_nop 0
	v_lshlrev_b32_e32 v28, 16, v36
	v_and_b32_e32 v29, 0xffff0000, v36
	v_lshlrev_b32_e32 v30, 16, v37
	v_and_b32_e32 v31, 0xffff0000, v37
	v_lshlrev_b32_e32 v36, 16, v38
	v_and_b32_e32 v37, 0xffff0000, v38
	v_lshlrev_b32_e32 v38, 16, v39
	v_and_b32_e32 v39, 0xffff0000, v39
	v_mul_f32_e32 v28, v32, v28
	v_mul_f32_e32 v29, v33, v29
	v_mul_f32_e32 v30, v34, v30
	v_mul_f32_e32 v31, v35, v31
	v_mul_f32_e32 v27, v27, v39
	v_mul_f32_e32 v32, v24, v36
	v_mul_f32_e32 v33, v25, v37
	v_mul_f32_e32 v34, v26, v38
	v_cvt_pk_bf16_f32 v24, v28, v29
	v_cvt_pk_bf16_f32 v25, v30, v31
	v_cvt_pk_bf16_f32 v26, v32, v33
	v_cvt_pk_bf16_f32 v27, v34, v27
	global_load_dwordx4 v[28:31], v[50:51], off offset:3328
	v_lshlrev_b64 v[36:37], 11, v[48:49]
	v_lshl_add_u64 v[36:37], s[0:1], 0, v[36:37]
	v_add_u32_e32 v32, 0xb0, v146
	v_lshl_add_u64 v[36:37], v[36:37], 0, v[144:145]
	v_mad_i64_i32 v[34:35], s[18:19], v32, s41, v[148:149]
	global_store_dwordx4 v[36:37], v[24:27], off
	v_lshl_add_u64 v[34:35], v[34:35], 0, v[144:145]
	v_ashrrev_i32_e32 v33, 31, v32
	s_mov_b64 s[18:19], s[12:13]
	s_waitcnt vmcnt(0)
	v_lshlrev_b32_e32 v24, 16, v28
	v_and_b32_e32 v25, 0xffff0000, v28
	v_lshlrev_b32_e32 v26, 16, v29
	v_and_b32_e32 v27, 0xffff0000, v29
	v_lshlrev_b32_e32 v28, 16, v30
	v_and_b32_e32 v29, 0xffff0000, v30
	v_lshlrev_b32_e32 v30, 16, v31
	v_and_b32_e32 v31, 0xffff0000, v31
	v_mul_f32_e32 v20, v20, v24
	v_mul_f32_e32 v21, v21, v25
	v_mul_f32_e32 v22, v22, v26
	v_mul_f32_e32 v23, v23, v27
	v_mul_f32_e32 v15, v15, v31
	v_mul_f32_e32 v24, v12, v28
	v_mul_f32_e32 v25, v13, v29
	v_mul_f32_e32 v26, v14, v30
	v_cvt_pk_bf16_f32 v12, v20, v21
	v_cvt_pk_bf16_f32 v13, v22, v23
	v_cvt_pk_bf16_f32 v14, v24, v25
	v_cvt_pk_bf16_f32 v15, v26, v15
	global_load_dwordx4 v[20:23], v[34:35], off offset:3072
	s_nop 0
	global_store_dwordx4 v[36:37], v[12:15], off offset:256
	s_waitcnt vmcnt(0)
	s_nop 0
	v_lshlrev_b32_e32 v12, 16, v20
	v_and_b32_e32 v13, 0xffff0000, v20
	v_lshlrev_b32_e32 v14, 16, v21
	v_and_b32_e32 v15, 0xffff0000, v21
	v_lshlrev_b32_e32 v20, 16, v22
	v_and_b32_e32 v21, 0xffff0000, v22
	v_lshlrev_b32_e32 v22, 16, v23
	v_and_b32_e32 v23, 0xffff0000, v23
	v_mul_f32_e32 v12, v16, v12
	v_mul_f32_e32 v13, v17, v13
	v_mul_f32_e32 v14, v18, v14
	v_mul_f32_e32 v15, v19, v15
	v_mul_f32_e32 v11, v11, v23
	v_mul_f32_e32 v16, v8, v20
	v_mul_f32_e32 v17, v9, v21
	v_mul_f32_e32 v18, v10, v22
	v_cvt_pk_bf16_f32 v8, v12, v13
	v_cvt_pk_bf16_f32 v9, v14, v15
	v_cvt_pk_bf16_f32 v10, v16, v17
	v_cvt_pk_bf16_f32 v11, v18, v11
	global_load_dwordx4 v[12:15], v[34:35], off offset:3328
	v_lshlrev_b64 v[16:17], 11, v[32:33]
	v_lshl_add_u64 v[16:17], s[0:1], 0, v[16:17]
	v_lshl_add_u64 v[16:17], v[16:17], 0, v[144:145]
	global_store_dwordx4 v[16:17], v[8:11], off
	s_waitcnt vmcnt(0)
	s_nop 0
	v_lshlrev_b32_e32 v8, 16, v12
	v_and_b32_e32 v9, 0xffff0000, v12
	v_lshlrev_b32_e32 v10, 16, v13
	v_and_b32_e32 v11, 0xffff0000, v13
	v_lshlrev_b32_e32 v12, 16, v14
	v_and_b32_e32 v13, 0xffff0000, v14
	v_lshlrev_b32_e32 v14, 16, v15
	v_and_b32_e32 v15, 0xffff0000, v15
	v_mul_f32_e32 v3, v3, v15
	v_mul_f32_e32 v4, v4, v8
	v_mul_f32_e32 v5, v5, v9
	v_mul_f32_e32 v6, v6, v10
	v_mul_f32_e32 v7, v7, v11
	v_mul_f32_e32 v8, v0, v12
	v_mul_f32_e32 v9, v1, v13
	v_mul_f32_e32 v10, v2, v14
	v_cvt_pk_bf16_f32 v0, v4, v5
	v_cvt_pk_bf16_f32 v1, v6, v7
	v_cvt_pk_bf16_f32 v2, v8, v9
	v_cvt_pk_bf16_f32 v3, v10, v3
	global_store_dwordx4 v[16:17], v[0:3], off offset:256
	s_cbranch_vccz .LBB0_984
	s_waitcnt vmcnt(0)
	s_cmpk_gt_u32 s25, 0xff
	s_cbranch_scc1 .LBB0_995
	s_barrier

; #define PG8_STAGE(bufoff, gbase, voff) do { _Pragma("unroll") for (int _i = 0; _i < 2; ++_i) \
;         __builtin_amdgcn_global_load_lds((const unsigned*)((const char*)(gbase) + (voff)[_i]), (PG8_LAS unsigned*)(lds + (bufoff) + ldsw + _i * 8192), 16, 0, 0); } while (0)
; #define PG8_LDA(dst, b, h) do { _Pragma("unroll") for (int m = 0; m < 4; ++m) _Pragma("unroll") for (int k = 0; k < 2; ++k) dst[m][k] = *(const PG8_LAS bf16x8*)(lds + PG8_SA(b, h) + aoff + m * 2048 + k * 1024); } while (0)
; #define PG8_LDB(dst, b, h) do { _Pragma("unroll") for (int n = 0; n < 2; ++n) _Pragma("unroll") for (int k = 0; k < 2; ++k) dst[n][k] = *(const PG8_LAS bf16x8*)(lds + PG8_SB(b, h) + boff + n * 2048 + k * 1024); } while (0)
; #define PG8_MMA(ai, bj, At, Bt) do { __builtin_amdgcn_s_setprio(1); _Pragma("unroll") for (int m = 0; m < 4; ++m) _Pragma("unroll") for (int n = 0; n < 2; ++n) _Pragma("unroll") for (int k = 0; k < 2; ++k) \
;         acc[ai][bj][m][n] = __builtin_amdgcn_mfma_f32_16x16x32_bf16(Bt[n][k], At[m][k], acc[ai][bj][m][n], 0, 0, 0); __builtin_amdgcn_s_setprio(0); } while (0)
; #define PG8_WAIT_L(n) asm volatile("s_waitcnt lgkmcnt(" #n ")" ::: "memory")
; #define PG8_BAR __builtin_amdgcn_s_barrier()
; #define PG8_SCHED __builtin_amdgcn_sched_barrier(0)
; template <class Epi, class Sched>
; __device__ __forceinline__ void gemm_phase(PG8_LAS unsigned char* lds, const Gemm g, const Sched& S, const Epi& E) {
;     ...
;             PG8_LDB(B0, 0, 0); PG8_SCHED; PG8_LDA(At, 0, 0); PG8_STAGE(PG8_SA(1, 1), a1 + hstep, voffA);
;             PG8_WAIT_L(8); PG8_BAR; PG8_WAIT_L(0); PG8_MMA(0, 0, At, B0); PG8_BAR; PG8_SCHED;
;             PG8_LDB(B1, 0, 1); PG8_STAGE(PG8_SB(0, 0), b2, voffB);
;             PG8_BAR; PG8_WAIT_L(0); PG8_MMA(0, 1, At, B1); PG8_BAR;
;             PG8_LDA(At, 0, 1); PG8_STAGE(PG8_SA(0, 0), a2, voffA);
;             PG8_BAR; PG8_WAIT_L(0); PG8_MMA(1, 0, At, B0); PG8_BAR; PG8_SCHED;
.LBB0_1011:
	ds_read_b128 v[144:147], v153
	ds_read_b128 v[156:159], v153 offset:1024
	ds_read_b128 v[160:163], v153 offset:2048
	ds_read_b128 v[164:167], v153 offset:3072
	s_add_u32 s20, s18, 0xfffc0080
	s_addc_u32 s21, s19, -1
	s_cmp_eq_u32 s47, 12
	s_cselect_b32 s23, s11, s21
	s_cselect_b32 s22, s43, s20
	s_cselect_b32 s21, s9, s46
	s_cselect_b32 s20, s44, s45
	v_lshl_add_u64 v[148:149], s[18:19], 0, v[136:137]
	s_add_i32 m0, s17, 0xc000
	ds_read_b128 v[168:171], v154
	ds_read_b128 v[172:175], v154 offset:1024
	ds_read_b128 v[182:185], v154 offset:2048
	ds_read_b128 v[190:193], v154 offset:3072
	ds_read_b128 v[194:197], v154 offset:4096
	ds_read_b128 v[198:201], v154 offset:5120
	ds_read_b128 v[202:205], v154 offset:6144
	ds_read_b128 v[206:209], v154 offset:7168
	global_load_lds_dwordx4 v[148:149], off
	v_lshl_add_u64 v[148:149], s[18:19], 0, v[138:139]
	s_add_i32 m0, s17, 0xe000
	s_nop 0
	global_load_lds_dwordx4 v[148:149], off
	s_waitcnt lgkmcnt(8)
	s_barrier
	s_waitcnt lgkmcnt(0)
	s_setprio 0
	s_waitcnt lgkmcnt(0)
	v_mfma_f32_16x16x32_bf16 v[124:127], v[144:147], v[168:171], v[124:127]
	v_mfma_f32_16x16x32_bf16 v[120:123], v[160:163], v[168:171], v[120:123]
	v_mfma_f32_16x16x32_bf16 v[108:111], v[144:147], v[182:185], v[108:111]
	v_mfma_f32_16x16x32_bf16 v[104:107], v[160:163], v[182:185], v[104:107]
	v_mfma_f32_16x16x32_bf16 v[92:95], v[144:147], v[194:197], v[92:95]
	v_mfma_f32_16x16x32_bf16 v[88:91], v[160:163], v[194:197], v[88:91]
	v_mfma_f32_16x16x32_bf16 v[76:79], v[144:147], v[202:205], v[76:79]
	v_mfma_f32_16x16x32_bf16 v[72:75], v[160:163], v[202:205], v[72:75]
	v_mfma_f32_16x16x32_bf16 v[124:127], v[156:159], v[172:175], v[124:127]
	v_mfma_f32_16x16x32_bf16 v[120:123], v[164:167], v[172:175], v[120:123]
	v_mfma_f32_16x16x32_bf16 v[108:111], v[156:159], v[190:193], v[108:111]
	v_mfma_f32_16x16x32_bf16 v[104:107], v[164:167], v[190:193], v[104:107]
	v_mfma_f32_16x16x32_bf16 v[92:95], v[156:159], v[198:201], v[92:95]
	v_mfma_f32_16x16x32_bf16 v[88:91], v[164:167], v[198:201], v[88:91]
	v_mfma_f32_16x16x32_bf16 v[76:79], v[156:159], v[206:209], v[76:79]
	v_mfma_f32_16x16x32_bf16 v[72:75], v[164:167], v[206:209], v[72:75]
	s_setprio 1
	s_barrier
	s_add_i32 s48, s39, s29
	v_lshl_add_u64 v[148:149], s[20:21], 0, v[130:131]
	s_mov_b32 m0, s48
	ds_read_b128 v[210:213], v155
	ds_read_b128 v[214:217], v155 offset:1024
	ds_read_b128 v[218:221], v155 offset:2048
	ds_read_b128 v[222:225], v155 offset:3072
	global_load_lds_dwordx4 v[148:149], off
	v_lshl_add_u64 v[186:187], s[20:21], 0, v[134:135]
	s_add_i32 m0, s48, 0x2000
	s_nop 0
	global_load_lds_dwordx4 v[186:187], off
	s_barrier
	s_waitcnt lgkmcnt(0)
	s_setprio 0
	s_waitcnt lgkmcnt(0)
	v_mfma_f32_16x16x32_bf16 v[116:119], v[210:213], v[168:171], v[116:119]
	v_mfma_f32_16x16x32_bf16 v[112:115], v[218:221], v[168:171], v[112:115]
	v_mfma_f32_16x16x32_bf16 v[100:103], v[210:213], v[182:185], v[100:103]
	v_mfma_f32_16x16x32_bf16 v[96:99], v[218:221], v[182:185], v[96:99]
	v_mfma_f32_16x16x32_bf16 v[84:87], v[210:213], v[194:197], v[84:87]
	v_mfma_f32_16x16x32_bf16 v[80:83], v[218:221], v[194:197], v[80:83]
	v_mfma_f32_16x16x32_bf16 v[68:71], v[210:213], v[202:205], v[68:71]
	v_mfma_f32_16x16x32_bf16 v[64:67], v[218:221], v[202:205], v[64:67]
	v_mfma_f32_16x16x32_bf16 v[116:119], v[214:217], v[172:175], v[116:119]
	v_mfma_f32_16x16x32_bf16 v[112:115], v[222:225], v[172:175], v[112:115]
	v_mfma_f32_16x16x32_bf16 v[100:103], v[214:217], v[190:193], v[100:103]
	v_mfma_f32_16x16x32_bf16 v[96:99], v[222:225], v[190:193], v[96:99]
	v_mfma_f32_16x16x32_bf16 v[84:87], v[214:217], v[198:201], v[84:87]
	v_mfma_f32_16x16x32_bf16 v[80:83], v[222:225], v[198:201], v[80:83]
	v_mfma_f32_16x16x32_bf16 v[68:71], v[214:217], v[206:209], v[68:71]
	v_mfma_f32_16x16x32_bf16 v[64:67], v[222:225], v[206:209], v[64:67]
	s_setprio 1
	s_mov_b32 m0, s17
	v_lshl_add_u64 v[226:227], s[22:23], 0, v[128:129]
	s_barrier
	ds_read_b128 v[168:171], v154 offset:16384
	ds_read_b128 v[172:175], v154 offset:17408
	ds_read_b128 v[182:185], v154 offset:18432
	ds_read_b128 v[190:193], v154 offset:19456
	ds_read_b128 v[194:197], v154 offset:20480
	ds_read_b128 v[198:201], v154 offset:21504
	ds_read_b128 v[202:205], v154 offset:22528
	ds_read_b128 v[206:209], v154 offset:23552
	global_load_lds_dwordx4 v[226:227], off
	v_lshl_add_u64 v[228:229], s[22:23], 0, v[132:133]
	s_mov_b32 m0, s30
	s_nop 0
	global_load_lds_dwordx4 v[228:229], off
	s_barrier
	s_waitcnt lgkmcnt(0)
	s_setprio 0
	s_waitcnt lgkmcnt(0)
	v_mfma_f32_16x16x32_bf16 v[60:63], v[144:147], v[168:171], v[60:63]
	v_mfma_f32_16x16x32_bf16 v[56:59], v[160:163], v[168:171], v[56:59]
	v_mfma_f32_16x16x32_bf16 v[44:47], v[144:147], v[182:185], v[44:47]
	v_mfma_f32_16x16x32_bf16 v[40:43], v[160:163], v[182:185], v[40:43]
	v_mfma_f32_16x16x32_bf16 v[28:31], v[144:147], v[194:197], v[28:31]
	v_mfma_f32_16x16x32_bf16 v[24:27], v[160:163], v[194:197], v[24:27]
	v_mfma_f32_16x16x32_bf16 v[12:15], v[144:147], v[202:205], v[12:15]
	v_mfma_f32_16x16x32_bf16 v[8:11], v[160:163], v[202:205], v[8:11]
	v_mfma_f32_16x16x32_bf16 v[60:63], v[156:159], v[172:175], v[60:63]
	v_mfma_f32_16x16x32_bf16 v[56:59], v[164:167], v[172:175], v[56:59]
	v_mfma_f32_16x16x32_bf16 v[44:47], v[156:159], v[190:193], v[44:47]
	v_mfma_f32_16x16x32_bf16 v[40:43], v[164:167], v[190:193], v[40:43]
	v_mfma_f32_16x16x32_bf16 v[28:31], v[156:159], v[198:201], v[28:31]
	v_mfma_f32_16x16x32_bf16 v[24:27], v[164:167], v[198:201], v[24:27]
	v_mfma_f32_16x16x32_bf16 v[12:15], v[156:159], v[206:209], v[12:15]
	v_mfma_f32_16x16x32_bf16 v[8:11], v[164:167], v[206:209], v[8:11]
	s_setprio 1
	s_barrier
; #define PG8_STAGE(bufoff, gbase, voff) do { _Pragma("unroll") for (int _i = 0; _i < 2; ++_i) \
;         __builtin_amdgcn_global_load_lds((const unsigned*)((const char*)(gbase) + (voff)[_i]), (PG8_LAS unsigned*)(lds + (bufoff) + ldsw + _i * 8192), 16, 0, 0); } while (0)
; #define PG8_LDA(dst, b, h) do { _Pragma("unroll") for (int m = 0; m < 4; ++m) _Pragma("unroll") for (int k = 0; k < 2; ++k) dst[m][k] = *(const PG8_LAS bf16x8*)(lds + PG8_SA(b, h) + aoff + m * 2048 + k * 1024); } while (0)
; #define PG8_LDB(dst, b, h) do { _Pragma("unroll") for (int n = 0; n < 2; ++n) _Pragma("unroll") for (int k = 0; k < 2; ++k) dst[n][k] = *(const PG8_LAS bf16x8*)(lds + PG8_SB(b, h) + boff + n * 2048 + k * 1024); } while (0)
; #define PG8_MMA(ai, bj, At, Bt) do { __builtin_amdgcn_s_setprio(1); _Pragma("unroll") for (int m = 0; m < 4; ++m) _Pragma("unroll") for (int n = 0; n < 2; ++n) _Pragma("unroll") for (int k = 0; k < 2; ++k) \
;         acc[ai][bj][m][n] = __builtin_amdgcn_mfma_f32_16x16x32_bf16(Bt[n][k], At[m][k], acc[ai][bj][m][n], 0, 0, 0); __builtin_amdgcn_s_setprio(0); } while (0)
; #define PG8_WAIT_V(n) asm volatile("s_waitcnt vmcnt(" #n ")" ::: "memory")
; #define PG8_WAIT_L(n) asm volatile("s_waitcnt lgkmcnt(" #n ")" ::: "memory")
; #define PG8_BAR __builtin_amdgcn_s_barrier()
; #define PG8_SCHED __builtin_amdgcn_sched_barrier(0)
; template <class Epi, class Sched>
; __device__ __forceinline__ void gemm_phase(PG8_LAS unsigned char* lds, const Gemm g, const Sched& S, const Epi& E) {
;     ...
;             PG8_STAGE(PG8_SB(0, 1), b2 + hstep, voffB);
;             PG8_WAIT_V(6); PG8_BAR; PG8_MMA(1, 1, At, B1); PG8_BAR;
;             PG8_LDB(B0, 1, 0); PG8_SCHED; PG8_LDA(At, 1, 0); PG8_STAGE(PG8_SA(0, 1), a2 + hstep, voffA);
;             PG8_WAIT_L(8); PG8_BAR; PG8_WAIT_L(0); PG8_MMA(0, 0, At, B0); PG8_BAR; PG8_SCHED;
;             PG8_LDB(B1, 1, 1); PG8_STAGE(PG8_SB(1, 0), b3, voffB);
;             PG8_BAR; PG8_WAIT_L(0); PG8_MMA(0, 1, At, B1); PG8_BAR;
;             PG8_LDA(At, 1, 1); PG8_STAGE(PG8_SA(1, 0), a3, voffA);
	s_add_u32 s48, s20, 0x40000
	s_addc_u32 s49, s21, 0
	s_add_i32 s50, s40, s29
	v_lshl_add_u64 v[144:145], s[48:49], 0, v[130:131]
	s_mov_b32 m0, s50
	s_nop 0
	global_load_lds_dwordx4 v[144:145], off
	v_lshl_add_u64 v[144:145], s[48:49], 0, v[134:135]
	s_add_i32 m0, s50, 0x2000
	s_nop 0
	global_load_lds_dwordx4 v[144:145], off
	s_waitcnt vmcnt(6)
	s_barrier
	s_setprio 0
	v_mfma_f32_16x16x32_bf16 v[52:55], v[210:213], v[168:171], v[52:55]
	v_mfma_f32_16x16x32_bf16 v[48:51], v[218:221], v[168:171], v[48:51]
	v_mfma_f32_16x16x32_bf16 v[36:39], v[210:213], v[182:185], v[36:39]
	v_mfma_f32_16x16x32_bf16 v[32:35], v[218:221], v[182:185], v[32:35]
	v_mfma_f32_16x16x32_bf16 v[20:23], v[210:213], v[194:197], v[20:23]
	v_mfma_f32_16x16x32_bf16 v[16:19], v[218:221], v[194:197], v[16:19]
	v_mfma_f32_16x16x32_bf16 v[4:7], v[210:213], v[202:205], v[4:7]
	v_mfma_f32_16x16x32_bf16 v[0:3], v[218:221], v[202:205], v[0:3]
	v_mfma_f32_16x16x32_bf16 v[52:55], v[214:217], v[172:175], v[52:55]
	v_mfma_f32_16x16x32_bf16 v[48:51], v[222:225], v[172:175], v[48:51]
	v_mfma_f32_16x16x32_bf16 v[36:39], v[214:217], v[190:193], v[36:39]
	v_mfma_f32_16x16x32_bf16 v[32:35], v[222:225], v[190:193], v[32:35]
	v_mfma_f32_16x16x32_bf16 v[20:23], v[214:217], v[198:201], v[20:23]
	v_mfma_f32_16x16x32_bf16 v[16:19], v[222:225], v[198:201], v[16:19]
	v_mfma_f32_16x16x32_bf16 v[4:7], v[214:217], v[206:209], v[4:7]
	v_mfma_f32_16x16x32_bf16 v[0:3], v[222:225], v[206:209], v[0:3]
	s_setprio 1
	s_add_i32 s48, 0, 0x18000
	v_add_u32_e32 v164, s48, v151
	s_barrier
	ds_read_b128 v[144:147], v164
	ds_read_b128 v[156:159], v164 offset:1024
	ds_read_b128 v[160:163], v164 offset:2048
	ds_read_b128 v[164:167], v164 offset:3072
	s_add_u32 s22, s22, 0x40000
	s_addc_u32 s23, s23, 0
	s_mov_b32 m0, s31
	v_lshl_add_u64 v[210:211], s[22:23], 0, v[128:129]
	ds_read_b128 v[168:171], v154 offset:32768
	ds_read_b128 v[172:175], v154 offset:33792
	ds_read_b128 v[182:185], v154 offset:34816
	ds_read_b128 v[190:193], v154 offset:35840
	ds_read_b128 v[194:197], v154 offset:36864
	ds_read_b128 v[198:201], v154 offset:37888
	ds_read_b128 v[202:205], v154 offset:38912
	ds_read_b128 v[206:209], v154 offset:39936
	global_load_lds_dwordx4 v[210:211], off
	v_lshl_add_u64 v[210:211], s[22:23], 0, v[132:133]
	s_mov_b32 m0, s34
	s_nop 0
	global_load_lds_dwordx4 v[210:211], off
	s_waitcnt lgkmcnt(8)
	s_barrier
	s_waitcnt lgkmcnt(0)
	s_setprio 0
	s_waitcnt lgkmcnt(0)
	v_mfma_f32_16x16x32_bf16 v[124:127], v[144:147], v[168:171], v[124:127]
	v_mfma_f32_16x16x32_bf16 v[120:123], v[160:163], v[168:171], v[120:123]
	v_mfma_f32_16x16x32_bf16 v[108:111], v[144:147], v[182:185], v[108:111]
	v_mfma_f32_16x16x32_bf16 v[104:107], v[160:163], v[182:185], v[104:107]
	v_mfma_f32_16x16x32_bf16 v[92:95], v[144:147], v[194:197], v[92:95]
	v_mfma_f32_16x16x32_bf16 v[88:91], v[160:163], v[194:197], v[88:91]
	v_mfma_f32_16x16x32_bf16 v[76:79], v[144:147], v[202:205], v[76:79]
	v_mfma_f32_16x16x32_bf16 v[72:75], v[160:163], v[202:205], v[72:75]
	v_mfma_f32_16x16x32_bf16 v[124:127], v[156:159], v[172:175], v[124:127]
	v_mfma_f32_16x16x32_bf16 v[120:123], v[164:167], v[172:175], v[120:123]
	v_mfma_f32_16x16x32_bf16 v[108:111], v[156:159], v[190:193], v[108:111]
	v_mfma_f32_16x16x32_bf16 v[104:107], v[164:167], v[190:193], v[104:107]
	v_mfma_f32_16x16x32_bf16 v[92:95], v[156:159], v[198:201], v[92:95]
	v_mfma_f32_16x16x32_bf16 v[88:91], v[164:167], v[198:201], v[88:91]
	v_mfma_f32_16x16x32_bf16 v[76:79], v[156:159], v[206:209], v[76:79]
	v_mfma_f32_16x16x32_bf16 v[72:75], v[164:167], v[206:209], v[72:75]
	s_setprio 1
	s_barrier
	s_add_i32 s22, 0, 0x1c000
	s_add_i32 s23, s48, s29
	v_add_u32_e32 v179, s22, v151
	v_lshl_add_u64 v[148:149], v[148:149], 0, s[6:7]
	s_mov_b32 m0, s23
	ds_read_b128 v[210:213], v179
	ds_read_b128 v[214:217], v179 offset:1024
	ds_read_b128 v[218:221], v179 offset:2048
	ds_read_b128 v[222:225], v179 offset:3072
	global_load_lds_dwordx4 v[148:149], off
	v_lshl_add_u64 v[148:149], v[186:187], 0, s[6:7]
	s_add_i32 m0, s23, 0x2000
	s_nop 0
	global_load_lds_dwordx4 v[148:149], off
	s_barrier
	s_waitcnt lgkmcnt(0)
	s_setprio 0
	s_waitcnt lgkmcnt(0)
	v_mfma_f32_16x16x32_bf16 v[116:119], v[210:213], v[168:171], v[116:119]
	v_mfma_f32_16x16x32_bf16 v[112:115], v[218:221], v[168:171], v[112:115]
	v_mfma_f32_16x16x32_bf16 v[100:103], v[210:213], v[182:185], v[100:103]
	v_mfma_f32_16x16x32_bf16 v[96:99], v[218:221], v[182:185], v[96:99]
	v_mfma_f32_16x16x32_bf16 v[84:87], v[210:213], v[194:197], v[84:87]
	v_mfma_f32_16x16x32_bf16 v[80:83], v[218:221], v[194:197], v[80:83]
	v_mfma_f32_16x16x32_bf16 v[68:71], v[210:213], v[202:205], v[68:71]
	v_mfma_f32_16x16x32_bf16 v[64:67], v[218:221], v[202:205], v[64:67]
	v_mfma_f32_16x16x32_bf16 v[116:119], v[214:217], v[172:175], v[116:119]
	v_mfma_f32_16x16x32_bf16 v[112:115], v[222:225], v[172:175], v[112:115]
	v_mfma_f32_16x16x32_bf16 v[100:103], v[214:217], v[190:193], v[100:103]
	v_mfma_f32_16x16x32_bf16 v[96:99], v[222:225], v[190:193], v[96:99]
	v_mfma_f32_16x16x32_bf16 v[84:87], v[214:217], v[198:201], v[84:87]
	v_mfma_f32_16x16x32_bf16 v[80:83], v[222:225], v[198:201], v[80:83]
	v_mfma_f32_16x16x32_bf16 v[68:71], v[214:217], v[206:209], v[68:71]
	v_mfma_f32_16x16x32_bf16 v[64:67], v[222:225], v[206:209], v[64:67]
	s_setprio 1
	s_mov_b32 m0, s36
	v_lshl_add_u64 v[148:149], v[226:227], 0, s[6:7]
	s_barrier
	ds_read_b128 v[168:171], v154 offset:49152
	ds_read_b128 v[172:175], v154 offset:50176
	ds_read_b128 v[182:185], v154 offset:51200
	ds_read_b128 v[190:193], v154 offset:52224
	ds_read_b128 v[194:197], v154 offset:53248
	ds_read_b128 v[198:201], v154 offset:54272
	ds_read_b128 v[202:205], v154 offset:55296
	ds_read_b128 v[206:209], v154 offset:56320
	global_load_lds_dwordx4 v[148:149], off
	v_lshl_add_u64 v[148:149], v[228:229], 0, s[6:7]
	s_mov_b32 m0, s37
	s_nop 0
	global_load_lds_dwordx4 v[148:149], off
	s_barrier
; __device__ __forceinline__ unsigned cvt_pk_bf16(float lo, float hi) { unsigned r; asm volatile("v_cvt_pk_bf16_f32 %0, %1, %2" : "=v"(r) : "v"(lo), "v"(hi)); return r; }
; __device__ __forceinline__ float bf_lo(unsigned u) { return __uint_as_float(u << 16); }
; __device__ __forceinline__ float bf_hi(unsigned u) { return __uint_as_float(u & 0xffff0000u); }
; #define PG8_STAGE(bufoff, gbase, voff) do { _Pragma("unroll") for (int _i = 0; _i < 2; ++_i) \
;         __builtin_amdgcn_global_load_lds((const unsigned*)((const char*)(gbase) + (voff)[_i]), (PG8_LAS unsigned*)(lds + (bufoff) + ldsw + _i * 8192), 16, 0, 0); } while (0)
; #define PG8_BAR __builtin_amdgcn_s_barrier()
;     __device__ __forceinline__ void operator()(const f32x4 (&acc)[2][2][4][2], const Unit& u, int wr, int wc, int fr, int fq) const {
;     ...
;             for (int m = 0; m < 4; ++m) { const size_t r = (size_t)(row0 + ai * HALF + m * 16); bf16_t* rowp = O + r * ldc + col0; const bf16_t* gp = G + r * ldg + col0;
; #pragma unroll
;                 for (int bj = 0; bj < 2; ++bj) { const u32x4 gw = *(const u32x4*)(gp + bj * HALF);
;                     f32x4 v0 = acc[ai][bj][m][0], v1 = acc[ai][bj][m][1];
;                     v0[0] *= bf_lo(gw.x); v0[1] *= bf_hi(gw.x); v0[2] *= bf_lo(gw.y); v0[3] *= bf_hi(gw.y);
;                     v1[0] *= bf_lo(gw.z); v1[1] *= bf_hi(gw.z); v1[2] *= bf_lo(gw.w); v1[3] *= bf_hi(gw.w);
;                     if (ACCUM) { const u32x4 pw = *(const u32x4*)(rowp + bj * HALF);
;                         v0[0] += bf_lo(pw.x); v0[1] += bf_hi(pw.x); v0[2] += bf_lo(pw.y); v0[3] += bf_hi(pw.y);
;                         v1[0] += bf_lo(pw.z); v1[1] += bf_hi(pw.z); v1[2] += bf_lo(pw.w); v1[3] += bf_hi(pw.w); }
;                     u32x4 w; w.x = cvt_pk_bf16(v0[0], v0[1]); w.y = cvt_pk_bf16(v0[2], v0[3]); w.z = cvt_pk_bf16(v1[0], v1[1]); w.w = cvt_pk_bf16(v1[2], v1[3]);
;                     *(u32x4*)(rowp + bj * HALF) = w; } }
; template <class Epi, class Sched>
; __device__ __forceinline__ void gemm_phase(PG8_LAS unsigned char* lds, const Gemm g, const Sched& S, const Epi& E) {
;     ...
;             PG8_LDA(At, 1, 1); PG8_STAGE(PG8_SA(1, 0), a3, voffA);
;             PG8_BAR; PG8_WAIT_L(0); PG8_MMA(1, 0, At, B0); PG8_BAR; PG8_SCHED;
;             PG8_STAGE(PG8_SB(1, 1), b3 + hstep, voffB);
;             PG8_WAIT_V(6); PG8_BAR; PG8_MMA(1, 1, At, B1); PG8_BAR;
;         }
	s_waitcnt lgkmcnt(0)
	s_setprio 0
	s_waitcnt lgkmcnt(0)
	v_mfma_f32_16x16x32_bf16 v[60:63], v[144:147], v[168:171], v[60:63]
	v_mfma_f32_16x16x32_bf16 v[56:59], v[160:163], v[168:171], v[56:59]
	v_mfma_f32_16x16x32_bf16 v[44:47], v[144:147], v[182:185], v[44:47]
	v_mfma_f32_16x16x32_bf16 v[40:43], v[160:163], v[182:185], v[40:43]
	v_mfma_f32_16x16x32_bf16 v[28:31], v[144:147], v[194:197], v[28:31]
	v_mfma_f32_16x16x32_bf16 v[24:27], v[160:163], v[194:197], v[24:27]
	v_mfma_f32_16x16x32_bf16 v[12:15], v[144:147], v[202:205], v[12:15]
	v_mfma_f32_16x16x32_bf16 v[8:11], v[160:163], v[202:205], v[8:11]
	v_mfma_f32_16x16x32_bf16 v[60:63], v[156:159], v[172:175], v[60:63]
	v_mfma_f32_16x16x32_bf16 v[56:59], v[164:167], v[172:175], v[56:59]
	v_mfma_f32_16x16x32_bf16 v[44:47], v[156:159], v[190:193], v[44:47]
	v_mfma_f32_16x16x32_bf16 v[40:43], v[164:167], v[190:193], v[40:43]
	v_mfma_f32_16x16x32_bf16 v[28:31], v[156:159], v[198:201], v[28:31]
	v_mfma_f32_16x16x32_bf16 v[24:27], v[164:167], v[198:201], v[24:27]
	v_mfma_f32_16x16x32_bf16 v[12:15], v[156:159], v[206:209], v[12:15]
	v_mfma_f32_16x16x32_bf16 v[8:11], v[164:167], v[206:209], v[8:11]
	s_setprio 1
	s_barrier
	s_add_u32 s20, s20, 0x40080
	s_addc_u32 s21, s21, 0
	s_add_i32 s22, s22, s29
	v_lshl_add_u64 v[144:145], s[20:21], 0, v[130:131]
	s_mov_b32 m0, s22
	s_nop 0
	global_load_lds_dwordx4 v[144:145], off
	v_lshl_add_u64 v[144:145], s[20:21], 0, v[134:135]
	s_add_i32 m0, s22, 0x2000
	s_nop 0
	global_load_lds_dwordx4 v[144:145], off
	s_waitcnt vmcnt(6)
	s_barrier
	s_setprio 0
	v_mfma_f32_16x16x32_bf16 v[52:55], v[210:213], v[168:171], v[52:55]
	v_mfma_f32_16x16x32_bf16 v[48:51], v[218:221], v[168:171], v[48:51]
	v_mfma_f32_16x16x32_bf16 v[36:39], v[210:213], v[182:185], v[36:39]
	v_mfma_f32_16x16x32_bf16 v[32:35], v[218:221], v[182:185], v[32:35]
	v_mfma_f32_16x16x32_bf16 v[20:23], v[210:213], v[194:197], v[20:23]
	v_mfma_f32_16x16x32_bf16 v[16:19], v[218:221], v[194:197], v[16:19]
	v_mfma_f32_16x16x32_bf16 v[4:7], v[210:213], v[202:205], v[4:7]
	v_mfma_f32_16x16x32_bf16 v[0:3], v[218:221], v[202:205], v[0:3]
	v_mfma_f32_16x16x32_bf16 v[52:55], v[214:217], v[172:175], v[52:55]
	v_mfma_f32_16x16x32_bf16 v[48:51], v[222:225], v[172:175], v[48:51]
	v_mfma_f32_16x16x32_bf16 v[36:39], v[214:217], v[190:193], v[36:39]
	v_mfma_f32_16x16x32_bf16 v[32:35], v[222:225], v[190:193], v[32:35]
	v_mfma_f32_16x16x32_bf16 v[20:23], v[214:217], v[198:201], v[20:23]
	v_mfma_f32_16x16x32_bf16 v[16:19], v[222:225], v[198:201], v[16:19]
	v_mfma_f32_16x16x32_bf16 v[4:7], v[214:217], v[206:209], v[4:7]
	v_mfma_f32_16x16x32_bf16 v[0:3], v[222:225], v[206:209], v[0:3]
	s_setprio 1
	s_add_i32 s47, s47, 2
	s_add_u32 s18, s18, 0x100
	s_addc_u32 s19, s19, 0
	s_add_u32 s45, s45, 0x100
	s_addc_u32 s46, s46, 0
	s_cmp_gt_u32 s47, 13
	s_barrier
	s_cbranch_scc0 .LBB0_1011
	v_lshl_add_u32 v146, s16, 8, v150
	v_lshl_or_b32 v144, s42, 8, v152
	v_ashrrev_i32_e32 v147, 31, v146
	v_ashrrev_i32_e32 v145, 31, v144
	v_mov_b64_e32 v[148:149], s[4:5]
	v_lshlrev_b64 v[160:161], 11, v[146:147]
	v_lshlrev_b64 v[144:145], 1, v[144:145]
	v_mad_i64_i32 v[156:157], s[18:19], v146, s41, v[148:149]
	v_lshl_add_u64 v[160:161], s[0:1], 0, v[160:161]
	v_lshl_add_u64 v[164:165], v[156:157], 0, v[144:145]
	v_lshl_add_u64 v[166:167], v[160:161], 0, v[144:145]
	global_load_dwordx4 v[156:159], v[164:165], off
	global_load_dwordx4 v[160:163], v[166:167], off
	s_and_b64 vcc, exec, s[2:3]
	s_mov_b32 s42, s8
	s_mov_b32 s16, s10
	s_mov_b64 s[20:21], s[14:15]
	s_waitcnt vmcnt(0)
	v_lshlrev_b32_e32 v147, 16, v156
	v_and_b32_e32 v156, 0xffff0000, v156
	v_lshlrev_b32_e32 v168, 16, v157
	v_and_b32_e32 v157, 0xffff0000, v157
	v_lshlrev_b32_e32 v169, 16, v158
	v_and_b32_e32 v158, 0xffff0000, v158
	v_lshlrev_b32_e32 v170, 16, v159
	v_and_b32_e32 v159, 0xffff0000, v159
	v_lshlrev_b32_e32 v171, 16, v160
	v_and_b32_e32 v160, 0xffff0000, v160
	v_lshlrev_b32_e32 v172, 16, v161
	v_and_b32_e32 v161, 0xffff0000, v161
	v_lshlrev_b32_e32 v173, 16, v162
	v_and_b32_e32 v162, 0xffff0000, v162
	v_lshlrev_b32_e32 v174, 16, v163
	v_and_b32_e32 v163, 0xffff0000, v163
	v_fmac_f32_e32 v171, v124, v147
	v_fmac_f32_e32 v160, v125, v156
	v_fmac_f32_e32 v172, v126, v168
	v_fmac_f32_e32 v161, v127, v157
	v_fmac_f32_e32 v173, v120, v169
	v_fmac_f32_e32 v162, v121, v158
	v_fmac_f32_e32 v174, v122, v170
	v_fmac_f32_e32 v163, v123, v159
	v_cvt_pk_bf16_f32 v120, v171, v160
	v_cvt_pk_bf16_f32 v121, v172, v161
	v_cvt_pk_bf16_f32 v122, v173, v162
	v_cvt_pk_bf16_f32 v123, v174, v163
	global_load_dwordx4 v[124:127], v[164:165], off offset:256
	global_load_dwordx4 v[156:159], v[166:167], off offset:256
	v_or_b32_e32 v160, 16, v146
	global_store_dwordx4 v[166:167], v[120:123], off
	v_mad_i64_i32 v[162:163], s[18:19], v160, s41, v[148:149]
	v_lshl_add_u64 v[162:163], v[162:163], 0, v[144:145]
	s_waitcnt vmcnt(0)
	v_lshlrev_b32_e32 v122, 16, v125
	v_lshlrev_b32_e32 v161, 16, v157
	v_lshlrev_b32_e32 v120, 16, v124
	v_and_b32_e32 v121, 0xffff0000, v124
	v_and_b32_e32 v123, 0xffff0000, v125
	v_lshlrev_b32_e32 v124, 16, v126
	v_and_b32_e32 v125, 0xffff0000, v126
	v_lshlrev_b32_e32 v147, 16, v156
	v_and_b32_e32 v156, 0xffff0000, v156
	v_and_b32_e32 v157, 0xffff0000, v157
	v_lshlrev_b32_e32 v164, 16, v158
	v_and_b32_e32 v158, 0xffff0000, v158
	v_fmac_f32_e32 v161, v118, v122
	v_fmac_f32_e32 v147, v116, v120
	v_fmac_f32_e32 v156, v117, v121
	v_fmac_f32_e32 v157, v119, v123
	v_fmac_f32_e32 v164, v112, v124
	v_fmac_f32_e32 v158, v113, v125
	v_cvt_pk_bf16_f32 v112, v147, v156
	v_cvt_pk_bf16_f32 v113, v161, v157
	v_ashrrev_i32_e32 v161, 31, v160
	v_lshlrev_b64 v[120:121], 11, v[160:161]
	v_lshl_add_u64 v[120:121], s[0:1], 0, v[120:121]
	v_lshlrev_b32_e32 v126, 16, v127
	v_and_b32_e32 v127, 0xffff0000, v127
	v_lshlrev_b32_e32 v165, 16, v159
	v_and_b32_e32 v159, 0xffff0000, v159
	v_lshl_add_u64 v[124:125], v[120:121], 0, v[144:145]
	v_fmac_f32_e32 v165, v114, v126
	v_fmac_f32_e32 v159, v115, v127
	v_cvt_pk_bf16_f32 v114, v164, v158
	v_cvt_pk_bf16_f32 v115, v165, v159
	global_load_dwordx4 v[116:119], v[162:163], off
	global_load_dwordx4 v[120:123], v[124:125], off
	s_waitcnt vmcnt(0)
; __device__ __forceinline__ unsigned cvt_pk_bf16(float lo, float hi) { unsigned r; asm volatile("v_cvt_pk_bf16_f32 %0, %1, %2" : "=v"(r) : "v"(lo), "v"(hi)); return r; }
; __device__ __forceinline__ float bf_lo(unsigned u) { return __uint_as_float(u << 16); }
; __device__ __forceinline__ float bf_hi(unsigned u) { return __uint_as_float(u & 0xffff0000u); }
;     __device__ __forceinline__ void operator()(const f32x4 (&acc)[2][2][4][2], const Unit& u, int wr, int wc, int fr, int fq) const {
;     ...
;             for (int m = 0; m < 4; ++m) { const size_t r = (size_t)(row0 + ai * HALF + m * 16); bf16_t* rowp = O + r * ldc + col0; const bf16_t* gp = G + r * ldg + col0;
; #pragma unroll
;                 for (int bj = 0; bj < 2; ++bj) { const u32x4 gw = *(const u32x4*)(gp + bj * HALF);
;                     f32x4 v0 = acc[ai][bj][m][0], v1 = acc[ai][bj][m][1];
;                     v0[0] *= bf_lo(gw.x); v0[1] *= bf_hi(gw.x); v0[2] *= bf_lo(gw.y); v0[3] *= bf_hi(gw.y);
;                     v1[0] *= bf_lo(gw.z); v1[1] *= bf_hi(gw.z); v1[2] *= bf_lo(gw.w); v1[3] *= bf_hi(gw.w);
;                     if (ACCUM) { const u32x4 pw = *(const u32x4*)(rowp + bj * HALF);
;                         v0[0] += bf_lo(pw.x); v0[1] += bf_hi(pw.x); v0[2] += bf_lo(pw.y); v0[3] += bf_hi(pw.y);
;                         v1[0] += bf_lo(pw.z); v1[1] += bf_hi(pw.z); v1[2] += bf_lo(pw.w); v1[3] += bf_hi(pw.w); }
;                     u32x4 w; w.x = cvt_pk_bf16(v0[0], v0[1]); w.y = cvt_pk_bf16(v0[2], v0[3]); w.z = cvt_pk_bf16(v1[0], v1[1]); w.w = cvt_pk_bf16(v1[2], v1[3]);
;                     *(u32x4*)(rowp + bj * HALF) = w; } }
	v_lshlrev_b32_e32 v126, 16, v120
	global_store_dwordx4 v[166:167], v[112:115], off offset:256
	v_and_b32_e32 v120, 0xffff0000, v120
	v_lshlrev_b32_e32 v127, 16, v121
	v_lshlrev_b32_e32 v112, 16, v116
	v_and_b32_e32 v113, 0xffff0000, v116
	v_lshlrev_b32_e32 v114, 16, v117
	v_and_b32_e32 v115, 0xffff0000, v117
	v_lshlrev_b32_e32 v116, 16, v118
	v_and_b32_e32 v117, 0xffff0000, v118
	v_lshlrev_b32_e32 v118, 16, v119
	v_and_b32_e32 v119, 0xffff0000, v119
	v_and_b32_e32 v121, 0xffff0000, v121
	v_lshlrev_b32_e32 v147, 16, v122
	v_and_b32_e32 v122, 0xffff0000, v122
	v_lshlrev_b32_e32 v156, 16, v123
	v_and_b32_e32 v123, 0xffff0000, v123
	v_fmac_f32_e32 v126, v108, v112
	v_fmac_f32_e32 v120, v109, v113
	v_fmac_f32_e32 v127, v110, v114
	v_fmac_f32_e32 v121, v111, v115
	v_fmac_f32_e32 v147, v104, v116
	v_fmac_f32_e32 v122, v105, v117
	v_fmac_f32_e32 v156, v106, v118
	v_fmac_f32_e32 v123, v107, v119
	v_cvt_pk_bf16_f32 v104, v126, v120
	v_cvt_pk_bf16_f32 v105, v127, v121
	v_cvt_pk_bf16_f32 v106, v147, v122
	v_cvt_pk_bf16_f32 v107, v156, v123
	global_load_dwordx4 v[108:111], v[162:163], off offset:256
	global_load_dwordx4 v[112:115], v[124:125], off offset:256
	v_or_b32_e32 v116, 32, v146
	global_store_dwordx4 v[124:125], v[104:107], off
	v_mad_i64_i32 v[118:119], s[18:19], v116, s41, v[148:149]
	v_lshl_add_u64 v[118:119], v[118:119], 0, v[144:145]
	s_waitcnt vmcnt(0)
	v_lshlrev_b32_e32 v104, 16, v108
	v_lshlrev_b32_e32 v117, 16, v112
	v_and_b32_e32 v105, 0xffff0000, v108
	v_lshlrev_b32_e32 v108, 16, v110
	v_and_b32_e32 v112, 0xffff0000, v112
	v_lshlrev_b32_e32 v121, 16, v114
	v_fmac_f32_e32 v117, v100, v104
	v_fmac_f32_e32 v112, v101, v105
	v_fmac_f32_e32 v121, v96, v108
	v_cvt_pk_bf16_f32 v96, v117, v112
	v_ashrrev_i32_e32 v117, 31, v116
	v_lshlrev_b64 v[104:105], 11, v[116:117]
	v_lshlrev_b32_e32 v106, 16, v109
	v_and_b32_e32 v107, 0xffff0000, v109
	v_and_b32_e32 v109, 0xffff0000, v110
	v_and_b32_e32 v114, 0xffff0000, v114
	v_lshl_add_u64 v[104:105], s[0:1], 0, v[104:105]
	v_lshlrev_b32_e32 v110, 16, v111
	v_and_b32_e32 v111, 0xffff0000, v111
	v_lshlrev_b32_e32 v120, 16, v113
	v_and_b32_e32 v113, 0xffff0000, v113
	v_lshlrev_b32_e32 v122, 16, v115
	v_and_b32_e32 v115, 0xffff0000, v115
	v_fmac_f32_e32 v114, v97, v109
	v_lshl_add_u64 v[108:109], v[104:105], 0, v[144:145]
	v_fmac_f32_e32 v120, v102, v106
	v_fmac_f32_e32 v113, v103, v107
	v_fmac_f32_e32 v122, v98, v110
	v_fmac_f32_e32 v115, v99, v111
	v_cvt_pk_bf16_f32 v97, v120, v113
	v_cvt_pk_bf16_f32 v98, v121, v114
	v_cvt_pk_bf16_f32 v99, v122, v115
	global_load_dwordx4 v[100:103], v[118:119], off
	global_load_dwordx4 v[104:107], v[108:109], off
	s_waitcnt vmcnt(0)
	v_lshlrev_b32_e32 v110, 16, v104
	global_store_dwordx4 v[124:125], v[96:99], off offset:256
	v_and_b32_e32 v104, 0xffff0000, v104
	v_lshlrev_b32_e32 v111, 16, v105
	v_lshlrev_b32_e32 v96, 16, v100
	v_and_b32_e32 v97, 0xffff0000, v100
	v_lshlrev_b32_e32 v98, 16, v101
	v_and_b32_e32 v99, 0xffff0000, v101
	v_lshlrev_b32_e32 v100, 16, v102
	v_and_b32_e32 v101, 0xffff0000, v102
	v_lshlrev_b32_e32 v102, 16, v103
	v_and_b32_e32 v103, 0xffff0000, v103
	v_and_b32_e32 v105, 0xffff0000, v105
	v_lshlrev_b32_e32 v112, 16, v106
	v_and_b32_e32 v106, 0xffff0000, v106
	v_lshlrev_b32_e32 v113, 16, v107
	v_and_b32_e32 v107, 0xffff0000, v107
	v_fmac_f32_e32 v110, v92, v96
	v_fmac_f32_e32 v104, v93, v97
	v_fmac_f32_e32 v111, v94, v98
	v_fmac_f32_e32 v105, v95, v99
	v_fmac_f32_e32 v112, v88, v100
	v_fmac_f32_e32 v106, v89, v101
	v_fmac_f32_e32 v113, v90, v102
	v_fmac_f32_e32 v107, v91, v103
	v_cvt_pk_bf16_f32 v88, v110, v104
	v_cvt_pk_bf16_f32 v89, v111, v105
	v_cvt_pk_bf16_f32 v90, v112, v106
	v_cvt_pk_bf16_f32 v91, v113, v107
	global_load_dwordx4 v[92:95], v[118:119], off offset:256
	global_load_dwordx4 v[96:99], v[108:109], off offset:256
	v_or_b32_e32 v100, 48, v146
	global_store_dwordx4 v[108:109], v[88:91], off
	v_mad_i64_i32 v[102:103], s[18:19], v100, s41, v[148:149]
	v_lshl_add_u64 v[102:103], v[102:103], 0, v[144:145]
	s_waitcnt vmcnt(0)
	v_lshlrev_b32_e32 v88, 16, v92
	v_lshlrev_b32_e32 v101, 16, v96
	v_and_b32_e32 v89, 0xffff0000, v92
	v_lshlrev_b32_e32 v92, 16, v94
	v_and_b32_e32 v96, 0xffff0000, v96
	v_lshlrev_b32_e32 v105, 16, v98
	v_fmac_f32_e32 v101, v84, v88
	v_fmac_f32_e32 v96, v85, v89
	v_fmac_f32_e32 v105, v80, v92
	v_cvt_pk_bf16_f32 v80, v101, v96
	v_ashrrev_i32_e32 v101, 31, v100
	v_lshlrev_b64 v[88:89], 11, v[100:101]
	v_lshlrev_b32_e32 v90, 16, v93
	v_and_b32_e32 v91, 0xffff0000, v93
	v_and_b32_e32 v93, 0xffff0000, v94
	v_and_b32_e32 v98, 0xffff0000, v98
	v_lshl_add_u64 v[88:89], s[0:1], 0, v[88:89]
	v_lshlrev_b32_e32 v94, 16, v95
	v_and_b32_e32 v95, 0xffff0000, v95
	v_lshlrev_b32_e32 v104, 16, v97
	v_and_b32_e32 v97, 0xffff0000, v97
	v_lshlrev_b32_e32 v106, 16, v99
	v_and_b32_e32 v99, 0xffff0000, v99
	v_fmac_f32_e32 v98, v81, v93
	v_lshl_add_u64 v[92:93], v[88:89], 0, v[144:145]
	v_fmac_f32_e32 v104, v86, v90
	v_fmac_f32_e32 v97, v87, v91
	v_fmac_f32_e32 v106, v82, v94
	v_fmac_f32_e32 v99, v83, v95
	v_cvt_pk_bf16_f32 v81, v104, v97
	v_cvt_pk_bf16_f32 v82, v105, v98
	v_cvt_pk_bf16_f32 v83, v106, v99
	global_load_dwordx4 v[84:87], v[102:103], off
	global_load_dwordx4 v[88:91], v[92:93], off
	s_waitcnt vmcnt(0)
; __device__ __forceinline__ unsigned cvt_pk_bf16(float lo, float hi) { unsigned r; asm volatile("v_cvt_pk_bf16_f32 %0, %1, %2" : "=v"(r) : "v"(lo), "v"(hi)); return r; }
; __device__ __forceinline__ float bf_lo(unsigned u) { return __uint_as_float(u << 16); }
; __device__ __forceinline__ float bf_hi(unsigned u) { return __uint_as_float(u & 0xffff0000u); }
;     __device__ __forceinline__ void operator()(const f32x4 (&acc)[2][2][4][2], const Unit& u, int wr, int wc, int fr, int fq) const {
;     ...
;             for (int m = 0; m < 4; ++m) { const size_t r = (size_t)(row0 + ai * HALF + m * 16); bf16_t* rowp = O + r * ldc + col0; const bf16_t* gp = G + r * ldg + col0;
; #pragma unroll
;                 for (int bj = 0; bj < 2; ++bj) { const u32x4 gw = *(const u32x4*)(gp + bj * HALF);
;                     f32x4 v0 = acc[ai][bj][m][0], v1 = acc[ai][bj][m][1];
;                     v0[0] *= bf_lo(gw.x); v0[1] *= bf_hi(gw.x); v0[2] *= bf_lo(gw.y); v0[3] *= bf_hi(gw.y);
;                     v1[0] *= bf_lo(gw.z); v1[1] *= bf_hi(gw.z); v1[2] *= bf_lo(gw.w); v1[3] *= bf_hi(gw.w);
;                     if (ACCUM) { const u32x4 pw = *(const u32x4*)(rowp + bj * HALF);
;                         v0[0] += bf_lo(pw.x); v0[1] += bf_hi(pw.x); v0[2] += bf_lo(pw.y); v0[3] += bf_hi(pw.y);
;                         v1[0] += bf_lo(pw.z); v1[1] += bf_hi(pw.z); v1[2] += bf_lo(pw.w); v1[3] += bf_hi(pw.w); }
;                     u32x4 w; w.x = cvt_pk_bf16(v0[0], v0[1]); w.y = cvt_pk_bf16(v0[2], v0[3]); w.z = cvt_pk_bf16(v1[0], v1[1]); w.w = cvt_pk_bf16(v1[2], v1[3]);
;                     *(u32x4*)(rowp + bj * HALF) = w; } }
	v_lshlrev_b32_e32 v94, 16, v88
	global_store_dwordx4 v[108:109], v[80:83], off offset:256
	v_and_b32_e32 v88, 0xffff0000, v88
	v_lshlrev_b32_e32 v95, 16, v89
	v_lshlrev_b32_e32 v80, 16, v84
	v_and_b32_e32 v81, 0xffff0000, v84
	v_lshlrev_b32_e32 v82, 16, v85
	v_and_b32_e32 v83, 0xffff0000, v85
	v_lshlrev_b32_e32 v84, 16, v86
	v_and_b32_e32 v85, 0xffff0000, v86
	v_lshlrev_b32_e32 v86, 16, v87
	v_and_b32_e32 v87, 0xffff0000, v87
	v_and_b32_e32 v89, 0xffff0000, v89
	v_lshlrev_b32_e32 v96, 16, v90
	v_and_b32_e32 v90, 0xffff0000, v90
	v_lshlrev_b32_e32 v97, 16, v91
	v_and_b32_e32 v91, 0xffff0000, v91
	v_fmac_f32_e32 v94, v76, v80
	v_fmac_f32_e32 v88, v77, v81
	v_fmac_f32_e32 v95, v78, v82
	v_fmac_f32_e32 v89, v79, v83
	v_fmac_f32_e32 v96, v72, v84
	v_fmac_f32_e32 v90, v73, v85
	v_fmac_f32_e32 v97, v74, v86
	v_fmac_f32_e32 v91, v75, v87
	v_cvt_pk_bf16_f32 v72, v94, v88
	v_cvt_pk_bf16_f32 v73, v95, v89
	v_cvt_pk_bf16_f32 v74, v96, v90
	v_cvt_pk_bf16_f32 v75, v97, v91
	global_load_dwordx4 v[76:79], v[102:103], off offset:256
	global_load_dwordx4 v[80:83], v[92:93], off offset:256
	v_add_u32_e32 v84, 0x80, v146
	global_store_dwordx4 v[92:93], v[72:75], off
	v_mad_i64_i32 v[86:87], s[18:19], v84, s41, v[148:149]
	v_lshl_add_u64 v[86:87], v[86:87], 0, v[144:145]
	s_waitcnt vmcnt(0)
	v_lshlrev_b32_e32 v72, 16, v76
	v_lshlrev_b32_e32 v85, 16, v80
	v_and_b32_e32 v73, 0xffff0000, v76
	v_lshlrev_b32_e32 v76, 16, v78
	v_and_b32_e32 v80, 0xffff0000, v80
	v_lshlrev_b32_e32 v89, 16, v82
	v_fmac_f32_e32 v85, v68, v72
	v_fmac_f32_e32 v80, v69, v73
	v_fmac_f32_e32 v89, v64, v76
	v_cvt_pk_bf16_f32 v64, v85, v80
	v_ashrrev_i32_e32 v85, 31, v84
	v_lshlrev_b64 v[72:73], 11, v[84:85]
	v_lshlrev_b32_e32 v74, 16, v77
	v_and_b32_e32 v75, 0xffff0000, v77
	v_and_b32_e32 v77, 0xffff0000, v78
	v_and_b32_e32 v82, 0xffff0000, v82
	v_lshl_add_u64 v[72:73], s[0:1], 0, v[72:73]
	v_lshlrev_b32_e32 v78, 16, v79
	v_and_b32_e32 v79, 0xffff0000, v79
	v_lshlrev_b32_e32 v88, 16, v81
	v_and_b32_e32 v81, 0xffff0000, v81
	v_lshlrev_b32_e32 v90, 16, v83
	v_and_b32_e32 v83, 0xffff0000, v83
	v_fmac_f32_e32 v82, v65, v77
	v_lshl_add_u64 v[76:77], v[72:73], 0, v[144:145]
	v_fmac_f32_e32 v88, v70, v74
	v_fmac_f32_e32 v81, v71, v75
	v_fmac_f32_e32 v90, v66, v78
	v_fmac_f32_e32 v83, v67, v79
	v_cvt_pk_bf16_f32 v65, v88, v81
	v_cvt_pk_bf16_f32 v66, v89, v82
	v_cvt_pk_bf16_f32 v67, v90, v83
	global_load_dwordx4 v[68:71], v[86:87], off
	global_load_dwordx4 v[72:75], v[76:77], off
	s_waitcnt vmcnt(0)
	v_lshlrev_b32_e32 v78, 16, v72
	global_store_dwordx4 v[92:93], v[64:67], off offset:256
	v_and_b32_e32 v72, 0xffff0000, v72
	v_lshlrev_b32_e32 v79, 16, v73
	v_lshlrev_b32_e32 v64, 16, v68
	v_and_b32_e32 v65, 0xffff0000, v68
	v_lshlrev_b32_e32 v66, 16, v69
	v_and_b32_e32 v67, 0xffff0000, v69
	v_lshlrev_b32_e32 v68, 16, v70
	v_and_b32_e32 v69, 0xffff0000, v70
	v_lshlrev_b32_e32 v70, 16, v71
	v_and_b32_e32 v71, 0xffff0000, v71
	v_and_b32_e32 v73, 0xffff0000, v73
	v_lshlrev_b32_e32 v80, 16, v74
	v_and_b32_e32 v74, 0xffff0000, v74
	v_lshlrev_b32_e32 v81, 16, v75
	v_and_b32_e32 v75, 0xffff0000, v75
	v_fmac_f32_e32 v78, v60, v64
	v_fmac_f32_e32 v72, v61, v65
	v_fmac_f32_e32 v79, v62, v66
	v_fmac_f32_e32 v73, v63, v67
	v_fmac_f32_e32 v80, v56, v68
	v_fmac_f32_e32 v74, v57, v69
	v_fmac_f32_e32 v81, v58, v70
	v_fmac_f32_e32 v75, v59, v71
	v_cvt_pk_bf16_f32 v56, v78, v72
	v_cvt_pk_bf16_f32 v57, v79, v73
	v_cvt_pk_bf16_f32 v58, v80, v74
	v_cvt_pk_bf16_f32 v59, v81, v75
	global_load_dwordx4 v[60:63], v[86:87], off offset:256
	global_load_dwordx4 v[64:67], v[76:77], off offset:256
	v_add_u32_e32 v68, 0x90, v146
	global_store_dwordx4 v[76:77], v[56:59], off
	v_mad_i64_i32 v[70:71], s[18:19], v68, s41, v[148:149]
	v_lshl_add_u64 v[70:71], v[70:71], 0, v[144:145]
	s_waitcnt vmcnt(0)
	v_lshlrev_b32_e32 v56, 16, v60
	v_lshlrev_b32_e32 v69, 16, v64
	v_and_b32_e32 v57, 0xffff0000, v60
	v_lshlrev_b32_e32 v60, 16, v62
	v_and_b32_e32 v64, 0xffff0000, v64
	v_lshlrev_b32_e32 v73, 16, v66
	v_fmac_f32_e32 v69, v52, v56
	v_fmac_f32_e32 v64, v53, v57
	v_fmac_f32_e32 v73, v48, v60
	v_cvt_pk_bf16_f32 v48, v69, v64
	v_ashrrev_i32_e32 v69, 31, v68
	v_lshlrev_b64 v[56:57], 11, v[68:69]
	v_lshlrev_b32_e32 v58, 16, v61
	v_and_b32_e32 v59, 0xffff0000, v61
	v_and_b32_e32 v61, 0xffff0000, v62
	v_and_b32_e32 v66, 0xffff0000, v66
	v_lshl_add_u64 v[56:57], s[0:1], 0, v[56:57]
	v_lshlrev_b32_e32 v62, 16, v63
	v_and_b32_e32 v63, 0xffff0000, v63
	v_lshlrev_b32_e32 v72, 16, v65
	v_and_b32_e32 v65, 0xffff0000, v65
	v_lshlrev_b32_e32 v74, 16, v67
	v_and_b32_e32 v67, 0xffff0000, v67
	v_fmac_f32_e32 v66, v49, v61
	v_lshl_add_u64 v[60:61], v[56:57], 0, v[144:145]
	v_fmac_f32_e32 v72, v54, v58
	v_fmac_f32_e32 v65, v55, v59
	v_fmac_f32_e32 v74, v50, v62
	v_fmac_f32_e32 v67, v51, v63
	v_cvt_pk_bf16_f32 v49, v72, v65
	v_cvt_pk_bf16_f32 v50, v73, v66
	v_cvt_pk_bf16_f32 v51, v74, v67
	global_load_dwordx4 v[52:55], v[70:71], off
	global_load_dwordx4 v[56:59], v[60:61], off
	s_waitcnt vmcnt(0)
	v_lshlrev_b32_e32 v62, 16, v56
	global_store_dwordx4 v[76:77], v[48:51], off offset:256
	v_and_b32_e32 v56, 0xffff0000, v56
	v_lshlrev_b32_e32 v63, 16, v57
	v_lshlrev_b32_e32 v48, 16, v52
	v_and_b32_e32 v49, 0xffff0000, v52
	v_lshlrev_b32_e32 v50, 16, v53
	v_and_b32_e32 v51, 0xffff0000, v53
	v_lshlrev_b32_e32 v52, 16, v54
	v_and_b32_e32 v53, 0xffff0000, v54
	v_lshlrev_b32_e32 v54, 16, v55
	v_and_b32_e32 v55, 0xffff0000, v55
	v_and_b32_e32 v57, 0xffff0000, v57
	v_lshlrev_b32_e32 v64, 16, v58
	v_and_b32_e32 v58, 0xffff0000, v58
	v_lshlrev_b32_e32 v65, 16, v59
	v_and_b32_e32 v59, 0xffff0000, v59
	v_fmac_f32_e32 v62, v44, v48
	v_fmac_f32_e32 v56, v45, v49
	v_fmac_f32_e32 v63, v46, v50
	v_fmac_f32_e32 v57, v47, v51
	v_fmac_f32_e32 v64, v40, v52
	v_fmac_f32_e32 v58, v41, v53
	v_fmac_f32_e32 v65, v42, v54
	v_fmac_f32_e32 v59, v43, v55
	v_cvt_pk_bf16_f32 v40, v62, v56
	v_cvt_pk_bf16_f32 v41, v63, v57
	v_cvt_pk_bf16_f32 v42, v64, v58
	v_cvt_pk_bf16_f32 v43, v65, v59
	global_load_dwordx4 v[44:47], v[70:71], off offset:256
	global_load_dwordx4 v[48:51], v[60:61], off offset:256
	v_add_u32_e32 v52, 0xa0, v146
	global_store_dwordx4 v[60:61], v[40:43], off
	v_mad_i64_i32 v[54:55], s[18:19], v52, s41, v[148:149]
	v_lshl_add_u64 v[54:55], v[54:55], 0, v[144:145]
	s_waitcnt vmcnt(0)
; __device__ __forceinline__ unsigned cvt_pk_bf16(float lo, float hi) { unsigned r; asm volatile("v_cvt_pk_bf16_f32 %0, %1, %2" : "=v"(r) : "v"(lo), "v"(hi)); return r; }
; __device__ __forceinline__ float bf_lo(unsigned u) { return __uint_as_float(u << 16); }
; __device__ __forceinline__ float bf_hi(unsigned u) { return __uint_as_float(u & 0xffff0000u); }
; #define PG8_WAIT_V(n) asm volatile("s_waitcnt vmcnt(" #n ")" ::: "memory")
;     __device__ __forceinline__ void operator()(const f32x4 (&acc)[2][2][4][2], const Unit& u, int wr, int wc, int fr, int fq) const {
;     ...
;             for (int m = 0; m < 4; ++m) { const size_t r = (size_t)(row0 + ai * HALF + m * 16); bf16_t* rowp = O + r * ldc + col0; const bf16_t* gp = G + r * ldg + col0;
; #pragma unroll
;                 for (int bj = 0; bj < 2; ++bj) { const u32x4 gw = *(const u32x4*)(gp + bj * HALF);
;                     f32x4 v0 = acc[ai][bj][m][0], v1 = acc[ai][bj][m][1];
;                     v0[0] *= bf_lo(gw.x); v0[1] *= bf_hi(gw.x); v0[2] *= bf_lo(gw.y); v0[3] *= bf_hi(gw.y);
;                     v1[0] *= bf_lo(gw.z); v1[1] *= bf_hi(gw.z); v1[2] *= bf_lo(gw.w); v1[3] *= bf_hi(gw.w);
;                     if (ACCUM) { const u32x4 pw = *(const u32x4*)(rowp + bj * HALF);
;                         v0[0] += bf_lo(pw.x); v0[1] += bf_hi(pw.x); v0[2] += bf_lo(pw.y); v0[3] += bf_hi(pw.y);
;                         v1[0] += bf_lo(pw.z); v1[1] += bf_hi(pw.z); v1[2] += bf_lo(pw.w); v1[3] += bf_hi(pw.w); }
;                     u32x4 w; w.x = cvt_pk_bf16(v0[0], v0[1]); w.y = cvt_pk_bf16(v0[2], v0[3]); w.z = cvt_pk_bf16(v1[0], v1[1]); w.w = cvt_pk_bf16(v1[2], v1[3]);
;                     *(u32x4*)(rowp + bj * HALF) = w; } }
; template <class Epi, class Sched>
; __device__ __forceinline__ void gemm_phase(PG8_LAS unsigned char* lds, const Gemm g, const Sched& S, const Epi& E) {
;     ...
;         if constexpr (!Epi::AFTER_DRAIN) { E(acc, cur, wr, wc, fr, fq); S.done(cur); }
;         if (!has_next) break;
; #pragma unroll
;         for (int a = 0; a < 2; ++a)
; #pragma unroll
;             for (int b = 0; b < 2; ++b)
; #pragma unroll
;                 for (int m = 0; m < 4; ++m)
; #pragma unroll
;                     for (int n = 0; n < 2; ++n) acc[a][b][m][n] = (f32x4){0.f, 0.f, 0.f, 0.f};
;         cur = nxt; cA = nA; cB = nB; ++ui;
;     }
;     PG8_WAIT_V(0);
;     if (wr == 0) PG8_BAR;
	v_lshlrev_b32_e32 v40, 16, v44
	v_lshlrev_b32_e32 v53, 16, v48
	v_and_b32_e32 v41, 0xffff0000, v44
	v_lshlrev_b32_e32 v44, 16, v46
	v_and_b32_e32 v48, 0xffff0000, v48
	v_lshlrev_b32_e32 v57, 16, v50
	v_fmac_f32_e32 v53, v36, v40
	v_fmac_f32_e32 v48, v37, v41
	v_fmac_f32_e32 v57, v32, v44
	v_cvt_pk_bf16_f32 v32, v53, v48
	v_ashrrev_i32_e32 v53, 31, v52
	v_lshlrev_b64 v[40:41], 11, v[52:53]
	v_lshlrev_b32_e32 v42, 16, v45
	v_and_b32_e32 v43, 0xffff0000, v45
	v_and_b32_e32 v45, 0xffff0000, v46
	v_and_b32_e32 v50, 0xffff0000, v50
	v_lshl_add_u64 v[40:41], s[0:1], 0, v[40:41]
	v_lshlrev_b32_e32 v46, 16, v47
	v_and_b32_e32 v47, 0xffff0000, v47
	v_lshlrev_b32_e32 v56, 16, v49
	v_and_b32_e32 v49, 0xffff0000, v49
	v_lshlrev_b32_e32 v58, 16, v51
	v_and_b32_e32 v51, 0xffff0000, v51
	v_fmac_f32_e32 v50, v33, v45
	v_lshl_add_u64 v[44:45], v[40:41], 0, v[144:145]
	v_fmac_f32_e32 v56, v38, v42
	v_fmac_f32_e32 v49, v39, v43
	v_fmac_f32_e32 v58, v34, v46
	v_fmac_f32_e32 v51, v35, v47
	v_cvt_pk_bf16_f32 v33, v56, v49
	v_cvt_pk_bf16_f32 v34, v57, v50
	v_cvt_pk_bf16_f32 v35, v58, v51
	global_load_dwordx4 v[36:39], v[54:55], off
	global_load_dwordx4 v[40:43], v[44:45], off
	s_waitcnt vmcnt(0)
	v_lshlrev_b32_e32 v46, 16, v40
	global_store_dwordx4 v[60:61], v[32:35], off offset:256
	v_and_b32_e32 v40, 0xffff0000, v40
	v_lshlrev_b32_e32 v47, 16, v41
	v_lshlrev_b32_e32 v32, 16, v36
	v_and_b32_e32 v33, 0xffff0000, v36
	v_lshlrev_b32_e32 v34, 16, v37
	v_and_b32_e32 v35, 0xffff0000, v37
	v_lshlrev_b32_e32 v36, 16, v38
	v_and_b32_e32 v37, 0xffff0000, v38
	v_lshlrev_b32_e32 v38, 16, v39
	v_and_b32_e32 v39, 0xffff0000, v39
	v_and_b32_e32 v41, 0xffff0000, v41
	v_lshlrev_b32_e32 v48, 16, v42
	v_and_b32_e32 v42, 0xffff0000, v42
	v_lshlrev_b32_e32 v49, 16, v43
	v_and_b32_e32 v43, 0xffff0000, v43
	v_fmac_f32_e32 v46, v28, v32
	v_fmac_f32_e32 v40, v29, v33
	v_fmac_f32_e32 v47, v30, v34
	v_fmac_f32_e32 v41, v31, v35
	v_fmac_f32_e32 v48, v24, v36
	v_fmac_f32_e32 v42, v25, v37
	v_fmac_f32_e32 v49, v26, v38
	v_fmac_f32_e32 v43, v27, v39
	v_cvt_pk_bf16_f32 v24, v46, v40
	v_cvt_pk_bf16_f32 v25, v47, v41
	v_cvt_pk_bf16_f32 v26, v48, v42
	v_cvt_pk_bf16_f32 v27, v49, v43
	global_load_dwordx4 v[28:31], v[54:55], off offset:256
	global_load_dwordx4 v[32:35], v[44:45], off offset:256
	v_add_u32_e32 v36, 0xb0, v146
	global_store_dwordx4 v[44:45], v[24:27], off
	v_mad_i64_i32 v[38:39], s[18:19], v36, s41, v[148:149]
	v_lshl_add_u64 v[38:39], v[38:39], 0, v[144:145]
	s_mov_b64 s[18:19], s[12:13]
	s_waitcnt vmcnt(0)
	v_lshlrev_b32_e32 v24, 16, v28
	v_lshlrev_b32_e32 v37, 16, v32
	v_and_b32_e32 v25, 0xffff0000, v28
	v_lshlrev_b32_e32 v28, 16, v30
	v_and_b32_e32 v32, 0xffff0000, v32
	v_lshlrev_b32_e32 v41, 16, v34
	v_fmac_f32_e32 v37, v20, v24
	v_fmac_f32_e32 v32, v21, v25
	v_fmac_f32_e32 v41, v16, v28
	v_cvt_pk_bf16_f32 v16, v37, v32
	v_ashrrev_i32_e32 v37, 31, v36
	v_lshlrev_b64 v[24:25], 11, v[36:37]
	v_lshlrev_b32_e32 v26, 16, v29
	v_and_b32_e32 v27, 0xffff0000, v29
	v_and_b32_e32 v29, 0xffff0000, v30
	v_and_b32_e32 v34, 0xffff0000, v34
	v_lshl_add_u64 v[24:25], s[0:1], 0, v[24:25]
	v_lshlrev_b32_e32 v30, 16, v31
	v_and_b32_e32 v31, 0xffff0000, v31
	v_lshlrev_b32_e32 v40, 16, v33
	v_and_b32_e32 v33, 0xffff0000, v33
	v_lshlrev_b32_e32 v42, 16, v35
	v_and_b32_e32 v35, 0xffff0000, v35
	v_fmac_f32_e32 v34, v17, v29
	v_lshl_add_u64 v[28:29], v[24:25], 0, v[144:145]
	v_fmac_f32_e32 v40, v22, v26
	v_fmac_f32_e32 v33, v23, v27
	v_fmac_f32_e32 v42, v18, v30
	v_fmac_f32_e32 v35, v19, v31
	v_cvt_pk_bf16_f32 v17, v40, v33
	v_cvt_pk_bf16_f32 v18, v41, v34
	v_cvt_pk_bf16_f32 v19, v42, v35
	global_load_dwordx4 v[20:23], v[38:39], off
	global_load_dwordx4 v[24:27], v[28:29], off
	s_waitcnt vmcnt(0)
	v_lshlrev_b32_e32 v30, 16, v24
	global_store_dwordx4 v[44:45], v[16:19], off offset:256
	v_and_b32_e32 v24, 0xffff0000, v24
	v_lshlrev_b32_e32 v31, 16, v25
	v_lshlrev_b32_e32 v16, 16, v20
	v_and_b32_e32 v17, 0xffff0000, v20
	v_lshlrev_b32_e32 v18, 16, v21
	v_and_b32_e32 v19, 0xffff0000, v21
	v_lshlrev_b32_e32 v20, 16, v22
	v_and_b32_e32 v21, 0xffff0000, v22
	v_lshlrev_b32_e32 v22, 16, v23
	v_and_b32_e32 v23, 0xffff0000, v23
	v_and_b32_e32 v25, 0xffff0000, v25
	v_lshlrev_b32_e32 v32, 16, v26
	v_and_b32_e32 v26, 0xffff0000, v26
	v_lshlrev_b32_e32 v33, 16, v27
	v_and_b32_e32 v27, 0xffff0000, v27
	v_fmac_f32_e32 v30, v12, v16
	v_fmac_f32_e32 v24, v13, v17
	v_fmac_f32_e32 v31, v14, v18
	v_fmac_f32_e32 v25, v15, v19
	v_fmac_f32_e32 v32, v8, v20
	v_fmac_f32_e32 v26, v9, v21
	v_fmac_f32_e32 v33, v10, v22
	v_fmac_f32_e32 v27, v11, v23
	v_cvt_pk_bf16_f32 v8, v30, v24
	v_cvt_pk_bf16_f32 v9, v31, v25
	v_cvt_pk_bf16_f32 v10, v32, v26
	v_cvt_pk_bf16_f32 v11, v33, v27
	global_load_dwordx4 v[12:15], v[38:39], off offset:256
	global_load_dwordx4 v[16:19], v[28:29], off offset:256
	s_waitcnt vmcnt(0)
	v_lshlrev_b32_e32 v20, 16, v16
	global_store_dwordx4 v[28:29], v[8:11], off
	v_and_b32_e32 v16, 0xffff0000, v16
	v_lshlrev_b32_e32 v21, 16, v17
	v_lshlrev_b32_e32 v8, 16, v12
	v_and_b32_e32 v9, 0xffff0000, v12
	v_lshlrev_b32_e32 v10, 16, v13
	v_and_b32_e32 v11, 0xffff0000, v13
	v_lshlrev_b32_e32 v12, 16, v14
	v_and_b32_e32 v13, 0xffff0000, v14
	v_lshlrev_b32_e32 v14, 16, v15
	v_and_b32_e32 v15, 0xffff0000, v15
	v_and_b32_e32 v17, 0xffff0000, v17
	v_lshlrev_b32_e32 v22, 16, v18
	v_and_b32_e32 v18, 0xffff0000, v18
	v_lshlrev_b32_e32 v23, 16, v19
	v_and_b32_e32 v19, 0xffff0000, v19
	v_fmac_f32_e32 v20, v4, v8
	v_fmac_f32_e32 v16, v5, v9
	v_fmac_f32_e32 v21, v6, v10
	v_fmac_f32_e32 v17, v7, v11
	v_fmac_f32_e32 v22, v0, v12
	v_fmac_f32_e32 v18, v1, v13
	v_fmac_f32_e32 v23, v2, v14
	v_fmac_f32_e32 v19, v3, v15
	v_cvt_pk_bf16_f32 v0, v20, v16
	v_cvt_pk_bf16_f32 v1, v21, v17
	v_cvt_pk_bf16_f32 v2, v22, v18
	v_cvt_pk_bf16_f32 v3, v23, v19
	global_store_dwordx4 v[28:29], v[0:3], off offset:256
	s_cbranch_vccz .LBB0_1004
	s_waitcnt vmcnt(0)
	s_cmpk_gt_u32 s25, 0xff
	s_cbranch_scc1 .LBB0_1015
	s_barrier

; #define PG8_STAGE(bufoff, gbase, voff) do { _Pragma("unroll") for (int _i = 0; _i < 2; ++_i) \
;         __builtin_amdgcn_global_load_lds((const unsigned*)((const char*)(gbase) + (voff)[_i]), (PG8_LAS unsigned*)(lds + (bufoff) + ldsw + _i * 8192), 16, 0, 0); } while (0)
; #define PG8_LDA(dst, b, h) do { _Pragma("unroll") for (int m = 0; m < 4; ++m) _Pragma("unroll") for (int k = 0; k < 2; ++k) dst[m][k] = *(const PG8_LAS bf16x8*)(lds + PG8_SA(b, h) + aoff + m * 2048 + k * 1024); } while (0)
; #define PG8_LDB(dst, b, h) do { _Pragma("unroll") for (int n = 0; n < 2; ++n) _Pragma("unroll") for (int k = 0; k < 2; ++k) dst[n][k] = *(const PG8_LAS bf16x8*)(lds + PG8_SB(b, h) + boff + n * 2048 + k * 1024); } while (0)
; #define PG8_MMA(ai, bj, At, Bt) do { __builtin_amdgcn_s_setprio(1); _Pragma("unroll") for (int m = 0; m < 4; ++m) _Pragma("unroll") for (int n = 0; n < 2; ++n) _Pragma("unroll") for (int k = 0; k < 2; ++k) \
;         acc[ai][bj][m][n] = __builtin_amdgcn_mfma_f32_16x16x32_bf16(Bt[n][k], At[m][k], acc[ai][bj][m][n], 0, 0, 0); __builtin_amdgcn_s_setprio(0); } while (0)
; #define PG8_WAIT_L(n) asm volatile("s_waitcnt lgkmcnt(" #n ")" ::: "memory")
; #define PG8_BAR __builtin_amdgcn_s_barrier()
; #define PG8_SCHED __builtin_amdgcn_sched_barrier(0)
; template <class Epi, class Sched>
; __device__ __forceinline__ void gemm_phase(PG8_LAS unsigned char* lds, const Gemm g, const Sched& S, const Epi& E) {
;     ...
;             PG8_LDB(B0, 0, 0); PG8_SCHED; PG8_LDA(At, 0, 0); PG8_STAGE(PG8_SA(1, 1), a1 + hstep, voffA);
;             PG8_WAIT_L(8); PG8_BAR; PG8_WAIT_L(0); PG8_MMA(0, 0, At, B0); PG8_BAR; PG8_SCHED;
;             PG8_LDB(B1, 0, 1); PG8_STAGE(PG8_SB(0, 0), b2, voffB);
;             PG8_BAR; PG8_WAIT_L(0); PG8_MMA(0, 1, At, B1); PG8_BAR;
;             PG8_LDA(At, 0, 1); PG8_STAGE(PG8_SA(0, 0), a2, voffA);
;             PG8_BAR; PG8_WAIT_L(0); PG8_MMA(1, 0, At, B0); PG8_BAR; PG8_SCHED;
.LBB0_1083:
	ds_read_b128 v[152:155], v149
	ds_read_b128 v[156:159], v149 offset:1024
	ds_read_b128 v[160:163], v149 offset:2048
	ds_read_b128 v[164:167], v149 offset:3072
	s_add_u32 s26, s24, 0xfffc0080
	s_addc_u32 s27, s25, -1
	s_cmp_eq_u32 s56, 12
	s_cselect_b32 s29, s17, s27
	s_cselect_b32 s28, s52, s26
	s_cselect_b32 s27, s15, s55
	s_cselect_b32 s26, s53, s54
	v_lshl_add_u64 v[144:145], s[24:25], 0, v[136:137]
	s_add_i32 m0, s23, 0xc000
	ds_read_b128 v[168:171], v150
	ds_read_b128 v[172:175], v150 offset:1024
	ds_read_b128 v[182:185], v150 offset:2048
	ds_read_b128 v[190:193], v150 offset:3072
	ds_read_b128 v[194:197], v150 offset:4096
	ds_read_b128 v[198:201], v150 offset:5120
	ds_read_b128 v[202:205], v150 offset:6144
	ds_read_b128 v[206:209], v150 offset:7168
	global_load_lds_dwordx4 v[144:145], off
	v_lshl_add_u64 v[144:145], s[24:25], 0, v[138:139]
	s_add_i32 m0, s23, 0xe000
	s_nop 0
	global_load_lds_dwordx4 v[144:145], off
	s_waitcnt lgkmcnt(8)
	s_barrier
	s_waitcnt lgkmcnt(0)
	s_setprio 0
	s_waitcnt lgkmcnt(0)
	v_mfma_f32_16x16x32_bf16 v[124:127], v[152:155], v[168:171], v[124:127]
	v_mfma_f32_16x16x32_bf16 v[120:123], v[160:163], v[168:171], v[120:123]
	v_mfma_f32_16x16x32_bf16 v[108:111], v[152:155], v[182:185], v[108:111]
	v_mfma_f32_16x16x32_bf16 v[104:107], v[160:163], v[182:185], v[104:107]
	v_mfma_f32_16x16x32_bf16 v[92:95], v[152:155], v[194:197], v[92:95]
	v_mfma_f32_16x16x32_bf16 v[88:91], v[160:163], v[194:197], v[88:91]
	v_mfma_f32_16x16x32_bf16 v[76:79], v[152:155], v[202:205], v[76:79]
	v_mfma_f32_16x16x32_bf16 v[72:75], v[160:163], v[202:205], v[72:75]
	v_mfma_f32_16x16x32_bf16 v[124:127], v[156:159], v[172:175], v[124:127]
	v_mfma_f32_16x16x32_bf16 v[120:123], v[164:167], v[172:175], v[120:123]
	v_mfma_f32_16x16x32_bf16 v[108:111], v[156:159], v[190:193], v[108:111]
	v_mfma_f32_16x16x32_bf16 v[104:107], v[164:167], v[190:193], v[104:107]
	v_mfma_f32_16x16x32_bf16 v[92:95], v[156:159], v[198:201], v[92:95]
	v_mfma_f32_16x16x32_bf16 v[88:91], v[164:167], v[198:201], v[88:91]
	v_mfma_f32_16x16x32_bf16 v[76:79], v[156:159], v[206:209], v[76:79]
	v_mfma_f32_16x16x32_bf16 v[72:75], v[164:167], v[206:209], v[72:75]
	s_setprio 1
	s_barrier
	s_add_i32 s57, s45, s37
	v_lshl_add_u64 v[144:145], s[26:27], 0, v[130:131]
	s_mov_b32 m0, s57
	ds_read_b128 v[210:213], v151
	ds_read_b128 v[214:217], v151 offset:1024
	ds_read_b128 v[218:221], v151 offset:2048
	ds_read_b128 v[222:225], v151 offset:3072
	global_load_lds_dwordx4 v[144:145], off
	v_lshl_add_u64 v[186:187], s[26:27], 0, v[134:135]
	s_add_i32 m0, s57, 0x2000
	s_nop 0
	global_load_lds_dwordx4 v[186:187], off
	s_barrier
	s_waitcnt lgkmcnt(0)
	s_setprio 0
	s_waitcnt lgkmcnt(0)
	v_mfma_f32_16x16x32_bf16 v[116:119], v[210:213], v[168:171], v[116:119]
	v_mfma_f32_16x16x32_bf16 v[112:115], v[218:221], v[168:171], v[112:115]
	v_mfma_f32_16x16x32_bf16 v[100:103], v[210:213], v[182:185], v[100:103]
	v_mfma_f32_16x16x32_bf16 v[96:99], v[218:221], v[182:185], v[96:99]
	v_mfma_f32_16x16x32_bf16 v[84:87], v[210:213], v[194:197], v[84:87]
	v_mfma_f32_16x16x32_bf16 v[80:83], v[218:221], v[194:197], v[80:83]
	v_mfma_f32_16x16x32_bf16 v[68:71], v[210:213], v[202:205], v[68:71]
	v_mfma_f32_16x16x32_bf16 v[64:67], v[218:221], v[202:205], v[64:67]
	v_mfma_f32_16x16x32_bf16 v[116:119], v[214:217], v[172:175], v[116:119]
	v_mfma_f32_16x16x32_bf16 v[112:115], v[222:225], v[172:175], v[112:115]
	v_mfma_f32_16x16x32_bf16 v[100:103], v[214:217], v[190:193], v[100:103]
	v_mfma_f32_16x16x32_bf16 v[96:99], v[222:225], v[190:193], v[96:99]
	v_mfma_f32_16x16x32_bf16 v[84:87], v[214:217], v[198:201], v[84:87]
	v_mfma_f32_16x16x32_bf16 v[80:83], v[222:225], v[198:201], v[80:83]
	v_mfma_f32_16x16x32_bf16 v[68:71], v[214:217], v[206:209], v[68:71]
	v_mfma_f32_16x16x32_bf16 v[64:67], v[222:225], v[206:209], v[64:67]
	s_setprio 1
	s_mov_b32 m0, s23
	v_lshl_add_u64 v[226:227], s[28:29], 0, v[128:129]
	s_barrier
	ds_read_b128 v[168:171], v150 offset:16384
	ds_read_b128 v[172:175], v150 offset:17408
	ds_read_b128 v[182:185], v150 offset:18432
	ds_read_b128 v[190:193], v150 offset:19456
	ds_read_b128 v[194:197], v150 offset:20480
	ds_read_b128 v[198:201], v150 offset:21504
	ds_read_b128 v[202:205], v150 offset:22528
	ds_read_b128 v[206:209], v150 offset:23552
	global_load_lds_dwordx4 v[226:227], off
	v_lshl_add_u64 v[228:229], s[28:29], 0, v[132:133]
	s_mov_b32 m0, s38
	s_nop 0
	global_load_lds_dwordx4 v[228:229], off
	s_barrier
	s_waitcnt lgkmcnt(0)
	s_setprio 0
	s_waitcnt lgkmcnt(0)
	v_mfma_f32_16x16x32_bf16 v[60:63], v[152:155], v[168:171], v[60:63]
	v_mfma_f32_16x16x32_bf16 v[56:59], v[160:163], v[168:171], v[56:59]
	v_mfma_f32_16x16x32_bf16 v[48:51], v[152:155], v[182:185], v[48:51]
	v_mfma_f32_16x16x32_bf16 v[40:43], v[160:163], v[182:185], v[40:43]
	v_mfma_f32_16x16x32_bf16 v[32:35], v[152:155], v[194:197], v[32:35]
	v_mfma_f32_16x16x32_bf16 v[24:27], v[160:163], v[194:197], v[24:27]
	v_mfma_f32_16x16x32_bf16 v[16:19], v[152:155], v[202:205], v[16:19]
	v_mfma_f32_16x16x32_bf16 v[8:11], v[160:163], v[202:205], v[8:11]
	v_mfma_f32_16x16x32_bf16 v[60:63], v[156:159], v[172:175], v[60:63]
	v_mfma_f32_16x16x32_bf16 v[56:59], v[164:167], v[172:175], v[56:59]
	v_mfma_f32_16x16x32_bf16 v[48:51], v[156:159], v[190:193], v[48:51]
	v_mfma_f32_16x16x32_bf16 v[40:43], v[164:167], v[190:193], v[40:43]
	v_mfma_f32_16x16x32_bf16 v[32:35], v[156:159], v[198:201], v[32:35]
	v_mfma_f32_16x16x32_bf16 v[24:27], v[164:167], v[198:201], v[24:27]
	v_mfma_f32_16x16x32_bf16 v[16:19], v[156:159], v[206:209], v[16:19]
	v_mfma_f32_16x16x32_bf16 v[8:11], v[164:167], v[206:209], v[8:11]
	s_setprio 1
	s_barrier
; #define PG8_STAGE(bufoff, gbase, voff) do { _Pragma("unroll") for (int _i = 0; _i < 2; ++_i) \
;         __builtin_amdgcn_global_load_lds((const unsigned*)((const char*)(gbase) + (voff)[_i]), (PG8_LAS unsigned*)(lds + (bufoff) + ldsw + _i * 8192), 16, 0, 0); } while (0)
; #define PG8_LDA(dst, b, h) do { _Pragma("unroll") for (int m = 0; m < 4; ++m) _Pragma("unroll") for (int k = 0; k < 2; ++k) dst[m][k] = *(const PG8_LAS bf16x8*)(lds + PG8_SA(b, h) + aoff + m * 2048 + k * 1024); } while (0)
; #define PG8_LDB(dst, b, h) do { _Pragma("unroll") for (int n = 0; n < 2; ++n) _Pragma("unroll") for (int k = 0; k < 2; ++k) dst[n][k] = *(const PG8_LAS bf16x8*)(lds + PG8_SB(b, h) + boff + n * 2048 + k * 1024); } while (0)
; #define PG8_MMA(ai, bj, At, Bt) do { __builtin_amdgcn_s_setprio(1); _Pragma("unroll") for (int m = 0; m < 4; ++m) _Pragma("unroll") for (int n = 0; n < 2; ++n) _Pragma("unroll") for (int k = 0; k < 2; ++k) \
;         acc[ai][bj][m][n] = __builtin_amdgcn_mfma_f32_16x16x32_bf16(Bt[n][k], At[m][k], acc[ai][bj][m][n], 0, 0, 0); __builtin_amdgcn_s_setprio(0); } while (0)
; #define PG8_WAIT_V(n) asm volatile("s_waitcnt vmcnt(" #n ")" ::: "memory")
; #define PG8_WAIT_L(n) asm volatile("s_waitcnt lgkmcnt(" #n ")" ::: "memory")
; #define PG8_BAR __builtin_amdgcn_s_barrier()
; #define PG8_SCHED __builtin_amdgcn_sched_barrier(0)
; template <class Epi, class Sched>
; __device__ __forceinline__ void gemm_phase(PG8_LAS unsigned char* lds, const Gemm g, const Sched& S, const Epi& E) {
;     ...
;             PG8_STAGE(PG8_SB(0, 1), b2 + hstep, voffB);
;             PG8_WAIT_V(6); PG8_BAR; PG8_MMA(1, 1, At, B1); PG8_BAR;
;             PG8_LDB(B0, 1, 0); PG8_SCHED; PG8_LDA(At, 1, 0); PG8_STAGE(PG8_SA(0, 1), a2 + hstep, voffA);
;             PG8_WAIT_L(8); PG8_BAR; PG8_WAIT_L(0); PG8_MMA(0, 0, At, B0); PG8_BAR; PG8_SCHED;
;             PG8_LDB(B1, 1, 1); PG8_STAGE(PG8_SB(1, 0), b3, voffB);
;             PG8_BAR; PG8_WAIT_L(0); PG8_MMA(0, 1, At, B1); PG8_BAR;
;             PG8_LDA(At, 1, 1); PG8_STAGE(PG8_SA(1, 0), a3, voffA);
	s_add_u32 s58, s26, 0x40000
	s_addc_u32 s59, s27, 0
	s_add_i32 s57, s46, s37
	v_lshl_add_u64 v[152:153], s[58:59], 0, v[130:131]
	s_mov_b32 m0, s57
	s_nop 0
	global_load_lds_dwordx4 v[152:153], off
	v_lshl_add_u64 v[152:153], s[58:59], 0, v[134:135]
	s_add_i32 m0, s57, 0x2000
	s_nop 0
	global_load_lds_dwordx4 v[152:153], off
	s_waitcnt vmcnt(6)
	s_barrier
	s_setprio 0
	v_mfma_f32_16x16x32_bf16 v[52:55], v[210:213], v[168:171], v[52:55]
	v_mfma_f32_16x16x32_bf16 v[44:47], v[218:221], v[168:171], v[44:47]
	v_mfma_f32_16x16x32_bf16 v[36:39], v[210:213], v[182:185], v[36:39]
	v_mfma_f32_16x16x32_bf16 v[28:31], v[218:221], v[182:185], v[28:31]
	v_mfma_f32_16x16x32_bf16 v[20:23], v[210:213], v[194:197], v[20:23]
	v_mfma_f32_16x16x32_bf16 v[12:15], v[218:221], v[194:197], v[12:15]
	v_mfma_f32_16x16x32_bf16 v[4:7], v[210:213], v[202:205], v[4:7]
	v_mfma_f32_16x16x32_bf16 v[0:3], v[218:221], v[202:205], v[0:3]
	v_mfma_f32_16x16x32_bf16 v[52:55], v[214:217], v[172:175], v[52:55]
	v_mfma_f32_16x16x32_bf16 v[44:47], v[222:225], v[172:175], v[44:47]
	v_mfma_f32_16x16x32_bf16 v[36:39], v[214:217], v[190:193], v[36:39]
	v_mfma_f32_16x16x32_bf16 v[28:31], v[222:225], v[190:193], v[28:31]
	v_mfma_f32_16x16x32_bf16 v[20:23], v[214:217], v[198:201], v[20:23]
	v_mfma_f32_16x16x32_bf16 v[12:15], v[222:225], v[198:201], v[12:15]
	v_mfma_f32_16x16x32_bf16 v[4:7], v[214:217], v[206:209], v[4:7]
	v_mfma_f32_16x16x32_bf16 v[0:3], v[222:225], v[206:209], v[0:3]
	s_setprio 1
	s_add_i32 s57, 0, 0x18000
	v_add_u32_e32 v164, s57, v147
	s_barrier
	ds_read_b128 v[152:155], v164
	ds_read_b128 v[156:159], v164 offset:1024
	ds_read_b128 v[160:163], v164 offset:2048
	ds_read_b128 v[164:167], v164 offset:3072
	s_add_u32 s28, s28, 0x40000
	s_addc_u32 s29, s29, 0
	s_mov_b32 m0, s39
	v_lshl_add_u64 v[210:211], s[28:29], 0, v[128:129]
	ds_read_b128 v[168:171], v150 offset:32768
	ds_read_b128 v[172:175], v150 offset:33792
	ds_read_b128 v[182:185], v150 offset:34816
	ds_read_b128 v[190:193], v150 offset:35840
	ds_read_b128 v[194:197], v150 offset:36864
	ds_read_b128 v[198:201], v150 offset:37888
	ds_read_b128 v[202:205], v150 offset:38912
	ds_read_b128 v[206:209], v150 offset:39936
	global_load_lds_dwordx4 v[210:211], off
	v_lshl_add_u64 v[210:211], s[28:29], 0, v[132:133]
	s_mov_b32 m0, s40
	s_nop 0
	global_load_lds_dwordx4 v[210:211], off
	s_waitcnt lgkmcnt(8)
	s_barrier
	s_waitcnt lgkmcnt(0)
	s_setprio 0
	s_waitcnt lgkmcnt(0)
	v_mfma_f32_16x16x32_bf16 v[124:127], v[152:155], v[168:171], v[124:127]
	v_mfma_f32_16x16x32_bf16 v[120:123], v[160:163], v[168:171], v[120:123]
	v_mfma_f32_16x16x32_bf16 v[108:111], v[152:155], v[182:185], v[108:111]
	v_mfma_f32_16x16x32_bf16 v[104:107], v[160:163], v[182:185], v[104:107]
	v_mfma_f32_16x16x32_bf16 v[92:95], v[152:155], v[194:197], v[92:95]
	v_mfma_f32_16x16x32_bf16 v[88:91], v[160:163], v[194:197], v[88:91]
	v_mfma_f32_16x16x32_bf16 v[76:79], v[152:155], v[202:205], v[76:79]
	v_mfma_f32_16x16x32_bf16 v[72:75], v[160:163], v[202:205], v[72:75]
	v_mfma_f32_16x16x32_bf16 v[124:127], v[156:159], v[172:175], v[124:127]
	v_mfma_f32_16x16x32_bf16 v[120:123], v[164:167], v[172:175], v[120:123]
	v_mfma_f32_16x16x32_bf16 v[108:111], v[156:159], v[190:193], v[108:111]
	v_mfma_f32_16x16x32_bf16 v[104:107], v[164:167], v[190:193], v[104:107]
	v_mfma_f32_16x16x32_bf16 v[92:95], v[156:159], v[198:201], v[92:95]
	v_mfma_f32_16x16x32_bf16 v[88:91], v[164:167], v[198:201], v[88:91]
	v_mfma_f32_16x16x32_bf16 v[76:79], v[156:159], v[206:209], v[76:79]
	v_mfma_f32_16x16x32_bf16 v[72:75], v[164:167], v[206:209], v[72:75]
	s_setprio 1
	s_barrier
	s_add_i32 s28, 0, 0x1c000
	s_add_i32 s29, s57, s37
	v_add_u32_e32 v179, s28, v147
	v_lshl_add_u64 v[144:145], v[144:145], 0, s[6:7]
	s_mov_b32 m0, s29
	ds_read_b128 v[210:213], v179
	ds_read_b128 v[214:217], v179 offset:1024
	ds_read_b128 v[218:221], v179 offset:2048
	ds_read_b128 v[222:225], v179 offset:3072
	global_load_lds_dwordx4 v[144:145], off
	v_lshl_add_u64 v[144:145], v[186:187], 0, s[6:7]
	s_add_i32 m0, s29, 0x2000
	s_nop 0
	global_load_lds_dwordx4 v[144:145], off
	s_barrier
	s_waitcnt lgkmcnt(0)
	s_setprio 0
	s_waitcnt lgkmcnt(0)
	v_mfma_f32_16x16x32_bf16 v[116:119], v[210:213], v[168:171], v[116:119]
	v_mfma_f32_16x16x32_bf16 v[112:115], v[218:221], v[168:171], v[112:115]
	v_mfma_f32_16x16x32_bf16 v[100:103], v[210:213], v[182:185], v[100:103]
	v_mfma_f32_16x16x32_bf16 v[96:99], v[218:221], v[182:185], v[96:99]
	v_mfma_f32_16x16x32_bf16 v[84:87], v[210:213], v[194:197], v[84:87]
	v_mfma_f32_16x16x32_bf16 v[80:83], v[218:221], v[194:197], v[80:83]
	v_mfma_f32_16x16x32_bf16 v[68:71], v[210:213], v[202:205], v[68:71]
	v_mfma_f32_16x16x32_bf16 v[64:67], v[218:221], v[202:205], v[64:67]
	v_mfma_f32_16x16x32_bf16 v[116:119], v[214:217], v[172:175], v[116:119]
	v_mfma_f32_16x16x32_bf16 v[112:115], v[222:225], v[172:175], v[112:115]
	v_mfma_f32_16x16x32_bf16 v[100:103], v[214:217], v[190:193], v[100:103]
	v_mfma_f32_16x16x32_bf16 v[96:99], v[222:225], v[190:193], v[96:99]
	v_mfma_f32_16x16x32_bf16 v[84:87], v[214:217], v[198:201], v[84:87]
	v_mfma_f32_16x16x32_bf16 v[80:83], v[222:225], v[198:201], v[80:83]
	v_mfma_f32_16x16x32_bf16 v[68:71], v[214:217], v[206:209], v[68:71]
	v_mfma_f32_16x16x32_bf16 v[64:67], v[222:225], v[206:209], v[64:67]
	s_setprio 1
	s_mov_b32 m0, s42
	v_lshl_add_u64 v[144:145], v[226:227], 0, s[6:7]
	s_barrier
	ds_read_b128 v[168:171], v150 offset:49152
	ds_read_b128 v[172:175], v150 offset:50176
	ds_read_b128 v[182:185], v150 offset:51200
	ds_read_b128 v[190:193], v150 offset:52224
	ds_read_b128 v[194:197], v150 offset:53248
	ds_read_b128 v[198:201], v150 offset:54272
	ds_read_b128 v[202:205], v150 offset:55296
	ds_read_b128 v[206:209], v150 offset:56320
	global_load_lds_dwordx4 v[144:145], off
	v_lshl_add_u64 v[144:145], v[228:229], 0, s[6:7]
	s_mov_b32 m0, s43
	s_nop 0
	global_load_lds_dwordx4 v[144:145], off
	s_barrier
; __device__ __forceinline__ unsigned cvt_pk_bf16(float lo, float hi) { unsigned r; asm volatile("v_cvt_pk_bf16_f32 %0, %1, %2" : "=v"(r) : "v"(lo), "v"(hi)); return r; }
; __device__ __forceinline__ float flogsig16(float x) { return (fminf(x, 0.f) - __logf(1.0f + __expf(-fabsf(x)))) * 0.0625f; }
; #define PG8_STAGE(bufoff, gbase, voff) do { _Pragma("unroll") for (int _i = 0; _i < 2; ++_i) \
;         __builtin_amdgcn_global_load_lds((const unsigned*)((const char*)(gbase) + (voff)[_i]), (PG8_LAS unsigned*)(lds + (bufoff) + ldsw + _i * 8192), 16, 0, 0); } while (0)
; #define PG8_LDA(dst, b, h) do { _Pragma("unroll") for (int m = 0; m < 4; ++m) _Pragma("unroll") for (int k = 0; k < 2; ++k) dst[m][k] = *(const PG8_LAS bf16x8*)(lds + PG8_SA(b, h) + aoff + m * 2048 + k * 1024); } while (0)
; #define PG8_BAR __builtin_amdgcn_s_barrier()
;     __device__ __forceinline__ void operator()(const f32x4 (&acc)[2][2][4][2], const Unit& u, int wr, int wc, int fr, int fq) const {
;     ...
;             for (int m = 0; m < 4; ++m) { bf16_t* rowp = O + (size_t)(row0 + ai * HALF + m * 16) * ldc + col0;
; #pragma unroll
;                 for (int bj = 0; bj < 2; ++bj) { f32x4 v0 = acc[ai][bj][m][0] + bv[bj][0], v1 = acc[ai][bj][m][1] + bv[bj][1];
;                     if (act == 1) {
; #pragma unroll
;                         for (int j = 0; j < 1; ++j) { v0 = v0 * sigmoid4(v0); v1 = v1 * sigmoid4(v1); } }
;                     else if (act == 2) {
; #pragma unroll
;                         for (int j = 0; j < 1; ++j) { v0 = sigmoid4(v0); v1 = sigmoid4(v1); } }
;                     else if (act == 3) {
; #pragma unroll
;                         for (int j = 0; j < 4; ++j) { v0[j] = flogsig16(v0[j]); v1[j] = flogsig16(v1[j]); } }
;                     u32x4 w; w.x = cvt_pk_bf16(v0[0], v0[1]); w.y = cvt_pk_bf16(v0[2], v0[3]); w.z = cvt_pk_bf16(v1[0], v1[1]); w.w = cvt_pk_bf16(v1[2], v1[3]);
;                     *(u32x4*)(rowp + bj * HALF) = w; } }
; template <class Epi, class Sched>
; __device__ __forceinline__ void gemm_phase(PG8_LAS unsigned char* lds, const Gemm g, const Sched& S, const Epi& E) {
;     ...
;             PG8_LDA(At, 1, 1); PG8_STAGE(PG8_SA(1, 0), a3, voffA);
;             PG8_BAR; PG8_WAIT_L(0); PG8_MMA(1, 0, At, B0); PG8_BAR; PG8_SCHED;
;             PG8_STAGE(PG8_SB(1, 1), b3 + hstep, voffB);
;             PG8_WAIT_V(6); PG8_BAR; PG8_MMA(1, 1, At, B1); PG8_BAR;
;         }
	s_waitcnt lgkmcnt(0)
	s_setprio 0
	s_waitcnt lgkmcnt(0)
	v_mfma_f32_16x16x32_bf16 v[60:63], v[152:155], v[168:171], v[60:63]
	v_mfma_f32_16x16x32_bf16 v[56:59], v[160:163], v[168:171], v[56:59]
	v_mfma_f32_16x16x32_bf16 v[48:51], v[152:155], v[182:185], v[48:51]
	v_mfma_f32_16x16x32_bf16 v[40:43], v[160:163], v[182:185], v[40:43]
	v_mfma_f32_16x16x32_bf16 v[32:35], v[152:155], v[194:197], v[32:35]
	v_mfma_f32_16x16x32_bf16 v[24:27], v[160:163], v[194:197], v[24:27]
	v_mfma_f32_16x16x32_bf16 v[16:19], v[152:155], v[202:205], v[16:19]
	v_mfma_f32_16x16x32_bf16 v[8:11], v[160:163], v[202:205], v[8:11]
	v_mfma_f32_16x16x32_bf16 v[60:63], v[156:159], v[172:175], v[60:63]
	v_mfma_f32_16x16x32_bf16 v[56:59], v[164:167], v[172:175], v[56:59]
	v_mfma_f32_16x16x32_bf16 v[48:51], v[156:159], v[190:193], v[48:51]
	v_mfma_f32_16x16x32_bf16 v[40:43], v[164:167], v[190:193], v[40:43]
	v_mfma_f32_16x16x32_bf16 v[32:35], v[156:159], v[198:201], v[32:35]
	v_mfma_f32_16x16x32_bf16 v[24:27], v[164:167], v[198:201], v[24:27]
	v_mfma_f32_16x16x32_bf16 v[16:19], v[156:159], v[206:209], v[16:19]
	v_mfma_f32_16x16x32_bf16 v[8:11], v[164:167], v[206:209], v[8:11]
	s_setprio 1
	s_barrier
	s_add_u32 s26, s26, 0x40080
	s_addc_u32 s27, s27, 0
	s_add_i32 s28, s28, s37
	v_lshl_add_u64 v[144:145], s[26:27], 0, v[130:131]
	s_mov_b32 m0, s28
	s_nop 0
	global_load_lds_dwordx4 v[144:145], off
	v_lshl_add_u64 v[144:145], s[26:27], 0, v[134:135]
	s_add_i32 m0, s28, 0x2000
	s_nop 0
	global_load_lds_dwordx4 v[144:145], off
	s_waitcnt vmcnt(6)
	s_barrier
	s_setprio 0
	v_mfma_f32_16x16x32_bf16 v[52:55], v[210:213], v[168:171], v[52:55]
	v_mfma_f32_16x16x32_bf16 v[44:47], v[218:221], v[168:171], v[44:47]
	v_mfma_f32_16x16x32_bf16 v[36:39], v[210:213], v[182:185], v[36:39]
	v_mfma_f32_16x16x32_bf16 v[28:31], v[218:221], v[182:185], v[28:31]
	v_mfma_f32_16x16x32_bf16 v[20:23], v[210:213], v[194:197], v[20:23]
	v_mfma_f32_16x16x32_bf16 v[12:15], v[218:221], v[194:197], v[12:15]
	v_mfma_f32_16x16x32_bf16 v[4:7], v[210:213], v[202:205], v[4:7]
	v_mfma_f32_16x16x32_bf16 v[0:3], v[218:221], v[202:205], v[0:3]
	v_mfma_f32_16x16x32_bf16 v[52:55], v[214:217], v[172:175], v[52:55]
	v_mfma_f32_16x16x32_bf16 v[44:47], v[222:225], v[172:175], v[44:47]
	v_mfma_f32_16x16x32_bf16 v[36:39], v[214:217], v[190:193], v[36:39]
	v_mfma_f32_16x16x32_bf16 v[28:31], v[222:225], v[190:193], v[28:31]
	v_mfma_f32_16x16x32_bf16 v[20:23], v[214:217], v[198:201], v[20:23]
	v_mfma_f32_16x16x32_bf16 v[12:15], v[222:225], v[198:201], v[12:15]
	v_mfma_f32_16x16x32_bf16 v[4:7], v[214:217], v[206:209], v[4:7]
	v_mfma_f32_16x16x32_bf16 v[0:3], v[222:225], v[206:209], v[0:3]
	s_setprio 1
	s_add_i32 s56, s56, 2
	s_add_u32 s24, s24, 0x100
	s_addc_u32 s25, s25, 0
	s_add_u32 s54, s54, 0x100
	s_addc_u32 s55, s55, 0
	s_cmp_gt_u32 s56, 13
	s_barrier
	s_cbranch_scc0 .LBB0_1083
	v_lshl_add_u32 v152, s22, 8, v146
	v_lshl_or_b32 v144, s51, 8, v148
	v_ashrrev_i32_e32 v153, 31, v152
	v_ashrrev_i32_e32 v145, 31, v144
	v_lshlrev_b64 v[154:155], 11, v[152:153]
	v_lshl_add_u64 v[154:155], s[4:5], 0, v[154:155]
	v_lshlrev_b64 v[156:157], 1, v[144:145]
	v_lshl_add_u64 v[144:145], v[154:155], 0, v[156:157]
	v_pk_add_f32 v[126:127], v[126:127], 0 op_sel_hi:[1,0]
	v_pk_add_f32 v[124:125], v[124:125], 0 op_sel_hi:[1,0]
	v_pk_add_f32 v[154:155], v[122:123], 0 op_sel_hi:[1,0]
	v_pk_add_f32 v[122:123], v[120:121], 0 op_sel_hi:[1,0]
	v_cvt_pk_bf16_f32 v120, v124, v125
	v_cvt_pk_bf16_f32 v121, v126, v127
	v_pk_add_f32 v[116:117], v[116:117], 0 op_sel_hi:[1,0]
	v_cvt_pk_bf16_f32 v122, v122, v123
	v_cvt_pk_bf16_f32 v123, v154, v155
	global_store_dwordx4 v[144:145], v[120:123], off
	v_pk_add_f32 v[118:119], v[118:119], 0 op_sel_hi:[1,0]
	v_pk_add_f32 v[110:111], v[110:111], 0 op_sel_hi:[1,0]
	v_pk_add_f32 v[120:121], v[114:115], 0 op_sel_hi:[1,0]
	v_pk_add_f32 v[114:115], v[112:113], 0 op_sel_hi:[1,0]
	v_cvt_pk_bf16_f32 v112, v116, v117
	v_cvt_pk_bf16_f32 v113, v118, v119
	v_pk_add_f32 v[108:109], v[108:109], 0 op_sel_hi:[1,0]
	v_cvt_pk_bf16_f32 v114, v114, v115
	v_cvt_pk_bf16_f32 v115, v120, v121
	global_store_dwordx4 v[144:145], v[112:115], off offset:256
	v_pk_add_f32 v[100:101], v[100:101], 0 op_sel_hi:[1,0]
	v_pk_add_f32 v[102:103], v[102:103], 0 op_sel_hi:[1,0]
	v_or_b32_e32 v112, 16, v152
	v_ashrrev_i32_e32 v113, 31, v112
	v_lshlrev_b64 v[112:113], 11, v[112:113]
	v_lshl_add_u64 v[112:113], s[4:5], 0, v[112:113]
	v_lshl_add_u64 v[112:113], v[112:113], 0, v[156:157]
	v_pk_add_f32 v[114:115], v[106:107], 0 op_sel_hi:[1,0]
	v_pk_add_f32 v[106:107], v[104:105], 0 op_sel_hi:[1,0]
	v_cvt_pk_bf16_f32 v104, v108, v109
	v_cvt_pk_bf16_f32 v105, v110, v111
	v_pk_add_f32 v[94:95], v[94:95], 0 op_sel_hi:[1,0]
	v_cvt_pk_bf16_f32 v106, v106, v107
	v_cvt_pk_bf16_f32 v107, v114, v115
	global_store_dwordx4 v[112:113], v[104:107], off
	v_pk_add_f32 v[92:93], v[92:93], 0 op_sel_hi:[1,0]
	v_pk_add_f32 v[84:85], v[84:85], 0 op_sel_hi:[1,0]
	v_pk_add_f32 v[104:105], v[98:99], 0 op_sel_hi:[1,0]
	v_pk_add_f32 v[98:99], v[96:97], 0 op_sel_hi:[1,0]
	v_cvt_pk_bf16_f32 v96, v100, v101
	v_cvt_pk_bf16_f32 v97, v102, v103
	v_pk_add_f32 v[86:87], v[86:87], 0 op_sel_hi:[1,0]
	v_cvt_pk_bf16_f32 v98, v98, v99
	v_cvt_pk_bf16_f32 v99, v104, v105
	global_store_dwordx4 v[112:113], v[96:99], off offset:256
	v_pk_add_f32 v[78:79], v[78:79], 0 op_sel_hi:[1,0]
	v_pk_add_f32 v[76:77], v[76:77], 0 op_sel_hi:[1,0]
	v_or_b32_e32 v96, 32, v152
	v_ashrrev_i32_e32 v97, 31, v96
	v_lshlrev_b64 v[96:97], 11, v[96:97]
; __device__ __forceinline__ unsigned cvt_pk_bf16(float lo, float hi) { unsigned r; asm volatile("v_cvt_pk_bf16_f32 %0, %1, %2" : "=v"(r) : "v"(lo), "v"(hi)); return r; }
; __device__ __forceinline__ float flogsig16(float x) { return (fminf(x, 0.f) - __logf(1.0f + __expf(-fabsf(x)))) * 0.0625f; }
; #define PG8_WAIT_V(n) asm volatile("s_waitcnt vmcnt(" #n ")" ::: "memory")
; #define PG8_BAR __builtin_amdgcn_s_barrier()
;     __device__ __forceinline__ void operator()(const f32x4 (&acc)[2][2][4][2], const Unit& u, int wr, int wc, int fr, int fq) const {
;     ...
;             for (int m = 0; m < 4; ++m) { bf16_t* rowp = O + (size_t)(row0 + ai * HALF + m * 16) * ldc + col0;
; #pragma unroll
;                 for (int bj = 0; bj < 2; ++bj) { f32x4 v0 = acc[ai][bj][m][0] + bv[bj][0], v1 = acc[ai][bj][m][1] + bv[bj][1];
;                     if (act == 1) {
; #pragma unroll
;                         for (int j = 0; j < 1; ++j) { v0 = v0 * sigmoid4(v0); v1 = v1 * sigmoid4(v1); } }
;                     else if (act == 2) {
; #pragma unroll
;                         for (int j = 0; j < 1; ++j) { v0 = sigmoid4(v0); v1 = sigmoid4(v1); } }
;                     else if (act == 3) {
; #pragma unroll
;                         for (int j = 0; j < 4; ++j) { v0[j] = flogsig16(v0[j]); v1[j] = flogsig16(v1[j]); } }
;                     u32x4 w; w.x = cvt_pk_bf16(v0[0], v0[1]); w.y = cvt_pk_bf16(v0[2], v0[3]); w.z = cvt_pk_bf16(v1[0], v1[1]); w.w = cvt_pk_bf16(v1[2], v1[3]);
;                     *(u32x4*)(rowp + bj * HALF) = w; } }
; template <class Epi, class Sched>
; __device__ __forceinline__ void gemm_phase(PG8_LAS unsigned char* lds, const Gemm g, const Sched& S, const Epi& E) {
;     ...
;         if constexpr (!Epi::AFTER_DRAIN) { E(acc, cur, wr, wc, fr, fq); S.done(cur); }
;         if (!has_next) break;
; #pragma unroll
;         for (int a = 0; a < 2; ++a)
; #pragma unroll
;             for (int b = 0; b < 2; ++b)
; #pragma unroll
;                 for (int m = 0; m < 4; ++m)
; #pragma unroll
;                     for (int n = 0; n < 2; ++n) acc[a][b][m][n] = (f32x4){0.f, 0.f, 0.f, 0.f};
;         cur = nxt; cA = nA; cB = nB; ++ui;
;     }
;     PG8_WAIT_V(0);
;     if (wr == 0) PG8_BAR;
	v_lshl_add_u64 v[96:97], s[4:5], 0, v[96:97]
	v_lshl_add_u64 v[96:97], v[96:97], 0, v[156:157]
	v_pk_add_f32 v[98:99], v[90:91], 0 op_sel_hi:[1,0]
	v_pk_add_f32 v[90:91], v[88:89], 0 op_sel_hi:[1,0]
	v_cvt_pk_bf16_f32 v88, v92, v93
	v_cvt_pk_bf16_f32 v89, v94, v95
	v_pk_add_f32 v[70:71], v[70:71], 0 op_sel_hi:[1,0]
	v_cvt_pk_bf16_f32 v90, v90, v91
	v_cvt_pk_bf16_f32 v91, v98, v99
	global_store_dwordx4 v[96:97], v[88:91], off
	v_pk_add_f32 v[68:69], v[68:69], 0 op_sel_hi:[1,0]
	v_pk_add_f32 v[60:61], v[60:61], 0 op_sel_hi:[1,0]
	v_pk_add_f32 v[88:89], v[82:83], 0 op_sel_hi:[1,0]
	v_pk_add_f32 v[82:83], v[80:81], 0 op_sel_hi:[1,0]
	v_cvt_pk_bf16_f32 v80, v84, v85
	v_cvt_pk_bf16_f32 v81, v86, v87
	v_pk_add_f32 v[62:63], v[62:63], 0 op_sel_hi:[1,0]
	v_cvt_pk_bf16_f32 v82, v82, v83
	v_cvt_pk_bf16_f32 v83, v88, v89
	global_store_dwordx4 v[96:97], v[80:83], off offset:256
	v_pk_add_f32 v[54:55], v[54:55], 0 op_sel_hi:[1,0]
	v_pk_add_f32 v[52:53], v[52:53], 0 op_sel_hi:[1,0]
	v_or_b32_e32 v80, 48, v152
	v_ashrrev_i32_e32 v81, 31, v80
	v_lshlrev_b64 v[80:81], 11, v[80:81]
	v_lshl_add_u64 v[80:81], s[4:5], 0, v[80:81]
	v_lshl_add_u64 v[80:81], v[80:81], 0, v[156:157]
	v_pk_add_f32 v[82:83], v[74:75], 0 op_sel_hi:[1,0]
	v_pk_add_f32 v[74:75], v[72:73], 0 op_sel_hi:[1,0]
	v_cvt_pk_bf16_f32 v72, v76, v77
	v_cvt_pk_bf16_f32 v73, v78, v79
	v_pk_add_f32 v[48:49], v[48:49], 0 op_sel_hi:[1,0]
	v_cvt_pk_bf16_f32 v74, v74, v75
	v_cvt_pk_bf16_f32 v75, v82, v83
	global_store_dwordx4 v[80:81], v[72:75], off
	v_pk_add_f32 v[38:39], v[38:39], 0 op_sel_hi:[1,0]
	v_pk_add_f32 v[36:37], v[36:37], 0 op_sel_hi:[1,0]
	v_pk_add_f32 v[72:73], v[66:67], 0 op_sel_hi:[1,0]
	v_pk_add_f32 v[66:67], v[64:65], 0 op_sel_hi:[1,0]
	v_cvt_pk_bf16_f32 v64, v68, v69
	v_cvt_pk_bf16_f32 v65, v70, v71
	v_pk_add_f32 v[32:33], v[32:33], 0 op_sel_hi:[1,0]
	v_cvt_pk_bf16_f32 v66, v66, v67
	v_cvt_pk_bf16_f32 v67, v72, v73
	global_store_dwordx4 v[80:81], v[64:67], off offset:256
	v_pk_add_f32 v[22:23], v[22:23], 0 op_sel_hi:[1,0]
	v_pk_add_f32 v[20:21], v[20:21], 0 op_sel_hi:[1,0]
	v_pk_add_f32 v[66:67], v[58:59], 0 op_sel_hi:[1,0]
	v_pk_add_f32 v[58:59], v[56:57], 0 op_sel_hi:[1,0]
	v_cvt_pk_bf16_f32 v56, v60, v61
	v_add_co_u32_e32 v60, vcc, s47, v144
	v_cvt_pk_bf16_f32 v57, v62, v63
	v_cvt_pk_bf16_f32 v58, v58, v59
	v_cvt_pk_bf16_f32 v59, v66, v67
	v_lshl_add_u64 v[64:65], v[144:145], 0, s[0:1]
	s_nop 0
	v_addc_co_u32_e32 v61, vcc, 0, v145, vcc
	global_store_dwordx4 v[60:61], v[56:59], off
	v_pk_add_f32 v[16:17], v[16:17], 0 op_sel_hi:[1,0]
	s_mov_b32 s51, s14
	v_pk_add_f32 v[56:57], v[46:47], 0 op_sel_hi:[1,0]
	v_pk_add_f32 v[46:47], v[44:45], 0 op_sel_hi:[1,0]
	v_cvt_pk_bf16_f32 v44, v52, v53
	v_cvt_pk_bf16_f32 v45, v54, v55
	s_mov_b32 s22, s16
	v_cvt_pk_bf16_f32 v46, v46, v47
	v_cvt_pk_bf16_f32 v47, v56, v57
	global_store_dwordx4 v[64:65], v[44:47], off offset:256
	s_mov_b64 s[26:27], s[20:21]
	s_mov_b64 s[24:25], s[18:19]
	v_pk_add_f32 v[46:47], v[50:51], 0 op_sel_hi:[1,0]
	v_pk_add_f32 v[50:51], v[42:43], 0 op_sel_hi:[1,0]
	v_pk_add_f32 v[42:43], v[40:41], 0 op_sel_hi:[1,0]
	v_cvt_pk_bf16_f32 v40, v48, v49
	v_cvt_pk_bf16_f32 v41, v46, v47
	v_add_co_u32_e32 v46, vcc, s48, v144
	v_cvt_pk_bf16_f32 v42, v42, v43
	v_cvt_pk_bf16_f32 v43, v50, v51
	v_lshl_add_u64 v[44:45], v[144:145], 0, s[8:9]
	s_nop 0
	v_addc_co_u32_e32 v47, vcc, 0, v145, vcc
	global_store_dwordx4 v[46:47], v[40:43], off
	v_pk_add_f32 v[6:7], v[6:7], 0 op_sel_hi:[1,0]
	v_pk_add_f32 v[4:5], v[4:5], 0 op_sel_hi:[1,0]
	v_pk_add_f32 v[40:41], v[30:31], 0 op_sel_hi:[1,0]
	v_pk_add_f32 v[30:31], v[28:29], 0 op_sel_hi:[1,0]
	v_cvt_pk_bf16_f32 v28, v36, v37
	v_cvt_pk_bf16_f32 v29, v38, v39
	s_nop 0
	v_cvt_pk_bf16_f32 v30, v30, v31
	v_cvt_pk_bf16_f32 v31, v40, v41
	global_store_dwordx4 v[44:45], v[28:31], off offset:256
	s_nop 1
	v_pk_add_f32 v[30:31], v[34:35], 0 op_sel_hi:[1,0]
	v_pk_add_f32 v[34:35], v[26:27], 0 op_sel_hi:[1,0]
	v_pk_add_f32 v[26:27], v[24:25], 0 op_sel_hi:[1,0]
	v_cvt_pk_bf16_f32 v24, v32, v33
	v_cvt_pk_bf16_f32 v25, v30, v31
	v_add_co_u32_e32 v30, vcc, s49, v144
	v_cvt_pk_bf16_f32 v26, v26, v27
	v_cvt_pk_bf16_f32 v27, v34, v35
	v_lshl_add_u64 v[28:29], v[144:145], 0, s[10:11]
	s_nop 0
	v_addc_co_u32_e32 v31, vcc, 0, v145, vcc
	global_store_dwordx4 v[30:31], v[24:27], off
	s_nop 1
	v_pk_add_f32 v[24:25], v[14:15], 0 op_sel_hi:[1,0]
	v_pk_add_f32 v[14:15], v[12:13], 0 op_sel_hi:[1,0]
	v_cvt_pk_bf16_f32 v12, v20, v21
	v_cvt_pk_bf16_f32 v13, v22, v23
	s_nop 0
	v_cvt_pk_bf16_f32 v14, v14, v15
	v_cvt_pk_bf16_f32 v15, v24, v25
	global_store_dwordx4 v[28:29], v[12:15], off offset:256
	s_nop 1
	v_pk_add_f32 v[14:15], v[18:19], 0 op_sel_hi:[1,0]
	v_pk_add_f32 v[18:19], v[10:11], 0 op_sel_hi:[1,0]
	v_pk_add_f32 v[10:11], v[8:9], 0 op_sel_hi:[1,0]
	v_cvt_pk_bf16_f32 v8, v16, v17
	v_cvt_pk_bf16_f32 v9, v14, v15
	v_add_co_u32_e32 v14, vcc, s50, v144
	v_lshl_add_u64 v[12:13], v[144:145], 0, s[12:13]
	s_nop 0
	v_addc_co_u32_e32 v15, vcc, 0, v145, vcc
	v_cvt_pk_bf16_f32 v10, v10, v11
	v_cvt_pk_bf16_f32 v11, v18, v19
	global_store_dwordx4 v[14:15], v[8:11], off
	s_and_b64 vcc, exec, s[2:3]
	s_nop 0
	v_pk_add_f32 v[8:9], v[2:3], 0 op_sel_hi:[1,0]
	v_pk_add_f32 v[2:3], v[0:1], 0 op_sel_hi:[1,0]
	v_cvt_pk_bf16_f32 v0, v4, v5
	v_cvt_pk_bf16_f32 v1, v6, v7
	s_nop 0
	v_cvt_pk_bf16_f32 v2, v2, v3
	v_cvt_pk_bf16_f32 v3, v8, v9
	global_store_dwordx4 v[12:13], v[0:3], off offset:256
	s_cbranch_vccz .LBB0_1076
	s_waitcnt vmcnt(0)
	s_cmpk_gt_u32 s31, 0xff
	s_cbranch_scc1 .LBB0_1087
	s_barrier

; #define PG8_STAGE(bufoff, gbase, voff) do { _Pragma("unroll") for (int _i = 0; _i < 2; ++_i) \
;         __builtin_amdgcn_global_load_lds((const unsigned*)((const char*)(gbase) + (voff)[_i]), (PG8_LAS unsigned*)(lds + (bufoff) + ldsw + _i * 8192), 16, 0, 0); } while (0)
; #define PG8_LDA(dst, b, h) do { _Pragma("unroll") for (int m = 0; m < 4; ++m) _Pragma("unroll") for (int k = 0; k < 2; ++k) dst[m][k] = *(const PG8_LAS bf16x8*)(lds + PG8_SA(b, h) + aoff + m * 2048 + k * 1024); } while (0)
; #define PG8_LDB(dst, b, h) do { _Pragma("unroll") for (int n = 0; n < 2; ++n) _Pragma("unroll") for (int k = 0; k < 2; ++k) dst[n][k] = *(const PG8_LAS bf16x8*)(lds + PG8_SB(b, h) + boff + n * 2048 + k * 1024); } while (0)
; #define PG8_MMA(ai, bj, At, Bt) do { __builtin_amdgcn_s_setprio(1); _Pragma("unroll") for (int m = 0; m < 4; ++m) _Pragma("unroll") for (int n = 0; n < 2; ++n) _Pragma("unroll") for (int k = 0; k < 2; ++k) \
;         acc[ai][bj][m][n] = __builtin_amdgcn_mfma_f32_16x16x32_bf16(Bt[n][k], At[m][k], acc[ai][bj][m][n], 0, 0, 0); __builtin_amdgcn_s_setprio(0); } while (0)
; #define PG8_WAIT_L(n) asm volatile("s_waitcnt lgkmcnt(" #n ")" ::: "memory")
; #define PG8_BAR __builtin_amdgcn_s_barrier()
; #define PG8_SCHED __builtin_amdgcn_sched_barrier(0)
; template <class Epi, class Sched>
; __device__ __forceinline__ void gemm_phase(PG8_LAS unsigned char* lds, const Gemm g, const Sched& S, const Epi& E) {
;     ...
;             PG8_LDB(B0, 0, 0); PG8_SCHED; PG8_LDA(At, 0, 0); PG8_STAGE(PG8_SA(1, 1), a1 + hstep, voffA);
;             PG8_WAIT_L(8); PG8_BAR; PG8_WAIT_L(0); PG8_MMA(0, 0, At, B0); PG8_BAR; PG8_SCHED;
;             PG8_LDB(B1, 0, 1); PG8_STAGE(PG8_SB(0, 0), b2, voffB);
;             PG8_BAR; PG8_WAIT_L(0); PG8_MMA(0, 1, At, B1); PG8_BAR;
;             PG8_LDA(At, 0, 1); PG8_STAGE(PG8_SA(0, 0), a2, voffA);
;             PG8_BAR; PG8_WAIT_L(0); PG8_MMA(1, 0, At, B0); PG8_BAR; PG8_SCHED;
.LBB0_1202:
	ds_read_b128 v[144:147], v151
	ds_read_b128 v[154:157], v151 offset:1024
	ds_read_b128 v[158:161], v151 offset:2048
	ds_read_b128 v[162:165], v151 offset:3072
	s_add_u32 s18, s16, 0xfffc0080
	s_addc_u32 s19, s17, -1
	s_cmp_eq_u32 s46, 12
	s_cselect_b32 s21, s9, s19
	s_cselect_b32 s20, s42, s18
	s_cselect_b32 s19, s7, s45
	s_cselect_b32 s18, s43, s44
	v_lshl_add_u64 v[174:175], s[16:17], 0, v[136:137]
	s_add_i32 m0, s15, 0xc000
	ds_read_b128 v[166:169], v152
	ds_read_b128 v[170:173], v152 offset:1024
	ds_read_b128 v[182:185], v152 offset:2048
	ds_read_b128 v[190:193], v152 offset:3072
	ds_read_b128 v[194:197], v152 offset:4096
	ds_read_b128 v[198:201], v152 offset:5120
	ds_read_b128 v[202:205], v152 offset:6144
	ds_read_b128 v[206:209], v152 offset:7168
	global_load_lds_dwordx4 v[174:175], off
	v_lshl_add_u64 v[174:175], s[16:17], 0, v[138:139]
	s_add_i32 m0, s15, 0xe000
	s_nop 0
	global_load_lds_dwordx4 v[174:175], off
	s_waitcnt lgkmcnt(8)
	s_barrier
	s_waitcnt lgkmcnt(0)
	s_setprio 0
	s_waitcnt lgkmcnt(0)
	v_mfma_f32_16x16x32_bf16 v[124:127], v[144:147], v[166:169], v[124:127]
	v_mfma_f32_16x16x32_bf16 v[120:123], v[158:161], v[166:169], v[120:123]
	v_mfma_f32_16x16x32_bf16 v[108:111], v[144:147], v[182:185], v[108:111]
	v_mfma_f32_16x16x32_bf16 v[104:107], v[158:161], v[182:185], v[104:107]
	v_mfma_f32_16x16x32_bf16 v[92:95], v[144:147], v[194:197], v[92:95]
	v_mfma_f32_16x16x32_bf16 v[88:91], v[158:161], v[194:197], v[88:91]
	v_mfma_f32_16x16x32_bf16 v[76:79], v[144:147], v[202:205], v[76:79]
	v_mfma_f32_16x16x32_bf16 v[72:75], v[158:161], v[202:205], v[72:75]
	v_mfma_f32_16x16x32_bf16 v[124:127], v[154:157], v[170:173], v[124:127]
	v_mfma_f32_16x16x32_bf16 v[120:123], v[162:165], v[170:173], v[120:123]
	v_mfma_f32_16x16x32_bf16 v[108:111], v[154:157], v[190:193], v[108:111]
	v_mfma_f32_16x16x32_bf16 v[104:107], v[162:165], v[190:193], v[104:107]
	v_mfma_f32_16x16x32_bf16 v[92:95], v[154:157], v[198:201], v[92:95]
	v_mfma_f32_16x16x32_bf16 v[88:91], v[162:165], v[198:201], v[88:91]
	v_mfma_f32_16x16x32_bf16 v[76:79], v[154:157], v[206:209], v[76:79]
	v_mfma_f32_16x16x32_bf16 v[72:75], v[162:165], v[206:209], v[72:75]
	s_setprio 1
	s_barrier
	s_add_i32 s47, s38, s26
	v_lshl_add_u64 v[174:175], s[18:19], 0, v[132:133]
	s_mov_b32 m0, s47
	ds_read_b128 v[210:213], v153
	ds_read_b128 v[214:217], v153 offset:1024
	ds_read_b128 v[218:221], v153 offset:2048
	ds_read_b128 v[222:225], v153 offset:3072
	global_load_lds_dwordx4 v[174:175], off
	v_lshl_add_u64 v[186:187], s[18:19], 0, v[128:129]
	s_add_i32 m0, s47, 0x2000
	s_nop 0
	global_load_lds_dwordx4 v[186:187], off
	s_barrier
	s_waitcnt lgkmcnt(0)
	s_setprio 0
	s_waitcnt lgkmcnt(0)
	v_mfma_f32_16x16x32_bf16 v[116:119], v[210:213], v[166:169], v[116:119]
	v_mfma_f32_16x16x32_bf16 v[112:115], v[218:221], v[166:169], v[112:115]
	v_mfma_f32_16x16x32_bf16 v[100:103], v[210:213], v[182:185], v[100:103]
	v_mfma_f32_16x16x32_bf16 v[96:99], v[218:221], v[182:185], v[96:99]
	v_mfma_f32_16x16x32_bf16 v[84:87], v[210:213], v[194:197], v[84:87]
	v_mfma_f32_16x16x32_bf16 v[80:83], v[218:221], v[194:197], v[80:83]
	v_mfma_f32_16x16x32_bf16 v[68:71], v[210:213], v[202:205], v[68:71]
	v_mfma_f32_16x16x32_bf16 v[64:67], v[218:221], v[202:205], v[64:67]
	v_mfma_f32_16x16x32_bf16 v[116:119], v[214:217], v[170:173], v[116:119]
	v_mfma_f32_16x16x32_bf16 v[112:115], v[222:225], v[170:173], v[112:115]
	v_mfma_f32_16x16x32_bf16 v[100:103], v[214:217], v[190:193], v[100:103]
	v_mfma_f32_16x16x32_bf16 v[96:99], v[222:225], v[190:193], v[96:99]
	v_mfma_f32_16x16x32_bf16 v[84:87], v[214:217], v[198:201], v[84:87]
	v_mfma_f32_16x16x32_bf16 v[80:83], v[222:225], v[198:201], v[80:83]
	v_mfma_f32_16x16x32_bf16 v[68:71], v[214:217], v[206:209], v[68:71]
	v_mfma_f32_16x16x32_bf16 v[64:67], v[222:225], v[206:209], v[64:67]
	s_setprio 1
	s_mov_b32 m0, s15
	v_lshl_add_u64 v[226:227], s[20:21], 0, v[134:135]
	s_barrier
	ds_read_b128 v[166:169], v152 offset:16384
	ds_read_b128 v[170:173], v152 offset:17408
	ds_read_b128 v[182:185], v152 offset:18432
	ds_read_b128 v[190:193], v152 offset:19456
	ds_read_b128 v[194:197], v152 offset:20480
	ds_read_b128 v[198:201], v152 offset:21504
	ds_read_b128 v[202:205], v152 offset:22528
	ds_read_b128 v[206:209], v152 offset:23552
	global_load_lds_dwordx4 v[226:227], off
	v_lshl_add_u64 v[228:229], s[20:21], 0, v[130:131]
	s_mov_b32 m0, s29
	s_nop 0
	global_load_lds_dwordx4 v[228:229], off
	s_barrier
	s_waitcnt lgkmcnt(0)
	s_setprio 0
	s_waitcnt lgkmcnt(0)
	v_mfma_f32_16x16x32_bf16 v[60:63], v[144:147], v[166:169], v[60:63]
	v_mfma_f32_16x16x32_bf16 v[56:59], v[158:161], v[166:169], v[56:59]
	v_mfma_f32_16x16x32_bf16 v[44:47], v[144:147], v[182:185], v[44:47]
	v_mfma_f32_16x16x32_bf16 v[40:43], v[158:161], v[182:185], v[40:43]
	v_mfma_f32_16x16x32_bf16 v[28:31], v[144:147], v[194:197], v[28:31]
	v_mfma_f32_16x16x32_bf16 v[24:27], v[158:161], v[194:197], v[24:27]
	v_mfma_f32_16x16x32_bf16 v[12:15], v[144:147], v[202:205], v[12:15]
	v_mfma_f32_16x16x32_bf16 v[8:11], v[158:161], v[202:205], v[8:11]
	v_mfma_f32_16x16x32_bf16 v[60:63], v[154:157], v[170:173], v[60:63]
	v_mfma_f32_16x16x32_bf16 v[56:59], v[162:165], v[170:173], v[56:59]
	v_mfma_f32_16x16x32_bf16 v[44:47], v[154:157], v[190:193], v[44:47]
	v_mfma_f32_16x16x32_bf16 v[40:43], v[162:165], v[190:193], v[40:43]
	v_mfma_f32_16x16x32_bf16 v[28:31], v[154:157], v[198:201], v[28:31]
	v_mfma_f32_16x16x32_bf16 v[24:27], v[162:165], v[198:201], v[24:27]
	v_mfma_f32_16x16x32_bf16 v[12:15], v[154:157], v[206:209], v[12:15]
	v_mfma_f32_16x16x32_bf16 v[8:11], v[162:165], v[206:209], v[8:11]
	s_setprio 1
	s_barrier
; #define PG8_STAGE(bufoff, gbase, voff) do { _Pragma("unroll") for (int _i = 0; _i < 2; ++_i) \
;         __builtin_amdgcn_global_load_lds((const unsigned*)((const char*)(gbase) + (voff)[_i]), (PG8_LAS unsigned*)(lds + (bufoff) + ldsw + _i * 8192), 16, 0, 0); } while (0)
; #define PG8_LDA(dst, b, h) do { _Pragma("unroll") for (int m = 0; m < 4; ++m) _Pragma("unroll") for (int k = 0; k < 2; ++k) dst[m][k] = *(const PG8_LAS bf16x8*)(lds + PG8_SA(b, h) + aoff + m * 2048 + k * 1024); } while (0)
; #define PG8_LDB(dst, b, h) do { _Pragma("unroll") for (int n = 0; n < 2; ++n) _Pragma("unroll") for (int k = 0; k < 2; ++k) dst[n][k] = *(const PG8_LAS bf16x8*)(lds + PG8_SB(b, h) + boff + n * 2048 + k * 1024); } while (0)
; #define PG8_MMA(ai, bj, At, Bt) do { __builtin_amdgcn_s_setprio(1); _Pragma("unroll") for (int m = 0; m < 4; ++m) _Pragma("unroll") for (int n = 0; n < 2; ++n) _Pragma("unroll") for (int k = 0; k < 2; ++k) \
;         acc[ai][bj][m][n] = __builtin_amdgcn_mfma_f32_16x16x32_bf16(Bt[n][k], At[m][k], acc[ai][bj][m][n], 0, 0, 0); __builtin_amdgcn_s_setprio(0); } while (0)
; #define PG8_WAIT_V(n) asm volatile("s_waitcnt vmcnt(" #n ")" ::: "memory")
; #define PG8_WAIT_L(n) asm volatile("s_waitcnt lgkmcnt(" #n ")" ::: "memory")
; #define PG8_BAR __builtin_amdgcn_s_barrier()
; #define PG8_SCHED __builtin_amdgcn_sched_barrier(0)
; template <class Epi, class Sched>
; __device__ __forceinline__ void gemm_phase(PG8_LAS unsigned char* lds, const Gemm g, const Sched& S, const Epi& E) {
;     ...
;             PG8_STAGE(PG8_SB(0, 1), b2 + hstep, voffB);
;             PG8_WAIT_V(6); PG8_BAR; PG8_MMA(1, 1, At, B1); PG8_BAR;
;             PG8_LDB(B0, 1, 0); PG8_SCHED; PG8_LDA(At, 1, 0); PG8_STAGE(PG8_SA(0, 1), a2 + hstep, voffA);
;             PG8_WAIT_L(8); PG8_BAR; PG8_WAIT_L(0); PG8_MMA(0, 0, At, B0); PG8_BAR; PG8_SCHED;
;             PG8_LDB(B1, 1, 1); PG8_STAGE(PG8_SB(1, 0), b3, voffB);
;             PG8_BAR; PG8_WAIT_L(0); PG8_MMA(0, 1, At, B1); PG8_BAR;
;             PG8_LDA(At, 1, 1); PG8_STAGE(PG8_SA(1, 0), a3, voffA);
	s_add_u32 s48, s18, 0x40000
	s_addc_u32 s49, s19, 0
	s_add_i32 s47, s39, s26
	v_lshl_add_u64 v[144:145], s[48:49], 0, v[132:133]
	s_mov_b32 m0, s47
	s_nop 0
	global_load_lds_dwordx4 v[144:145], off
	v_lshl_add_u64 v[144:145], s[48:49], 0, v[128:129]
	s_add_i32 m0, s47, 0x2000
	s_nop 0
	global_load_lds_dwordx4 v[144:145], off
	s_waitcnt vmcnt(6)
	s_barrier
	s_setprio 0
	v_mfma_f32_16x16x32_bf16 v[52:55], v[210:213], v[166:169], v[52:55]
	v_mfma_f32_16x16x32_bf16 v[48:51], v[218:221], v[166:169], v[48:51]
	v_mfma_f32_16x16x32_bf16 v[36:39], v[210:213], v[182:185], v[36:39]
	v_mfma_f32_16x16x32_bf16 v[32:35], v[218:221], v[182:185], v[32:35]
	v_mfma_f32_16x16x32_bf16 v[20:23], v[210:213], v[194:197], v[20:23]
	v_mfma_f32_16x16x32_bf16 v[16:19], v[218:221], v[194:197], v[16:19]
	v_mfma_f32_16x16x32_bf16 v[4:7], v[210:213], v[202:205], v[4:7]
	v_mfma_f32_16x16x32_bf16 v[0:3], v[218:221], v[202:205], v[0:3]
	v_mfma_f32_16x16x32_bf16 v[52:55], v[214:217], v[170:173], v[52:55]
	v_mfma_f32_16x16x32_bf16 v[48:51], v[222:225], v[170:173], v[48:51]
	v_mfma_f32_16x16x32_bf16 v[36:39], v[214:217], v[190:193], v[36:39]
	v_mfma_f32_16x16x32_bf16 v[32:35], v[222:225], v[190:193], v[32:35]
	v_mfma_f32_16x16x32_bf16 v[20:23], v[214:217], v[198:201], v[20:23]
	v_mfma_f32_16x16x32_bf16 v[16:19], v[222:225], v[198:201], v[16:19]
	v_mfma_f32_16x16x32_bf16 v[4:7], v[214:217], v[206:209], v[4:7]
	v_mfma_f32_16x16x32_bf16 v[0:3], v[222:225], v[206:209], v[0:3]
	s_setprio 1
	s_add_i32 s47, 0, 0x18000
	v_add_u32_e32 v162, s47, v149
	s_barrier
	ds_read_b128 v[144:147], v162
	ds_read_b128 v[154:157], v162 offset:1024
	ds_read_b128 v[158:161], v162 offset:2048
	ds_read_b128 v[162:165], v162 offset:3072
	s_add_u32 s20, s20, 0x40000
	s_addc_u32 s21, s21, 0
	s_mov_b32 m0, s30
	v_lshl_add_u64 v[210:211], s[20:21], 0, v[134:135]
	ds_read_b128 v[166:169], v152 offset:32768
	ds_read_b128 v[170:173], v152 offset:33792
	ds_read_b128 v[182:185], v152 offset:34816
	ds_read_b128 v[190:193], v152 offset:35840
	ds_read_b128 v[194:197], v152 offset:36864
	ds_read_b128 v[198:201], v152 offset:37888
	ds_read_b128 v[202:205], v152 offset:38912
	ds_read_b128 v[206:209], v152 offset:39936
	global_load_lds_dwordx4 v[210:211], off
	v_lshl_add_u64 v[210:211], s[20:21], 0, v[130:131]
	s_mov_b32 m0, s31
	s_nop 0
	global_load_lds_dwordx4 v[210:211], off
	s_waitcnt lgkmcnt(8)
	s_barrier
	s_waitcnt lgkmcnt(0)
	s_setprio 0
	s_waitcnt lgkmcnt(0)
	v_mfma_f32_16x16x32_bf16 v[124:127], v[144:147], v[166:169], v[124:127]
	v_mfma_f32_16x16x32_bf16 v[120:123], v[158:161], v[166:169], v[120:123]
	v_mfma_f32_16x16x32_bf16 v[108:111], v[144:147], v[182:185], v[108:111]
	v_mfma_f32_16x16x32_bf16 v[104:107], v[158:161], v[182:185], v[104:107]
	v_mfma_f32_16x16x32_bf16 v[92:95], v[144:147], v[194:197], v[92:95]
	v_mfma_f32_16x16x32_bf16 v[88:91], v[158:161], v[194:197], v[88:91]
	v_mfma_f32_16x16x32_bf16 v[76:79], v[144:147], v[202:205], v[76:79]
	v_mfma_f32_16x16x32_bf16 v[72:75], v[158:161], v[202:205], v[72:75]
	v_mfma_f32_16x16x32_bf16 v[124:127], v[154:157], v[170:173], v[124:127]
	v_mfma_f32_16x16x32_bf16 v[120:123], v[162:165], v[170:173], v[120:123]
	v_mfma_f32_16x16x32_bf16 v[108:111], v[154:157], v[190:193], v[108:111]
	v_mfma_f32_16x16x32_bf16 v[104:107], v[162:165], v[190:193], v[104:107]
	v_mfma_f32_16x16x32_bf16 v[92:95], v[154:157], v[198:201], v[92:95]
	v_mfma_f32_16x16x32_bf16 v[88:91], v[162:165], v[198:201], v[88:91]
	v_mfma_f32_16x16x32_bf16 v[76:79], v[154:157], v[206:209], v[76:79]
	v_mfma_f32_16x16x32_bf16 v[72:75], v[162:165], v[206:209], v[72:75]
	s_setprio 1
	s_barrier
	s_add_i32 s20, 0, 0x1c000
	s_add_i32 s21, s47, s26
	v_add_u32_e32 v179, s20, v149
	v_lshl_add_u64 v[174:175], v[174:175], 0, s[4:5]
	s_mov_b32 m0, s21
	ds_read_b128 v[210:213], v179
	ds_read_b128 v[214:217], v179 offset:1024
	ds_read_b128 v[218:221], v179 offset:2048
	ds_read_b128 v[222:225], v179 offset:3072
	global_load_lds_dwordx4 v[174:175], off
	v_lshl_add_u64 v[174:175], v[186:187], 0, s[4:5]
	s_add_i32 m0, s21, 0x2000
	s_nop 0
	global_load_lds_dwordx4 v[174:175], off
	s_barrier
	s_waitcnt lgkmcnt(0)
	s_setprio 0
	s_waitcnt lgkmcnt(0)
	v_mfma_f32_16x16x32_bf16 v[116:119], v[210:213], v[166:169], v[116:119]
	v_mfma_f32_16x16x32_bf16 v[112:115], v[218:221], v[166:169], v[112:115]
	v_mfma_f32_16x16x32_bf16 v[100:103], v[210:213], v[182:185], v[100:103]
	v_mfma_f32_16x16x32_bf16 v[96:99], v[218:221], v[182:185], v[96:99]
	v_mfma_f32_16x16x32_bf16 v[84:87], v[210:213], v[194:197], v[84:87]
	v_mfma_f32_16x16x32_bf16 v[80:83], v[218:221], v[194:197], v[80:83]
	v_mfma_f32_16x16x32_bf16 v[68:71], v[210:213], v[202:205], v[68:71]
	v_mfma_f32_16x16x32_bf16 v[64:67], v[218:221], v[202:205], v[64:67]
	v_mfma_f32_16x16x32_bf16 v[116:119], v[214:217], v[170:173], v[116:119]
	v_mfma_f32_16x16x32_bf16 v[112:115], v[222:225], v[170:173], v[112:115]
	v_mfma_f32_16x16x32_bf16 v[100:103], v[214:217], v[190:193], v[100:103]
	v_mfma_f32_16x16x32_bf16 v[96:99], v[222:225], v[190:193], v[96:99]
	v_mfma_f32_16x16x32_bf16 v[84:87], v[214:217], v[198:201], v[84:87]
	v_mfma_f32_16x16x32_bf16 v[80:83], v[222:225], v[198:201], v[80:83]
	v_mfma_f32_16x16x32_bf16 v[68:71], v[214:217], v[206:209], v[68:71]
	v_mfma_f32_16x16x32_bf16 v[64:67], v[222:225], v[206:209], v[64:67]
	s_setprio 1
	s_mov_b32 m0, s35
	v_lshl_add_u64 v[174:175], v[226:227], 0, s[4:5]
	s_barrier
	ds_read_b128 v[166:169], v152 offset:49152
	ds_read_b128 v[170:173], v152 offset:50176
	ds_read_b128 v[182:185], v152 offset:51200
	ds_read_b128 v[190:193], v152 offset:52224
	ds_read_b128 v[194:197], v152 offset:53248
	ds_read_b128 v[198:201], v152 offset:54272
	ds_read_b128 v[202:205], v152 offset:55296
	ds_read_b128 v[206:209], v152 offset:56320
	global_load_lds_dwordx4 v[174:175], off
	v_lshl_add_u64 v[174:175], v[228:229], 0, s[4:5]
	s_mov_b32 m0, s36
	s_nop 0
	global_load_lds_dwordx4 v[174:175], off
	s_barrier
; __device__ __forceinline__ unsigned cvt_pk_bf16(float lo, float hi) { unsigned r; asm volatile("v_cvt_pk_bf16_f32 %0, %1, %2" : "=v"(r) : "v"(lo), "v"(hi)); return r; }
; #define PG8_STAGE(bufoff, gbase, voff) do { _Pragma("unroll") for (int _i = 0; _i < 2; ++_i) \
;         __builtin_amdgcn_global_load_lds((const unsigned*)((const char*)(gbase) + (voff)[_i]), (PG8_LAS unsigned*)(lds + (bufoff) + ldsw + _i * 8192), 16, 0, 0); } while (0)
; #define PG8_MMA(ai, bj, At, Bt) do { __builtin_amdgcn_s_setprio(1); _Pragma("unroll") for (int m = 0; m < 4; ++m) _Pragma("unroll") for (int n = 0; n < 2; ++n) _Pragma("unroll") for (int k = 0; k < 2; ++k) \
;         acc[ai][bj][m][n] = __builtin_amdgcn_mfma_f32_16x16x32_bf16(Bt[n][k], At[m][k], acc[ai][bj][m][n], 0, 0, 0); __builtin_amdgcn_s_setprio(0); } while (0)
; #define PG8_WAIT_V(n) asm volatile("s_waitcnt vmcnt(" #n ")" ::: "memory")
; #define PG8_WAIT_L(n) asm volatile("s_waitcnt lgkmcnt(" #n ")" ::: "memory")
; #define PG8_BAR __builtin_amdgcn_s_barrier()
; #define PG8_SCHED __builtin_amdgcn_sched_barrier(0)
;     __device__ __forceinline__ void operator()(const f32x4 (&acc)[2][2][4][2], const Unit& u, int wr, int wc, int fr, int fq) const {
;     ...
;             for (int m = 0; m < 4; ++m) { bf16_t* rowp = O + (size_t)(row0 + ai * HALF + m * 16) * ldc + col0;
;                 f32x4 v0, v1;
; #pragma unroll
;                 for (int j = 0; j < 1; ++j) { v0 = acc[ai][0][m][0] * sigmoid4(acc[ai][0][m][0]) * acc[ai][1][m][0]; v1 = acc[ai][0][m][1] * sigmoid4(acc[ai][0][m][1]) * acc[ai][1][m][1]; }
;                 u32x4 w; w.x = cvt_pk_bf16(v0[0], v0[1]); w.y = cvt_pk_bf16(v0[2], v0[3]); w.z = cvt_pk_bf16(v1[0], v1[1]); w.w = cvt_pk_bf16(v1[2], v1[3]);
;                 *(u32x4*)rowp = w; }
; template <class Epi, class Sched>
; __device__ __forceinline__ void gemm_phase(PG8_LAS unsigned char* lds, const Gemm g, const Sched& S, const Epi& E) {
;     ...
;             PG8_BAR; PG8_WAIT_L(0); PG8_MMA(1, 0, At, B0); PG8_BAR; PG8_SCHED;
;             PG8_STAGE(PG8_SB(1, 1), b3 + hstep, voffB);
;             PG8_WAIT_V(6); PG8_BAR; PG8_MMA(1, 1, At, B1); PG8_BAR;
	s_waitcnt lgkmcnt(0)
	s_setprio 0
	s_waitcnt lgkmcnt(0)
	v_mfma_f32_16x16x32_bf16 v[60:63], v[144:147], v[166:169], v[60:63]
	v_mfma_f32_16x16x32_bf16 v[56:59], v[158:161], v[166:169], v[56:59]
	v_mfma_f32_16x16x32_bf16 v[44:47], v[144:147], v[182:185], v[44:47]
	v_mfma_f32_16x16x32_bf16 v[40:43], v[158:161], v[182:185], v[40:43]
	v_mfma_f32_16x16x32_bf16 v[28:31], v[144:147], v[194:197], v[28:31]
	v_mfma_f32_16x16x32_bf16 v[24:27], v[158:161], v[194:197], v[24:27]
	v_mfma_f32_16x16x32_bf16 v[12:15], v[144:147], v[202:205], v[12:15]
	v_mfma_f32_16x16x32_bf16 v[8:11], v[158:161], v[202:205], v[8:11]
	v_mfma_f32_16x16x32_bf16 v[60:63], v[154:157], v[170:173], v[60:63]
	v_mfma_f32_16x16x32_bf16 v[56:59], v[162:165], v[170:173], v[56:59]
	v_mfma_f32_16x16x32_bf16 v[44:47], v[154:157], v[190:193], v[44:47]
	v_mfma_f32_16x16x32_bf16 v[40:43], v[162:165], v[190:193], v[40:43]
	v_mfma_f32_16x16x32_bf16 v[28:31], v[154:157], v[198:201], v[28:31]
	v_mfma_f32_16x16x32_bf16 v[24:27], v[162:165], v[198:201], v[24:27]
	v_mfma_f32_16x16x32_bf16 v[12:15], v[154:157], v[206:209], v[12:15]
	v_mfma_f32_16x16x32_bf16 v[8:11], v[162:165], v[206:209], v[8:11]
	s_setprio 1
	s_barrier
	s_add_u32 s18, s18, 0x40080
	s_addc_u32 s19, s19, 0
	s_add_i32 s20, s20, s26
	v_lshl_add_u64 v[144:145], s[18:19], 0, v[132:133]
	s_mov_b32 m0, s20
	s_nop 0
	global_load_lds_dwordx4 v[144:145], off
	v_lshl_add_u64 v[144:145], s[18:19], 0, v[128:129]
	s_add_i32 m0, s20, 0x2000
	s_nop 0
	global_load_lds_dwordx4 v[144:145], off
	s_waitcnt vmcnt(6)
	s_barrier
	s_setprio 0
	v_mfma_f32_16x16x32_bf16 v[52:55], v[210:213], v[166:169], v[52:55]
	v_mfma_f32_16x16x32_bf16 v[48:51], v[218:221], v[166:169], v[48:51]
	v_mfma_f32_16x16x32_bf16 v[36:39], v[210:213], v[182:185], v[36:39]
	v_mfma_f32_16x16x32_bf16 v[32:35], v[218:221], v[182:185], v[32:35]
	v_mfma_f32_16x16x32_bf16 v[20:23], v[210:213], v[194:197], v[20:23]
	v_mfma_f32_16x16x32_bf16 v[16:19], v[218:221], v[194:197], v[16:19]
	v_mfma_f32_16x16x32_bf16 v[4:7], v[210:213], v[202:205], v[4:7]
	v_mfma_f32_16x16x32_bf16 v[0:3], v[218:221], v[202:205], v[0:3]
	v_mfma_f32_16x16x32_bf16 v[52:55], v[214:217], v[170:173], v[52:55]
	v_mfma_f32_16x16x32_bf16 v[48:51], v[222:225], v[170:173], v[48:51]
	v_mfma_f32_16x16x32_bf16 v[36:39], v[214:217], v[190:193], v[36:39]
	v_mfma_f32_16x16x32_bf16 v[32:35], v[222:225], v[190:193], v[32:35]
	v_mfma_f32_16x16x32_bf16 v[20:23], v[214:217], v[198:201], v[20:23]
	v_mfma_f32_16x16x32_bf16 v[16:19], v[222:225], v[198:201], v[16:19]
	v_mfma_f32_16x16x32_bf16 v[4:7], v[214:217], v[206:209], v[4:7]
	v_mfma_f32_16x16x32_bf16 v[0:3], v[222:225], v[206:209], v[0:3]
	s_setprio 1
	s_add_i32 s46, s46, 2
	s_add_u32 s16, s16, 0x100
	s_addc_u32 s17, s17, 0
	s_add_u32 s44, s44, 0x100
	s_addc_u32 s45, s45, 0
	s_cmp_gt_u32 s46, 13
	s_barrier
	s_cbranch_scc0 .LBB0_1202
	v_max_f32_e32 v144, v124, v124
	v_max_f32_e32 v144, 0xc1a00000, v144
	v_mul_f32_e32 v144, 0xbfb8aa3b, v144
	v_exp_f32_e32 v157, v144
	v_max_f32_e32 v144, v125, v125
	v_max_f32_e32 v144, 0xc1a00000, v144
	v_mul_f32_e32 v144, 0xbfb8aa3b, v144
	v_exp_f32_e32 v156, v144
	v_max_f32_e32 v144, v126, v126
	v_max_f32_e32 v144, 0xc1a00000, v144
	v_mul_f32_e32 v144, 0xbfb8aa3b, v144
	v_exp_f32_e32 v159, v144
	v_max_f32_e32 v144, v127, v127
	v_max_f32_e32 v144, 0xc1a00000, v144
	v_mul_f32_e32 v144, 0xbfb8aa3b, v144
	v_exp_f32_e32 v158, v144
	v_pk_add_f32 v[156:157], v[156:157], 1.0 op_sel_hi:[1,0]
	v_lshl_or_b32 v146, s41, 7, v150
	v_mov_b32_e32 v160, v157
	v_pk_add_f32 v[158:159], v[158:159], 1.0 op_sel_hi:[1,0]
	v_mov_b32_e32 v162, v156
	v_mov_b32_e32 v161, v159
	v_mov_b32_e32 v163, v158
	v_pk_mul_f32 v[160:161], v[160:161], v[162:163]
	v_lshl_add_u32 v154, s14, 8, v148
	v_mul_f32_e32 v155, v160, v161
	v_rcp_f32_e32 v155, v155
	v_ashrrev_i32_e32 v147, 31, v146
	v_mov_b64_e32 v[144:145], s[0:1]
	v_mad_i64_i32 v[162:163], s[16:17], v154, s40, v[144:145]
	v_mul_f32_e32 v164, v161, v155
	v_mul_f32_e32 v160, v160, v155
	v_max_f32_e32 v155, v120, v120
	v_max_f32_e32 v155, 0xc1a00000, v155
	v_mul_f32_e32 v155, 0xbfb8aa3b, v155
	v_pk_mul_f32 v[158:159], v[158:159], v[160:161] op_sel_hi:[1,0]
	v_exp_f32_e32 v161, v155
	v_max_f32_e32 v155, v121, v121
	v_max_f32_e32 v155, 0xc1a00000, v155
	v_mul_f32_e32 v155, 0xbfb8aa3b, v155
	v_exp_f32_e32 v160, v155
	v_max_f32_e32 v155, v122, v122
	v_max_f32_e32 v155, 0xc1a00000, v155
	v_mul_f32_e32 v155, 0xbfb8aa3b, v155
	v_exp_f32_e32 v167, v155
	v_max_f32_e32 v155, v123, v123
	v_max_f32_e32 v155, 0xc1a00000, v155
	v_mul_f32_e32 v155, 0xbfb8aa3b, v155
	v_exp_f32_e32 v166, v155
	v_pk_mul_f32 v[156:157], v[156:157], v[164:165] op_sel_hi:[1,0]
	v_pk_mul_f32 v[126:127], v[126:127], v[158:159]
	v_pk_mul_f32 v[124:125], v[124:125], v[156:157]
	v_pk_add_f32 v[156:157], v[160:161], 1.0 op_sel_hi:[1,0]
	v_pk_add_f32 v[160:161], v[166:167], 1.0 op_sel_hi:[1,0]
	v_mov_b32_e32 v164, v157
	v_mov_b32_e32 v165, v161
	v_mov_b32_e32 v166, v156
	v_mov_b32_e32 v167, v160
	v_pk_mul_f32 v[164:165], v[164:165], v[166:167]
	v_pk_mul_f32 v[118:119], v[126:127], v[118:119]
	v_mul_f32_e32 v155, v164, v165
	v_rcp_f32_e32 v155, v155
	v_pk_mul_f32 v[116:117], v[124:125], v[116:117]
	v_lshlrev_b64 v[146:147], 1, v[146:147]
	v_lshl_add_u64 v[162:163], v[162:163], 0, v[146:147]
	v_mul_f32_e32 v124, v165, v155
	v_mul_f32_e32 v126, v164, v155
	v_pk_mul_f32 v[126:127], v[160:161], v[126:127] op_sel_hi:[1,0]
	v_pk_mul_f32 v[124:125], v[156:157], v[124:125] op_sel_hi:[1,0]
	v_pk_mul_f32 v[122:123], v[122:123], v[126:127]
	v_pk_mul_f32 v[120:121], v[120:121], v[124:125]
	v_pk_mul_f32 v[122:123], v[122:123], v[114:115]
	v_pk_mul_f32 v[114:115], v[120:121], v[112:113]
; __device__ __forceinline__ unsigned cvt_pk_bf16(float lo, float hi) { unsigned r; asm volatile("v_cvt_pk_bf16_f32 %0, %1, %2" : "=v"(r) : "v"(lo), "v"(hi)); return r; }
; __device__ __forceinline__ f32x4 sigmoid4(f32x4 x) {
;     f32x4 d;
; #pragma unroll
;     for (int j = 0; j < 4; ++j) d[j] = 1.0f + __expf(-fmaxf(x[j], -20.0f));
;     const float p01 = d[0] * d[1], p23 = d[2] * d[3], r = __builtin_amdgcn_rcpf(p01 * p23), r01 = r * p23, r23 = r * p01;
;     return (f32x4){r01 * d[1], r01 * d[0], r23 * d[3], r23 * d[2]};
; }
;     __device__ __forceinline__ void operator()(const f32x4 (&acc)[2][2][4][2], const Unit& u, int wr, int wc, int fr, int fq) const {
;     ...
;             for (int m = 0; m < 4; ++m) { bf16_t* rowp = O + (size_t)(row0 + ai * HALF + m * 16) * ldc + col0;
;                 f32x4 v0, v1;
; #pragma unroll
;                 for (int j = 0; j < 1; ++j) { v0 = acc[ai][0][m][0] * sigmoid4(acc[ai][0][m][0]) * acc[ai][1][m][0]; v1 = acc[ai][0][m][1] * sigmoid4(acc[ai][0][m][1]) * acc[ai][1][m][1]; }
;                 u32x4 w; w.x = cvt_pk_bf16(v0[0], v0[1]); w.y = cvt_pk_bf16(v0[2], v0[3]); w.z = cvt_pk_bf16(v1[0], v1[1]); w.w = cvt_pk_bf16(v1[2], v1[3]);
;                 *(u32x4*)rowp = w; }
	v_cvt_pk_bf16_f32 v112, v116, v117
	v_cvt_pk_bf16_f32 v113, v118, v119
	v_max_f32_e32 v116, v108, v108
	v_max_f32_e32 v118, v110, v110
	v_max_f32_e32 v116, 0xc1a00000, v116
	v_max_f32_e32 v118, 0xc1a00000, v118
	v_mul_f32_e32 v116, 0xbfb8aa3b, v116
	v_mul_f32_e32 v118, 0xbfb8aa3b, v118
	v_exp_f32_e32 v117, v116
	v_max_f32_e32 v116, v109, v109
	v_exp_f32_e32 v119, v118
	v_max_f32_e32 v118, v111, v111
	v_max_f32_e32 v116, 0xc1a00000, v116
	v_max_f32_e32 v118, 0xc1a00000, v118
	v_mul_f32_e32 v116, 0xbfb8aa3b, v116
	v_mul_f32_e32 v118, 0xbfb8aa3b, v118
	v_exp_f32_e32 v116, v116
	v_exp_f32_e32 v118, v118
	v_cvt_pk_bf16_f32 v114, v114, v115
	v_cvt_pk_bf16_f32 v115, v122, v123
	global_store_dwordx4 v[162:163], v[112:115], off
	v_or_b32_e32 v120, 16, v154
	s_and_b64 vcc, exec, s[2:3]
	v_pk_add_f32 v[112:113], v[116:117], 1.0 op_sel_hi:[1,0]
	v_pk_add_f32 v[114:115], v[118:119], 1.0 op_sel_hi:[1,0]
	v_mov_b32_e32 v116, v113
	v_mov_b32_e32 v117, v115
	v_mov_b32_e32 v118, v112
	v_mov_b32_e32 v119, v114
	v_pk_mul_f32 v[116:117], v[116:117], v[118:119]
	s_mov_b32 s41, s6
	v_mul_f32_e32 v118, v116, v117
	v_rcp_f32_e32 v121, v118
	v_mad_i64_i32 v[118:119], s[16:17], v120, s40, v[144:145]
	v_lshl_add_u64 v[118:119], v[118:119], 0, v[146:147]
	v_mul_f32_e32 v116, v116, v121
	v_mul_f32_e32 v120, v117, v121
	v_pk_mul_f32 v[114:115], v[114:115], v[116:117] op_sel_hi:[1,0]
	v_max_f32_e32 v116, v104, v104
	v_max_f32_e32 v121, v106, v106
	v_max_f32_e32 v116, 0xc1a00000, v116
	v_max_f32_e32 v121, 0xc1a00000, v121
	v_mul_f32_e32 v116, 0xbfb8aa3b, v116
	v_mul_f32_e32 v121, 0xbfb8aa3b, v121
	v_exp_f32_e32 v117, v116
	v_max_f32_e32 v116, v105, v105
	v_exp_f32_e32 v123, v121
	v_max_f32_e32 v121, v107, v107
	v_max_f32_e32 v116, 0xc1a00000, v116
	v_max_f32_e32 v121, 0xc1a00000, v121
	v_mul_f32_e32 v116, 0xbfb8aa3b, v116
	v_mul_f32_e32 v121, 0xbfb8aa3b, v121
	v_exp_f32_e32 v116, v116
	v_exp_f32_e32 v122, v121
	v_pk_mul_f32 v[112:113], v[112:113], v[120:121] op_sel_hi:[1,0]
	v_pk_mul_f32 v[110:111], v[110:111], v[114:115]
	v_pk_mul_f32 v[108:109], v[108:109], v[112:113]
	v_pk_add_f32 v[112:113], v[116:117], 1.0 op_sel_hi:[1,0]
	v_pk_add_f32 v[116:117], v[122:123], 1.0 op_sel_hi:[1,0]
	v_mov_b32_e32 v120, v113
	v_mov_b32_e32 v121, v117
	v_mov_b32_e32 v122, v112
	v_mov_b32_e32 v123, v116
	v_pk_mul_f32 v[120:121], v[120:121], v[122:123]
	v_pk_mul_f32 v[102:103], v[110:111], v[102:103]
	v_mul_f32_e32 v122, v120, v121
	v_rcp_f32_e32 v122, v122
	v_pk_mul_f32 v[100:101], v[108:109], v[100:101]
	s_mov_b32 s14, s8
	s_mov_b64 s[18:19], s[12:13]
	v_mul_f32_e32 v108, v121, v122
	v_mul_f32_e32 v110, v120, v122
	v_pk_mul_f32 v[110:111], v[116:117], v[110:111] op_sel_hi:[1,0]
	v_pk_mul_f32 v[108:109], v[112:113], v[108:109] op_sel_hi:[1,0]
	v_pk_mul_f32 v[106:107], v[106:107], v[110:111]
	v_pk_mul_f32 v[104:105], v[104:105], v[108:109]
	v_pk_mul_f32 v[106:107], v[106:107], v[98:99]
	v_pk_mul_f32 v[98:99], v[104:105], v[96:97]
	v_cvt_pk_bf16_f32 v96, v100, v101
	v_cvt_pk_bf16_f32 v97, v102, v103
	v_max_f32_e32 v100, v92, v92
	v_max_f32_e32 v102, v94, v94
	v_max_f32_e32 v100, 0xc1a00000, v100
	v_max_f32_e32 v102, 0xc1a00000, v102
	v_mul_f32_e32 v100, 0xbfb8aa3b, v100
	v_mul_f32_e32 v102, 0xbfb8aa3b, v102
	v_exp_f32_e32 v101, v100
	v_max_f32_e32 v100, v93, v93
	v_exp_f32_e32 v103, v102
	v_max_f32_e32 v102, v95, v95
	v_max_f32_e32 v100, 0xc1a00000, v100
	v_max_f32_e32 v102, 0xc1a00000, v102
	v_mul_f32_e32 v100, 0xbfb8aa3b, v100
	v_mul_f32_e32 v102, 0xbfb8aa3b, v102
	v_exp_f32_e32 v100, v100
	v_exp_f32_e32 v102, v102
	v_cvt_pk_bf16_f32 v98, v98, v99
	v_cvt_pk_bf16_f32 v99, v106, v107
	global_store_dwordx4 v[118:119], v[96:99], off
	v_or_b32_e32 v104, 32, v154
	s_nop 0
	v_pk_add_f32 v[96:97], v[100:101], 1.0 op_sel_hi:[1,0]
	v_pk_add_f32 v[98:99], v[102:103], 1.0 op_sel_hi:[1,0]
	v_mov_b32_e32 v100, v97
	v_mov_b32_e32 v101, v99
	v_mov_b32_e32 v102, v96
	v_mov_b32_e32 v103, v98
	v_pk_mul_f32 v[100:101], v[100:101], v[102:103]
	s_nop 0
	v_mul_f32_e32 v102, v100, v101
	v_rcp_f32_e32 v105, v102
	v_mad_i64_i32 v[102:103], s[16:17], v104, s40, v[144:145]
	v_lshl_add_u64 v[102:103], v[102:103], 0, v[146:147]
	v_mul_f32_e32 v100, v100, v105
	v_mul_f32_e32 v104, v101, v105
	v_pk_mul_f32 v[98:99], v[98:99], v[100:101] op_sel_hi:[1,0]
	v_max_f32_e32 v100, v88, v88
	v_max_f32_e32 v105, v90, v90
	v_max_f32_e32 v100, 0xc1a00000, v100
	v_max_f32_e32 v105, 0xc1a00000, v105
	v_mul_f32_e32 v100, 0xbfb8aa3b, v100
	v_mul_f32_e32 v105, 0xbfb8aa3b, v105
	v_exp_f32_e32 v101, v100
	v_max_f32_e32 v100, v89, v89
	v_exp_f32_e32 v107, v105
	v_max_f32_e32 v105, v91, v91
	v_max_f32_e32 v100, 0xc1a00000, v100
	v_max_f32_e32 v105, 0xc1a00000, v105
	v_mul_f32_e32 v100, 0xbfb8aa3b, v100
	v_mul_f32_e32 v105, 0xbfb8aa3b, v105
	v_exp_f32_e32 v100, v100
	v_exp_f32_e32 v106, v105
	v_pk_mul_f32 v[96:97], v[96:97], v[104:105] op_sel_hi:[1,0]
	v_pk_mul_f32 v[94:95], v[94:95], v[98:99]
	v_pk_mul_f32 v[92:93], v[92:93], v[96:97]
	v_pk_add_f32 v[96:97], v[100:101], 1.0 op_sel_hi:[1,0]
	v_pk_add_f32 v[100:101], v[106:107], 1.0 op_sel_hi:[1,0]
	v_mov_b32_e32 v104, v97
	v_mov_b32_e32 v105, v101
	v_mov_b32_e32 v106, v96
	v_mov_b32_e32 v107, v100
	v_pk_mul_f32 v[104:105], v[104:105], v[106:107]
	v_pk_mul_f32 v[86:87], v[94:95], v[86:87]
	v_mul_f32_e32 v106, v104, v105
	v_rcp_f32_e32 v106, v106
	v_pk_mul_f32 v[84:85], v[92:93], v[84:85]
	v_mul_f32_e32 v92, v105, v106
	v_mul_f32_e32 v94, v104, v106
	v_pk_mul_f32 v[94:95], v[100:101], v[94:95] op_sel_hi:[1,0]
	v_pk_mul_f32 v[92:93], v[96:97], v[92:93] op_sel_hi:[1,0]
	v_pk_mul_f32 v[90:91], v[90:91], v[94:95]
	v_pk_mul_f32 v[88:89], v[88:89], v[92:93]
	v_pk_mul_f32 v[90:91], v[90:91], v[82:83]
; __device__ __forceinline__ unsigned cvt_pk_bf16(float lo, float hi) { unsigned r; asm volatile("v_cvt_pk_bf16_f32 %0, %1, %2" : "=v"(r) : "v"(lo), "v"(hi)); return r; }
; __device__ __forceinline__ f32x4 sigmoid4(f32x4 x) {
;     f32x4 d;
; #pragma unroll
;     for (int j = 0; j < 4; ++j) d[j] = 1.0f + __expf(-fmaxf(x[j], -20.0f));
;     const float p01 = d[0] * d[1], p23 = d[2] * d[3], r = __builtin_amdgcn_rcpf(p01 * p23), r01 = r * p23, r23 = r * p01;
;     return (f32x4){r01 * d[1], r01 * d[0], r23 * d[3], r23 * d[2]};
; }
;     __device__ __forceinline__ void operator()(const f32x4 (&acc)[2][2][4][2], const Unit& u, int wr, int wc, int fr, int fq) const {
;     ...
;             for (int m = 0; m < 4; ++m) { bf16_t* rowp = O + (size_t)(row0 + ai * HALF + m * 16) * ldc + col0;
;                 f32x4 v0, v1;
; #pragma unroll
;                 for (int j = 0; j < 1; ++j) { v0 = acc[ai][0][m][0] * sigmoid4(acc[ai][0][m][0]) * acc[ai][1][m][0]; v1 = acc[ai][0][m][1] * sigmoid4(acc[ai][0][m][1]) * acc[ai][1][m][1]; }
;                 u32x4 w; w.x = cvt_pk_bf16(v0[0], v0[1]); w.y = cvt_pk_bf16(v0[2], v0[3]); w.z = cvt_pk_bf16(v1[0], v1[1]); w.w = cvt_pk_bf16(v1[2], v1[3]);
;                 *(u32x4*)rowp = w; }
	v_pk_mul_f32 v[82:83], v[88:89], v[80:81]
	v_cvt_pk_bf16_f32 v80, v84, v85
	v_cvt_pk_bf16_f32 v81, v86, v87
	v_max_f32_e32 v84, v76, v76
	v_max_f32_e32 v86, v78, v78
	v_max_f32_e32 v84, 0xc1a00000, v84
	v_max_f32_e32 v86, 0xc1a00000, v86
	v_mul_f32_e32 v84, 0xbfb8aa3b, v84
	v_mul_f32_e32 v86, 0xbfb8aa3b, v86
	v_exp_f32_e32 v85, v84
	v_max_f32_e32 v84, v77, v77
	v_exp_f32_e32 v87, v86
	v_max_f32_e32 v86, v79, v79
	v_max_f32_e32 v84, 0xc1a00000, v84
	v_max_f32_e32 v86, 0xc1a00000, v86
	v_mul_f32_e32 v84, 0xbfb8aa3b, v84
	v_mul_f32_e32 v86, 0xbfb8aa3b, v86
	v_exp_f32_e32 v84, v84
	v_exp_f32_e32 v86, v86
	v_cvt_pk_bf16_f32 v82, v82, v83
	v_cvt_pk_bf16_f32 v83, v90, v91
	global_store_dwordx4 v[102:103], v[80:83], off
	v_or_b32_e32 v88, 48, v154
	s_nop 0
	v_pk_add_f32 v[80:81], v[84:85], 1.0 op_sel_hi:[1,0]
	v_pk_add_f32 v[82:83], v[86:87], 1.0 op_sel_hi:[1,0]
	v_mov_b32_e32 v84, v81
	v_mov_b32_e32 v85, v83
	v_mov_b32_e32 v86, v80
	v_mov_b32_e32 v87, v82
	v_pk_mul_f32 v[84:85], v[84:85], v[86:87]
	s_nop 0
	v_mul_f32_e32 v86, v84, v85
	v_rcp_f32_e32 v89, v86
	v_mad_i64_i32 v[86:87], s[16:17], v88, s40, v[144:145]
	v_lshl_add_u64 v[86:87], v[86:87], 0, v[146:147]
	v_mul_f32_e32 v84, v84, v89
	v_mul_f32_e32 v88, v85, v89
	v_pk_mul_f32 v[82:83], v[82:83], v[84:85] op_sel_hi:[1,0]
	v_max_f32_e32 v84, v72, v72
	v_max_f32_e32 v89, v74, v74
	v_max_f32_e32 v84, 0xc1a00000, v84
	v_max_f32_e32 v89, 0xc1a00000, v89
	v_mul_f32_e32 v84, 0xbfb8aa3b, v84
	v_mul_f32_e32 v89, 0xbfb8aa3b, v89
	v_exp_f32_e32 v85, v84
	v_max_f32_e32 v84, v73, v73
	v_exp_f32_e32 v91, v89
	v_max_f32_e32 v89, v75, v75
	v_max_f32_e32 v84, 0xc1a00000, v84
	v_max_f32_e32 v89, 0xc1a00000, v89
	v_mul_f32_e32 v84, 0xbfb8aa3b, v84
	v_mul_f32_e32 v89, 0xbfb8aa3b, v89
	v_exp_f32_e32 v84, v84
	v_exp_f32_e32 v90, v89
	v_pk_mul_f32 v[80:81], v[80:81], v[88:89] op_sel_hi:[1,0]
	v_pk_mul_f32 v[78:79], v[78:79], v[82:83]
	v_pk_mul_f32 v[76:77], v[76:77], v[80:81]
	v_pk_add_f32 v[80:81], v[84:85], 1.0 op_sel_hi:[1,0]
	v_pk_add_f32 v[84:85], v[90:91], 1.0 op_sel_hi:[1,0]
	v_mov_b32_e32 v88, v81
	v_mov_b32_e32 v89, v85
	v_mov_b32_e32 v90, v80
	v_mov_b32_e32 v91, v84
	v_pk_mul_f32 v[88:89], v[88:89], v[90:91]
	v_pk_mul_f32 v[70:71], v[78:79], v[70:71]
	v_mul_f32_e32 v90, v88, v89
	v_rcp_f32_e32 v90, v90
	v_pk_mul_f32 v[68:69], v[76:77], v[68:69]
	v_mul_f32_e32 v76, v89, v90
	v_mul_f32_e32 v78, v88, v90
	v_pk_mul_f32 v[78:79], v[84:85], v[78:79] op_sel_hi:[1,0]
	v_pk_mul_f32 v[76:77], v[80:81], v[76:77] op_sel_hi:[1,0]
	v_pk_mul_f32 v[74:75], v[74:75], v[78:79]
	v_pk_mul_f32 v[72:73], v[72:73], v[76:77]
	v_pk_mul_f32 v[74:75], v[74:75], v[66:67]
	v_pk_mul_f32 v[66:67], v[72:73], v[64:65]
	v_cvt_pk_bf16_f32 v64, v68, v69
	v_cvt_pk_bf16_f32 v65, v70, v71
	v_max_f32_e32 v68, v60, v60
	v_max_f32_e32 v70, v62, v62
	v_max_f32_e32 v68, 0xc1a00000, v68
	v_max_f32_e32 v70, 0xc1a00000, v70
	v_mul_f32_e32 v68, 0xbfb8aa3b, v68
	v_mul_f32_e32 v70, 0xbfb8aa3b, v70
	v_exp_f32_e32 v69, v68
	v_max_f32_e32 v68, v61, v61
	v_exp_f32_e32 v71, v70
	v_max_f32_e32 v70, v63, v63
	v_max_f32_e32 v68, 0xc1a00000, v68
	v_max_f32_e32 v70, 0xc1a00000, v70
	v_mul_f32_e32 v68, 0xbfb8aa3b, v68
	v_mul_f32_e32 v70, 0xbfb8aa3b, v70
	v_exp_f32_e32 v68, v68
	v_exp_f32_e32 v70, v70
	v_cvt_pk_bf16_f32 v66, v66, v67
	v_cvt_pk_bf16_f32 v67, v74, v75
	global_store_dwordx4 v[86:87], v[64:67], off
	v_add_u32_e32 v72, 0x80, v154
	s_nop 0
	v_pk_add_f32 v[64:65], v[68:69], 1.0 op_sel_hi:[1,0]
	v_pk_add_f32 v[66:67], v[70:71], 1.0 op_sel_hi:[1,0]
	v_mov_b32_e32 v68, v65
	v_mov_b32_e32 v69, v67
	v_mov_b32_e32 v70, v64
	v_mov_b32_e32 v71, v66
	v_pk_mul_f32 v[68:69], v[68:69], v[70:71]
	s_nop 0
	v_mul_f32_e32 v70, v68, v69
	v_rcp_f32_e32 v73, v70
	v_mad_i64_i32 v[70:71], s[16:17], v72, s40, v[144:145]
	v_lshl_add_u64 v[70:71], v[70:71], 0, v[146:147]
	v_mul_f32_e32 v68, v68, v73
	v_mul_f32_e32 v72, v69, v73
	v_pk_mul_f32 v[66:67], v[66:67], v[68:69] op_sel_hi:[1,0]
	v_max_f32_e32 v68, v56, v56
	v_max_f32_e32 v73, v58, v58
	v_max_f32_e32 v68, 0xc1a00000, v68
	v_max_f32_e32 v73, 0xc1a00000, v73
	v_mul_f32_e32 v68, 0xbfb8aa3b, v68
	v_mul_f32_e32 v73, 0xbfb8aa3b, v73
	v_exp_f32_e32 v69, v68
	v_max_f32_e32 v68, v57, v57
	v_exp_f32_e32 v75, v73
	v_max_f32_e32 v73, v59, v59
	v_max_f32_e32 v68, 0xc1a00000, v68
	v_max_f32_e32 v73, 0xc1a00000, v73
	v_mul_f32_e32 v68, 0xbfb8aa3b, v68
	v_mul_f32_e32 v73, 0xbfb8aa3b, v73
	v_exp_f32_e32 v68, v68
	v_exp_f32_e32 v74, v73
	v_pk_mul_f32 v[64:65], v[64:65], v[72:73] op_sel_hi:[1,0]
	v_pk_mul_f32 v[62:63], v[62:63], v[66:67]
	v_pk_mul_f32 v[60:61], v[60:61], v[64:65]
	v_pk_add_f32 v[64:65], v[68:69], 1.0 op_sel_hi:[1,0]
	v_pk_add_f32 v[68:69], v[74:75], 1.0 op_sel_hi:[1,0]
	v_mov_b32_e32 v72, v65
	v_mov_b32_e32 v73, v69
	v_mov_b32_e32 v74, v64
	v_mov_b32_e32 v75, v68
	v_pk_mul_f32 v[72:73], v[72:73], v[74:75]
	v_pk_mul_f32 v[54:55], v[62:63], v[54:55]
	v_mul_f32_e32 v74, v72, v73
	v_rcp_f32_e32 v74, v74
	v_pk_mul_f32 v[52:53], v[60:61], v[52:53]
	v_mul_f32_e32 v60, v73, v74
	v_mul_f32_e32 v62, v72, v74
	v_pk_mul_f32 v[62:63], v[68:69], v[62:63] op_sel_hi:[1,0]
	v_pk_mul_f32 v[60:61], v[64:65], v[60:61] op_sel_hi:[1,0]
	v_pk_mul_f32 v[58:59], v[58:59], v[62:63]
	v_pk_mul_f32 v[56:57], v[56:57], v[60:61]
	v_pk_mul_f32 v[58:59], v[58:59], v[50:51]
	v_pk_mul_f32 v[50:51], v[56:57], v[48:49]
	v_cvt_pk_bf16_f32 v48, v52, v53
	v_cvt_pk_bf16_f32 v49, v54, v55
	v_max_f32_e32 v52, v44, v44
	v_max_f32_e32 v54, v46, v46
	v_max_f32_e32 v52, 0xc1a00000, v52
	v_max_f32_e32 v54, 0xc1a00000, v54
	v_mul_f32_e32 v52, 0xbfb8aa3b, v52
	v_mul_f32_e32 v54, 0xbfb8aa3b, v54
	v_exp_f32_e32 v53, v52
	v_max_f32_e32 v52, v45, v45
	v_exp_f32_e32 v55, v54
; __device__ __forceinline__ unsigned cvt_pk_bf16(float lo, float hi) { unsigned r; asm volatile("v_cvt_pk_bf16_f32 %0, %1, %2" : "=v"(r) : "v"(lo), "v"(hi)); return r; }
; __device__ __forceinline__ f32x4 sigmoid4(f32x4 x) {
;     f32x4 d;
; #pragma unroll
;     for (int j = 0; j < 4; ++j) d[j] = 1.0f + __expf(-fmaxf(x[j], -20.0f));
;     const float p01 = d[0] * d[1], p23 = d[2] * d[3], r = __builtin_amdgcn_rcpf(p01 * p23), r01 = r * p23, r23 = r * p01;
;     return (f32x4){r01 * d[1], r01 * d[0], r23 * d[3], r23 * d[2]};
; }
;     __device__ __forceinline__ void operator()(const f32x4 (&acc)[2][2][4][2], const Unit& u, int wr, int wc, int fr, int fq) const {
;     ...
;             for (int m = 0; m < 4; ++m) { bf16_t* rowp = O + (size_t)(row0 + ai * HALF + m * 16) * ldc + col0;
;                 f32x4 v0, v1;
; #pragma unroll
;                 for (int j = 0; j < 1; ++j) { v0 = acc[ai][0][m][0] * sigmoid4(acc[ai][0][m][0]) * acc[ai][1][m][0]; v1 = acc[ai][0][m][1] * sigmoid4(acc[ai][0][m][1]) * acc[ai][1][m][1]; }
;                 u32x4 w; w.x = cvt_pk_bf16(v0[0], v0[1]); w.y = cvt_pk_bf16(v0[2], v0[3]); w.z = cvt_pk_bf16(v1[0], v1[1]); w.w = cvt_pk_bf16(v1[2], v1[3]);
;                 *(u32x4*)rowp = w; }
	v_max_f32_e32 v54, v47, v47
	v_max_f32_e32 v52, 0xc1a00000, v52
	v_max_f32_e32 v54, 0xc1a00000, v54
	v_mul_f32_e32 v52, 0xbfb8aa3b, v52
	v_mul_f32_e32 v54, 0xbfb8aa3b, v54
	v_exp_f32_e32 v52, v52
	v_exp_f32_e32 v54, v54
	v_cvt_pk_bf16_f32 v50, v50, v51
	v_cvt_pk_bf16_f32 v51, v58, v59
	global_store_dwordx4 v[70:71], v[48:51], off
	v_add_u32_e32 v56, 0x90, v154
	s_nop 0
	v_pk_add_f32 v[48:49], v[52:53], 1.0 op_sel_hi:[1,0]
	v_pk_add_f32 v[50:51], v[54:55], 1.0 op_sel_hi:[1,0]
	v_mov_b32_e32 v52, v49
	v_mov_b32_e32 v53, v51
	v_mov_b32_e32 v54, v48
	v_mov_b32_e32 v55, v50
	v_pk_mul_f32 v[52:53], v[52:53], v[54:55]
	s_nop 0
	v_mul_f32_e32 v54, v52, v53
	v_rcp_f32_e32 v57, v54
	v_mad_i64_i32 v[54:55], s[16:17], v56, s40, v[144:145]
	v_lshl_add_u64 v[54:55], v[54:55], 0, v[146:147]
	v_mul_f32_e32 v52, v52, v57
	v_mul_f32_e32 v56, v53, v57
	v_pk_mul_f32 v[50:51], v[50:51], v[52:53] op_sel_hi:[1,0]
	v_max_f32_e32 v52, v40, v40
	v_max_f32_e32 v57, v42, v42
	v_max_f32_e32 v52, 0xc1a00000, v52
	v_max_f32_e32 v57, 0xc1a00000, v57
	v_mul_f32_e32 v52, 0xbfb8aa3b, v52
	v_mul_f32_e32 v57, 0xbfb8aa3b, v57
	v_exp_f32_e32 v53, v52
	v_max_f32_e32 v52, v41, v41
	v_exp_f32_e32 v59, v57
	v_max_f32_e32 v57, v43, v43
	v_max_f32_e32 v52, 0xc1a00000, v52
	v_max_f32_e32 v57, 0xc1a00000, v57
	v_mul_f32_e32 v52, 0xbfb8aa3b, v52
	v_mul_f32_e32 v57, 0xbfb8aa3b, v57
	v_exp_f32_e32 v52, v52
	v_exp_f32_e32 v58, v57
	v_pk_mul_f32 v[48:49], v[48:49], v[56:57] op_sel_hi:[1,0]
	v_pk_mul_f32 v[46:47], v[46:47], v[50:51]
	v_pk_mul_f32 v[44:45], v[44:45], v[48:49]
	v_pk_add_f32 v[48:49], v[52:53], 1.0 op_sel_hi:[1,0]
	v_pk_add_f32 v[52:53], v[58:59], 1.0 op_sel_hi:[1,0]
	v_mov_b32_e32 v56, v49
	v_mov_b32_e32 v57, v53
	v_mov_b32_e32 v58, v48
	v_mov_b32_e32 v59, v52
	v_pk_mul_f32 v[56:57], v[56:57], v[58:59]
	v_pk_mul_f32 v[38:39], v[46:47], v[38:39]
	v_mul_f32_e32 v58, v56, v57
	v_rcp_f32_e32 v58, v58
	v_pk_mul_f32 v[36:37], v[44:45], v[36:37]
	v_mul_f32_e32 v44, v57, v58
	v_mul_f32_e32 v46, v56, v58
	v_pk_mul_f32 v[46:47], v[52:53], v[46:47] op_sel_hi:[1,0]
	v_pk_mul_f32 v[44:45], v[48:49], v[44:45] op_sel_hi:[1,0]
	v_pk_mul_f32 v[42:43], v[42:43], v[46:47]
	v_pk_mul_f32 v[40:41], v[40:41], v[44:45]
	v_pk_mul_f32 v[42:43], v[42:43], v[34:35]
	v_pk_mul_f32 v[34:35], v[40:41], v[32:33]
	v_cvt_pk_bf16_f32 v32, v36, v37
	v_cvt_pk_bf16_f32 v33, v38, v39
	v_max_f32_e32 v36, v28, v28
	v_max_f32_e32 v38, v30, v30
	v_max_f32_e32 v36, 0xc1a00000, v36
	v_max_f32_e32 v38, 0xc1a00000, v38
	v_mul_f32_e32 v36, 0xbfb8aa3b, v36
	v_mul_f32_e32 v38, 0xbfb8aa3b, v38
	v_exp_f32_e32 v37, v36
	v_max_f32_e32 v36, v29, v29
	v_exp_f32_e32 v39, v38
	v_max_f32_e32 v38, v31, v31
	v_max_f32_e32 v36, 0xc1a00000, v36
	v_max_f32_e32 v38, 0xc1a00000, v38
	v_mul_f32_e32 v36, 0xbfb8aa3b, v36
	v_mul_f32_e32 v38, 0xbfb8aa3b, v38
	v_exp_f32_e32 v36, v36
	v_exp_f32_e32 v38, v38
	v_cvt_pk_bf16_f32 v34, v34, v35
	v_cvt_pk_bf16_f32 v35, v42, v43
	global_store_dwordx4 v[54:55], v[32:35], off
	v_add_u32_e32 v40, 0xa0, v154
	s_nop 0
	v_pk_add_f32 v[32:33], v[36:37], 1.0 op_sel_hi:[1,0]
	v_pk_add_f32 v[34:35], v[38:39], 1.0 op_sel_hi:[1,0]
	v_mov_b32_e32 v36, v33
	v_mov_b32_e32 v37, v35
	v_mov_b32_e32 v38, v32
	v_mov_b32_e32 v39, v34
	v_pk_mul_f32 v[36:37], v[36:37], v[38:39]
	s_nop 0
	v_mul_f32_e32 v38, v36, v37
	v_rcp_f32_e32 v41, v38
	v_mad_i64_i32 v[38:39], s[16:17], v40, s40, v[144:145]
	v_lshl_add_u64 v[38:39], v[38:39], 0, v[146:147]
	v_mul_f32_e32 v36, v36, v41
	v_mul_f32_e32 v40, v37, v41
	v_pk_mul_f32 v[34:35], v[34:35], v[36:37] op_sel_hi:[1,0]
	v_max_f32_e32 v36, v24, v24
	v_max_f32_e32 v41, v26, v26
	v_max_f32_e32 v36, 0xc1a00000, v36
	v_max_f32_e32 v41, 0xc1a00000, v41
	v_mul_f32_e32 v36, 0xbfb8aa3b, v36
	v_mul_f32_e32 v41, 0xbfb8aa3b, v41
	v_exp_f32_e32 v37, v36
	v_max_f32_e32 v36, v25, v25
	v_exp_f32_e32 v43, v41
	v_max_f32_e32 v41, v27, v27
	v_max_f32_e32 v36, 0xc1a00000, v36
	v_max_f32_e32 v41, 0xc1a00000, v41
; __device__ __forceinline__ unsigned cvt_pk_bf16(float lo, float hi) { unsigned r; asm volatile("v_cvt_pk_bf16_f32 %0, %1, %2" : "=v"(r) : "v"(lo), "v"(hi)); return r; }
; #define PG8_WAIT_V(n) asm volatile("s_waitcnt vmcnt(" #n ")" ::: "memory")
; #define PG8_BAR __builtin_amdgcn_s_barrier()
; __device__ __forceinline__ f32x4 sigmoid4(f32x4 x) {
;     f32x4 d;
; #pragma unroll
;     for (int j = 0; j < 4; ++j) d[j] = 1.0f + __expf(-fmaxf(x[j], -20.0f));
;     const float p01 = d[0] * d[1], p23 = d[2] * d[3], r = __builtin_amdgcn_rcpf(p01 * p23), r01 = r * p23, r23 = r * p01;
;     return (f32x4){r01 * d[1], r01 * d[0], r23 * d[3], r23 * d[2]};
; }
;     __device__ __forceinline__ void operator()(const f32x4 (&acc)[2][2][4][2], const Unit& u, int wr, int wc, int fr, int fq) const {
;     ...
;             for (int m = 0; m < 4; ++m) { bf16_t* rowp = O + (size_t)(row0 + ai * HALF + m * 16) * ldc + col0;
;                 f32x4 v0, v1;
; #pragma unroll
;                 for (int j = 0; j < 1; ++j) { v0 = acc[ai][0][m][0] * sigmoid4(acc[ai][0][m][0]) * acc[ai][1][m][0]; v1 = acc[ai][0][m][1] * sigmoid4(acc[ai][0][m][1]) * acc[ai][1][m][1]; }
;                 u32x4 w; w.x = cvt_pk_bf16(v0[0], v0[1]); w.y = cvt_pk_bf16(v0[2], v0[3]); w.z = cvt_pk_bf16(v1[0], v1[1]); w.w = cvt_pk_bf16(v1[2], v1[3]);
;                 *(u32x4*)rowp = w; }
; template <class Epi, class Sched>
; __device__ __forceinline__ void gemm_phase(PG8_LAS unsigned char* lds, const Gemm g, const Sched& S, const Epi& E) {
;     ...
;         if (!has_next) break;
; #pragma unroll
;         for (int a = 0; a < 2; ++a)
; #pragma unroll
;             for (int b = 0; b < 2; ++b)
; #pragma unroll
;                 for (int m = 0; m < 4; ++m)
; #pragma unroll
;                     for (int n = 0; n < 2; ++n) acc[a][b][m][n] = (f32x4){0.f, 0.f, 0.f, 0.f};
;         cur = nxt; cA = nA; cB = nB; ++ui;
;     }
;     PG8_WAIT_V(0);
;     if (wr == 0) PG8_BAR;
;     PG8_BAR;
	v_mul_f32_e32 v36, 0xbfb8aa3b, v36
	v_mul_f32_e32 v41, 0xbfb8aa3b, v41
	v_exp_f32_e32 v36, v36
	v_exp_f32_e32 v42, v41
	v_pk_mul_f32 v[32:33], v[32:33], v[40:41] op_sel_hi:[1,0]
	v_pk_mul_f32 v[30:31], v[30:31], v[34:35]
	v_pk_mul_f32 v[28:29], v[28:29], v[32:33]
	v_pk_add_f32 v[32:33], v[36:37], 1.0 op_sel_hi:[1,0]
	v_pk_add_f32 v[36:37], v[42:43], 1.0 op_sel_hi:[1,0]
	v_mov_b32_e32 v40, v33
	v_mov_b32_e32 v41, v37
	v_mov_b32_e32 v42, v32
	v_mov_b32_e32 v43, v36
	v_pk_mul_f32 v[40:41], v[40:41], v[42:43]
	v_pk_mul_f32 v[22:23], v[30:31], v[22:23]
	v_mul_f32_e32 v42, v40, v41
	v_rcp_f32_e32 v42, v42
	v_pk_mul_f32 v[20:21], v[28:29], v[20:21]
	v_mul_f32_e32 v28, v41, v42
	v_mul_f32_e32 v30, v40, v42
	v_pk_mul_f32 v[30:31], v[36:37], v[30:31] op_sel_hi:[1,0]
	v_pk_mul_f32 v[28:29], v[32:33], v[28:29] op_sel_hi:[1,0]
	v_pk_mul_f32 v[26:27], v[26:27], v[30:31]
	v_pk_mul_f32 v[24:25], v[24:25], v[28:29]
	v_pk_mul_f32 v[26:27], v[26:27], v[18:19]
	v_pk_mul_f32 v[18:19], v[24:25], v[16:17]
	v_cvt_pk_bf16_f32 v16, v20, v21
	v_cvt_pk_bf16_f32 v17, v22, v23
	v_max_f32_e32 v20, v12, v12
	v_max_f32_e32 v22, v14, v14
	v_max_f32_e32 v20, 0xc1a00000, v20
	v_max_f32_e32 v22, 0xc1a00000, v22
	v_mul_f32_e32 v20, 0xbfb8aa3b, v20
	v_mul_f32_e32 v22, 0xbfb8aa3b, v22
	v_exp_f32_e32 v21, v20
	v_max_f32_e32 v20, v13, v13
	v_exp_f32_e32 v23, v22
	v_max_f32_e32 v22, v15, v15
	v_max_f32_e32 v20, 0xc1a00000, v20
	v_max_f32_e32 v22, 0xc1a00000, v22
	v_mul_f32_e32 v20, 0xbfb8aa3b, v20
	v_mul_f32_e32 v22, 0xbfb8aa3b, v22
	v_exp_f32_e32 v20, v20
	v_exp_f32_e32 v22, v22
	v_cvt_pk_bf16_f32 v18, v18, v19
	v_cvt_pk_bf16_f32 v19, v26, v27
	global_store_dwordx4 v[38:39], v[16:19], off
	v_add_u32_e32 v24, 0xb0, v154
	s_nop 0
	v_pk_add_f32 v[16:17], v[20:21], 1.0 op_sel_hi:[1,0]
	v_pk_add_f32 v[18:19], v[22:23], 1.0 op_sel_hi:[1,0]
	v_mov_b32_e32 v20, v17
	v_mov_b32_e32 v21, v19
	v_mov_b32_e32 v22, v16
	v_mov_b32_e32 v23, v18
	v_pk_mul_f32 v[20:21], v[20:21], v[22:23]
	s_nop 0
	v_mul_f32_e32 v22, v20, v21
	v_rcp_f32_e32 v25, v22
	v_mad_i64_i32 v[22:23], s[16:17], v24, s40, v[144:145]
	v_lshl_add_u64 v[22:23], v[22:23], 0, v[146:147]
	v_mul_f32_e32 v20, v20, v25
	v_mul_f32_e32 v24, v21, v25
	v_pk_mul_f32 v[18:19], v[18:19], v[20:21] op_sel_hi:[1,0]
	v_max_f32_e32 v20, v8, v8
	v_max_f32_e32 v25, v10, v10
	v_max_f32_e32 v20, 0xc1a00000, v20
	v_max_f32_e32 v25, 0xc1a00000, v25
	v_mul_f32_e32 v20, 0xbfb8aa3b, v20
	v_mul_f32_e32 v25, 0xbfb8aa3b, v25
	v_exp_f32_e32 v21, v20
	v_max_f32_e32 v20, v9, v9
	v_exp_f32_e32 v27, v25
	v_max_f32_e32 v25, v11, v11
	v_max_f32_e32 v20, 0xc1a00000, v20
	v_max_f32_e32 v25, 0xc1a00000, v25
	v_mul_f32_e32 v20, 0xbfb8aa3b, v20
	v_mul_f32_e32 v25, 0xbfb8aa3b, v25
	v_exp_f32_e32 v20, v20
	v_exp_f32_e32 v26, v25
	v_pk_mul_f32 v[16:17], v[16:17], v[24:25] op_sel_hi:[1,0]
	v_pk_mul_f32 v[14:15], v[14:15], v[18:19]
	v_pk_mul_f32 v[12:13], v[12:13], v[16:17]
	v_pk_add_f32 v[16:17], v[20:21], 1.0 op_sel_hi:[1,0]
	v_pk_add_f32 v[20:21], v[26:27], 1.0 op_sel_hi:[1,0]
	v_mov_b32_e32 v24, v17
	v_mov_b32_e32 v25, v21
	v_mov_b32_e32 v26, v16
	v_mov_b32_e32 v27, v20
	v_pk_mul_f32 v[24:25], v[24:25], v[26:27]
	v_pk_mul_f32 v[6:7], v[14:15], v[6:7]
	v_mul_f32_e32 v26, v24, v25
	v_rcp_f32_e32 v26, v26
	v_pk_mul_f32 v[4:5], v[12:13], v[4:5]
	s_mov_b64 s[16:17], s[10:11]
	v_mul_f32_e32 v12, v25, v26
	v_mul_f32_e32 v14, v24, v26
	v_pk_mul_f32 v[14:15], v[20:21], v[14:15] op_sel_hi:[1,0]
	v_pk_mul_f32 v[12:13], v[16:17], v[12:13] op_sel_hi:[1,0]
	v_pk_mul_f32 v[10:11], v[10:11], v[14:15]
	v_pk_mul_f32 v[8:9], v[8:9], v[12:13]
	v_pk_mul_f32 v[10:11], v[10:11], v[2:3]
	v_pk_mul_f32 v[2:3], v[8:9], v[0:1]
	v_cvt_pk_bf16_f32 v0, v4, v5
	v_cvt_pk_bf16_f32 v1, v6, v7
	s_nop 0
	v_cvt_pk_bf16_f32 v2, v2, v3
	v_cvt_pk_bf16_f32 v3, v10, v11
	global_store_dwordx4 v[22:23], v[0:3], off
	s_cbranch_vccz .LBB0_1199
	s_waitcnt vmcnt(0)
	s_cmpk_gt_u32 s23, 0xff
	s_cbranch_scc1 .LBB0_1206
	s_barrier

; #define PG8_STAGE(bufoff, gbase, voff) do { _Pragma("unroll") for (int _i = 0; _i < 2; ++_i) \
;         __builtin_amdgcn_global_load_lds((const unsigned*)((const char*)(gbase) + (voff)[_i]), (PG8_LAS unsigned*)(lds + (bufoff) + ldsw + _i * 8192), 16, 0, 0); } while (0)
; #define PG8_LDA(dst, b, h) do { _Pragma("unroll") for (int m = 0; m < 4; ++m) _Pragma("unroll") for (int k = 0; k < 2; ++k) dst[m][k] = *(const PG8_LAS bf16x8*)(lds + PG8_SA(b, h) + aoff + m * 2048 + k * 1024); } while (0)
; #define PG8_LDB(dst, b, h) do { _Pragma("unroll") for (int n = 0; n < 2; ++n) _Pragma("unroll") for (int k = 0; k < 2; ++k) dst[n][k] = *(const PG8_LAS bf16x8*)(lds + PG8_SB(b, h) + boff + n * 2048 + k * 1024); } while (0)
; #define PG8_MMA(ai, bj, At, Bt) do { __builtin_amdgcn_s_setprio(1); _Pragma("unroll") for (int m = 0; m < 4; ++m) _Pragma("unroll") for (int n = 0; n < 2; ++n) _Pragma("unroll") for (int k = 0; k < 2; ++k) \
;         acc[ai][bj][m][n] = __builtin_amdgcn_mfma_f32_16x16x32_bf16(Bt[n][k], At[m][k], acc[ai][bj][m][n], 0, 0, 0); __builtin_amdgcn_s_setprio(0); } while (0)
; #define PG8_WAIT_L(n) asm volatile("s_waitcnt lgkmcnt(" #n ")" ::: "memory")
; #define PG8_BAR __builtin_amdgcn_s_barrier()
; #define PG8_SCHED __builtin_amdgcn_sched_barrier(0)
; template <class Epi, class Sched>
; __device__ __forceinline__ void gemm_phase(PG8_LAS unsigned char* lds, const Gemm g, const Sched& S, const Epi& E) {
;     ...
;             const bool last = (t == nt - 2);
;             const char* a1 = cA + (size_t)(t + 1) * kstep;
;             const char* a2 = last ? nA : cA + (size_t)(t + 2) * kstep; const char* b2 = last ? nB : cB + (size_t)(t + 2) * kstep;
;             const char* a3 = a2 + kstep; const char* b3 = b2 + kstep;
;             if (last && has_next) S.a_ready(nxt);
;             PG8_LDB(B0, 0, 0); PG8_SCHED; PG8_LDA(At, 0, 0); PG8_STAGE(PG8_SA(1, 1), a1 + hstep, voffA);
;             PG8_WAIT_L(8); PG8_BAR; PG8_WAIT_L(0); PG8_MMA(0, 0, At, B0); PG8_BAR; PG8_SCHED;
;             PG8_LDB(B1, 0, 1); PG8_STAGE(PG8_SB(0, 0), b2, voffB);
;             PG8_BAR; PG8_WAIT_L(0); PG8_MMA(0, 1, At, B1); PG8_BAR;
;             PG8_LDA(At, 0, 1); PG8_STAGE(PG8_SA(0, 0), a2, voffA);
;             PG8_BAR; PG8_WAIT_L(0); PG8_MMA(1, 0, At, B0); PG8_BAR; PG8_SCHED;
.LBB0_1278:
	ds_read_b128 v[152:155], v149
	ds_read_b128 v[156:159], v149 offset:1024
	ds_read_b128 v[160:163], v149 offset:2048
	ds_read_b128 v[164:167], v149 offset:3072
	s_add_u32 s20, s18, 0x100
	s_addc_u32 s21, s19, 0
	s_cmp_eq_u32 s54, 40
	s_cselect_b32 s25, s1, s21
	s_cselect_b32 s24, s0, s20
	s_cselect_b32 s23, s5, s53
	s_cselect_b32 s22, s4, s52
	v_lshl_add_u64 v[144:145], s[18:19], 0, v[136:137]
	s_add_i32 m0, s34, 0xc000
	ds_read_b128 v[168:171], v150
	ds_read_b128 v[172:175], v150 offset:1024
	ds_read_b128 v[182:185], v150 offset:2048
	ds_read_b128 v[190:193], v150 offset:3072
	ds_read_b128 v[194:197], v150 offset:4096
	ds_read_b128 v[198:201], v150 offset:5120
	ds_read_b128 v[202:205], v150 offset:6144
	ds_read_b128 v[206:209], v150 offset:7168
	global_load_lds_dwordx4 v[144:145], off
	v_lshl_add_u64 v[144:145], s[18:19], 0, v[138:139]
	s_add_i32 m0, s34, 0xe000
	s_nop 0
	global_load_lds_dwordx4 v[144:145], off
	s_waitcnt lgkmcnt(8)
	s_barrier
	s_waitcnt lgkmcnt(0)
	s_setprio 0
	s_waitcnt lgkmcnt(0)
	v_mfma_f32_16x16x32_bf16 v[124:127], v[152:155], v[168:171], v[124:127]
	v_mfma_f32_16x16x32_bf16 v[120:123], v[160:163], v[168:171], v[120:123]
	v_mfma_f32_16x16x32_bf16 v[108:111], v[152:155], v[182:185], v[108:111]
	v_mfma_f32_16x16x32_bf16 v[104:107], v[160:163], v[182:185], v[104:107]
	v_mfma_f32_16x16x32_bf16 v[92:95], v[152:155], v[194:197], v[92:95]
	v_mfma_f32_16x16x32_bf16 v[88:91], v[160:163], v[194:197], v[88:91]
	v_mfma_f32_16x16x32_bf16 v[76:79], v[152:155], v[202:205], v[76:79]
	v_mfma_f32_16x16x32_bf16 v[72:75], v[160:163], v[202:205], v[72:75]
	v_mfma_f32_16x16x32_bf16 v[124:127], v[156:159], v[172:175], v[124:127]
	v_mfma_f32_16x16x32_bf16 v[120:123], v[164:167], v[172:175], v[120:123]
	v_mfma_f32_16x16x32_bf16 v[108:111], v[156:159], v[190:193], v[108:111]
	v_mfma_f32_16x16x32_bf16 v[104:107], v[164:167], v[190:193], v[104:107]
	v_mfma_f32_16x16x32_bf16 v[92:95], v[156:159], v[198:201], v[92:95]
	v_mfma_f32_16x16x32_bf16 v[88:91], v[164:167], v[198:201], v[88:91]
	v_mfma_f32_16x16x32_bf16 v[76:79], v[156:159], v[206:209], v[76:79]
	v_mfma_f32_16x16x32_bf16 v[72:75], v[164:167], v[206:209], v[72:75]
	s_setprio 1
	s_barrier
	s_add_i32 s18, s42, s31
	v_lshl_add_u64 v[144:145], s[22:23], 0, v[130:131]
	s_mov_b32 m0, s18
	ds_read_b128 v[210:213], v151
	ds_read_b128 v[214:217], v151 offset:1024
	ds_read_b128 v[218:221], v151 offset:2048
	ds_read_b128 v[222:225], v151 offset:3072
	global_load_lds_dwordx4 v[144:145], off
	v_lshl_add_u64 v[186:187], s[22:23], 0, v[134:135]
	s_add_i32 m0, s18, 0x2000
	s_nop 0
	global_load_lds_dwordx4 v[186:187], off
	s_barrier
	s_waitcnt lgkmcnt(0)
	s_setprio 0
	s_waitcnt lgkmcnt(0)
	v_mfma_f32_16x16x32_bf16 v[116:119], v[210:213], v[168:171], v[116:119]
	v_mfma_f32_16x16x32_bf16 v[112:115], v[218:221], v[168:171], v[112:115]
	v_mfma_f32_16x16x32_bf16 v[100:103], v[210:213], v[182:185], v[100:103]
	v_mfma_f32_16x16x32_bf16 v[96:99], v[218:221], v[182:185], v[96:99]
	v_mfma_f32_16x16x32_bf16 v[84:87], v[210:213], v[194:197], v[84:87]
	v_mfma_f32_16x16x32_bf16 v[80:83], v[218:221], v[194:197], v[80:83]
	v_mfma_f32_16x16x32_bf16 v[68:71], v[210:213], v[202:205], v[68:71]
	v_mfma_f32_16x16x32_bf16 v[64:67], v[218:221], v[202:205], v[64:67]
	v_mfma_f32_16x16x32_bf16 v[116:119], v[214:217], v[172:175], v[116:119]
	v_mfma_f32_16x16x32_bf16 v[112:115], v[222:225], v[172:175], v[112:115]
	v_mfma_f32_16x16x32_bf16 v[100:103], v[214:217], v[190:193], v[100:103]
	v_mfma_f32_16x16x32_bf16 v[96:99], v[222:225], v[190:193], v[96:99]
	v_mfma_f32_16x16x32_bf16 v[84:87], v[214:217], v[198:201], v[84:87]
	v_mfma_f32_16x16x32_bf16 v[80:83], v[222:225], v[198:201], v[80:83]
	v_mfma_f32_16x16x32_bf16 v[68:71], v[214:217], v[206:209], v[68:71]
	v_mfma_f32_16x16x32_bf16 v[64:67], v[222:225], v[206:209], v[64:67]
	s_setprio 1
	s_mov_b32 m0, s34
	v_lshl_add_u64 v[226:227], s[24:25], 0, v[128:129]
	s_barrier
	ds_read_b128 v[168:171], v150 offset:16384
	ds_read_b128 v[172:175], v150 offset:17408
	ds_read_b128 v[182:185], v150 offset:18432
	ds_read_b128 v[190:193], v150 offset:19456
	ds_read_b128 v[194:197], v150 offset:20480
	ds_read_b128 v[198:201], v150 offset:21504
	ds_read_b128 v[202:205], v150 offset:22528
	ds_read_b128 v[206:209], v150 offset:23552
	global_load_lds_dwordx4 v[226:227], off
	v_lshl_add_u64 v[228:229], s[24:25], 0, v[132:133]
	s_mov_b32 m0, s35
	s_nop 0
	global_load_lds_dwordx4 v[228:229], off
	s_barrier
	s_waitcnt lgkmcnt(0)
	s_setprio 0
	s_waitcnt lgkmcnt(0)
	v_mfma_f32_16x16x32_bf16 v[60:63], v[152:155], v[168:171], v[60:63]
	v_mfma_f32_16x16x32_bf16 v[56:59], v[160:163], v[168:171], v[56:59]
	v_mfma_f32_16x16x32_bf16 v[48:51], v[152:155], v[182:185], v[48:51]
	v_mfma_f32_16x16x32_bf16 v[40:43], v[160:163], v[182:185], v[40:43]
	v_mfma_f32_16x16x32_bf16 v[32:35], v[152:155], v[194:197], v[32:35]
	v_mfma_f32_16x16x32_bf16 v[24:27], v[160:163], v[194:197], v[24:27]
	v_mfma_f32_16x16x32_bf16 v[16:19], v[152:155], v[202:205], v[16:19]
	v_mfma_f32_16x16x32_bf16 v[8:11], v[160:163], v[202:205], v[8:11]
	v_mfma_f32_16x16x32_bf16 v[60:63], v[156:159], v[172:175], v[60:63]
	v_mfma_f32_16x16x32_bf16 v[56:59], v[164:167], v[172:175], v[56:59]
	v_mfma_f32_16x16x32_bf16 v[48:51], v[156:159], v[190:193], v[48:51]
	v_mfma_f32_16x16x32_bf16 v[40:43], v[164:167], v[190:193], v[40:43]
	v_mfma_f32_16x16x32_bf16 v[32:35], v[156:159], v[198:201], v[32:35]
	v_mfma_f32_16x16x32_bf16 v[24:27], v[164:167], v[198:201], v[24:27]
	v_mfma_f32_16x16x32_bf16 v[16:19], v[156:159], v[206:209], v[16:19]
	v_mfma_f32_16x16x32_bf16 v[8:11], v[164:167], v[206:209], v[8:11]
	s_setprio 1
	s_barrier
; #define PG8_STAGE(bufoff, gbase, voff) do { _Pragma("unroll") for (int _i = 0; _i < 2; ++_i) \
;         __builtin_amdgcn_global_load_lds((const unsigned*)((const char*)(gbase) + (voff)[_i]), (PG8_LAS unsigned*)(lds + (bufoff) + ldsw + _i * 8192), 16, 0, 0); } while (0)
; #define PG8_LDA(dst, b, h) do { _Pragma("unroll") for (int m = 0; m < 4; ++m) _Pragma("unroll") for (int k = 0; k < 2; ++k) dst[m][k] = *(const PG8_LAS bf16x8*)(lds + PG8_SA(b, h) + aoff + m * 2048 + k * 1024); } while (0)
; #define PG8_LDB(dst, b, h) do { _Pragma("unroll") for (int n = 0; n < 2; ++n) _Pragma("unroll") for (int k = 0; k < 2; ++k) dst[n][k] = *(const PG8_LAS bf16x8*)(lds + PG8_SB(b, h) + boff + n * 2048 + k * 1024); } while (0)
; #define PG8_MMA(ai, bj, At, Bt) do { __builtin_amdgcn_s_setprio(1); _Pragma("unroll") for (int m = 0; m < 4; ++m) _Pragma("unroll") for (int n = 0; n < 2; ++n) _Pragma("unroll") for (int k = 0; k < 2; ++k) \
;         acc[ai][bj][m][n] = __builtin_amdgcn_mfma_f32_16x16x32_bf16(Bt[n][k], At[m][k], acc[ai][bj][m][n], 0, 0, 0); __builtin_amdgcn_s_setprio(0); } while (0)
; #define PG8_WAIT_V(n) asm volatile("s_waitcnt vmcnt(" #n ")" ::: "memory")
; #define PG8_WAIT_L(n) asm volatile("s_waitcnt lgkmcnt(" #n ")" ::: "memory")
; #define PG8_BAR __builtin_amdgcn_s_barrier()
; #define PG8_SCHED __builtin_amdgcn_sched_barrier(0)
; template <class Epi, class Sched>
; __device__ __forceinline__ void gemm_phase(PG8_LAS unsigned char* lds, const Gemm g, const Sched& S, const Epi& E) {
;     ...
;             PG8_STAGE(PG8_SB(0, 1), b2 + hstep, voffB);
;             PG8_WAIT_V(6); PG8_BAR; PG8_MMA(1, 1, At, B1); PG8_BAR;
;             PG8_LDB(B0, 1, 0); PG8_SCHED; PG8_LDA(At, 1, 0); PG8_STAGE(PG8_SA(0, 1), a2 + hstep, voffA);
;             PG8_WAIT_L(8); PG8_BAR; PG8_WAIT_L(0); PG8_MMA(0, 0, At, B0); PG8_BAR; PG8_SCHED;
;             PG8_LDB(B1, 1, 1); PG8_STAGE(PG8_SB(1, 0), b3, voffB);
;             PG8_BAR; PG8_WAIT_L(0); PG8_MMA(0, 1, At, B1); PG8_BAR;
;             PG8_LDA(At, 1, 1); PG8_STAGE(PG8_SA(1, 0), a3, voffA);
	s_add_u32 s18, s22, 0xb0000
	s_addc_u32 s19, s23, 0
	s_add_i32 s55, s43, s31
	v_lshl_add_u64 v[152:153], s[18:19], 0, v[130:131]
	s_mov_b32 m0, s55
	s_nop 0
	global_load_lds_dwordx4 v[152:153], off
	v_lshl_add_u64 v[152:153], s[18:19], 0, v[134:135]
	s_add_i32 m0, s55, 0x2000
	s_nop 0
	global_load_lds_dwordx4 v[152:153], off
	s_waitcnt vmcnt(6)
	s_barrier
	s_setprio 0
	v_mfma_f32_16x16x32_bf16 v[52:55], v[210:213], v[168:171], v[52:55]
	v_mfma_f32_16x16x32_bf16 v[44:47], v[218:221], v[168:171], v[44:47]
	v_mfma_f32_16x16x32_bf16 v[36:39], v[210:213], v[182:185], v[36:39]
	v_mfma_f32_16x16x32_bf16 v[28:31], v[218:221], v[182:185], v[28:31]
	v_mfma_f32_16x16x32_bf16 v[20:23], v[210:213], v[194:197], v[20:23]
	v_mfma_f32_16x16x32_bf16 v[12:15], v[218:221], v[194:197], v[12:15]
	v_mfma_f32_16x16x32_bf16 v[4:7], v[210:213], v[202:205], v[4:7]
	v_mfma_f32_16x16x32_bf16 v[0:3], v[218:221], v[202:205], v[0:3]
	v_mfma_f32_16x16x32_bf16 v[52:55], v[214:217], v[172:175], v[52:55]
	v_mfma_f32_16x16x32_bf16 v[44:47], v[222:225], v[172:175], v[44:47]
	v_mfma_f32_16x16x32_bf16 v[36:39], v[214:217], v[190:193], v[36:39]
	v_mfma_f32_16x16x32_bf16 v[28:31], v[222:225], v[190:193], v[28:31]
	v_mfma_f32_16x16x32_bf16 v[20:23], v[214:217], v[198:201], v[20:23]
	v_mfma_f32_16x16x32_bf16 v[12:15], v[222:225], v[198:201], v[12:15]
	v_mfma_f32_16x16x32_bf16 v[4:7], v[214:217], v[206:209], v[4:7]
	v_mfma_f32_16x16x32_bf16 v[0:3], v[222:225], v[206:209], v[0:3]
	s_setprio 1
	s_add_i32 s55, 0, 0x18000
	v_add_u32_e32 v164, s55, v147
	s_barrier
	ds_read_b128 v[152:155], v164
	ds_read_b128 v[156:159], v164 offset:1024
	ds_read_b128 v[160:163], v164 offset:2048
	ds_read_b128 v[164:167], v164 offset:3072
	s_add_u32 s18, s24, 0xb0000
	s_addc_u32 s19, s25, 0
	s_mov_b32 m0, s36
	v_lshl_add_u64 v[210:211], s[18:19], 0, v[128:129]
	ds_read_b128 v[168:171], v150 offset:32768
	ds_read_b128 v[172:175], v150 offset:33792
	ds_read_b128 v[182:185], v150 offset:34816
	ds_read_b128 v[190:193], v150 offset:35840
	ds_read_b128 v[194:197], v150 offset:36864
	ds_read_b128 v[198:201], v150 offset:37888
	ds_read_b128 v[202:205], v150 offset:38912
	ds_read_b128 v[206:209], v150 offset:39936
	global_load_lds_dwordx4 v[210:211], off
	v_lshl_add_u64 v[210:211], s[18:19], 0, v[132:133]
	s_mov_b32 m0, s37
	s_nop 0
	global_load_lds_dwordx4 v[210:211], off
	s_waitcnt lgkmcnt(8)
	s_barrier
	s_waitcnt lgkmcnt(0)
	s_setprio 0
	s_waitcnt lgkmcnt(0)
	v_mfma_f32_16x16x32_bf16 v[124:127], v[152:155], v[168:171], v[124:127]
	v_mfma_f32_16x16x32_bf16 v[120:123], v[160:163], v[168:171], v[120:123]
	v_mfma_f32_16x16x32_bf16 v[108:111], v[152:155], v[182:185], v[108:111]
	v_mfma_f32_16x16x32_bf16 v[104:107], v[160:163], v[182:185], v[104:107]
	v_mfma_f32_16x16x32_bf16 v[92:95], v[152:155], v[194:197], v[92:95]
	v_mfma_f32_16x16x32_bf16 v[88:91], v[160:163], v[194:197], v[88:91]
	v_mfma_f32_16x16x32_bf16 v[76:79], v[152:155], v[202:205], v[76:79]
	v_mfma_f32_16x16x32_bf16 v[72:75], v[160:163], v[202:205], v[72:75]
	v_mfma_f32_16x16x32_bf16 v[124:127], v[156:159], v[172:175], v[124:127]
	v_mfma_f32_16x16x32_bf16 v[120:123], v[164:167], v[172:175], v[120:123]
	v_mfma_f32_16x16x32_bf16 v[108:111], v[156:159], v[190:193], v[108:111]
	v_mfma_f32_16x16x32_bf16 v[104:107], v[164:167], v[190:193], v[104:107]
	v_mfma_f32_16x16x32_bf16 v[92:95], v[156:159], v[198:201], v[92:95]
	v_mfma_f32_16x16x32_bf16 v[88:91], v[164:167], v[198:201], v[88:91]
	v_mfma_f32_16x16x32_bf16 v[76:79], v[156:159], v[206:209], v[76:79]
	v_mfma_f32_16x16x32_bf16 v[72:75], v[164:167], v[206:209], v[72:75]
	s_setprio 1
	s_barrier
	s_add_i32 s24, 0, 0x1c000
	s_add_i32 s18, s55, s31
	v_add_u32_e32 v179, s24, v147
	v_lshl_add_u64 v[144:145], v[144:145], 0, s[8:9]
	s_mov_b32 m0, s18
	ds_read_b128 v[210:213], v179
	ds_read_b128 v[214:217], v179 offset:1024
	ds_read_b128 v[218:221], v179 offset:2048
	ds_read_b128 v[222:225], v179 offset:3072
	global_load_lds_dwordx4 v[144:145], off
	v_lshl_add_u64 v[144:145], v[186:187], 0, s[8:9]
	s_add_i32 m0, s18, 0x2000
	s_nop 0
	global_load_lds_dwordx4 v[144:145], off
	s_barrier
	s_waitcnt lgkmcnt(0)
	s_setprio 0
	s_waitcnt lgkmcnt(0)
	v_mfma_f32_16x16x32_bf16 v[116:119], v[210:213], v[168:171], v[116:119]
	v_mfma_f32_16x16x32_bf16 v[112:115], v[218:221], v[168:171], v[112:115]
	v_mfma_f32_16x16x32_bf16 v[100:103], v[210:213], v[182:185], v[100:103]
	v_mfma_f32_16x16x32_bf16 v[96:99], v[218:221], v[182:185], v[96:99]
	v_mfma_f32_16x16x32_bf16 v[84:87], v[210:213], v[194:197], v[84:87]
	v_mfma_f32_16x16x32_bf16 v[80:83], v[218:221], v[194:197], v[80:83]
	v_mfma_f32_16x16x32_bf16 v[68:71], v[210:213], v[202:205], v[68:71]
	v_mfma_f32_16x16x32_bf16 v[64:67], v[218:221], v[202:205], v[64:67]
	v_mfma_f32_16x16x32_bf16 v[116:119], v[214:217], v[172:175], v[116:119]
	v_mfma_f32_16x16x32_bf16 v[112:115], v[222:225], v[172:175], v[112:115]
	v_mfma_f32_16x16x32_bf16 v[100:103], v[214:217], v[190:193], v[100:103]
	v_mfma_f32_16x16x32_bf16 v[96:99], v[222:225], v[190:193], v[96:99]
	v_mfma_f32_16x16x32_bf16 v[84:87], v[214:217], v[198:201], v[84:87]
	v_mfma_f32_16x16x32_bf16 v[80:83], v[222:225], v[198:201], v[80:83]
	v_mfma_f32_16x16x32_bf16 v[68:71], v[214:217], v[206:209], v[68:71]
	v_mfma_f32_16x16x32_bf16 v[64:67], v[222:225], v[206:209], v[64:67]
	s_setprio 1
	s_mov_b32 m0, s39
	v_lshl_add_u64 v[144:145], v[226:227], 0, s[8:9]
	s_barrier
	ds_read_b128 v[168:171], v150 offset:49152
	ds_read_b128 v[172:175], v150 offset:50176
	ds_read_b128 v[182:185], v150 offset:51200
	ds_read_b128 v[190:193], v150 offset:52224
	ds_read_b128 v[194:197], v150 offset:53248
	ds_read_b128 v[198:201], v150 offset:54272
	ds_read_b128 v[202:205], v150 offset:55296
	ds_read_b128 v[206:209], v150 offset:56320
	global_load_lds_dwordx4 v[144:145], off
	v_lshl_add_u64 v[144:145], v[228:229], 0, s[8:9]
	s_mov_b32 m0, s40
	s_nop 0
	global_load_lds_dwordx4 v[144:145], off
	s_barrier
; __device__ __forceinline__ unsigned cvt_pk_bf16(float lo, float hi) { unsigned r; asm volatile("v_cvt_pk_bf16_f32 %0, %1, %2" : "=v"(r) : "v"(lo), "v"(hi)); return r; }
; __device__ __forceinline__ float flogsig16(float x) { return (fminf(x, 0.f) - __logf(1.0f + __expf(-fabsf(x)))) * 0.0625f; }
; #define PG8_WAIT_V(n) asm volatile("s_waitcnt vmcnt(" #n ")" ::: "memory")
; #define PG8_WAIT_L(n) asm volatile("s_waitcnt lgkmcnt(" #n ")" ::: "memory")
;     __device__ __forceinline__ void operator()(const f32x4 (&acc)[2][2][4][2], const Unit& u, int wr, int wc, int fr, int fq) const {
;     ...
;         const int row0 = u.pm * BM + wr * 64 + fr, col0 = u.pn * BM + wc * 32 + 8 * fq, bcol0 = wc * 32 + 8 * fq;
;         f32x4 bv[2][2];
; #pragma unroll
;         for (int bj = 0; bj < 2; ++bj)
; #pragma unroll
;             for (int n = 0; n < 2; ++n) bv[bj][n] = bias ? *(const f32x4*)(bias + bcol0 + bj * HALF + 4 * n) : (f32x4){0.f, 0.f, 0.f, 0.f};
; #pragma unroll
;         for (int ai = 0; ai < 2; ++ai)
; #pragma unroll
;             for (int m = 0; m < 4; ++m) { bf16_t* rowp = O + (size_t)(row0 + ai * HALF + m * 16) * ldc + col0;
; #pragma unroll
;                 for (int bj = 0; bj < 2; ++bj) { f32x4 v0 = acc[ai][bj][m][0] + bv[bj][0], v1 = acc[ai][bj][m][1] + bv[bj][1];
;                     if (act == 1) {
; #pragma unroll
;                         for (int j = 0; j < 1; ++j) { v0 = v0 * sigmoid4(v0); v1 = v1 * sigmoid4(v1); } }
;                     else if (act == 2) {
; #pragma unroll
;                         for (int j = 0; j < 1; ++j) { v0 = sigmoid4(v0); v1 = sigmoid4(v1); } }
;                     else if (act == 3) {
; #pragma unroll
;                         for (int j = 0; j < 4; ++j) { v0[j] = flogsig16(v0[j]); v1[j] = flogsig16(v1[j]); } }
;                     u32x4 w; w.x = cvt_pk_bf16(v0[0], v0[1]); w.y = cvt_pk_bf16(v0[2], v0[3]); w.z = cvt_pk_bf16(v1[0], v1[1]); w.w = cvt_pk_bf16(v1[2], v1[3]);
;                     *(u32x4*)(rowp + bj * HALF) = w; } }
; template <class Epi, class Sched>
; __device__ __forceinline__ void gemm_phase(PG8_LAS unsigned char* lds, const Gemm g, const Sched& S, const Epi& E) {
;     ...
;             PG8_BAR; PG8_WAIT_L(0); PG8_MMA(1, 0, At, B0); PG8_BAR; PG8_SCHED;
;             PG8_STAGE(PG8_SB(1, 1), b3 + hstep, voffB);
;             PG8_WAIT_V(6); PG8_BAR; PG8_MMA(1, 1, At, B1); PG8_BAR;
	s_waitcnt lgkmcnt(0)
	s_setprio 0
	s_waitcnt lgkmcnt(0)
	v_mfma_f32_16x16x32_bf16 v[60:63], v[152:155], v[168:171], v[60:63]
	v_mfma_f32_16x16x32_bf16 v[56:59], v[160:163], v[168:171], v[56:59]
	v_mfma_f32_16x16x32_bf16 v[48:51], v[152:155], v[182:185], v[48:51]
	v_mfma_f32_16x16x32_bf16 v[40:43], v[160:163], v[182:185], v[40:43]
	v_mfma_f32_16x16x32_bf16 v[32:35], v[152:155], v[194:197], v[32:35]
	v_mfma_f32_16x16x32_bf16 v[24:27], v[160:163], v[194:197], v[24:27]
	v_mfma_f32_16x16x32_bf16 v[16:19], v[152:155], v[202:205], v[16:19]
	v_mfma_f32_16x16x32_bf16 v[8:11], v[160:163], v[202:205], v[8:11]
	v_mfma_f32_16x16x32_bf16 v[60:63], v[156:159], v[172:175], v[60:63]
	v_mfma_f32_16x16x32_bf16 v[56:59], v[164:167], v[172:175], v[56:59]
	v_mfma_f32_16x16x32_bf16 v[48:51], v[156:159], v[190:193], v[48:51]
	v_mfma_f32_16x16x32_bf16 v[40:43], v[164:167], v[190:193], v[40:43]
	v_mfma_f32_16x16x32_bf16 v[32:35], v[156:159], v[198:201], v[32:35]
	v_mfma_f32_16x16x32_bf16 v[24:27], v[164:167], v[198:201], v[24:27]
	v_mfma_f32_16x16x32_bf16 v[16:19], v[156:159], v[206:209], v[16:19]
	v_mfma_f32_16x16x32_bf16 v[8:11], v[164:167], v[206:209], v[8:11]
	s_setprio 1
	s_barrier
	s_add_u32 s18, s22, 0xb0080
	s_addc_u32 s19, s23, 0
	s_add_i32 s22, s24, s31
	v_lshl_add_u64 v[144:145], s[18:19], 0, v[130:131]
	s_mov_b32 m0, s22
	s_nop 0
	global_load_lds_dwordx4 v[144:145], off
	v_lshl_add_u64 v[144:145], s[18:19], 0, v[134:135]
	s_add_i32 m0, s22, 0x2000
	s_nop 0
	global_load_lds_dwordx4 v[144:145], off
	s_waitcnt vmcnt(6)
	s_barrier
	s_setprio 0
	v_mfma_f32_16x16x32_bf16 v[52:55], v[210:213], v[168:171], v[52:55]
	v_mfma_f32_16x16x32_bf16 v[44:47], v[218:221], v[168:171], v[44:47]
	v_mfma_f32_16x16x32_bf16 v[36:39], v[210:213], v[182:185], v[36:39]
	v_mfma_f32_16x16x32_bf16 v[28:31], v[218:221], v[182:185], v[28:31]
	v_mfma_f32_16x16x32_bf16 v[20:23], v[210:213], v[194:197], v[20:23]
	v_mfma_f32_16x16x32_bf16 v[12:15], v[218:221], v[194:197], v[12:15]
	v_mfma_f32_16x16x32_bf16 v[4:7], v[210:213], v[202:205], v[4:7]
	v_mfma_f32_16x16x32_bf16 v[0:3], v[218:221], v[202:205], v[0:3]
	v_mfma_f32_16x16x32_bf16 v[52:55], v[214:217], v[172:175], v[52:55]
	v_mfma_f32_16x16x32_bf16 v[44:47], v[222:225], v[172:175], v[44:47]
	v_mfma_f32_16x16x32_bf16 v[36:39], v[214:217], v[190:193], v[36:39]
	v_mfma_f32_16x16x32_bf16 v[28:31], v[222:225], v[190:193], v[28:31]
	v_mfma_f32_16x16x32_bf16 v[20:23], v[214:217], v[198:201], v[20:23]
	v_mfma_f32_16x16x32_bf16 v[12:15], v[222:225], v[198:201], v[12:15]
	v_mfma_f32_16x16x32_bf16 v[4:7], v[214:217], v[206:209], v[4:7]
	v_mfma_f32_16x16x32_bf16 v[0:3], v[222:225], v[206:209], v[0:3]
	s_setprio 1
	s_add_i32 s54, s54, 2
	s_add_u32 s52, s52, 0x100
	s_addc_u32 s53, s53, 0
	s_cmp_gt_u32 s54, 41
	s_mov_b64 s[18:19], s[20:21]
	s_barrier
	s_cbranch_scc0 .LBB0_1278
	v_lshl_add_u32 v152, s50, 8, v146
	v_lshl_or_b32 v144, s51, 8, v148
	v_ashrrev_i32_e32 v153, 31, v152
	v_ashrrev_i32_e32 v145, 31, v144
	v_lshlrev_b64 v[154:155], 11, v[152:153]
	v_lshl_add_u64 v[154:155], s[6:7], 0, v[154:155]
	v_lshlrev_b64 v[156:157], 1, v[144:145]
	v_lshl_add_u64 v[144:145], v[154:155], 0, v[156:157]
	v_pk_add_f32 v[126:127], v[126:127], 0 op_sel_hi:[1,0]
	v_pk_add_f32 v[124:125], v[124:125], 0 op_sel_hi:[1,0]
	v_pk_add_f32 v[154:155], v[122:123], 0 op_sel_hi:[1,0]
	v_pk_add_f32 v[122:123], v[120:121], 0 op_sel_hi:[1,0]
	v_cvt_pk_bf16_f32 v120, v124, v125
	v_cvt_pk_bf16_f32 v121, v126, v127
	v_pk_add_f32 v[116:117], v[116:117], 0 op_sel_hi:[1,0]
	v_cvt_pk_bf16_f32 v122, v122, v123
	v_cvt_pk_bf16_f32 v123, v154, v155
	global_store_dwordx4 v[144:145], v[120:123], off
	v_pk_add_f32 v[118:119], v[118:119], 0 op_sel_hi:[1,0]
	v_pk_add_f32 v[110:111], v[110:111], 0 op_sel_hi:[1,0]
	v_pk_add_f32 v[120:121], v[114:115], 0 op_sel_hi:[1,0]
	v_pk_add_f32 v[114:115], v[112:113], 0 op_sel_hi:[1,0]
	v_cvt_pk_bf16_f32 v112, v116, v117
	v_cvt_pk_bf16_f32 v113, v118, v119
	v_pk_add_f32 v[108:109], v[108:109], 0 op_sel_hi:[1,0]
	v_cvt_pk_bf16_f32 v114, v114, v115
	v_cvt_pk_bf16_f32 v115, v120, v121
	global_store_dwordx4 v[144:145], v[112:115], off offset:256
	v_pk_add_f32 v[100:101], v[100:101], 0 op_sel_hi:[1,0]
	v_pk_add_f32 v[102:103], v[102:103], 0 op_sel_hi:[1,0]
	v_or_b32_e32 v112, 16, v152
	v_ashrrev_i32_e32 v113, 31, v112
	v_lshlrev_b64 v[112:113], 11, v[112:113]
	v_lshl_add_u64 v[112:113], s[6:7], 0, v[112:113]
	v_lshl_add_u64 v[112:113], v[112:113], 0, v[156:157]
	v_pk_add_f32 v[114:115], v[106:107], 0 op_sel_hi:[1,0]
	v_pk_add_f32 v[106:107], v[104:105], 0 op_sel_hi:[1,0]
	v_cvt_pk_bf16_f32 v104, v108, v109
	v_cvt_pk_bf16_f32 v105, v110, v111
	v_pk_add_f32 v[94:95], v[94:95], 0 op_sel_hi:[1,0]
	v_cvt_pk_bf16_f32 v106, v106, v107
	v_cvt_pk_bf16_f32 v107, v114, v115
	global_store_dwordx4 v[112:113], v[104:107], off
	v_pk_add_f32 v[92:93], v[92:93], 0 op_sel_hi:[1,0]
	v_pk_add_f32 v[84:85], v[84:85], 0 op_sel_hi:[1,0]
	v_pk_add_f32 v[104:105], v[98:99], 0 op_sel_hi:[1,0]
	v_pk_add_f32 v[98:99], v[96:97], 0 op_sel_hi:[1,0]
	v_cvt_pk_bf16_f32 v96, v100, v101
	v_cvt_pk_bf16_f32 v97, v102, v103
	v_pk_add_f32 v[86:87], v[86:87], 0 op_sel_hi:[1,0]
	v_cvt_pk_bf16_f32 v98, v98, v99
	v_cvt_pk_bf16_f32 v99, v104, v105
	global_store_dwordx4 v[112:113], v[96:99], off offset:256
	v_pk_add_f32 v[78:79], v[78:79], 0 op_sel_hi:[1,0]
	v_pk_add_f32 v[76:77], v[76:77], 0 op_sel_hi:[1,0]
	v_or_b32_e32 v96, 32, v152
	v_ashrrev_i32_e32 v97, 31, v96
	v_lshlrev_b64 v[96:97], 11, v[96:97]
	v_lshl_add_u64 v[96:97], s[6:7], 0, v[96:97]
; __device__ __forceinline__ unsigned cvt_pk_bf16(float lo, float hi) { unsigned r; asm volatile("v_cvt_pk_bf16_f32 %0, %1, %2" : "=v"(r) : "v"(lo), "v"(hi)); return r; }
; __device__ __forceinline__ float flogsig16(float x) { return (fminf(x, 0.f) - __logf(1.0f + __expf(-fabsf(x)))) * 0.0625f; }
; #define PG8_WAIT_V(n) asm volatile("s_waitcnt vmcnt(" #n ")" ::: "memory")
; #define PG8_BAR __builtin_amdgcn_s_barrier()
;     __device__ __forceinline__ void operator()(const f32x4 (&acc)[2][2][4][2], const Unit& u, int wr, int wc, int fr, int fq) const {
;     ...
;             for (int m = 0; m < 4; ++m) { bf16_t* rowp = O + (size_t)(row0 + ai * HALF + m * 16) * ldc + col0;
; #pragma unroll
;                 for (int bj = 0; bj < 2; ++bj) { f32x4 v0 = acc[ai][bj][m][0] + bv[bj][0], v1 = acc[ai][bj][m][1] + bv[bj][1];
;                     if (act == 1) {
; #pragma unroll
;                         for (int j = 0; j < 1; ++j) { v0 = v0 * sigmoid4(v0); v1 = v1 * sigmoid4(v1); } }
;                     else if (act == 2) {
; #pragma unroll
;                         for (int j = 0; j < 1; ++j) { v0 = sigmoid4(v0); v1 = sigmoid4(v1); } }
;                     else if (act == 3) {
; #pragma unroll
;                         for (int j = 0; j < 4; ++j) { v0[j] = flogsig16(v0[j]); v1[j] = flogsig16(v1[j]); } }
;                     u32x4 w; w.x = cvt_pk_bf16(v0[0], v0[1]); w.y = cvt_pk_bf16(v0[2], v0[3]); w.z = cvt_pk_bf16(v1[0], v1[1]); w.w = cvt_pk_bf16(v1[2], v1[3]);
;                     *(u32x4*)(rowp + bj * HALF) = w; } }
; template <class Epi, class Sched>
; __device__ __forceinline__ void gemm_phase(PG8_LAS unsigned char* lds, const Gemm g, const Sched& S, const Epi& E) {
;     ...
;         if constexpr (!Epi::AFTER_DRAIN) { E(acc, cur, wr, wc, fr, fq); S.done(cur); }
;         if (!has_next) break;
; #pragma unroll
;         for (int a = 0; a < 2; ++a)
; #pragma unroll
;             for (int b = 0; b < 2; ++b)
; #pragma unroll
;                 for (int m = 0; m < 4; ++m)
; #pragma unroll
;                     for (int n = 0; n < 2; ++n) acc[a][b][m][n] = (f32x4){0.f, 0.f, 0.f, 0.f};
;         cur = nxt; cA = nA; cB = nB; ++ui;
;     }
;     PG8_WAIT_V(0);
;     if (wr == 0) PG8_BAR;
;     PG8_BAR;
	v_lshl_add_u64 v[96:97], v[96:97], 0, v[156:157]
	v_pk_add_f32 v[98:99], v[90:91], 0 op_sel_hi:[1,0]
	v_pk_add_f32 v[90:91], v[88:89], 0 op_sel_hi:[1,0]
	v_cvt_pk_bf16_f32 v88, v92, v93
	v_cvt_pk_bf16_f32 v89, v94, v95
	v_pk_add_f32 v[70:71], v[70:71], 0 op_sel_hi:[1,0]
	v_cvt_pk_bf16_f32 v90, v90, v91
	v_cvt_pk_bf16_f32 v91, v98, v99
	global_store_dwordx4 v[96:97], v[88:91], off
	v_pk_add_f32 v[68:69], v[68:69], 0 op_sel_hi:[1,0]
	v_pk_add_f32 v[60:61], v[60:61], 0 op_sel_hi:[1,0]
	v_pk_add_f32 v[88:89], v[82:83], 0 op_sel_hi:[1,0]
	v_pk_add_f32 v[82:83], v[80:81], 0 op_sel_hi:[1,0]
	v_cvt_pk_bf16_f32 v80, v84, v85
	v_cvt_pk_bf16_f32 v81, v86, v87
	v_pk_add_f32 v[62:63], v[62:63], 0 op_sel_hi:[1,0]
	v_cvt_pk_bf16_f32 v82, v82, v83
	v_cvt_pk_bf16_f32 v83, v88, v89
	global_store_dwordx4 v[96:97], v[80:83], off offset:256
	v_pk_add_f32 v[54:55], v[54:55], 0 op_sel_hi:[1,0]
	v_pk_add_f32 v[52:53], v[52:53], 0 op_sel_hi:[1,0]
	v_or_b32_e32 v80, 48, v152
	v_ashrrev_i32_e32 v81, 31, v80
	v_lshlrev_b64 v[80:81], 11, v[80:81]
	v_lshl_add_u64 v[80:81], s[6:7], 0, v[80:81]
	v_lshl_add_u64 v[80:81], v[80:81], 0, v[156:157]
	v_pk_add_f32 v[82:83], v[74:75], 0 op_sel_hi:[1,0]
	v_pk_add_f32 v[74:75], v[72:73], 0 op_sel_hi:[1,0]
	v_cvt_pk_bf16_f32 v72, v76, v77
	v_cvt_pk_bf16_f32 v73, v78, v79
	v_pk_add_f32 v[48:49], v[48:49], 0 op_sel_hi:[1,0]
	v_cvt_pk_bf16_f32 v74, v74, v75
	v_cvt_pk_bf16_f32 v75, v82, v83
	global_store_dwordx4 v[80:81], v[72:75], off
	v_pk_add_f32 v[38:39], v[38:39], 0 op_sel_hi:[1,0]
	v_pk_add_f32 v[36:37], v[36:37], 0 op_sel_hi:[1,0]
	v_pk_add_f32 v[72:73], v[66:67], 0 op_sel_hi:[1,0]
	v_pk_add_f32 v[66:67], v[64:65], 0 op_sel_hi:[1,0]
	v_cvt_pk_bf16_f32 v64, v68, v69
	v_cvt_pk_bf16_f32 v65, v70, v71
	v_pk_add_f32 v[32:33], v[32:33], 0 op_sel_hi:[1,0]
	v_cvt_pk_bf16_f32 v66, v66, v67
	v_cvt_pk_bf16_f32 v67, v72, v73
	global_store_dwordx4 v[80:81], v[64:67], off offset:256
	v_pk_add_f32 v[22:23], v[22:23], 0 op_sel_hi:[1,0]
	v_pk_add_f32 v[20:21], v[20:21], 0 op_sel_hi:[1,0]
	v_pk_add_f32 v[66:67], v[58:59], 0 op_sel_hi:[1,0]
	v_pk_add_f32 v[58:59], v[56:57], 0 op_sel_hi:[1,0]
	v_cvt_pk_bf16_f32 v56, v60, v61
	v_add_co_u32_e32 v60, vcc, s44, v144
	v_cvt_pk_bf16_f32 v57, v62, v63
	v_cvt_pk_bf16_f32 v58, v58, v59
	v_cvt_pk_bf16_f32 v59, v66, v67
	v_lshl_add_u64 v[64:65], v[144:145], 0, s[10:11]
	s_nop 0
	v_addc_co_u32_e32 v61, vcc, 0, v145, vcc
	global_store_dwordx4 v[60:61], v[56:59], off
	v_pk_add_f32 v[16:17], v[16:17], 0 op_sel_hi:[1,0]
	s_mov_b32 s51, s48
	v_pk_add_f32 v[56:57], v[46:47], 0 op_sel_hi:[1,0]
	v_pk_add_f32 v[46:47], v[44:45], 0 op_sel_hi:[1,0]
	v_cvt_pk_bf16_f32 v44, v52, v53
	v_cvt_pk_bf16_f32 v45, v54, v55
	s_mov_b32 s50, s49
	v_cvt_pk_bf16_f32 v46, v46, v47
	v_cvt_pk_bf16_f32 v47, v56, v57
	global_store_dwordx4 v[64:65], v[44:47], off offset:256
	s_mov_b64 s[20:21], s[4:5]
	s_mov_b64 s[18:19], s[0:1]
	v_pk_add_f32 v[46:47], v[50:51], 0 op_sel_hi:[1,0]
	v_pk_add_f32 v[50:51], v[42:43], 0 op_sel_hi:[1,0]
	v_pk_add_f32 v[42:43], v[40:41], 0 op_sel_hi:[1,0]
	v_cvt_pk_bf16_f32 v40, v48, v49
	v_cvt_pk_bf16_f32 v41, v46, v47
	v_add_co_u32_e32 v46, vcc, s45, v144
	v_cvt_pk_bf16_f32 v42, v42, v43
	v_cvt_pk_bf16_f32 v43, v50, v51
	v_lshl_add_u64 v[44:45], v[144:145], 0, s[12:13]
	s_nop 0
	v_addc_co_u32_e32 v47, vcc, 0, v145, vcc
	global_store_dwordx4 v[46:47], v[40:43], off
	v_pk_add_f32 v[6:7], v[6:7], 0 op_sel_hi:[1,0]
	v_pk_add_f32 v[4:5], v[4:5], 0 op_sel_hi:[1,0]
	v_pk_add_f32 v[40:41], v[30:31], 0 op_sel_hi:[1,0]
	v_pk_add_f32 v[30:31], v[28:29], 0 op_sel_hi:[1,0]
	v_cvt_pk_bf16_f32 v28, v36, v37
	v_cvt_pk_bf16_f32 v29, v38, v39
	s_nop 0
	v_cvt_pk_bf16_f32 v30, v30, v31
	v_cvt_pk_bf16_f32 v31, v40, v41
	global_store_dwordx4 v[44:45], v[28:31], off offset:256
	s_nop 1
	v_pk_add_f32 v[30:31], v[34:35], 0 op_sel_hi:[1,0]
	v_pk_add_f32 v[34:35], v[26:27], 0 op_sel_hi:[1,0]
	v_pk_add_f32 v[26:27], v[24:25], 0 op_sel_hi:[1,0]
	v_cvt_pk_bf16_f32 v24, v32, v33
	v_cvt_pk_bf16_f32 v25, v30, v31
	v_add_co_u32_e32 v30, vcc, s46, v144
	v_cvt_pk_bf16_f32 v26, v26, v27
	v_cvt_pk_bf16_f32 v27, v34, v35
	v_lshl_add_u64 v[28:29], v[144:145], 0, s[14:15]
	s_nop 0
	v_addc_co_u32_e32 v31, vcc, 0, v145, vcc
	global_store_dwordx4 v[30:31], v[24:27], off
	s_nop 1
	v_pk_add_f32 v[24:25], v[14:15], 0 op_sel_hi:[1,0]
	v_pk_add_f32 v[14:15], v[12:13], 0 op_sel_hi:[1,0]
	v_cvt_pk_bf16_f32 v12, v20, v21
	v_cvt_pk_bf16_f32 v13, v22, v23
	s_nop 0
	v_cvt_pk_bf16_f32 v14, v14, v15
	v_cvt_pk_bf16_f32 v15, v24, v25
	global_store_dwordx4 v[28:29], v[12:15], off offset:256
	s_nop 1
	v_pk_add_f32 v[14:15], v[18:19], 0 op_sel_hi:[1,0]
	v_pk_add_f32 v[18:19], v[10:11], 0 op_sel_hi:[1,0]
	v_pk_add_f32 v[10:11], v[8:9], 0 op_sel_hi:[1,0]
	v_cvt_pk_bf16_f32 v8, v16, v17
	v_cvt_pk_bf16_f32 v9, v14, v15
	v_add_co_u32_e32 v14, vcc, s47, v144
	v_lshl_add_u64 v[12:13], v[144:145], 0, s[16:17]
	s_nop 0
	v_addc_co_u32_e32 v15, vcc, 0, v145, vcc
	v_cvt_pk_bf16_f32 v10, v10, v11
	v_cvt_pk_bf16_f32 v11, v18, v19
	global_store_dwordx4 v[14:15], v[8:11], off
	s_and_b64 vcc, exec, s[2:3]
	s_nop 0
	v_pk_add_f32 v[8:9], v[2:3], 0 op_sel_hi:[1,0]
	v_pk_add_f32 v[2:3], v[0:1], 0 op_sel_hi:[1,0]
	v_cvt_pk_bf16_f32 v0, v4, v5
	v_cvt_pk_bf16_f32 v1, v6, v7
	s_nop 0
	v_cvt_pk_bf16_f32 v2, v2, v3
	v_cvt_pk_bf16_f32 v3, v8, v9
	global_store_dwordx4 v[12:13], v[0:3], off offset:256
	s_cbranch_vccz .LBB0_1267
	s_waitcnt vmcnt(0)
	s_cmpk_gt_u32 s27, 0xff
	s_cbranch_scc1 .LBB0_1282
	s_barrier
